# speedup vs baseline: 1.0190x; 1.0070x over previous
;     DI size_t aoff(const Unit& u, size_t tstep) const { return (size_t)u.pm * tstep; }
;     DI size_t boff(const Unit& u, size_t tstep) const { return (size_t)u.pn * tstep; }
;     DI bool next(int i, Unit& u) const { const long L = (long)i * G + c; if (L >= np) return false; u.pm = pmv; u.pn = (int)(L % nN); u.ks = (int)(L / nN); return true; }
;     DI size_t aoff(const Unit& u, size_t) const { return (size_t)u.ks * kbytes; }
;     DI size_t boff(const Unit& u, size_t tstep) const { return (size_t)u.pn * tstep + (size_t)u.ks * kbytes; }
;     DI bool next(int i, Unit& u) const { Unit t; if (!S.next(i / 3, t)) return false; u.pm = t.pm; u.pn = t.pn; u.ks = i % 3; return true; }
;     DI size_t aoff(const Unit& u, size_t tstep) const { return (u.ks < 2 ? offU : offOA) + (size_t)u.pm * tstep; }
; #define PG8_LDA(dst, b, h) do { _Pragma("unroll") for (int m = 0; m < 4; ++m) _Pragma("unroll") for (int k = 0; k < 2; ++k) dst[m][k] = *(const LAS bf16x8*)(lds + PG8_SA(b, h) + aoff + m * 2048 + k * 1024); } while (0)
; template <class Epi, class Sched>
; DI void gemm_phase(LAS unsigned char* lds, const Gemm g, const Sched& S, const Epi& E) {
;     ...
;         const bool has_next = S.next(ui + 1, nxt);
;         const char* nA = has_next ? (const char*)g.A + S.aoff(nxt, tstep) : cA; const char* nB = has_next ? (const char*)g.Bt + S.boff(nxt, tstep) : cB;
;         for (int t = 0; t < nt; t += 2) {
;             if constexpr (Epi::HAS_MID) { if (t == E.mid_t(nt)) { int fr3 = fr, fq3 = fq; asm volatile("" : "+v"(fr3), "+v"(fq3)); E.mid(acc, cur, wr, wc, fr3, fq3); } }
;             const bool last = (t == nt - 2);
;             const char* a1 = cA + (size_t)(t + 1) * kstep;
;             const char* a2 = last ? nA : cA + (size_t)(t + 2) * kstep; const char* b2 = last ? nB : cB + (size_t)(t + 2) * kstep;
;             const char* a3 = a2 + kstep; const char* b3 = b2 + kstep;
;             PG8_LDB(B0, 0, 0); PG8_SCHED; PG8_LDA(At, 0, 0); PG8_STAGE(PG8_SA(1, 1), a1 + hstep, voffA);
;             PG8_WAIT_L(8); PG8_BAR; PG8_WAIT_L(0); PG8_MMA(0, 0, At, B0); PG8_BAR; PG8_SCHED;
;             PG8_LDB(B1, 0, 1); PG8_STAGE(PG8_SB(0, 0), b2, voffB);
;             PG8_BAR; PG8_WAIT_L(0); PG8_MMA(0, 1, At, B1); PG8_BAR;
;             PG8_LDA(At, 0, 1); PG8_STAGE(PG8_SA(0, 0), a2, voffA);
;             PG8_BAR; PG8_WAIT_L(0); PG8_MMA(1, 0, At, B0); PG8_BAR; PG8_SCHED;
.LBB0_218:
	s_ashr_i32 s17, s16, 31
	s_lshl_b64 s[0:1], s[16:17], 20
	v_cmp_lt_i64_e32 vcc, s[18:19], v[140:141]
	s_add_u32 s18, s47, s0
	s_addc_u32 s19, s48, s1
	s_and_b64 s[0:1], vcc, exec
	s_cselect_b32 s17, s19, s41
	s_cselect_b32 s65, s18, s40
	s_ashr_i32 s15, s14, 31
	s_lshl_b64 s[0:1], s[14:15], 20
	s_add_u32 s36, s49, s0
	s_addc_u32 s37, s50, s1
	s_and_b64 s[0:1], vcc, exec
	s_cselect_b32 s15, s37, s43
	s_cselect_b32 s66, s36, s42
	s_add_u32 s40, s40, 0x80080
	s_addc_u32 s41, s41, 0
	s_add_u32 s67, s42, 0x100
	v_mov_b32_e32 v0, 0
	s_addc_u32 s68, s43, 0
	s_mov_b32 s69, -2
	ds_read_b128 v[150:153], v147
	ds_read_b128 v[154:157], v147 offset:1024
	ds_read_b128 v[162:165], v147 offset:2048
	ds_read_b128 v[166:169], v147 offset:3072
	s_add_u32 s0, s40, 0xfff80080
	s_addc_u32 s1, s41, -1
	s_cmp_eq_u32 s69, 28
	s_cselect_b32 s45, s17, s1
	s_cselect_b32 s44, s65, s0
	s_cselect_b32 s43, s15, s68
	s_cselect_b32 s42, s66, s67
	s_add_i32 m0, s39, 0xc000
	ds_read_b128 v[170:173], v148
	ds_read_b128 v[174:177], v148 offset:1024
	ds_read_b128 v[178:181], v148 offset:2048
	ds_read_b128 v[188:191], v148 offset:3072
	ds_read_b128 v[194:197], v148 offset:4096
	ds_read_b128 v[198:201], v148 offset:5120
	ds_read_b128 v[202:205], v148 offset:6144
	global_load_lds_dwordx4 v136, s[40:41]
	s_add_i32 m0, s39, 0xe000
	ds_read_b128 v[206:209], v148 offset:7168
	global_load_lds_dwordx4 v138, s[40:41]
	s_waitcnt lgkmcnt(8)
	s_barrier
	s_waitcnt lgkmcnt(0)
	s_setprio 1
	v_mfma_f32_16x16x32_bf16 v[124:127], v[150:153], v[170:173], 0
	v_mfma_f32_16x16x32_bf16 v[120:123], v[162:165], v[170:173], 0
	v_mfma_f32_16x16x32_bf16 v[108:111], v[150:153], v[178:181], 0
	v_mfma_f32_16x16x32_bf16 v[104:107], v[162:165], v[178:181], 0
	v_mfma_f32_16x16x32_bf16 v[92:95], v[150:153], v[194:197], 0
	v_mfma_f32_16x16x32_bf16 v[88:91], v[162:165], v[194:197], 0
	v_mfma_f32_16x16x32_bf16 v[76:79], v[150:153], v[202:205], 0
	v_mfma_f32_16x16x32_bf16 v[72:75], v[162:165], v[202:205], 0
	v_mfma_f32_16x16x32_bf16 v[124:127], v[154:157], v[174:177], v[124:127]
	v_mfma_f32_16x16x32_bf16 v[120:123], v[166:169], v[174:177], v[120:123]
	v_mfma_f32_16x16x32_bf16 v[108:111], v[154:157], v[188:191], v[108:111]
	v_mfma_f32_16x16x32_bf16 v[104:107], v[166:169], v[188:191], v[104:107]
	v_mfma_f32_16x16x32_bf16 v[92:95], v[154:157], v[198:201], v[92:95]
	v_mfma_f32_16x16x32_bf16 v[88:91], v[166:169], v[198:201], v[88:91]
	v_mfma_f32_16x16x32_bf16 v[76:79], v[154:157], v[206:209], v[76:79]
	v_mfma_f32_16x16x32_bf16 v[72:75], v[166:169], v[206:209], v[72:75]
	s_setprio 0
	s_barrier
	s_add_i32 s0, s34, s52
	s_mov_b32 m0, s0
	ds_read_b128 v[210:213], v149
	ds_read_b128 v[214:217], v149 offset:1024
	ds_read_b128 v[218:221], v149 offset:2048
	ds_read_b128 v[222:225], v149 offset:3072
	global_load_lds_dwordx4 v130, s[42:43]
	v_lshl_add_u64 v[182:183], s[42:43], 0, v[134:135]
	s_add_i32 m0, s0, 0x2000
	s_nop 0
	global_load_lds_dwordx4 v134, s[42:43]
	s_barrier
	s_waitcnt lgkmcnt(0)
	s_setprio 1
	v_mfma_f32_16x16x32_bf16 v[116:119], v[210:213], v[170:173], 0
	v_mfma_f32_16x16x32_bf16 v[112:115], v[218:221], v[170:173], 0
	v_mfma_f32_16x16x32_bf16 v[100:103], v[210:213], v[178:181], 0
	v_mfma_f32_16x16x32_bf16 v[96:99], v[218:221], v[178:181], 0
	v_mfma_f32_16x16x32_bf16 v[84:87], v[210:213], v[194:197], 0
	v_mfma_f32_16x16x32_bf16 v[80:83], v[218:221], v[194:197], 0
	v_mfma_f32_16x16x32_bf16 v[68:71], v[210:213], v[202:205], 0
	v_mfma_f32_16x16x32_bf16 v[64:67], v[218:221], v[202:205], 0
	v_mfma_f32_16x16x32_bf16 v[116:119], v[214:217], v[174:177], v[116:119]
	v_mfma_f32_16x16x32_bf16 v[112:115], v[222:225], v[174:177], v[112:115]
	v_mfma_f32_16x16x32_bf16 v[100:103], v[214:217], v[188:191], v[100:103]
	v_mfma_f32_16x16x32_bf16 v[96:99], v[222:225], v[188:191], v[96:99]
	v_mfma_f32_16x16x32_bf16 v[84:87], v[214:217], v[198:201], v[84:87]
	v_mfma_f32_16x16x32_bf16 v[80:83], v[222:225], v[198:201], v[80:83]
	v_mfma_f32_16x16x32_bf16 v[68:71], v[214:217], v[206:209], v[68:71]
	v_mfma_f32_16x16x32_bf16 v[64:67], v[222:225], v[206:209], v[64:67]
	s_setprio 0
	s_mov_b32 m0, s39
	v_lshl_add_u64 v[226:227], s[44:45], 0, v[128:129]
	s_barrier
	ds_read_b128 v[170:173], v148 offset:16384
	ds_read_b128 v[174:177], v148 offset:17408
	ds_read_b128 v[178:181], v148 offset:18432
	ds_read_b128 v[188:191], v148 offset:19456
	ds_read_b128 v[194:197], v148 offset:20480
	ds_read_b128 v[198:201], v148 offset:21504
	ds_read_b128 v[202:205], v148 offset:22528
	ds_read_b128 v[206:209], v148 offset:23552
	global_load_lds_dwordx4 v128, s[44:45]
	v_lshl_add_u64 v[228:229], s[44:45], 0, v[132:133]
	s_mov_b32 m0, s53
	s_nop 0
	global_load_lds_dwordx4 v132, s[44:45]
	s_barrier
	s_waitcnt lgkmcnt(0)
	s_setprio 1
	v_mfma_f32_16x16x32_bf16 v[60:63], v[150:153], v[170:173], 0
	v_mfma_f32_16x16x32_bf16 v[56:59], v[162:165], v[170:173], 0
	v_mfma_f32_16x16x32_bf16 v[44:47], v[150:153], v[178:181], 0
	v_mfma_f32_16x16x32_bf16 v[40:43], v[162:165], v[178:181], 0
	v_mfma_f32_16x16x32_bf16 v[28:31], v[150:153], v[194:197], 0
	v_mfma_f32_16x16x32_bf16 v[24:27], v[162:165], v[194:197], 0
	v_mfma_f32_16x16x32_bf16 v[12:15], v[150:153], v[202:205], 0
	v_mfma_f32_16x16x32_bf16 v[8:11], v[162:165], v[202:205], 0
	v_mfma_f32_16x16x32_bf16 v[60:63], v[154:157], v[174:177], v[60:63]
	v_mfma_f32_16x16x32_bf16 v[56:59], v[166:169], v[174:177], v[56:59]
	v_mfma_f32_16x16x32_bf16 v[44:47], v[154:157], v[188:191], v[44:47]
	v_mfma_f32_16x16x32_bf16 v[40:43], v[166:169], v[188:191], v[40:43]
	v_mfma_f32_16x16x32_bf16 v[28:31], v[154:157], v[198:201], v[28:31]
	v_mfma_f32_16x16x32_bf16 v[24:27], v[166:169], v[198:201], v[24:27]
	v_mfma_f32_16x16x32_bf16 v[12:15], v[154:157], v[206:209], v[12:15]
	v_mfma_f32_16x16x32_bf16 v[8:11], v[166:169], v[206:209], v[8:11]
	s_setprio 0
	s_barrier
; #define PG8_STAGE(bufoff, gbase, voff) do { _Pragma("unroll") for (int _i = 0; _i < 2; ++_i) \
;         __builtin_amdgcn_global_load_lds((const unsigned*)((const char*)(gbase) + (voff)[_i]), (LAS unsigned*)(lds + (bufoff) + ldsw + _i * 8192), 16, 0, 0); } while (0)
; #define PG8_LDA(dst, b, h) do { _Pragma("unroll") for (int m = 0; m < 4; ++m) _Pragma("unroll") for (int k = 0; k < 2; ++k) dst[m][k] = *(const LAS bf16x8*)(lds + PG8_SA(b, h) + aoff + m * 2048 + k * 1024); } while (0)
; #define PG8_LDB(dst, b, h) do { _Pragma("unroll") for (int n = 0; n < 2; ++n) _Pragma("unroll") for (int k = 0; k < 2; ++k) dst[n][k] = *(const LAS bf16x8*)(lds + PG8_SB(b, h) + boff + n * 2048 + k * 1024); } while (0)
; #define PG8_MMA(ai, bj, At, Bt) do { __builtin_amdgcn_s_setprio(1); _Pragma("unroll") for (int m = 0; m < 4; ++m) _Pragma("unroll") for (int n = 0; n < 2; ++n) _Pragma("unroll") for (int k = 0; k < 2; ++k) \
;         acc[ai][bj][m][n] = __builtin_amdgcn_mfma_f32_16x16x32_bf16(Bt[n][k], At[m][k], acc[ai][bj][m][n], 0, 0, 0); __builtin_amdgcn_s_setprio(0); } while (0)
; #define PG8_WAIT_V(n) asm volatile("s_waitcnt vmcnt(" #n ")" ::: "memory")
; #define PG8_WAIT_L(n) asm volatile("s_waitcnt lgkmcnt(" #n ")" ::: "memory")
; #define PG8_BAR __builtin_amdgcn_s_barrier()
; #define PG8_SCHED __builtin_amdgcn_sched_barrier(0)
; template <class Epi, class Sched>
; DI void gemm_phase(LAS unsigned char* lds, const Gemm g, const Sched& S, const Epi& E) {
;     ...
;             PG8_LDA(At, 0, 1); PG8_STAGE(PG8_SA(0, 0), a2, voffA);
;             PG8_BAR; PG8_WAIT_L(0); PG8_MMA(1, 0, At, B0); PG8_BAR; PG8_SCHED;
;             PG8_STAGE(PG8_SB(0, 1), b2 + hstep, voffB);
;             PG8_WAIT_V(6); PG8_BAR; PG8_MMA(1, 1, At, B1); PG8_BAR;
;             PG8_LDB(B0, 1, 0); PG8_SCHED; PG8_LDA(At, 1, 0); PG8_STAGE(PG8_SA(0, 1), a2 + hstep, voffA);
;             PG8_WAIT_L(8); PG8_BAR; PG8_WAIT_L(0); PG8_MMA(0, 0, At, B0); PG8_BAR; PG8_SCHED;
;             PG8_LDB(B1, 1, 1); PG8_STAGE(PG8_SB(1, 0), b3, voffB);
;             PG8_BAR; PG8_WAIT_L(0); PG8_MMA(0, 1, At, B1); PG8_BAR;
;             PG8_LDA(At, 1, 1); PG8_STAGE(PG8_SA(1, 0), a3, voffA);
;             PG8_BAR; PG8_WAIT_L(0); PG8_MMA(1, 0, At, B0); PG8_BAR; PG8_SCHED;
	s_add_u32 s0, s42, 0x80000
	s_addc_u32 s1, s43, 0
	s_add_i32 s4, s35, s52
	s_mov_b32 m0, s4
	s_nop 0
	global_load_lds_dwordx4 v130, s[0:1]
	s_add_i32 m0, s4, 0x2000
	s_nop 0
	global_load_lds_dwordx4 v134, s[0:1]
	s_waitcnt vmcnt(6)
	s_barrier
	s_setprio 1
	v_mfma_f32_16x16x32_bf16 v[52:55], v[210:213], v[170:173], 0
	v_mfma_f32_16x16x32_bf16 v[48:51], v[218:221], v[170:173], 0
	v_mfma_f32_16x16x32_bf16 v[36:39], v[210:213], v[178:181], 0
	v_mfma_f32_16x16x32_bf16 v[32:35], v[218:221], v[178:181], 0
	v_mfma_f32_16x16x32_bf16 v[20:23], v[210:213], v[194:197], 0
	v_mfma_f32_16x16x32_bf16 v[16:19], v[218:221], v[194:197], 0
	v_mfma_f32_16x16x32_bf16 v[4:7], v[210:213], v[202:205], 0
	v_mfma_f32_16x16x32_bf16 v[0:3], v[218:221], v[202:205], 0
	v_mfma_f32_16x16x32_bf16 v[52:55], v[214:217], v[174:177], v[52:55]
	v_mfma_f32_16x16x32_bf16 v[48:51], v[222:225], v[174:177], v[48:51]
	v_mfma_f32_16x16x32_bf16 v[36:39], v[214:217], v[188:191], v[36:39]
	v_mfma_f32_16x16x32_bf16 v[32:35], v[222:225], v[188:191], v[32:35]
	v_mfma_f32_16x16x32_bf16 v[20:23], v[214:217], v[198:201], v[20:23]
	v_mfma_f32_16x16x32_bf16 v[16:19], v[222:225], v[198:201], v[16:19]
	v_mfma_f32_16x16x32_bf16 v[4:7], v[214:217], v[206:209], v[4:7]
	v_mfma_f32_16x16x32_bf16 v[0:3], v[222:225], v[206:209], v[0:3]
	s_setprio 0
	s_add_i32 s4, 0, 0x18000
	v_add_u32_e32 v161, s4, v146
	s_barrier
	ds_read_b128 v[150:153], v161
	ds_read_b128 v[154:157], v161 offset:1024
	ds_read_b128 v[162:165], v161 offset:2048
	ds_read_b128 v[166:169], v161 offset:3072
	s_add_u32 s0, s44, 0x80000
	s_addc_u32 s1, s45, 0
	s_mov_b32 m0, s54
	ds_read_b128 v[170:173], v148 offset:32768
	ds_read_b128 v[174:177], v148 offset:33792
	ds_read_b128 v[178:181], v148 offset:34816
	ds_read_b128 v[188:191], v148 offset:35840
	ds_read_b128 v[194:197], v148 offset:36864
	ds_read_b128 v[198:201], v148 offset:37888
	ds_read_b128 v[202:205], v148 offset:38912
	global_load_lds_dwordx4 v128, s[0:1]
	s_mov_b32 m0, s55
	ds_read_b128 v[206:209], v148 offset:39936
	global_load_lds_dwordx4 v132, s[0:1]
	s_waitcnt lgkmcnt(8)
	s_barrier
	s_waitcnt lgkmcnt(0)
	s_setprio 1
	v_mfma_f32_16x16x32_bf16 v[124:127], v[150:153], v[170:173], v[124:127]
	v_mfma_f32_16x16x32_bf16 v[120:123], v[162:165], v[170:173], v[120:123]
	v_mfma_f32_16x16x32_bf16 v[108:111], v[150:153], v[178:181], v[108:111]
	v_mfma_f32_16x16x32_bf16 v[104:107], v[162:165], v[178:181], v[104:107]
	v_mfma_f32_16x16x32_bf16 v[92:95], v[150:153], v[194:197], v[92:95]
	v_mfma_f32_16x16x32_bf16 v[88:91], v[162:165], v[194:197], v[88:91]
	v_mfma_f32_16x16x32_bf16 v[76:79], v[150:153], v[202:205], v[76:79]
	v_mfma_f32_16x16x32_bf16 v[72:75], v[162:165], v[202:205], v[72:75]
	v_mfma_f32_16x16x32_bf16 v[124:127], v[154:157], v[174:177], v[124:127]
	v_mfma_f32_16x16x32_bf16 v[120:123], v[166:169], v[174:177], v[120:123]
	v_mfma_f32_16x16x32_bf16 v[108:111], v[154:157], v[188:191], v[108:111]
	v_mfma_f32_16x16x32_bf16 v[104:107], v[166:169], v[188:191], v[104:107]
	v_mfma_f32_16x16x32_bf16 v[92:95], v[154:157], v[198:201], v[92:95]
	v_mfma_f32_16x16x32_bf16 v[88:91], v[166:169], v[198:201], v[88:91]
	v_mfma_f32_16x16x32_bf16 v[76:79], v[154:157], v[206:209], v[76:79]
	v_mfma_f32_16x16x32_bf16 v[72:75], v[166:169], v[206:209], v[72:75]
	s_setprio 0
	s_barrier
	s_add_i32 s5, 0, 0x1c000
	s_add_i32 s0, s4, s52
	v_add_u32_e32 v161, s5, v146
	s_add_i32 m0, s0, 0xffffff80
	ds_read_b128 v[210:213], v161
	ds_read_b128 v[214:217], v161 offset:1024
	ds_read_b128 v[218:221], v161 offset:2048
	global_load_lds_dwordx4 v130, s[42:43] offset:128
	s_add_i32 m0, s0, 0x1f80
	ds_read_b128 v[222:225], v161 offset:3072
	global_load_lds_dwordx4 v134, s[42:43] offset:128
	s_barrier
	s_waitcnt lgkmcnt(0)
	s_setprio 1
	v_mfma_f32_16x16x32_bf16 v[116:119], v[210:213], v[170:173], v[116:119]
	v_mfma_f32_16x16x32_bf16 v[112:115], v[218:221], v[170:173], v[112:115]
	v_mfma_f32_16x16x32_bf16 v[100:103], v[210:213], v[178:181], v[100:103]
	v_mfma_f32_16x16x32_bf16 v[96:99], v[218:221], v[178:181], v[96:99]
	v_mfma_f32_16x16x32_bf16 v[84:87], v[210:213], v[194:197], v[84:87]
	v_mfma_f32_16x16x32_bf16 v[80:83], v[218:221], v[194:197], v[80:83]
	v_mfma_f32_16x16x32_bf16 v[68:71], v[210:213], v[202:205], v[68:71]
	v_mfma_f32_16x16x32_bf16 v[64:67], v[218:221], v[202:205], v[64:67]
	v_mfma_f32_16x16x32_bf16 v[116:119], v[214:217], v[174:177], v[116:119]
	v_mfma_f32_16x16x32_bf16 v[112:115], v[222:225], v[174:177], v[112:115]
	v_mfma_f32_16x16x32_bf16 v[100:103], v[214:217], v[188:191], v[100:103]
	v_mfma_f32_16x16x32_bf16 v[96:99], v[222:225], v[188:191], v[96:99]
	v_mfma_f32_16x16x32_bf16 v[84:87], v[214:217], v[198:201], v[84:87]
	v_mfma_f32_16x16x32_bf16 v[80:83], v[222:225], v[198:201], v[80:83]
	v_mfma_f32_16x16x32_bf16 v[68:71], v[214:217], v[206:209], v[68:71]
	v_mfma_f32_16x16x32_bf16 v[64:67], v[222:225], v[206:209], v[64:67]
	s_setprio 0
	s_add_i32 m0, s59, 0xffffff80
	s_barrier
	ds_read_b128 v[170:173], v148 offset:49152
	ds_read_b128 v[174:177], v148 offset:50176
	ds_read_b128 v[178:181], v148 offset:51200
	ds_read_b128 v[188:191], v148 offset:52224
	ds_read_b128 v[194:197], v148 offset:53248
	ds_read_b128 v[198:201], v148 offset:54272
	ds_read_b128 v[202:205], v148 offset:55296
	ds_read_b128 v[206:209], v148 offset:56320
	global_load_lds_dwordx4 v128, s[44:45] offset:128
	v_lshl_add_u64 v[158:159], v[228:229], 0, s[12:13]
	s_add_i32 m0, s60, 0xffffff80
	s_nop 0
	global_load_lds_dwordx4 v132, s[44:45] offset:128
	s_barrier
; #define PG8_STAGE(bufoff, gbase, voff) do { _Pragma("unroll") for (int _i = 0; _i < 2; ++_i) \
;         __builtin_amdgcn_global_load_lds((const unsigned*)((const char*)(gbase) + (voff)[_i]), (LAS unsigned*)(lds + (bufoff) + ldsw + _i * 8192), 16, 0, 0); } while (0)
; #define PG8_LDA(dst, b, h) do { _Pragma("unroll") for (int m = 0; m < 4; ++m) _Pragma("unroll") for (int k = 0; k < 2; ++k) dst[m][k] = *(const LAS bf16x8*)(lds + PG8_SA(b, h) + aoff + m * 2048 + k * 1024); } while (0)
; #define PG8_LDB(dst, b, h) do { _Pragma("unroll") for (int n = 0; n < 2; ++n) _Pragma("unroll") for (int k = 0; k < 2; ++k) dst[n][k] = *(const LAS bf16x8*)(lds + PG8_SB(b, h) + boff + n * 2048 + k * 1024); } while (0)
; #define PG8_MMA(ai, bj, At, Bt) do { __builtin_amdgcn_s_setprio(1); _Pragma("unroll") for (int m = 0; m < 4; ++m) _Pragma("unroll") for (int n = 0; n < 2; ++n) _Pragma("unroll") for (int k = 0; k < 2; ++k) \
;         acc[ai][bj][m][n] = __builtin_amdgcn_mfma_f32_16x16x32_bf16(Bt[n][k], At[m][k], acc[ai][bj][m][n], 0, 0, 0); __builtin_amdgcn_s_setprio(0); } while (0)
; #define PG8_WAIT_V(n) asm volatile("s_waitcnt vmcnt(" #n ")" ::: "memory")
; #define PG8_WAIT_L(n) asm volatile("s_waitcnt lgkmcnt(" #n ")" ::: "memory")
; #define PG8_BAR __builtin_amdgcn_s_barrier()
; #define PG8_SCHED __builtin_amdgcn_sched_barrier(0)
; template <class Epi, class Sched>
; DI void gemm_phase(LAS unsigned char* lds, const Gemm g, const Sched& S, const Epi& E) {
;     ...
;             PG8_LDB(B0, 0, 0); PG8_SCHED; PG8_LDA(At, 0, 0); PG8_STAGE(PG8_SA(1, 1), a1 + hstep, voffA);
;             PG8_WAIT_L(8); PG8_BAR; PG8_WAIT_L(0); PG8_MMA(0, 0, At, B0); PG8_BAR; PG8_SCHED;
;             PG8_LDB(B1, 0, 1); PG8_STAGE(PG8_SB(0, 0), b2, voffB);
;             PG8_BAR; PG8_WAIT_L(0); PG8_MMA(0, 1, At, B1); PG8_BAR;
;     ...
;             PG8_BAR; PG8_WAIT_L(0); PG8_MMA(1, 0, At, B0); PG8_BAR; PG8_SCHED;
;             PG8_STAGE(PG8_SB(1, 1), b3 + hstep, voffB);
;             PG8_WAIT_V(6); PG8_BAR; PG8_MMA(1, 1, At, B1); PG8_BAR;
	s_waitcnt lgkmcnt(0)
	s_setprio 1
	v_mfma_f32_16x16x32_bf16 v[60:63], v[150:153], v[170:173], v[60:63]
	v_mfma_f32_16x16x32_bf16 v[56:59], v[162:165], v[170:173], v[56:59]
	v_mfma_f32_16x16x32_bf16 v[44:47], v[150:153], v[178:181], v[44:47]
	v_mfma_f32_16x16x32_bf16 v[40:43], v[162:165], v[178:181], v[40:43]
	v_mfma_f32_16x16x32_bf16 v[28:31], v[150:153], v[194:197], v[28:31]
	v_mfma_f32_16x16x32_bf16 v[24:27], v[162:165], v[194:197], v[24:27]
	v_mfma_f32_16x16x32_bf16 v[12:15], v[150:153], v[202:205], v[12:15]
	v_mfma_f32_16x16x32_bf16 v[8:11], v[162:165], v[202:205], v[8:11]
	v_mfma_f32_16x16x32_bf16 v[60:63], v[154:157], v[174:177], v[60:63]
	v_mfma_f32_16x16x32_bf16 v[56:59], v[166:169], v[174:177], v[56:59]
	v_mfma_f32_16x16x32_bf16 v[44:47], v[154:157], v[188:191], v[44:47]
	v_mfma_f32_16x16x32_bf16 v[40:43], v[166:169], v[188:191], v[40:43]
	v_mfma_f32_16x16x32_bf16 v[28:31], v[154:157], v[198:201], v[28:31]
	v_mfma_f32_16x16x32_bf16 v[24:27], v[166:169], v[198:201], v[24:27]
	v_mfma_f32_16x16x32_bf16 v[12:15], v[154:157], v[206:209], v[12:15]
	v_mfma_f32_16x16x32_bf16 v[8:11], v[166:169], v[206:209], v[8:11]
	s_setprio 0
	s_barrier
	s_add_u32 s0, s42, 0x80080
	s_addc_u32 s1, s43, 0
	s_add_i32 s4, s5, s52
	s_mov_b32 m0, s4
	s_nop 0
	global_load_lds_dwordx4 v130, s[0:1]
	s_add_i32 m0, s4, 0x2000
	s_nop 0
	global_load_lds_dwordx4 v134, s[0:1]
	s_waitcnt vmcnt(6)
	s_barrier
	s_setprio 1
	v_mfma_f32_16x16x32_bf16 v[52:55], v[210:213], v[170:173], v[52:55]
	v_mfma_f32_16x16x32_bf16 v[48:51], v[218:221], v[170:173], v[48:51]
	v_mfma_f32_16x16x32_bf16 v[36:39], v[210:213], v[178:181], v[36:39]
	v_mfma_f32_16x16x32_bf16 v[32:35], v[218:221], v[178:181], v[32:35]
	v_mfma_f32_16x16x32_bf16 v[20:23], v[210:213], v[194:197], v[20:23]
	v_mfma_f32_16x16x32_bf16 v[16:19], v[218:221], v[194:197], v[16:19]
	v_mfma_f32_16x16x32_bf16 v[4:7], v[210:213], v[202:205], v[4:7]
	v_mfma_f32_16x16x32_bf16 v[0:3], v[218:221], v[202:205], v[0:3]
	v_mfma_f32_16x16x32_bf16 v[52:55], v[214:217], v[174:177], v[52:55]
	v_mfma_f32_16x16x32_bf16 v[48:51], v[222:225], v[174:177], v[48:51]
	v_mfma_f32_16x16x32_bf16 v[36:39], v[214:217], v[188:191], v[36:39]
	v_mfma_f32_16x16x32_bf16 v[32:35], v[222:225], v[188:191], v[32:35]
	v_mfma_f32_16x16x32_bf16 v[20:23], v[214:217], v[198:201], v[20:23]
	v_mfma_f32_16x16x32_bf16 v[16:19], v[222:225], v[198:201], v[16:19]
	v_mfma_f32_16x16x32_bf16 v[4:7], v[214:217], v[206:209], v[4:7]
	v_mfma_f32_16x16x32_bf16 v[0:3], v[222:225], v[206:209], v[0:3]
	s_setprio 0
	s_add_i32 s69, s69, 2
	s_add_u32 s40, s40, 0x100
	s_addc_u32 s41, s41, 0
	s_add_u32 s67, s67, 0x100
	s_addc_u32 s68, s68, 0
	s_cmp_gt_u32 s69, 29
	s_barrier
	s_cbranch_scc0 .LBB0_219
	s_branch .Lpeel_done_219
.LBB0_219:
	ds_read_b128 v[150:153], v147
	ds_read_b128 v[154:157], v147 offset:1024
	ds_read_b128 v[162:165], v147 offset:2048
	ds_read_b128 v[166:169], v147 offset:3072
	s_add_u32 s0, s40, 0xfff80080
	s_addc_u32 s1, s41, -1
	s_cmp_eq_u32 s69, 28
	s_cselect_b32 s45, s17, s1
	s_cselect_b32 s44, s65, s0
	s_cselect_b32 s43, s15, s68
	s_cselect_b32 s42, s66, s67
	s_add_i32 m0, s39, 0xc000
	ds_read_b128 v[170:173], v148
	ds_read_b128 v[174:177], v148 offset:1024
	ds_read_b128 v[178:181], v148 offset:2048
	ds_read_b128 v[188:191], v148 offset:3072
	ds_read_b128 v[194:197], v148 offset:4096
	ds_read_b128 v[198:201], v148 offset:5120
	ds_read_b128 v[202:205], v148 offset:6144
	global_load_lds_dwordx4 v136, s[40:41]
	s_add_i32 m0, s39, 0xe000
	ds_read_b128 v[206:209], v148 offset:7168
	global_load_lds_dwordx4 v138, s[40:41]
	s_waitcnt lgkmcnt(8)
	s_barrier
	s_waitcnt lgkmcnt(0)
	s_setprio 1
	v_mfma_f32_16x16x32_bf16 v[124:127], v[150:153], v[170:173], v[124:127]
	v_mfma_f32_16x16x32_bf16 v[120:123], v[162:165], v[170:173], v[120:123]
	v_mfma_f32_16x16x32_bf16 v[108:111], v[150:153], v[178:181], v[108:111]
	v_mfma_f32_16x16x32_bf16 v[104:107], v[162:165], v[178:181], v[104:107]
	v_mfma_f32_16x16x32_bf16 v[92:95], v[150:153], v[194:197], v[92:95]
	v_mfma_f32_16x16x32_bf16 v[88:91], v[162:165], v[194:197], v[88:91]
	v_mfma_f32_16x16x32_bf16 v[76:79], v[150:153], v[202:205], v[76:79]
	v_mfma_f32_16x16x32_bf16 v[72:75], v[162:165], v[202:205], v[72:75]
	v_mfma_f32_16x16x32_bf16 v[124:127], v[154:157], v[174:177], v[124:127]
	v_mfma_f32_16x16x32_bf16 v[120:123], v[166:169], v[174:177], v[120:123]
	v_mfma_f32_16x16x32_bf16 v[108:111], v[154:157], v[188:191], v[108:111]
	v_mfma_f32_16x16x32_bf16 v[104:107], v[166:169], v[188:191], v[104:107]
	v_mfma_f32_16x16x32_bf16 v[92:95], v[154:157], v[198:201], v[92:95]
	v_mfma_f32_16x16x32_bf16 v[88:91], v[166:169], v[198:201], v[88:91]
	v_mfma_f32_16x16x32_bf16 v[76:79], v[154:157], v[206:209], v[76:79]
	v_mfma_f32_16x16x32_bf16 v[72:75], v[166:169], v[206:209], v[72:75]
	s_setprio 0
	s_barrier
	s_add_i32 s0, s34, s52
	s_mov_b32 m0, s0
	ds_read_b128 v[210:213], v149
	ds_read_b128 v[214:217], v149 offset:1024
	ds_read_b128 v[218:221], v149 offset:2048
	ds_read_b128 v[222:225], v149 offset:3072
	global_load_lds_dwordx4 v130, s[42:43]
	v_lshl_add_u64 v[182:183], s[42:43], 0, v[134:135]
	s_add_i32 m0, s0, 0x2000
	s_nop 0
	global_load_lds_dwordx4 v134, s[42:43]
	s_barrier
; #define PG8_STAGE(bufoff, gbase, voff) do { _Pragma("unroll") for (int _i = 0; _i < 2; ++_i) \
;         __builtin_amdgcn_global_load_lds((const unsigned*)((const char*)(gbase) + (voff)[_i]), (LAS unsigned*)(lds + (bufoff) + ldsw + _i * 8192), 16, 0, 0); } while (0)
; #define PG8_LDA(dst, b, h) do { _Pragma("unroll") for (int m = 0; m < 4; ++m) _Pragma("unroll") for (int k = 0; k < 2; ++k) dst[m][k] = *(const LAS bf16x8*)(lds + PG8_SA(b, h) + aoff + m * 2048 + k * 1024); } while (0)
; #define PG8_LDB(dst, b, h) do { _Pragma("unroll") for (int n = 0; n < 2; ++n) _Pragma("unroll") for (int k = 0; k < 2; ++k) dst[n][k] = *(const LAS bf16x8*)(lds + PG8_SB(b, h) + boff + n * 2048 + k * 1024); } while (0)
; #define PG8_MMA(ai, bj, At, Bt) do { __builtin_amdgcn_s_setprio(1); _Pragma("unroll") for (int m = 0; m < 4; ++m) _Pragma("unroll") for (int n = 0; n < 2; ++n) _Pragma("unroll") for (int k = 0; k < 2; ++k) \
;         acc[ai][bj][m][n] = __builtin_amdgcn_mfma_f32_16x16x32_bf16(Bt[n][k], At[m][k], acc[ai][bj][m][n], 0, 0, 0); __builtin_amdgcn_s_setprio(0); } while (0)
; #define PG8_WAIT_V(n) asm volatile("s_waitcnt vmcnt(" #n ")" ::: "memory")
; #define PG8_WAIT_L(n) asm volatile("s_waitcnt lgkmcnt(" #n ")" ::: "memory")
; #define PG8_BAR __builtin_amdgcn_s_barrier()
; #define PG8_SCHED __builtin_amdgcn_sched_barrier(0)
; template <class Epi, class Sched>
; DI void gemm_phase(LAS unsigned char* lds, const Gemm g, const Sched& S, const Epi& E) {
;     ...
;             PG8_BAR; PG8_WAIT_L(0); PG8_MMA(0, 1, At, B1); PG8_BAR;
;             PG8_LDA(At, 0, 1); PG8_STAGE(PG8_SA(0, 0), a2, voffA);
;             PG8_BAR; PG8_WAIT_L(0); PG8_MMA(1, 0, At, B0); PG8_BAR; PG8_SCHED;
;             PG8_STAGE(PG8_SB(0, 1), b2 + hstep, voffB);
;             PG8_WAIT_V(6); PG8_BAR; PG8_MMA(1, 1, At, B1); PG8_BAR;
;             PG8_LDB(B0, 1, 0); PG8_SCHED; PG8_LDA(At, 1, 0); PG8_STAGE(PG8_SA(0, 1), a2 + hstep, voffA);
;             PG8_WAIT_L(8); PG8_BAR; PG8_WAIT_L(0); PG8_MMA(0, 0, At, B0); PG8_BAR; PG8_SCHED;
	s_waitcnt lgkmcnt(0)
	s_setprio 1
	v_mfma_f32_16x16x32_bf16 v[116:119], v[210:213], v[170:173], v[116:119]
	v_mfma_f32_16x16x32_bf16 v[112:115], v[218:221], v[170:173], v[112:115]
	v_mfma_f32_16x16x32_bf16 v[100:103], v[210:213], v[178:181], v[100:103]
	v_mfma_f32_16x16x32_bf16 v[96:99], v[218:221], v[178:181], v[96:99]
	v_mfma_f32_16x16x32_bf16 v[84:87], v[210:213], v[194:197], v[84:87]
	v_mfma_f32_16x16x32_bf16 v[80:83], v[218:221], v[194:197], v[80:83]
	v_mfma_f32_16x16x32_bf16 v[68:71], v[210:213], v[202:205], v[68:71]
	v_mfma_f32_16x16x32_bf16 v[64:67], v[218:221], v[202:205], v[64:67]
	v_mfma_f32_16x16x32_bf16 v[116:119], v[214:217], v[174:177], v[116:119]
	v_mfma_f32_16x16x32_bf16 v[112:115], v[222:225], v[174:177], v[112:115]
	v_mfma_f32_16x16x32_bf16 v[100:103], v[214:217], v[188:191], v[100:103]
	v_mfma_f32_16x16x32_bf16 v[96:99], v[222:225], v[188:191], v[96:99]
	v_mfma_f32_16x16x32_bf16 v[84:87], v[214:217], v[198:201], v[84:87]
	v_mfma_f32_16x16x32_bf16 v[80:83], v[222:225], v[198:201], v[80:83]
	v_mfma_f32_16x16x32_bf16 v[68:71], v[214:217], v[206:209], v[68:71]
	v_mfma_f32_16x16x32_bf16 v[64:67], v[222:225], v[206:209], v[64:67]
	s_setprio 0
	s_mov_b32 m0, s39
	v_lshl_add_u64 v[226:227], s[44:45], 0, v[128:129]
	s_barrier
	ds_read_b128 v[170:173], v148 offset:16384
	ds_read_b128 v[174:177], v148 offset:17408
	ds_read_b128 v[178:181], v148 offset:18432
	ds_read_b128 v[188:191], v148 offset:19456
	ds_read_b128 v[194:197], v148 offset:20480
	ds_read_b128 v[198:201], v148 offset:21504
	ds_read_b128 v[202:205], v148 offset:22528
	ds_read_b128 v[206:209], v148 offset:23552
	global_load_lds_dwordx4 v128, s[44:45]
	v_lshl_add_u64 v[228:229], s[44:45], 0, v[132:133]
	s_mov_b32 m0, s53
	s_nop 0
	global_load_lds_dwordx4 v132, s[44:45]
	s_barrier
	s_waitcnt lgkmcnt(0)
	s_setprio 1
	v_mfma_f32_16x16x32_bf16 v[60:63], v[150:153], v[170:173], v[60:63]
	v_mfma_f32_16x16x32_bf16 v[56:59], v[162:165], v[170:173], v[56:59]
	v_mfma_f32_16x16x32_bf16 v[44:47], v[150:153], v[178:181], v[44:47]
	v_mfma_f32_16x16x32_bf16 v[40:43], v[162:165], v[178:181], v[40:43]
	v_mfma_f32_16x16x32_bf16 v[28:31], v[150:153], v[194:197], v[28:31]
	v_mfma_f32_16x16x32_bf16 v[24:27], v[162:165], v[194:197], v[24:27]
	v_mfma_f32_16x16x32_bf16 v[12:15], v[150:153], v[202:205], v[12:15]
	v_mfma_f32_16x16x32_bf16 v[8:11], v[162:165], v[202:205], v[8:11]
	v_mfma_f32_16x16x32_bf16 v[60:63], v[154:157], v[174:177], v[60:63]
	v_mfma_f32_16x16x32_bf16 v[56:59], v[166:169], v[174:177], v[56:59]
	v_mfma_f32_16x16x32_bf16 v[44:47], v[154:157], v[188:191], v[44:47]
	v_mfma_f32_16x16x32_bf16 v[40:43], v[166:169], v[188:191], v[40:43]
	v_mfma_f32_16x16x32_bf16 v[28:31], v[154:157], v[198:201], v[28:31]
	v_mfma_f32_16x16x32_bf16 v[24:27], v[166:169], v[198:201], v[24:27]
	v_mfma_f32_16x16x32_bf16 v[12:15], v[154:157], v[206:209], v[12:15]
	v_mfma_f32_16x16x32_bf16 v[8:11], v[166:169], v[206:209], v[8:11]
	s_setprio 0
	s_barrier
	s_add_u32 s0, s42, 0x80000
	s_addc_u32 s1, s43, 0
	s_add_i32 s4, s35, s52
	s_mov_b32 m0, s4
	s_nop 0
	global_load_lds_dwordx4 v130, s[0:1]
	s_add_i32 m0, s4, 0x2000
	s_nop 0
	global_load_lds_dwordx4 v134, s[0:1]
	s_waitcnt vmcnt(6)
	s_barrier
	s_setprio 1
	v_mfma_f32_16x16x32_bf16 v[52:55], v[210:213], v[170:173], v[52:55]
	v_mfma_f32_16x16x32_bf16 v[48:51], v[218:221], v[170:173], v[48:51]
	v_mfma_f32_16x16x32_bf16 v[36:39], v[210:213], v[178:181], v[36:39]
	v_mfma_f32_16x16x32_bf16 v[32:35], v[218:221], v[178:181], v[32:35]
	v_mfma_f32_16x16x32_bf16 v[20:23], v[210:213], v[194:197], v[20:23]
	v_mfma_f32_16x16x32_bf16 v[16:19], v[218:221], v[194:197], v[16:19]
	v_mfma_f32_16x16x32_bf16 v[4:7], v[210:213], v[202:205], v[4:7]
	v_mfma_f32_16x16x32_bf16 v[0:3], v[218:221], v[202:205], v[0:3]
	v_mfma_f32_16x16x32_bf16 v[52:55], v[214:217], v[174:177], v[52:55]
	v_mfma_f32_16x16x32_bf16 v[48:51], v[222:225], v[174:177], v[48:51]
	v_mfma_f32_16x16x32_bf16 v[36:39], v[214:217], v[188:191], v[36:39]
	v_mfma_f32_16x16x32_bf16 v[32:35], v[222:225], v[188:191], v[32:35]
	v_mfma_f32_16x16x32_bf16 v[20:23], v[214:217], v[198:201], v[20:23]
	v_mfma_f32_16x16x32_bf16 v[16:19], v[222:225], v[198:201], v[16:19]
	v_mfma_f32_16x16x32_bf16 v[4:7], v[214:217], v[206:209], v[4:7]
	v_mfma_f32_16x16x32_bf16 v[0:3], v[222:225], v[206:209], v[0:3]
	s_setprio 0
	s_add_i32 s4, 0, 0x18000
	v_add_u32_e32 v161, s4, v146
	s_barrier
	ds_read_b128 v[150:153], v161
	ds_read_b128 v[154:157], v161 offset:1024
	ds_read_b128 v[162:165], v161 offset:2048
	ds_read_b128 v[166:169], v161 offset:3072
	s_add_u32 s0, s44, 0x80000
	s_addc_u32 s1, s45, 0
	s_mov_b32 m0, s54
	ds_read_b128 v[170:173], v148 offset:32768
	ds_read_b128 v[174:177], v148 offset:33792
	ds_read_b128 v[178:181], v148 offset:34816
	ds_read_b128 v[188:191], v148 offset:35840
	ds_read_b128 v[194:197], v148 offset:36864
	ds_read_b128 v[198:201], v148 offset:37888
	ds_read_b128 v[202:205], v148 offset:38912
	global_load_lds_dwordx4 v128, s[0:1]
	s_mov_b32 m0, s55
	ds_read_b128 v[206:209], v148 offset:39936
	global_load_lds_dwordx4 v132, s[0:1]
	s_waitcnt lgkmcnt(8)
	s_barrier
; #define PG8_STAGE(bufoff, gbase, voff) do { _Pragma("unroll") for (int _i = 0; _i < 2; ++_i) \
;         __builtin_amdgcn_global_load_lds((const unsigned*)((const char*)(gbase) + (voff)[_i]), (LAS unsigned*)(lds + (bufoff) + ldsw + _i * 8192), 16, 0, 0); } while (0)
; #define PG8_LDA(dst, b, h) do { _Pragma("unroll") for (int m = 0; m < 4; ++m) _Pragma("unroll") for (int k = 0; k < 2; ++k) dst[m][k] = *(const LAS bf16x8*)(lds + PG8_SA(b, h) + aoff + m * 2048 + k * 1024); } while (0)
; #define PG8_LDB(dst, b, h) do { _Pragma("unroll") for (int n = 0; n < 2; ++n) _Pragma("unroll") for (int k = 0; k < 2; ++k) dst[n][k] = *(const LAS bf16x8*)(lds + PG8_SB(b, h) + boff + n * 2048 + k * 1024); } while (0)
; #define PG8_MMA(ai, bj, At, Bt) do { __builtin_amdgcn_s_setprio(1); _Pragma("unroll") for (int m = 0; m < 4; ++m) _Pragma("unroll") for (int n = 0; n < 2; ++n) _Pragma("unroll") for (int k = 0; k < 2; ++k) \
;         acc[ai][bj][m][n] = __builtin_amdgcn_mfma_f32_16x16x32_bf16(Bt[n][k], At[m][k], acc[ai][bj][m][n], 0, 0, 0); __builtin_amdgcn_s_setprio(0); } while (0)
; #define PG8_WAIT_V(n) asm volatile("s_waitcnt vmcnt(" #n ")" ::: "memory")
; #define PG8_WAIT_L(n) asm volatile("s_waitcnt lgkmcnt(" #n ")" ::: "memory")
; #define PG8_BAR __builtin_amdgcn_s_barrier()
; #define PG8_SCHED __builtin_amdgcn_sched_barrier(0)
; template <class Epi, class Sched>
; DI void gemm_phase(LAS unsigned char* lds, const Gemm g, const Sched& S, const Epi& E) {
;     ...
;             PG8_WAIT_L(8); PG8_BAR; PG8_WAIT_L(0); PG8_MMA(0, 0, At, B0); PG8_BAR; PG8_SCHED;
;             PG8_LDB(B1, 1, 1); PG8_STAGE(PG8_SB(1, 0), b3, voffB);
;             PG8_BAR; PG8_WAIT_L(0); PG8_MMA(0, 1, At, B1); PG8_BAR;
;             PG8_LDA(At, 1, 1); PG8_STAGE(PG8_SA(1, 0), a3, voffA);
;             PG8_BAR; PG8_WAIT_L(0); PG8_MMA(1, 0, At, B0); PG8_BAR; PG8_SCHED;
;             PG8_STAGE(PG8_SB(1, 1), b3 + hstep, voffB);
;             PG8_WAIT_V(6); PG8_BAR; PG8_MMA(1, 1, At, B1); PG8_BAR;
	s_waitcnt lgkmcnt(0)
	s_setprio 1
	v_mfma_f32_16x16x32_bf16 v[124:127], v[150:153], v[170:173], v[124:127]
	v_mfma_f32_16x16x32_bf16 v[120:123], v[162:165], v[170:173], v[120:123]
	v_mfma_f32_16x16x32_bf16 v[108:111], v[150:153], v[178:181], v[108:111]
	v_mfma_f32_16x16x32_bf16 v[104:107], v[162:165], v[178:181], v[104:107]
	v_mfma_f32_16x16x32_bf16 v[92:95], v[150:153], v[194:197], v[92:95]
	v_mfma_f32_16x16x32_bf16 v[88:91], v[162:165], v[194:197], v[88:91]
	v_mfma_f32_16x16x32_bf16 v[76:79], v[150:153], v[202:205], v[76:79]
	v_mfma_f32_16x16x32_bf16 v[72:75], v[162:165], v[202:205], v[72:75]
	v_mfma_f32_16x16x32_bf16 v[124:127], v[154:157], v[174:177], v[124:127]
	v_mfma_f32_16x16x32_bf16 v[120:123], v[166:169], v[174:177], v[120:123]
	v_mfma_f32_16x16x32_bf16 v[108:111], v[154:157], v[188:191], v[108:111]
	v_mfma_f32_16x16x32_bf16 v[104:107], v[166:169], v[188:191], v[104:107]
	v_mfma_f32_16x16x32_bf16 v[92:95], v[154:157], v[198:201], v[92:95]
	v_mfma_f32_16x16x32_bf16 v[88:91], v[166:169], v[198:201], v[88:91]
	v_mfma_f32_16x16x32_bf16 v[76:79], v[154:157], v[206:209], v[76:79]
	v_mfma_f32_16x16x32_bf16 v[72:75], v[166:169], v[206:209], v[72:75]
	s_setprio 0
	s_barrier
	s_add_i32 s5, 0, 0x1c000
	s_add_i32 s0, s4, s52
	v_add_u32_e32 v161, s5, v146
	s_add_i32 m0, s0, 0xffffff80
	ds_read_b128 v[210:213], v161
	ds_read_b128 v[214:217], v161 offset:1024
	ds_read_b128 v[218:221], v161 offset:2048
	global_load_lds_dwordx4 v130, s[42:43] offset:128
	s_add_i32 m0, s0, 0x1f80
	ds_read_b128 v[222:225], v161 offset:3072
	global_load_lds_dwordx4 v134, s[42:43] offset:128
	s_barrier
	s_waitcnt lgkmcnt(0)
	s_setprio 1
	v_mfma_f32_16x16x32_bf16 v[116:119], v[210:213], v[170:173], v[116:119]
	v_mfma_f32_16x16x32_bf16 v[112:115], v[218:221], v[170:173], v[112:115]
	v_mfma_f32_16x16x32_bf16 v[100:103], v[210:213], v[178:181], v[100:103]
	v_mfma_f32_16x16x32_bf16 v[96:99], v[218:221], v[178:181], v[96:99]
	v_mfma_f32_16x16x32_bf16 v[84:87], v[210:213], v[194:197], v[84:87]
	v_mfma_f32_16x16x32_bf16 v[80:83], v[218:221], v[194:197], v[80:83]
	v_mfma_f32_16x16x32_bf16 v[68:71], v[210:213], v[202:205], v[68:71]
	v_mfma_f32_16x16x32_bf16 v[64:67], v[218:221], v[202:205], v[64:67]
	v_mfma_f32_16x16x32_bf16 v[116:119], v[214:217], v[174:177], v[116:119]
	v_mfma_f32_16x16x32_bf16 v[112:115], v[222:225], v[174:177], v[112:115]
	v_mfma_f32_16x16x32_bf16 v[100:103], v[214:217], v[188:191], v[100:103]
	v_mfma_f32_16x16x32_bf16 v[96:99], v[222:225], v[188:191], v[96:99]
	v_mfma_f32_16x16x32_bf16 v[84:87], v[214:217], v[198:201], v[84:87]
	v_mfma_f32_16x16x32_bf16 v[80:83], v[222:225], v[198:201], v[80:83]
	v_mfma_f32_16x16x32_bf16 v[68:71], v[214:217], v[206:209], v[68:71]
	v_mfma_f32_16x16x32_bf16 v[64:67], v[222:225], v[206:209], v[64:67]
	s_setprio 0
	s_add_i32 m0, s59, 0xffffff80
	s_barrier
	ds_read_b128 v[170:173], v148 offset:49152
	ds_read_b128 v[174:177], v148 offset:50176
	ds_read_b128 v[178:181], v148 offset:51200
	ds_read_b128 v[188:191], v148 offset:52224
	ds_read_b128 v[194:197], v148 offset:53248
	ds_read_b128 v[198:201], v148 offset:54272
	ds_read_b128 v[202:205], v148 offset:55296
	ds_read_b128 v[206:209], v148 offset:56320
	global_load_lds_dwordx4 v128, s[44:45] offset:128
	v_lshl_add_u64 v[158:159], v[228:229], 0, s[12:13]
	s_add_i32 m0, s60, 0xffffff80
	s_nop 0
	global_load_lds_dwordx4 v132, s[44:45] offset:128
	s_barrier
	s_waitcnt lgkmcnt(0)
	s_setprio 1
	v_mfma_f32_16x16x32_bf16 v[60:63], v[150:153], v[170:173], v[60:63]
	v_mfma_f32_16x16x32_bf16 v[56:59], v[162:165], v[170:173], v[56:59]
	v_mfma_f32_16x16x32_bf16 v[44:47], v[150:153], v[178:181], v[44:47]
	v_mfma_f32_16x16x32_bf16 v[40:43], v[162:165], v[178:181], v[40:43]
	v_mfma_f32_16x16x32_bf16 v[28:31], v[150:153], v[194:197], v[28:31]
	v_mfma_f32_16x16x32_bf16 v[24:27], v[162:165], v[194:197], v[24:27]
	v_mfma_f32_16x16x32_bf16 v[12:15], v[150:153], v[202:205], v[12:15]
	v_mfma_f32_16x16x32_bf16 v[8:11], v[162:165], v[202:205], v[8:11]
	v_mfma_f32_16x16x32_bf16 v[60:63], v[154:157], v[174:177], v[60:63]
	v_mfma_f32_16x16x32_bf16 v[56:59], v[166:169], v[174:177], v[56:59]
	v_mfma_f32_16x16x32_bf16 v[44:47], v[154:157], v[188:191], v[44:47]
	v_mfma_f32_16x16x32_bf16 v[40:43], v[166:169], v[188:191], v[40:43]
	v_mfma_f32_16x16x32_bf16 v[28:31], v[154:157], v[198:201], v[28:31]
	v_mfma_f32_16x16x32_bf16 v[24:27], v[166:169], v[198:201], v[24:27]
	v_mfma_f32_16x16x32_bf16 v[12:15], v[154:157], v[206:209], v[12:15]
	v_mfma_f32_16x16x32_bf16 v[8:11], v[166:169], v[206:209], v[8:11]
	s_setprio 0
	s_barrier
	s_add_u32 s0, s42, 0x80080
	s_addc_u32 s1, s43, 0
	s_add_i32 s4, s5, s52
	s_mov_b32 m0, s4
	s_nop 0
	global_load_lds_dwordx4 v130, s[0:1]
	s_add_i32 m0, s4, 0x2000
	s_nop 0
	global_load_lds_dwordx4 v134, s[0:1]
	s_waitcnt vmcnt(6)
	s_barrier
	s_setprio 1
	v_mfma_f32_16x16x32_bf16 v[52:55], v[210:213], v[170:173], v[52:55]
	v_mfma_f32_16x16x32_bf16 v[48:51], v[218:221], v[170:173], v[48:51]
	v_mfma_f32_16x16x32_bf16 v[36:39], v[210:213], v[178:181], v[36:39]
	v_mfma_f32_16x16x32_bf16 v[32:35], v[218:221], v[178:181], v[32:35]
	v_mfma_f32_16x16x32_bf16 v[20:23], v[210:213], v[194:197], v[20:23]
	v_mfma_f32_16x16x32_bf16 v[16:19], v[218:221], v[194:197], v[16:19]
	v_mfma_f32_16x16x32_bf16 v[4:7], v[210:213], v[202:205], v[4:7]
	v_mfma_f32_16x16x32_bf16 v[0:3], v[218:221], v[202:205], v[0:3]
	v_mfma_f32_16x16x32_bf16 v[52:55], v[214:217], v[174:177], v[52:55]
	v_mfma_f32_16x16x32_bf16 v[48:51], v[222:225], v[174:177], v[48:51]
	v_mfma_f32_16x16x32_bf16 v[36:39], v[214:217], v[188:191], v[36:39]
	v_mfma_f32_16x16x32_bf16 v[32:35], v[222:225], v[188:191], v[32:35]
	v_mfma_f32_16x16x32_bf16 v[20:23], v[214:217], v[198:201], v[20:23]
	v_mfma_f32_16x16x32_bf16 v[16:19], v[222:225], v[198:201], v[16:19]
	v_mfma_f32_16x16x32_bf16 v[4:7], v[214:217], v[206:209], v[4:7]
	v_mfma_f32_16x16x32_bf16 v[0:3], v[222:225], v[206:209], v[0:3]
	s_setprio 0
	s_add_i32 s69, s69, 2
	s_add_u32 s40, s40, 0x100
	s_addc_u32 s41, s41, 0
	s_add_u32 s67, s67, 0x100
	s_addc_u32 s68, s68, 0
	s_cmp_gt_u32 s69, 29
	s_barrier
	s_cbranch_scc0 .LBB0_219

;     DI size_t aoff(const Unit& u, size_t tstep) const { return (size_t)u.pm * tstep; }
;     DI size_t boff(const Unit& u, size_t tstep) const { return (size_t)u.pn * tstep; }
;     DI bool next(int i, Unit& u) const { const long L = (long)i * G + c; if (L >= np) return false; u.pm = pmv; u.pn = (int)(L % nN); u.ks = (int)(L / nN); return true; }
;     DI size_t aoff(const Unit& u, size_t) const { return (size_t)u.ks * kbytes; }
;     DI size_t boff(const Unit& u, size_t tstep) const { return (size_t)u.pn * tstep + (size_t)u.ks * kbytes; }
;     DI bool next(int i, Unit& u) const { Unit t; if (!S.next(i / 3, t)) return false; u.pm = t.pm; u.pn = t.pn; u.ks = i % 3; return true; }
;     DI size_t aoff(const Unit& u, size_t tstep) const { return (u.ks < 2 ? offU : offOA) + (size_t)u.pm * tstep; }
; #define PG8_WAIT_V(n) asm volatile("s_waitcnt vmcnt(" #n ")" ::: "memory")
; template <class Epi, class Sched>
; DI void gemm_phase(LAS unsigned char* lds, const Gemm g, const Sched& S, const Epi& E) {
;     ...
;         const bool has_next = S.next(ui + 1, nxt);
;         const char* nA = has_next ? (const char*)g.A + S.aoff(nxt, tstep) : cA; const char* nB = has_next ? (const char*)g.Bt + S.boff(nxt, tstep) : cB;
;         for (int t = 0; t < nt; t += 2) {
;             if constexpr (Epi::HAS_MID) { if (t == E.mid_t(nt)) { int fr3 = fr, fq3 = fq; asm volatile("" : "+v"(fr3), "+v"(fq3)); E.mid(acc, cur, wr, wc, fr3, fq3); } }
;             const bool last = (t == nt - 2);
;             const char* a1 = cA + (size_t)(t + 1) * kstep;
;             const char* a2 = last ? nA : cA + (size_t)(t + 2) * kstep; const char* b2 = last ? nB : cB + (size_t)(t + 2) * kstep;
;             const char* a3 = a2 + kstep; const char* b3 = b2 + kstep;
;             PG8_LDB(B0, 0, 0); PG8_SCHED; PG8_LDA(At, 0, 0); PG8_STAGE(PG8_SA(1, 1), a1 + hstep, voffA);
;             PG8_WAIT_L(8); PG8_BAR; PG8_WAIT_L(0); PG8_MMA(0, 0, At, B0); PG8_BAR; PG8_SCHED;
;             PG8_LDB(B1, 0, 1); PG8_STAGE(PG8_SB(0, 0), b2, voffB);
;             PG8_BAR; PG8_WAIT_L(0); PG8_MMA(0, 1, At, B1); PG8_BAR;
;             PG8_LDA(At, 0, 1); PG8_STAGE(PG8_SA(0, 0), a2, voffA);
;             PG8_BAR; PG8_WAIT_L(0); PG8_MMA(1, 0, At, B0); PG8_BAR; PG8_SCHED;
;             PG8_STAGE(PG8_SB(0, 1), b2 + hstep, voffB);
;             PG8_WAIT_V(6); PG8_BAR; PG8_MMA(1, 1, At, B1); PG8_BAR;
.LBB0_296:
	s_add_u32 s40, s40, 0x160080
	s_addc_u32 s41, s41, 0
	s_add_u32 s35, s42, 0x100
	v_mov_b32_e32 v0, 0
	s_addc_u32 s68, s43, 0
	s_mov_b32 s69, -2
	s_waitcnt lgkmcnt(0)
	ds_read_b128 v[144:147], v158
	ds_read_b128 v[164:167], v158 offset:1024
	ds_read_b128 v[168:171], v158 offset:2048
	ds_read_b128 v[172:175], v158 offset:3072
	s_add_u32 s0, s40, 0xffea0080
	s_addc_u32 s1, s41, -1
	s_cmpk_eq_i32 s69, 0x54
	s_cselect_b32 s45, s9, s1
	s_cselect_b32 s44, s8, s0
	s_cselect_b32 s43, s11, s68
	s_cselect_b32 s42, s10, s35
	s_add_i32 m0, s54, 0xc000
	ds_read_b128 v[176:179], v159
	ds_read_b128 v[180:183], v159 offset:1024
	ds_read_b128 v[188:191], v159 offset:2048
	ds_read_b128 v[194:197], v159 offset:3072
	ds_read_b128 v[198:201], v159 offset:4096
	ds_read_b128 v[202:205], v159 offset:5120
	ds_read_b128 v[206:209], v159 offset:6144
	global_load_lds_dwordx4 v136, s[40:41]
	s_add_i32 m0, s54, 0xe000
	ds_read_b128 v[210:213], v159 offset:7168
	global_load_lds_dwordx4 v138, s[40:41]
	s_waitcnt lgkmcnt(8)
	s_barrier
	s_waitcnt lgkmcnt(0)
	s_setprio 1
	v_mfma_f32_16x16x32_bf16 v[124:127], v[144:147], v[176:179], 0
	v_mfma_f32_16x16x32_bf16 v[120:123], v[168:171], v[176:179], 0
	v_mfma_f32_16x16x32_bf16 v[108:111], v[144:147], v[188:191], 0
	v_mfma_f32_16x16x32_bf16 v[104:107], v[168:171], v[188:191], 0
	v_mfma_f32_16x16x32_bf16 v[92:95], v[144:147], v[198:201], 0
	v_mfma_f32_16x16x32_bf16 v[88:91], v[168:171], v[198:201], 0
	v_mfma_f32_16x16x32_bf16 v[76:79], v[144:147], v[206:209], 0
	v_mfma_f32_16x16x32_bf16 v[72:75], v[168:171], v[206:209], 0
	v_mfma_f32_16x16x32_bf16 v[124:127], v[164:167], v[180:183], v[124:127]
	v_mfma_f32_16x16x32_bf16 v[120:123], v[172:175], v[180:183], v[120:123]
	v_mfma_f32_16x16x32_bf16 v[108:111], v[164:167], v[194:197], v[108:111]
	v_mfma_f32_16x16x32_bf16 v[104:107], v[172:175], v[194:197], v[104:107]
	v_mfma_f32_16x16x32_bf16 v[92:95], v[164:167], v[202:205], v[92:95]
	v_mfma_f32_16x16x32_bf16 v[88:91], v[172:175], v[202:205], v[88:91]
	v_mfma_f32_16x16x32_bf16 v[76:79], v[164:167], v[210:213], v[76:79]
	v_mfma_f32_16x16x32_bf16 v[72:75], v[172:175], v[210:213], v[72:75]
	s_setprio 0
	s_barrier
	s_add_i32 s0, s63, s53
	s_mov_b32 m0, s0
	ds_read_b128 v[214:217], v161
	ds_read_b128 v[218:221], v161 offset:1024
	ds_read_b128 v[222:225], v161 offset:2048
	global_load_lds_dwordx4 v130, s[42:43]
	s_add_i32 m0, s0, 0x2000
	ds_read_b128 v[226:229], v161 offset:3072
	global_load_lds_dwordx4 v134, s[42:43]
	s_barrier
	s_waitcnt lgkmcnt(0)
	s_setprio 1
	v_mfma_f32_16x16x32_bf16 v[116:119], v[214:217], v[176:179], 0
	v_mfma_f32_16x16x32_bf16 v[112:115], v[222:225], v[176:179], 0
	v_mfma_f32_16x16x32_bf16 v[100:103], v[214:217], v[188:191], 0
	v_mfma_f32_16x16x32_bf16 v[96:99], v[222:225], v[188:191], 0
	v_mfma_f32_16x16x32_bf16 v[84:87], v[214:217], v[198:201], 0
	v_mfma_f32_16x16x32_bf16 v[80:83], v[222:225], v[198:201], 0
	v_mfma_f32_16x16x32_bf16 v[68:71], v[214:217], v[206:209], 0
	v_mfma_f32_16x16x32_bf16 v[64:67], v[222:225], v[206:209], 0
	v_mfma_f32_16x16x32_bf16 v[116:119], v[218:221], v[180:183], v[116:119]
	v_mfma_f32_16x16x32_bf16 v[112:115], v[226:229], v[180:183], v[112:115]
	v_mfma_f32_16x16x32_bf16 v[100:103], v[218:221], v[194:197], v[100:103]
	v_mfma_f32_16x16x32_bf16 v[96:99], v[226:229], v[194:197], v[96:99]
	v_mfma_f32_16x16x32_bf16 v[84:87], v[218:221], v[202:205], v[84:87]
	v_mfma_f32_16x16x32_bf16 v[80:83], v[226:229], v[202:205], v[80:83]
	v_mfma_f32_16x16x32_bf16 v[68:71], v[218:221], v[210:213], v[68:71]
	v_mfma_f32_16x16x32_bf16 v[64:67], v[226:229], v[210:213], v[64:67]
	s_setprio 0
	s_mov_b32 m0, s54
	s_barrier
	ds_read_b128 v[176:179], v159 offset:16384
	ds_read_b128 v[180:183], v159 offset:17408
	ds_read_b128 v[188:191], v159 offset:18432
	ds_read_b128 v[194:197], v159 offset:19456
	ds_read_b128 v[198:201], v159 offset:20480
	ds_read_b128 v[202:205], v159 offset:21504
	ds_read_b128 v[206:209], v159 offset:22528
	global_load_lds_dwordx4 v128, s[44:45]
	s_mov_b32 m0, s55
	ds_read_b128 v[210:213], v159 offset:23552
	global_load_lds_dwordx4 v132, s[44:45]
	s_barrier
	s_waitcnt lgkmcnt(0)
	s_setprio 1
	v_mfma_f32_16x16x32_bf16 v[60:63], v[144:147], v[176:179], 0
	v_mfma_f32_16x16x32_bf16 v[56:59], v[168:171], v[176:179], 0
	v_mfma_f32_16x16x32_bf16 v[44:47], v[144:147], v[188:191], 0
	v_mfma_f32_16x16x32_bf16 v[40:43], v[168:171], v[188:191], 0
	v_mfma_f32_16x16x32_bf16 v[28:31], v[144:147], v[198:201], 0
	v_mfma_f32_16x16x32_bf16 v[24:27], v[168:171], v[198:201], 0
	v_mfma_f32_16x16x32_bf16 v[12:15], v[144:147], v[206:209], 0
	v_mfma_f32_16x16x32_bf16 v[8:11], v[168:171], v[206:209], 0
	v_mfma_f32_16x16x32_bf16 v[60:63], v[164:167], v[180:183], v[60:63]
	v_mfma_f32_16x16x32_bf16 v[56:59], v[172:175], v[180:183], v[56:59]
	v_mfma_f32_16x16x32_bf16 v[44:47], v[164:167], v[194:197], v[44:47]
	v_mfma_f32_16x16x32_bf16 v[40:43], v[172:175], v[194:197], v[40:43]
	v_mfma_f32_16x16x32_bf16 v[28:31], v[164:167], v[202:205], v[28:31]
	v_mfma_f32_16x16x32_bf16 v[24:27], v[172:175], v[202:205], v[24:27]
	v_mfma_f32_16x16x32_bf16 v[12:15], v[164:167], v[210:213], v[12:15]
	v_mfma_f32_16x16x32_bf16 v[8:11], v[172:175], v[210:213], v[8:11]
	s_setprio 0
	s_barrier
	s_add_u32 s0, s42, 0x160000
	s_addc_u32 s1, s43, 0
	s_add_i32 s4, s64, s53
	s_mov_b32 m0, s4
	s_nop 0
	global_load_lds_dwordx4 v130, s[0:1]
	s_add_i32 m0, s4, 0x2000
	s_nop 0
	global_load_lds_dwordx4 v134, s[0:1]
	s_waitcnt vmcnt(6)
	s_barrier
; #define PG8_STAGE(bufoff, gbase, voff) do { _Pragma("unroll") for (int _i = 0; _i < 2; ++_i) \
;         __builtin_amdgcn_global_load_lds((const unsigned*)((const char*)(gbase) + (voff)[_i]), (LAS unsigned*)(lds + (bufoff) + ldsw + _i * 8192), 16, 0, 0); } while (0)
; #define PG8_LDA(dst, b, h) do { _Pragma("unroll") for (int m = 0; m < 4; ++m) _Pragma("unroll") for (int k = 0; k < 2; ++k) dst[m][k] = *(const LAS bf16x8*)(lds + PG8_SA(b, h) + aoff + m * 2048 + k * 1024); } while (0)
; #define PG8_LDB(dst, b, h) do { _Pragma("unroll") for (int n = 0; n < 2; ++n) _Pragma("unroll") for (int k = 0; k < 2; ++k) dst[n][k] = *(const LAS bf16x8*)(lds + PG8_SB(b, h) + boff + n * 2048 + k * 1024); } while (0)
; #define PG8_MMA(ai, bj, At, Bt) do { __builtin_amdgcn_s_setprio(1); _Pragma("unroll") for (int m = 0; m < 4; ++m) _Pragma("unroll") for (int n = 0; n < 2; ++n) _Pragma("unroll") for (int k = 0; k < 2; ++k) \
;         acc[ai][bj][m][n] = __builtin_amdgcn_mfma_f32_16x16x32_bf16(Bt[n][k], At[m][k], acc[ai][bj][m][n], 0, 0, 0); __builtin_amdgcn_s_setprio(0); } while (0)
; #define PG8_WAIT_V(n) asm volatile("s_waitcnt vmcnt(" #n ")" ::: "memory")
; #define PG8_WAIT_L(n) asm volatile("s_waitcnt lgkmcnt(" #n ")" ::: "memory")
; #define PG8_BAR __builtin_amdgcn_s_barrier()
; #define PG8_SCHED __builtin_amdgcn_sched_barrier(0)
; template <class Epi, class Sched>
; DI void gemm_phase(LAS unsigned char* lds, const Gemm g, const Sched& S, const Epi& E) {
;     ...
;             PG8_WAIT_V(6); PG8_BAR; PG8_MMA(1, 1, At, B1); PG8_BAR;
;             PG8_LDB(B0, 1, 0); PG8_SCHED; PG8_LDA(At, 1, 0); PG8_STAGE(PG8_SA(0, 1), a2 + hstep, voffA);
;             PG8_WAIT_L(8); PG8_BAR; PG8_WAIT_L(0); PG8_MMA(0, 0, At, B0); PG8_BAR; PG8_SCHED;
;             PG8_LDB(B1, 1, 1); PG8_STAGE(PG8_SB(1, 0), b3, voffB);
;             PG8_BAR; PG8_WAIT_L(0); PG8_MMA(0, 1, At, B1); PG8_BAR;
;             PG8_LDA(At, 1, 1); PG8_STAGE(PG8_SA(1, 0), a3, voffA);
;             PG8_BAR; PG8_WAIT_L(0); PG8_MMA(1, 0, At, B0); PG8_BAR; PG8_SCHED;
;             PG8_STAGE(PG8_SB(1, 1), b3 + hstep, voffB);
;             PG8_WAIT_V(6); PG8_BAR; PG8_MMA(1, 1, At, B1); PG8_BAR;
	s_setprio 1
	v_mfma_f32_16x16x32_bf16 v[52:55], v[214:217], v[176:179], 0
	v_mfma_f32_16x16x32_bf16 v[48:51], v[222:225], v[176:179], 0
	v_mfma_f32_16x16x32_bf16 v[36:39], v[214:217], v[188:191], 0
	v_mfma_f32_16x16x32_bf16 v[32:35], v[222:225], v[188:191], 0
	v_mfma_f32_16x16x32_bf16 v[20:23], v[214:217], v[198:201], 0
	v_mfma_f32_16x16x32_bf16 v[16:19], v[222:225], v[198:201], 0
	v_mfma_f32_16x16x32_bf16 v[4:7], v[214:217], v[206:209], 0
	v_mfma_f32_16x16x32_bf16 v[0:3], v[222:225], v[206:209], 0
	v_mfma_f32_16x16x32_bf16 v[52:55], v[218:221], v[180:183], v[52:55]
	v_mfma_f32_16x16x32_bf16 v[48:51], v[226:229], v[180:183], v[48:51]
	v_mfma_f32_16x16x32_bf16 v[36:39], v[218:221], v[194:197], v[36:39]
	v_mfma_f32_16x16x32_bf16 v[32:35], v[226:229], v[194:197], v[32:35]
	v_mfma_f32_16x16x32_bf16 v[20:23], v[218:221], v[202:205], v[20:23]
	v_mfma_f32_16x16x32_bf16 v[16:19], v[226:229], v[202:205], v[16:19]
	v_mfma_f32_16x16x32_bf16 v[4:7], v[218:221], v[210:213], v[4:7]
	v_mfma_f32_16x16x32_bf16 v[0:3], v[226:229], v[210:213], v[0:3]
	s_setprio 0
	s_add_i32 s4, 0, 0x18000
	v_add_u32_e32 v163, s4, v157
	s_barrier
	ds_read_b128 v[144:147], v163
	ds_read_b128 v[164:167], v163 offset:1024
	ds_read_b128 v[168:171], v163 offset:2048
	ds_read_b128 v[172:175], v163 offset:3072
	s_add_u32 s0, s44, 0x160000
	s_addc_u32 s1, s45, 0
	s_mov_b32 m0, s56
	ds_read_b128 v[176:179], v159 offset:32768
	ds_read_b128 v[180:183], v159 offset:33792
	ds_read_b128 v[188:191], v159 offset:34816
	ds_read_b128 v[194:197], v159 offset:35840
	ds_read_b128 v[198:201], v159 offset:36864
	ds_read_b128 v[202:205], v159 offset:37888
	ds_read_b128 v[206:209], v159 offset:38912
	global_load_lds_dwordx4 v128, s[0:1]
	s_mov_b32 m0, s57
	ds_read_b128 v[210:213], v159 offset:39936
	global_load_lds_dwordx4 v132, s[0:1]
	s_waitcnt lgkmcnt(8)
	s_barrier
	s_waitcnt lgkmcnt(0)
	s_setprio 1
	v_mfma_f32_16x16x32_bf16 v[124:127], v[144:147], v[176:179], v[124:127]
	v_mfma_f32_16x16x32_bf16 v[120:123], v[168:171], v[176:179], v[120:123]
	v_mfma_f32_16x16x32_bf16 v[108:111], v[144:147], v[188:191], v[108:111]
	v_mfma_f32_16x16x32_bf16 v[104:107], v[168:171], v[188:191], v[104:107]
	v_mfma_f32_16x16x32_bf16 v[92:95], v[144:147], v[198:201], v[92:95]
	v_mfma_f32_16x16x32_bf16 v[88:91], v[168:171], v[198:201], v[88:91]
	v_mfma_f32_16x16x32_bf16 v[76:79], v[144:147], v[206:209], v[76:79]
	v_mfma_f32_16x16x32_bf16 v[72:75], v[168:171], v[206:209], v[72:75]
	v_mfma_f32_16x16x32_bf16 v[124:127], v[164:167], v[180:183], v[124:127]
	v_mfma_f32_16x16x32_bf16 v[120:123], v[172:175], v[180:183], v[120:123]
	v_mfma_f32_16x16x32_bf16 v[108:111], v[164:167], v[194:197], v[108:111]
	v_mfma_f32_16x16x32_bf16 v[104:107], v[172:175], v[194:197], v[104:107]
	v_mfma_f32_16x16x32_bf16 v[92:95], v[164:167], v[202:205], v[92:95]
	v_mfma_f32_16x16x32_bf16 v[88:91], v[172:175], v[202:205], v[88:91]
	v_mfma_f32_16x16x32_bf16 v[76:79], v[164:167], v[210:213], v[76:79]
	v_mfma_f32_16x16x32_bf16 v[72:75], v[172:175], v[210:213], v[72:75]
	s_setprio 0
	s_barrier
	s_add_i32 s5, 0, 0x1c000
	s_add_i32 s0, s4, s53
	v_add_u32_e32 v163, s5, v157
	s_add_i32 m0, s0, 0xffffff80
	ds_read_b128 v[214:217], v163
	ds_read_b128 v[218:221], v163 offset:1024
	ds_read_b128 v[222:225], v163 offset:2048
	global_load_lds_dwordx4 v130, s[42:43] offset:128
	s_add_i32 m0, s0, 0x1f80
	ds_read_b128 v[226:229], v163 offset:3072
	global_load_lds_dwordx4 v134, s[42:43] offset:128
	s_barrier
	s_waitcnt lgkmcnt(0)
	s_setprio 1
	v_mfma_f32_16x16x32_bf16 v[116:119], v[214:217], v[176:179], v[116:119]
	v_mfma_f32_16x16x32_bf16 v[112:115], v[222:225], v[176:179], v[112:115]
	v_mfma_f32_16x16x32_bf16 v[100:103], v[214:217], v[188:191], v[100:103]
	v_mfma_f32_16x16x32_bf16 v[96:99], v[222:225], v[188:191], v[96:99]
	v_mfma_f32_16x16x32_bf16 v[84:87], v[214:217], v[198:201], v[84:87]
	v_mfma_f32_16x16x32_bf16 v[80:83], v[222:225], v[198:201], v[80:83]
	v_mfma_f32_16x16x32_bf16 v[68:71], v[214:217], v[206:209], v[68:71]
	v_mfma_f32_16x16x32_bf16 v[64:67], v[222:225], v[206:209], v[64:67]
	v_mfma_f32_16x16x32_bf16 v[116:119], v[218:221], v[180:183], v[116:119]
	v_mfma_f32_16x16x32_bf16 v[112:115], v[226:229], v[180:183], v[112:115]
	v_mfma_f32_16x16x32_bf16 v[100:103], v[218:221], v[194:197], v[100:103]
	v_mfma_f32_16x16x32_bf16 v[96:99], v[226:229], v[194:197], v[96:99]
	v_mfma_f32_16x16x32_bf16 v[84:87], v[218:221], v[202:205], v[84:87]
	v_mfma_f32_16x16x32_bf16 v[80:83], v[226:229], v[202:205], v[80:83]
	v_mfma_f32_16x16x32_bf16 v[68:71], v[218:221], v[210:213], v[68:71]
	v_mfma_f32_16x16x32_bf16 v[64:67], v[226:229], v[210:213], v[64:67]
	s_setprio 0
	s_add_i32 m0, s61, 0xffffff80
	s_barrier
	ds_read_b128 v[176:179], v159 offset:49152
	ds_read_b128 v[180:183], v159 offset:50176
	ds_read_b128 v[188:191], v159 offset:51200
	ds_read_b128 v[194:197], v159 offset:52224
	ds_read_b128 v[198:201], v159 offset:53248
	ds_read_b128 v[202:205], v159 offset:54272
	ds_read_b128 v[206:209], v159 offset:55296
	global_load_lds_dwordx4 v128, s[44:45] offset:128
	s_add_i32 m0, s62, 0xffffff80
	ds_read_b128 v[210:213], v159 offset:56320
	global_load_lds_dwordx4 v132, s[44:45] offset:128
	s_barrier
; #define PG8_STAGE(bufoff, gbase, voff) do { _Pragma("unroll") for (int _i = 0; _i < 2; ++_i) \
;         __builtin_amdgcn_global_load_lds((const unsigned*)((const char*)(gbase) + (voff)[_i]), (LAS unsigned*)(lds + (bufoff) + ldsw + _i * 8192), 16, 0, 0); } while (0)
; #define PG8_LDA(dst, b, h) do { _Pragma("unroll") for (int m = 0; m < 4; ++m) _Pragma("unroll") for (int k = 0; k < 2; ++k) dst[m][k] = *(const LAS bf16x8*)(lds + PG8_SA(b, h) + aoff + m * 2048 + k * 1024); } while (0)
; #define PG8_LDB(dst, b, h) do { _Pragma("unroll") for (int n = 0; n < 2; ++n) _Pragma("unroll") for (int k = 0; k < 2; ++k) dst[n][k] = *(const LAS bf16x8*)(lds + PG8_SB(b, h) + boff + n * 2048 + k * 1024); } while (0)
; #define PG8_WAIT_V(n) asm volatile("s_waitcnt vmcnt(" #n ")" ::: "memory")
; #define PG8_WAIT_L(n) asm volatile("s_waitcnt lgkmcnt(" #n ")" ::: "memory")
; #define PG8_BAR __builtin_amdgcn_s_barrier()
; #define PG8_SCHED __builtin_amdgcn_sched_barrier(0)
; template <class Epi, class Sched>
; DI void gemm_phase(LAS unsigned char* lds, const Gemm g, const Sched& S, const Epi& E) {
;     ...
;             PG8_LDB(B0, 0, 0); PG8_SCHED; PG8_LDA(At, 0, 0); PG8_STAGE(PG8_SA(1, 1), a1 + hstep, voffA);
;             PG8_WAIT_L(8); PG8_BAR; PG8_WAIT_L(0); PG8_MMA(0, 0, At, B0); PG8_BAR; PG8_SCHED;
;             PG8_LDB(B1, 0, 1); PG8_STAGE(PG8_SB(0, 0), b2, voffB);
;             PG8_BAR; PG8_WAIT_L(0); PG8_MMA(0, 1, At, B1); PG8_BAR;
;             PG8_LDA(At, 0, 1); PG8_STAGE(PG8_SA(0, 0), a2, voffA);
;             PG8_BAR; PG8_WAIT_L(0); PG8_MMA(1, 0, At, B0); PG8_BAR; PG8_SCHED;
;             PG8_STAGE(PG8_SB(0, 1), b2 + hstep, voffB);
;             PG8_WAIT_V(6); PG8_BAR; PG8_MMA(1, 1, At, B1); PG8_BAR;
;             PG8_LDB(B0, 1, 0); PG8_SCHED; PG8_LDA(At, 1, 0); PG8_STAGE(PG8_SA(0, 1), a2 + hstep, voffA);
;             PG8_WAIT_L(8); PG8_BAR; PG8_WAIT_L(0); PG8_MMA(0, 0, At, B0); PG8_BAR; PG8_SCHED;
;             PG8_LDB(B1, 1, 1); PG8_STAGE(PG8_SB(1, 0), b3, voffB);
;             PG8_BAR; PG8_WAIT_L(0); PG8_MMA(0, 1, At, B1); PG8_BAR;
;             PG8_LDA(At, 1, 1); PG8_STAGE(PG8_SA(1, 0), a3, voffA);
;             PG8_BAR; PG8_WAIT_L(0); PG8_MMA(1, 0, At, B0); PG8_BAR; PG8_SCHED;
;             PG8_STAGE(PG8_SB(1, 1), b3 + hstep, voffB);
;             PG8_WAIT_V(6); PG8_BAR; PG8_MMA(1, 1, At, B1); PG8_BAR;
	s_waitcnt lgkmcnt(0)
	s_setprio 1
	v_mfma_f32_16x16x32_bf16 v[60:63], v[144:147], v[176:179], v[60:63]
	v_mfma_f32_16x16x32_bf16 v[56:59], v[168:171], v[176:179], v[56:59]
	v_mfma_f32_16x16x32_bf16 v[44:47], v[144:147], v[188:191], v[44:47]
	v_mfma_f32_16x16x32_bf16 v[40:43], v[168:171], v[188:191], v[40:43]
	v_mfma_f32_16x16x32_bf16 v[28:31], v[144:147], v[198:201], v[28:31]
	v_mfma_f32_16x16x32_bf16 v[24:27], v[168:171], v[198:201], v[24:27]
	v_mfma_f32_16x16x32_bf16 v[12:15], v[144:147], v[206:209], v[12:15]
	v_mfma_f32_16x16x32_bf16 v[8:11], v[168:171], v[206:209], v[8:11]
	v_mfma_f32_16x16x32_bf16 v[60:63], v[164:167], v[180:183], v[60:63]
	v_mfma_f32_16x16x32_bf16 v[56:59], v[172:175], v[180:183], v[56:59]
	v_mfma_f32_16x16x32_bf16 v[44:47], v[164:167], v[194:197], v[44:47]
	v_mfma_f32_16x16x32_bf16 v[40:43], v[172:175], v[194:197], v[40:43]
	v_mfma_f32_16x16x32_bf16 v[28:31], v[164:167], v[202:205], v[28:31]
	v_mfma_f32_16x16x32_bf16 v[24:27], v[172:175], v[202:205], v[24:27]
	v_mfma_f32_16x16x32_bf16 v[12:15], v[164:167], v[210:213], v[12:15]
	v_mfma_f32_16x16x32_bf16 v[8:11], v[172:175], v[210:213], v[8:11]
	s_setprio 0
	s_barrier
	s_add_u32 s0, s42, 0x160080
	s_addc_u32 s1, s43, 0
	s_add_i32 s4, s5, s53
	s_mov_b32 m0, s4
	s_nop 0
	global_load_lds_dwordx4 v130, s[0:1]
	s_add_i32 m0, s4, 0x2000
	s_nop 0
	global_load_lds_dwordx4 v134, s[0:1]
	s_waitcnt vmcnt(6)
	s_barrier
	s_setprio 1
	v_mfma_f32_16x16x32_bf16 v[52:55], v[214:217], v[176:179], v[52:55]
	v_mfma_f32_16x16x32_bf16 v[48:51], v[222:225], v[176:179], v[48:51]
	v_mfma_f32_16x16x32_bf16 v[36:39], v[214:217], v[188:191], v[36:39]
	v_mfma_f32_16x16x32_bf16 v[32:35], v[222:225], v[188:191], v[32:35]
	v_mfma_f32_16x16x32_bf16 v[20:23], v[214:217], v[198:201], v[20:23]
	v_mfma_f32_16x16x32_bf16 v[16:19], v[222:225], v[198:201], v[16:19]
	v_mfma_f32_16x16x32_bf16 v[4:7], v[214:217], v[206:209], v[4:7]
	v_mfma_f32_16x16x32_bf16 v[0:3], v[222:225], v[206:209], v[0:3]
	v_mfma_f32_16x16x32_bf16 v[52:55], v[218:221], v[180:183], v[52:55]
	v_mfma_f32_16x16x32_bf16 v[48:51], v[226:229], v[180:183], v[48:51]
	v_mfma_f32_16x16x32_bf16 v[36:39], v[218:221], v[194:197], v[36:39]
	v_mfma_f32_16x16x32_bf16 v[32:35], v[226:229], v[194:197], v[32:35]
	v_mfma_f32_16x16x32_bf16 v[20:23], v[218:221], v[202:205], v[20:23]
	v_mfma_f32_16x16x32_bf16 v[16:19], v[226:229], v[202:205], v[16:19]
	v_mfma_f32_16x16x32_bf16 v[4:7], v[218:221], v[210:213], v[4:7]
	v_mfma_f32_16x16x32_bf16 v[0:3], v[226:229], v[210:213], v[0:3]
	s_setprio 0
	s_add_i32 s69, s69, 2
	s_add_u32 s40, s40, 0x100
	s_addc_u32 s41, s41, 0
	s_add_u32 s35, s35, 0x100
	s_addc_u32 s68, s68, 0
	s_cmpk_gt_u32 s69, 0x55
	s_barrier
	s_cbranch_scc0 .LBB0_297
	s_branch .Lpeel_done_297
.LBB0_297:
	ds_read_b128 v[144:147], v158
	ds_read_b128 v[164:167], v158 offset:1024
	ds_read_b128 v[168:171], v158 offset:2048
	ds_read_b128 v[172:175], v158 offset:3072
	s_add_u32 s0, s40, 0xffea0080
	s_addc_u32 s1, s41, -1
	s_cmpk_eq_i32 s69, 0x54
	s_cselect_b32 s45, s9, s1
	s_cselect_b32 s44, s8, s0
	s_cselect_b32 s43, s11, s68
	s_cselect_b32 s42, s10, s35
	s_add_i32 m0, s54, 0xc000
	ds_read_b128 v[176:179], v159
	ds_read_b128 v[180:183], v159 offset:1024
	ds_read_b128 v[188:191], v159 offset:2048
	ds_read_b128 v[194:197], v159 offset:3072
	ds_read_b128 v[198:201], v159 offset:4096
	ds_read_b128 v[202:205], v159 offset:5120
	ds_read_b128 v[206:209], v159 offset:6144
	global_load_lds_dwordx4 v136, s[40:41]
	s_add_i32 m0, s54, 0xe000
	ds_read_b128 v[210:213], v159 offset:7168
	global_load_lds_dwordx4 v138, s[40:41]
	s_waitcnt lgkmcnt(8)
	s_barrier
	s_waitcnt lgkmcnt(0)
	s_setprio 1
	v_mfma_f32_16x16x32_bf16 v[124:127], v[144:147], v[176:179], v[124:127]
	v_mfma_f32_16x16x32_bf16 v[120:123], v[168:171], v[176:179], v[120:123]
	v_mfma_f32_16x16x32_bf16 v[108:111], v[144:147], v[188:191], v[108:111]
	v_mfma_f32_16x16x32_bf16 v[104:107], v[168:171], v[188:191], v[104:107]
	v_mfma_f32_16x16x32_bf16 v[92:95], v[144:147], v[198:201], v[92:95]
	v_mfma_f32_16x16x32_bf16 v[88:91], v[168:171], v[198:201], v[88:91]
	v_mfma_f32_16x16x32_bf16 v[76:79], v[144:147], v[206:209], v[76:79]
	v_mfma_f32_16x16x32_bf16 v[72:75], v[168:171], v[206:209], v[72:75]
	v_mfma_f32_16x16x32_bf16 v[124:127], v[164:167], v[180:183], v[124:127]
	v_mfma_f32_16x16x32_bf16 v[120:123], v[172:175], v[180:183], v[120:123]
	v_mfma_f32_16x16x32_bf16 v[108:111], v[164:167], v[194:197], v[108:111]
	v_mfma_f32_16x16x32_bf16 v[104:107], v[172:175], v[194:197], v[104:107]
	v_mfma_f32_16x16x32_bf16 v[92:95], v[164:167], v[202:205], v[92:95]
	v_mfma_f32_16x16x32_bf16 v[88:91], v[172:175], v[202:205], v[88:91]
	v_mfma_f32_16x16x32_bf16 v[76:79], v[164:167], v[210:213], v[76:79]
	v_mfma_f32_16x16x32_bf16 v[72:75], v[172:175], v[210:213], v[72:75]
	s_setprio 0
	s_barrier
	s_add_i32 s0, s63, s53
	s_mov_b32 m0, s0
	ds_read_b128 v[214:217], v161
	ds_read_b128 v[218:221], v161 offset:1024
	ds_read_b128 v[222:225], v161 offset:2048
	global_load_lds_dwordx4 v130, s[42:43]
	s_add_i32 m0, s0, 0x2000
	ds_read_b128 v[226:229], v161 offset:3072
	global_load_lds_dwordx4 v134, s[42:43]
	s_barrier
; #define PG8_STAGE(bufoff, gbase, voff) do { _Pragma("unroll") for (int _i = 0; _i < 2; ++_i) \
;         __builtin_amdgcn_global_load_lds((const unsigned*)((const char*)(gbase) + (voff)[_i]), (LAS unsigned*)(lds + (bufoff) + ldsw + _i * 8192), 16, 0, 0); } while (0)
; #define PG8_LDA(dst, b, h) do { _Pragma("unroll") for (int m = 0; m < 4; ++m) _Pragma("unroll") for (int k = 0; k < 2; ++k) dst[m][k] = *(const LAS bf16x8*)(lds + PG8_SA(b, h) + aoff + m * 2048 + k * 1024); } while (0)
; #define PG8_LDB(dst, b, h) do { _Pragma("unroll") for (int n = 0; n < 2; ++n) _Pragma("unroll") for (int k = 0; k < 2; ++k) dst[n][k] = *(const LAS bf16x8*)(lds + PG8_SB(b, h) + boff + n * 2048 + k * 1024); } while (0)
; #define PG8_MMA(ai, bj, At, Bt) do { __builtin_amdgcn_s_setprio(1); _Pragma("unroll") for (int m = 0; m < 4; ++m) _Pragma("unroll") for (int n = 0; n < 2; ++n) _Pragma("unroll") for (int k = 0; k < 2; ++k) \
;         acc[ai][bj][m][n] = __builtin_amdgcn_mfma_f32_16x16x32_bf16(Bt[n][k], At[m][k], acc[ai][bj][m][n], 0, 0, 0); __builtin_amdgcn_s_setprio(0); } while (0)
; #define PG8_WAIT_V(n) asm volatile("s_waitcnt vmcnt(" #n ")" ::: "memory")
; #define PG8_WAIT_L(n) asm volatile("s_waitcnt lgkmcnt(" #n ")" ::: "memory")
; #define PG8_BAR __builtin_amdgcn_s_barrier()
; #define PG8_SCHED __builtin_amdgcn_sched_barrier(0)
; template <class Epi, class Sched>
; DI void gemm_phase(LAS unsigned char* lds, const Gemm g, const Sched& S, const Epi& E) {
;     ...
;             PG8_BAR; PG8_WAIT_L(0); PG8_MMA(0, 1, At, B1); PG8_BAR;
;             PG8_LDA(At, 0, 1); PG8_STAGE(PG8_SA(0, 0), a2, voffA);
;             PG8_BAR; PG8_WAIT_L(0); PG8_MMA(1, 0, At, B0); PG8_BAR; PG8_SCHED;
;             PG8_STAGE(PG8_SB(0, 1), b2 + hstep, voffB);
;             PG8_WAIT_V(6); PG8_BAR; PG8_MMA(1, 1, At, B1); PG8_BAR;
;             PG8_LDB(B0, 1, 0); PG8_SCHED; PG8_LDA(At, 1, 0); PG8_STAGE(PG8_SA(0, 1), a2 + hstep, voffA);
;             PG8_WAIT_L(8); PG8_BAR; PG8_WAIT_L(0); PG8_MMA(0, 0, At, B0); PG8_BAR; PG8_SCHED;
;             PG8_LDB(B1, 1, 1); PG8_STAGE(PG8_SB(1, 0), b3, voffB);
;             PG8_BAR; PG8_WAIT_L(0); PG8_MMA(0, 1, At, B1); PG8_BAR;
;             PG8_LDA(At, 1, 1); PG8_STAGE(PG8_SA(1, 0), a3, voffA);
	s_waitcnt lgkmcnt(0)
	s_setprio 1
	v_mfma_f32_16x16x32_bf16 v[116:119], v[214:217], v[176:179], v[116:119]
	v_mfma_f32_16x16x32_bf16 v[112:115], v[222:225], v[176:179], v[112:115]
	v_mfma_f32_16x16x32_bf16 v[100:103], v[214:217], v[188:191], v[100:103]
	v_mfma_f32_16x16x32_bf16 v[96:99], v[222:225], v[188:191], v[96:99]
	v_mfma_f32_16x16x32_bf16 v[84:87], v[214:217], v[198:201], v[84:87]
	v_mfma_f32_16x16x32_bf16 v[80:83], v[222:225], v[198:201], v[80:83]
	v_mfma_f32_16x16x32_bf16 v[68:71], v[214:217], v[206:209], v[68:71]
	v_mfma_f32_16x16x32_bf16 v[64:67], v[222:225], v[206:209], v[64:67]
	v_mfma_f32_16x16x32_bf16 v[116:119], v[218:221], v[180:183], v[116:119]
	v_mfma_f32_16x16x32_bf16 v[112:115], v[226:229], v[180:183], v[112:115]
	v_mfma_f32_16x16x32_bf16 v[100:103], v[218:221], v[194:197], v[100:103]
	v_mfma_f32_16x16x32_bf16 v[96:99], v[226:229], v[194:197], v[96:99]
	v_mfma_f32_16x16x32_bf16 v[84:87], v[218:221], v[202:205], v[84:87]
	v_mfma_f32_16x16x32_bf16 v[80:83], v[226:229], v[202:205], v[80:83]
	v_mfma_f32_16x16x32_bf16 v[68:71], v[218:221], v[210:213], v[68:71]
	v_mfma_f32_16x16x32_bf16 v[64:67], v[226:229], v[210:213], v[64:67]
	s_setprio 0
	s_mov_b32 m0, s54
	s_barrier
	ds_read_b128 v[176:179], v159 offset:16384
	ds_read_b128 v[180:183], v159 offset:17408
	ds_read_b128 v[188:191], v159 offset:18432
	ds_read_b128 v[194:197], v159 offset:19456
	ds_read_b128 v[198:201], v159 offset:20480
	ds_read_b128 v[202:205], v159 offset:21504
	ds_read_b128 v[206:209], v159 offset:22528
	global_load_lds_dwordx4 v128, s[44:45]
	s_mov_b32 m0, s55
	ds_read_b128 v[210:213], v159 offset:23552
	global_load_lds_dwordx4 v132, s[44:45]
	s_barrier
	s_waitcnt lgkmcnt(0)
	s_setprio 1
	v_mfma_f32_16x16x32_bf16 v[60:63], v[144:147], v[176:179], v[60:63]
	v_mfma_f32_16x16x32_bf16 v[56:59], v[168:171], v[176:179], v[56:59]
	v_mfma_f32_16x16x32_bf16 v[44:47], v[144:147], v[188:191], v[44:47]
	v_mfma_f32_16x16x32_bf16 v[40:43], v[168:171], v[188:191], v[40:43]
	v_mfma_f32_16x16x32_bf16 v[28:31], v[144:147], v[198:201], v[28:31]
	v_mfma_f32_16x16x32_bf16 v[24:27], v[168:171], v[198:201], v[24:27]
	v_mfma_f32_16x16x32_bf16 v[12:15], v[144:147], v[206:209], v[12:15]
	v_mfma_f32_16x16x32_bf16 v[8:11], v[168:171], v[206:209], v[8:11]
	v_mfma_f32_16x16x32_bf16 v[60:63], v[164:167], v[180:183], v[60:63]
	v_mfma_f32_16x16x32_bf16 v[56:59], v[172:175], v[180:183], v[56:59]
	v_mfma_f32_16x16x32_bf16 v[44:47], v[164:167], v[194:197], v[44:47]
	v_mfma_f32_16x16x32_bf16 v[40:43], v[172:175], v[194:197], v[40:43]
	v_mfma_f32_16x16x32_bf16 v[28:31], v[164:167], v[202:205], v[28:31]
	v_mfma_f32_16x16x32_bf16 v[24:27], v[172:175], v[202:205], v[24:27]
	v_mfma_f32_16x16x32_bf16 v[12:15], v[164:167], v[210:213], v[12:15]
	v_mfma_f32_16x16x32_bf16 v[8:11], v[172:175], v[210:213], v[8:11]
	s_setprio 0
	s_barrier
	s_add_u32 s0, s42, 0x160000
	s_addc_u32 s1, s43, 0
	s_add_i32 s4, s64, s53
	s_mov_b32 m0, s4
	s_nop 0
	global_load_lds_dwordx4 v130, s[0:1]
	s_add_i32 m0, s4, 0x2000
	s_nop 0
	global_load_lds_dwordx4 v134, s[0:1]
	s_waitcnt vmcnt(6)
	s_barrier
	s_setprio 1
	v_mfma_f32_16x16x32_bf16 v[52:55], v[214:217], v[176:179], v[52:55]
	v_mfma_f32_16x16x32_bf16 v[48:51], v[222:225], v[176:179], v[48:51]
	v_mfma_f32_16x16x32_bf16 v[36:39], v[214:217], v[188:191], v[36:39]
	v_mfma_f32_16x16x32_bf16 v[32:35], v[222:225], v[188:191], v[32:35]
	v_mfma_f32_16x16x32_bf16 v[20:23], v[214:217], v[198:201], v[20:23]
	v_mfma_f32_16x16x32_bf16 v[16:19], v[222:225], v[198:201], v[16:19]
	v_mfma_f32_16x16x32_bf16 v[4:7], v[214:217], v[206:209], v[4:7]
	v_mfma_f32_16x16x32_bf16 v[0:3], v[222:225], v[206:209], v[0:3]
	v_mfma_f32_16x16x32_bf16 v[52:55], v[218:221], v[180:183], v[52:55]
	v_mfma_f32_16x16x32_bf16 v[48:51], v[226:229], v[180:183], v[48:51]
	v_mfma_f32_16x16x32_bf16 v[36:39], v[218:221], v[194:197], v[36:39]
	v_mfma_f32_16x16x32_bf16 v[32:35], v[226:229], v[194:197], v[32:35]
	v_mfma_f32_16x16x32_bf16 v[20:23], v[218:221], v[202:205], v[20:23]
	v_mfma_f32_16x16x32_bf16 v[16:19], v[226:229], v[202:205], v[16:19]
	v_mfma_f32_16x16x32_bf16 v[4:7], v[218:221], v[210:213], v[4:7]
	v_mfma_f32_16x16x32_bf16 v[0:3], v[226:229], v[210:213], v[0:3]
	s_setprio 0
	s_add_i32 s4, 0, 0x18000
	v_add_u32_e32 v163, s4, v157
	s_barrier
	ds_read_b128 v[144:147], v163
	ds_read_b128 v[164:167], v163 offset:1024
	ds_read_b128 v[168:171], v163 offset:2048
	ds_read_b128 v[172:175], v163 offset:3072
	s_add_u32 s0, s44, 0x160000
	s_addc_u32 s1, s45, 0
	s_mov_b32 m0, s56
	ds_read_b128 v[176:179], v159 offset:32768
	ds_read_b128 v[180:183], v159 offset:33792
	ds_read_b128 v[188:191], v159 offset:34816
	ds_read_b128 v[194:197], v159 offset:35840
	ds_read_b128 v[198:201], v159 offset:36864
	ds_read_b128 v[202:205], v159 offset:37888
	ds_read_b128 v[206:209], v159 offset:38912
	global_load_lds_dwordx4 v128, s[0:1]
	s_mov_b32 m0, s57
	ds_read_b128 v[210:213], v159 offset:39936
	global_load_lds_dwordx4 v132, s[0:1]
	s_waitcnt lgkmcnt(8)
	s_barrier
; #define PG8_STAGE(bufoff, gbase, voff) do { _Pragma("unroll") for (int _i = 0; _i < 2; ++_i) \
;         __builtin_amdgcn_global_load_lds((const unsigned*)((const char*)(gbase) + (voff)[_i]), (LAS unsigned*)(lds + (bufoff) + ldsw + _i * 8192), 16, 0, 0); } while (0)
; #define PG8_LDA(dst, b, h) do { _Pragma("unroll") for (int m = 0; m < 4; ++m) _Pragma("unroll") for (int k = 0; k < 2; ++k) dst[m][k] = *(const LAS bf16x8*)(lds + PG8_SA(b, h) + aoff + m * 2048 + k * 1024); } while (0)
; #define PG8_LDB(dst, b, h) do { _Pragma("unroll") for (int n = 0; n < 2; ++n) _Pragma("unroll") for (int k = 0; k < 2; ++k) dst[n][k] = *(const LAS bf16x8*)(lds + PG8_SB(b, h) + boff + n * 2048 + k * 1024); } while (0)
; #define PG8_MMA(ai, bj, At, Bt) do { __builtin_amdgcn_s_setprio(1); _Pragma("unroll") for (int m = 0; m < 4; ++m) _Pragma("unroll") for (int n = 0; n < 2; ++n) _Pragma("unroll") for (int k = 0; k < 2; ++k) \
;         acc[ai][bj][m][n] = __builtin_amdgcn_mfma_f32_16x16x32_bf16(Bt[n][k], At[m][k], acc[ai][bj][m][n], 0, 0, 0); __builtin_amdgcn_s_setprio(0); } while (0)
; #define PG8_WAIT_V(n) asm volatile("s_waitcnt vmcnt(" #n ")" ::: "memory")
; #define PG8_WAIT_L(n) asm volatile("s_waitcnt lgkmcnt(" #n ")" ::: "memory")
; #define PG8_BAR __builtin_amdgcn_s_barrier()
; #define PG8_SCHED __builtin_amdgcn_sched_barrier(0)
; template <class Epi, class Sched>
; DI void gemm_phase(LAS unsigned char* lds, const Gemm g, const Sched& S, const Epi& E) {
;     ...
;             PG8_WAIT_L(8); PG8_BAR; PG8_WAIT_L(0); PG8_MMA(0, 0, At, B0); PG8_BAR; PG8_SCHED;
;             PG8_LDB(B1, 1, 1); PG8_STAGE(PG8_SB(1, 0), b3, voffB);
;             PG8_BAR; PG8_WAIT_L(0); PG8_MMA(0, 1, At, B1); PG8_BAR;
;             PG8_LDA(At, 1, 1); PG8_STAGE(PG8_SA(1, 0), a3, voffA);
;             PG8_BAR; PG8_WAIT_L(0); PG8_MMA(1, 0, At, B0); PG8_BAR; PG8_SCHED;
;             PG8_STAGE(PG8_SB(1, 1), b3 + hstep, voffB);
;             PG8_WAIT_V(6); PG8_BAR; PG8_MMA(1, 1, At, B1); PG8_BAR;
	s_waitcnt lgkmcnt(0)
	s_setprio 1
	v_mfma_f32_16x16x32_bf16 v[124:127], v[144:147], v[176:179], v[124:127]
	v_mfma_f32_16x16x32_bf16 v[120:123], v[168:171], v[176:179], v[120:123]
	v_mfma_f32_16x16x32_bf16 v[108:111], v[144:147], v[188:191], v[108:111]
	v_mfma_f32_16x16x32_bf16 v[104:107], v[168:171], v[188:191], v[104:107]
	v_mfma_f32_16x16x32_bf16 v[92:95], v[144:147], v[198:201], v[92:95]
	v_mfma_f32_16x16x32_bf16 v[88:91], v[168:171], v[198:201], v[88:91]
	v_mfma_f32_16x16x32_bf16 v[76:79], v[144:147], v[206:209], v[76:79]
	v_mfma_f32_16x16x32_bf16 v[72:75], v[168:171], v[206:209], v[72:75]
	v_mfma_f32_16x16x32_bf16 v[124:127], v[164:167], v[180:183], v[124:127]
	v_mfma_f32_16x16x32_bf16 v[120:123], v[172:175], v[180:183], v[120:123]
	v_mfma_f32_16x16x32_bf16 v[108:111], v[164:167], v[194:197], v[108:111]
	v_mfma_f32_16x16x32_bf16 v[104:107], v[172:175], v[194:197], v[104:107]
	v_mfma_f32_16x16x32_bf16 v[92:95], v[164:167], v[202:205], v[92:95]
	v_mfma_f32_16x16x32_bf16 v[88:91], v[172:175], v[202:205], v[88:91]
	v_mfma_f32_16x16x32_bf16 v[76:79], v[164:167], v[210:213], v[76:79]
	v_mfma_f32_16x16x32_bf16 v[72:75], v[172:175], v[210:213], v[72:75]
	s_setprio 0
	s_barrier
	s_add_i32 s5, 0, 0x1c000
	s_add_i32 s0, s4, s53
	v_add_u32_e32 v163, s5, v157
	s_add_i32 m0, s0, 0xffffff80
	ds_read_b128 v[214:217], v163
	ds_read_b128 v[218:221], v163 offset:1024
	ds_read_b128 v[222:225], v163 offset:2048
	global_load_lds_dwordx4 v130, s[42:43] offset:128
	s_add_i32 m0, s0, 0x1f80
	ds_read_b128 v[226:229], v163 offset:3072
	global_load_lds_dwordx4 v134, s[42:43] offset:128
	s_barrier
	s_waitcnt lgkmcnt(0)
	s_setprio 1
	v_mfma_f32_16x16x32_bf16 v[116:119], v[214:217], v[176:179], v[116:119]
	v_mfma_f32_16x16x32_bf16 v[112:115], v[222:225], v[176:179], v[112:115]
	v_mfma_f32_16x16x32_bf16 v[100:103], v[214:217], v[188:191], v[100:103]
	v_mfma_f32_16x16x32_bf16 v[96:99], v[222:225], v[188:191], v[96:99]
	v_mfma_f32_16x16x32_bf16 v[84:87], v[214:217], v[198:201], v[84:87]
	v_mfma_f32_16x16x32_bf16 v[80:83], v[222:225], v[198:201], v[80:83]
	v_mfma_f32_16x16x32_bf16 v[68:71], v[214:217], v[206:209], v[68:71]
	v_mfma_f32_16x16x32_bf16 v[64:67], v[222:225], v[206:209], v[64:67]
	v_mfma_f32_16x16x32_bf16 v[116:119], v[218:221], v[180:183], v[116:119]
	v_mfma_f32_16x16x32_bf16 v[112:115], v[226:229], v[180:183], v[112:115]
	v_mfma_f32_16x16x32_bf16 v[100:103], v[218:221], v[194:197], v[100:103]
	v_mfma_f32_16x16x32_bf16 v[96:99], v[226:229], v[194:197], v[96:99]
	v_mfma_f32_16x16x32_bf16 v[84:87], v[218:221], v[202:205], v[84:87]
	v_mfma_f32_16x16x32_bf16 v[80:83], v[226:229], v[202:205], v[80:83]
	v_mfma_f32_16x16x32_bf16 v[68:71], v[218:221], v[210:213], v[68:71]
	v_mfma_f32_16x16x32_bf16 v[64:67], v[226:229], v[210:213], v[64:67]
	s_setprio 0
	s_add_i32 m0, s61, 0xffffff80
	s_barrier
	ds_read_b128 v[176:179], v159 offset:49152
	ds_read_b128 v[180:183], v159 offset:50176
	ds_read_b128 v[188:191], v159 offset:51200
	ds_read_b128 v[194:197], v159 offset:52224
	ds_read_b128 v[198:201], v159 offset:53248
	ds_read_b128 v[202:205], v159 offset:54272
	ds_read_b128 v[206:209], v159 offset:55296
	global_load_lds_dwordx4 v128, s[44:45] offset:128
	s_add_i32 m0, s62, 0xffffff80
	ds_read_b128 v[210:213], v159 offset:56320
	global_load_lds_dwordx4 v132, s[44:45] offset:128
	s_barrier
	s_waitcnt lgkmcnt(0)
	s_setprio 1
	v_mfma_f32_16x16x32_bf16 v[60:63], v[144:147], v[176:179], v[60:63]
	v_mfma_f32_16x16x32_bf16 v[56:59], v[168:171], v[176:179], v[56:59]
	v_mfma_f32_16x16x32_bf16 v[44:47], v[144:147], v[188:191], v[44:47]
	v_mfma_f32_16x16x32_bf16 v[40:43], v[168:171], v[188:191], v[40:43]
	v_mfma_f32_16x16x32_bf16 v[28:31], v[144:147], v[198:201], v[28:31]
	v_mfma_f32_16x16x32_bf16 v[24:27], v[168:171], v[198:201], v[24:27]
	v_mfma_f32_16x16x32_bf16 v[12:15], v[144:147], v[206:209], v[12:15]
	v_mfma_f32_16x16x32_bf16 v[8:11], v[168:171], v[206:209], v[8:11]
	v_mfma_f32_16x16x32_bf16 v[60:63], v[164:167], v[180:183], v[60:63]
	v_mfma_f32_16x16x32_bf16 v[56:59], v[172:175], v[180:183], v[56:59]
	v_mfma_f32_16x16x32_bf16 v[44:47], v[164:167], v[194:197], v[44:47]
	v_mfma_f32_16x16x32_bf16 v[40:43], v[172:175], v[194:197], v[40:43]
	v_mfma_f32_16x16x32_bf16 v[28:31], v[164:167], v[202:205], v[28:31]
	v_mfma_f32_16x16x32_bf16 v[24:27], v[172:175], v[202:205], v[24:27]
	v_mfma_f32_16x16x32_bf16 v[12:15], v[164:167], v[210:213], v[12:15]
	v_mfma_f32_16x16x32_bf16 v[8:11], v[172:175], v[210:213], v[8:11]
	s_setprio 0
	s_barrier
	s_add_u32 s0, s42, 0x160080
	s_addc_u32 s1, s43, 0
	s_add_i32 s4, s5, s53
	s_mov_b32 m0, s4
	s_nop 0
	global_load_lds_dwordx4 v130, s[0:1]
	s_add_i32 m0, s4, 0x2000
	s_nop 0
	global_load_lds_dwordx4 v134, s[0:1]
	s_waitcnt vmcnt(6)
	s_barrier
	s_setprio 1
	v_mfma_f32_16x16x32_bf16 v[52:55], v[214:217], v[176:179], v[52:55]
	v_mfma_f32_16x16x32_bf16 v[48:51], v[222:225], v[176:179], v[48:51]
	v_mfma_f32_16x16x32_bf16 v[36:39], v[214:217], v[188:191], v[36:39]
	v_mfma_f32_16x16x32_bf16 v[32:35], v[222:225], v[188:191], v[32:35]
	v_mfma_f32_16x16x32_bf16 v[20:23], v[214:217], v[198:201], v[20:23]
	v_mfma_f32_16x16x32_bf16 v[16:19], v[222:225], v[198:201], v[16:19]
	v_mfma_f32_16x16x32_bf16 v[4:7], v[214:217], v[206:209], v[4:7]
	v_mfma_f32_16x16x32_bf16 v[0:3], v[222:225], v[206:209], v[0:3]
	v_mfma_f32_16x16x32_bf16 v[52:55], v[218:221], v[180:183], v[52:55]
	v_mfma_f32_16x16x32_bf16 v[48:51], v[226:229], v[180:183], v[48:51]
	v_mfma_f32_16x16x32_bf16 v[36:39], v[218:221], v[194:197], v[36:39]
	v_mfma_f32_16x16x32_bf16 v[32:35], v[226:229], v[194:197], v[32:35]
	v_mfma_f32_16x16x32_bf16 v[20:23], v[218:221], v[202:205], v[20:23]
	v_mfma_f32_16x16x32_bf16 v[16:19], v[226:229], v[202:205], v[16:19]
	v_mfma_f32_16x16x32_bf16 v[4:7], v[218:221], v[210:213], v[4:7]
	v_mfma_f32_16x16x32_bf16 v[0:3], v[226:229], v[210:213], v[0:3]
	s_setprio 0
	s_add_i32 s69, s69, 2
	s_add_u32 s40, s40, 0x100
	s_addc_u32 s41, s41, 0
	s_add_u32 s35, s35, 0x100
	s_addc_u32 s68, s68, 0
	s_cmpk_gt_u32 s69, 0x55
	s_barrier
	s_cbranch_scc0 .LBB0_297

;     DI size_t aoff(const Unit& u, size_t tstep) const { return (size_t)u.pm * tstep; }
;     DI size_t boff(const Unit& u, size_t tstep) const { return (size_t)u.pn * tstep; }
;     DI bool next(int i, Unit& u) const { const long L = (long)i * G + c; if (L >= np) return false; u.pm = pmv; u.pn = (int)(L % nN); u.ks = (int)(L / nN); return true; }
;     DI size_t aoff(const Unit& u, size_t) const { return (size_t)u.ks * kbytes; }
;     DI size_t boff(const Unit& u, size_t tstep) const { return (size_t)u.pn * tstep + (size_t)u.ks * kbytes; }
;     DI bool next(int i, Unit& u) const { Unit t; if (!S.next(i / 3, t)) return false; u.pm = t.pm; u.pn = t.pn; u.ks = i % 3; return true; }
;     DI size_t aoff(const Unit& u, size_t tstep) const { return (u.ks < 2 ? offU : offOA) + (size_t)u.pm * tstep; }
; #define PG8_WAIT_V(n) asm volatile("s_waitcnt vmcnt(" #n ")" ::: "memory")
; template <class Epi, class Sched>
; DI void gemm_phase(LAS unsigned char* lds, const Gemm g, const Sched& S, const Epi& E) {
;     ...
;         const bool has_next = S.next(ui + 1, nxt);
;         const char* nA = has_next ? (const char*)g.A + S.aoff(nxt, tstep) : cA; const char* nB = has_next ? (const char*)g.Bt + S.boff(nxt, tstep) : cB;
;         for (int t = 0; t < nt; t += 2) {
;             if constexpr (Epi::HAS_MID) { if (t == E.mid_t(nt)) { int fr3 = fr, fq3 = fq; asm volatile("" : "+v"(fr3), "+v"(fq3)); E.mid(acc, cur, wr, wc, fr3, fq3); } }
;             const bool last = (t == nt - 2);
;             const char* a1 = cA + (size_t)(t + 1) * kstep;
;             const char* a2 = last ? nA : cA + (size_t)(t + 2) * kstep; const char* b2 = last ? nB : cB + (size_t)(t + 2) * kstep;
;             const char* a3 = a2 + kstep; const char* b3 = b2 + kstep;
;             PG8_LDB(B0, 0, 0); PG8_SCHED; PG8_LDA(At, 0, 0); PG8_STAGE(PG8_SA(1, 1), a1 + hstep, voffA);
;             PG8_WAIT_L(8); PG8_BAR; PG8_WAIT_L(0); PG8_MMA(0, 0, At, B0); PG8_BAR; PG8_SCHED;
;             PG8_LDB(B1, 0, 1); PG8_STAGE(PG8_SB(0, 0), b2, voffB);
;             PG8_BAR; PG8_WAIT_L(0); PG8_MMA(0, 1, At, B1); PG8_BAR;
;             PG8_LDA(At, 0, 1); PG8_STAGE(PG8_SA(0, 0), a2, voffA);
;             PG8_BAR; PG8_WAIT_L(0); PG8_MMA(1, 0, At, B0); PG8_BAR; PG8_SCHED;
;             PG8_STAGE(PG8_SB(0, 1), b2 + hstep, voffB);
;             PG8_WAIT_V(6); PG8_BAR; PG8_MMA(1, 1, At, B1); PG8_BAR;
.LBB0_325:
	s_add_u32 s28, s40, s28
	s_addc_u32 s29, s41, s29
	s_and_b64 s[0:1], s[8:9], exec
	s_cselect_b32 s15, s29, s39
	s_cselect_b32 s17, s28, s38
	s_add_u32 s8, s38, 0x160080
	s_addc_u32 s9, s39, 0
	s_add_u32 s66, s36, 0x100
	v_mov_b32_e32 v0, 0
	s_addc_u32 s67, s37, 0
	s_mov_b32 s68, -2
	ds_read_b128 v[150:153], v141
	ds_read_b128 v[154:157], v141 offset:1024
	ds_read_b128 v[162:165], v141 offset:2048
	ds_read_b128 v[166:169], v141 offset:3072
	s_add_u32 s0, s8, 0xffea0080
	s_addc_u32 s1, s9, -1
	s_cmp_eq_u32 s68, 4
	s_cselect_b32 s39, s15, s1
	s_cselect_b32 s38, s17, s0
	s_cselect_b32 s37, s19, s67
	s_cselect_b32 s36, s18, s66
	s_mov_b32 m0, s58
	ds_read_b128 v[170:173], v142
	ds_read_b128 v[174:177], v142 offset:1024
	ds_read_b128 v[178:181], v142 offset:2048
	ds_read_b128 v[188:191], v142 offset:3072
	ds_read_b128 v[194:197], v142 offset:4096
	ds_read_b128 v[198:201], v142 offset:5120
	ds_read_b128 v[202:205], v142 offset:6144
	global_load_lds_dwordx4 v132, s[8:9]
	s_mov_b32 m0, s59
	ds_read_b128 v[206:209], v142 offset:7168
	global_load_lds_dwordx4 v134, s[8:9]
	s_waitcnt lgkmcnt(8)
	s_barrier
	s_waitcnt lgkmcnt(0)
	s_setprio 1
	v_mfma_f32_16x16x32_bf16 v[124:127], v[150:153], v[170:173], 0
	v_mfma_f32_16x16x32_bf16 v[120:123], v[162:165], v[170:173], 0
	v_mfma_f32_16x16x32_bf16 v[116:119], v[150:153], v[178:181], 0
	v_mfma_f32_16x16x32_bf16 v[112:115], v[162:165], v[178:181], 0
	v_mfma_f32_16x16x32_bf16 v[104:107], v[150:153], v[194:197], 0
	v_mfma_f32_16x16x32_bf16 v[96:99], v[162:165], v[194:197], 0
	v_mfma_f32_16x16x32_bf16 v[88:91], v[150:153], v[202:205], 0
	v_mfma_f32_16x16x32_bf16 v[80:83], v[162:165], v[202:205], 0
	v_mfma_f32_16x16x32_bf16 v[124:127], v[154:157], v[174:177], v[124:127]
	v_mfma_f32_16x16x32_bf16 v[120:123], v[166:169], v[174:177], v[120:123]
	v_mfma_f32_16x16x32_bf16 v[116:119], v[154:157], v[188:191], v[116:119]
	v_mfma_f32_16x16x32_bf16 v[112:115], v[166:169], v[188:191], v[112:115]
	v_mfma_f32_16x16x32_bf16 v[104:107], v[154:157], v[198:201], v[104:107]
	v_mfma_f32_16x16x32_bf16 v[96:99], v[166:169], v[198:201], v[96:99]
	v_mfma_f32_16x16x32_bf16 v[88:91], v[154:157], v[206:209], v[88:91]
	v_mfma_f32_16x16x32_bf16 v[80:83], v[166:169], v[206:209], v[80:83]
	s_setprio 0
	s_barrier
	s_mov_b32 m0, s60
	ds_read_b128 v[210:213], v143
	ds_read_b128 v[214:217], v143 offset:1024
	ds_read_b128 v[218:221], v143 offset:2048
	ds_read_b128 v[222:225], v143 offset:3072
	global_load_lds_dwordx4 v130, s[36:37]
	v_lshl_add_u64 v[158:159], s[36:37], 0, v[128:129]
	s_mov_b32 m0, s61
	s_nop 0
	global_load_lds_dwordx4 v128, s[36:37]
	s_barrier
	s_waitcnt lgkmcnt(0)
	s_setprio 1
	v_mfma_f32_16x16x32_bf16 v[108:111], v[210:213], v[170:173], 0
	v_mfma_f32_16x16x32_bf16 v[100:103], v[218:221], v[170:173], 0
	v_mfma_f32_16x16x32_bf16 v[92:95], v[210:213], v[178:181], 0
	v_mfma_f32_16x16x32_bf16 v[84:87], v[218:221], v[178:181], 0
	v_mfma_f32_16x16x32_bf16 v[76:79], v[210:213], v[194:197], 0
	v_mfma_f32_16x16x32_bf16 v[72:75], v[218:221], v[194:197], 0
	v_mfma_f32_16x16x32_bf16 v[68:71], v[210:213], v[202:205], 0
	v_mfma_f32_16x16x32_bf16 v[64:67], v[218:221], v[202:205], 0
	v_mfma_f32_16x16x32_bf16 v[108:111], v[214:217], v[174:177], v[108:111]
	v_mfma_f32_16x16x32_bf16 v[100:103], v[222:225], v[174:177], v[100:103]
	v_mfma_f32_16x16x32_bf16 v[92:95], v[214:217], v[188:191], v[92:95]
	v_mfma_f32_16x16x32_bf16 v[84:87], v[222:225], v[188:191], v[84:87]
	v_mfma_f32_16x16x32_bf16 v[76:79], v[214:217], v[198:201], v[76:79]
	v_mfma_f32_16x16x32_bf16 v[72:75], v[222:225], v[198:201], v[72:75]
	v_mfma_f32_16x16x32_bf16 v[68:71], v[214:217], v[206:209], v[68:71]
	v_mfma_f32_16x16x32_bf16 v[64:67], v[222:225], v[206:209], v[64:67]
	s_setprio 0
	s_mov_b32 m0, s42
	v_lshl_add_u64 v[182:183], s[38:39], 0, v[130:131]
	s_barrier
	ds_read_b128 v[170:173], v142 offset:16384
	ds_read_b128 v[174:177], v142 offset:17408
	ds_read_b128 v[178:181], v142 offset:18432
	ds_read_b128 v[188:191], v142 offset:19456
	ds_read_b128 v[194:197], v142 offset:20480
	ds_read_b128 v[198:201], v142 offset:21504
	ds_read_b128 v[202:205], v142 offset:22528
	ds_read_b128 v[206:209], v142 offset:23552
	global_load_lds_dwordx4 v130, s[38:39]
	v_lshl_add_u64 v[226:227], s[38:39], 0, v[128:129]
	s_mov_b32 m0, s43
	s_nop 0
	global_load_lds_dwordx4 v128, s[38:39]
	s_barrier
	s_waitcnt lgkmcnt(0)
	s_setprio 1
	v_mfma_f32_16x16x32_bf16 v[60:63], v[150:153], v[170:173], 0
	v_mfma_f32_16x16x32_bf16 v[56:59], v[162:165], v[170:173], 0
	v_mfma_f32_16x16x32_bf16 v[52:55], v[150:153], v[178:181], 0
	v_mfma_f32_16x16x32_bf16 v[48:51], v[162:165], v[178:181], 0
	v_mfma_f32_16x16x32_bf16 v[40:43], v[150:153], v[194:197], 0
	v_mfma_f32_16x16x32_bf16 v[32:35], v[162:165], v[194:197], 0
	v_mfma_f32_16x16x32_bf16 v[24:27], v[150:153], v[202:205], 0
	v_mfma_f32_16x16x32_bf16 v[16:19], v[162:165], v[202:205], 0
	v_mfma_f32_16x16x32_bf16 v[60:63], v[154:157], v[174:177], v[60:63]
	v_mfma_f32_16x16x32_bf16 v[56:59], v[166:169], v[174:177], v[56:59]
	v_mfma_f32_16x16x32_bf16 v[52:55], v[154:157], v[188:191], v[52:55]
	v_mfma_f32_16x16x32_bf16 v[48:51], v[166:169], v[188:191], v[48:51]
	v_mfma_f32_16x16x32_bf16 v[40:43], v[154:157], v[198:201], v[40:43]
	v_mfma_f32_16x16x32_bf16 v[32:35], v[166:169], v[198:201], v[32:35]
	v_mfma_f32_16x16x32_bf16 v[24:27], v[154:157], v[206:209], v[24:27]
	v_mfma_f32_16x16x32_bf16 v[16:19], v[166:169], v[206:209], v[16:19]
	s_setprio 0
	s_barrier
	s_add_u32 s0, s36, 0x160000
	s_addc_u32 s1, s37, 0
	s_mov_b32 m0, s62
	s_nop 0
	global_load_lds_dwordx4 v130, s[0:1]
	s_mov_b32 m0, s63
	s_nop 0
	global_load_lds_dwordx4 v128, s[0:1]
	s_waitcnt vmcnt(6)
	s_barrier
; #define PG8_STAGE(bufoff, gbase, voff) do { _Pragma("unroll") for (int _i = 0; _i < 2; ++_i) \
;         __builtin_amdgcn_global_load_lds((const unsigned*)((const char*)(gbase) + (voff)[_i]), (LAS unsigned*)(lds + (bufoff) + ldsw + _i * 8192), 16, 0, 0); } while (0)
; #define PG8_LDA(dst, b, h) do { _Pragma("unroll") for (int m = 0; m < 4; ++m) _Pragma("unroll") for (int k = 0; k < 2; ++k) dst[m][k] = *(const LAS bf16x8*)(lds + PG8_SA(b, h) + aoff + m * 2048 + k * 1024); } while (0)
; #define PG8_LDB(dst, b, h) do { _Pragma("unroll") for (int n = 0; n < 2; ++n) _Pragma("unroll") for (int k = 0; k < 2; ++k) dst[n][k] = *(const LAS bf16x8*)(lds + PG8_SB(b, h) + boff + n * 2048 + k * 1024); } while (0)
; #define PG8_MMA(ai, bj, At, Bt) do { __builtin_amdgcn_s_setprio(1); _Pragma("unroll") for (int m = 0; m < 4; ++m) _Pragma("unroll") for (int n = 0; n < 2; ++n) _Pragma("unroll") for (int k = 0; k < 2; ++k) \
;         acc[ai][bj][m][n] = __builtin_amdgcn_mfma_f32_16x16x32_bf16(Bt[n][k], At[m][k], acc[ai][bj][m][n], 0, 0, 0); __builtin_amdgcn_s_setprio(0); } while (0)
; #define PG8_WAIT_V(n) asm volatile("s_waitcnt vmcnt(" #n ")" ::: "memory")
; #define PG8_WAIT_L(n) asm volatile("s_waitcnt lgkmcnt(" #n ")" ::: "memory")
; #define PG8_BAR __builtin_amdgcn_s_barrier()
; #define PG8_SCHED __builtin_amdgcn_sched_barrier(0)
; template <class Epi, class Sched>
; DI void gemm_phase(LAS unsigned char* lds, const Gemm g, const Sched& S, const Epi& E) {
;     ...
;             PG8_WAIT_V(6); PG8_BAR; PG8_MMA(1, 1, At, B1); PG8_BAR;
;             PG8_LDB(B0, 1, 0); PG8_SCHED; PG8_LDA(At, 1, 0); PG8_STAGE(PG8_SA(0, 1), a2 + hstep, voffA);
;             PG8_WAIT_L(8); PG8_BAR; PG8_WAIT_L(0); PG8_MMA(0, 0, At, B0); PG8_BAR; PG8_SCHED;
;             PG8_LDB(B1, 1, 1); PG8_STAGE(PG8_SB(1, 0), b3, voffB);
;             PG8_BAR; PG8_WAIT_L(0); PG8_MMA(0, 1, At, B1); PG8_BAR;
;             PG8_LDA(At, 1, 1); PG8_STAGE(PG8_SA(1, 0), a3, voffA);
;             PG8_BAR; PG8_WAIT_L(0); PG8_MMA(1, 0, At, B0); PG8_BAR; PG8_SCHED;
;             PG8_STAGE(PG8_SB(1, 1), b3 + hstep, voffB);
;             PG8_WAIT_V(6); PG8_BAR; PG8_MMA(1, 1, At, B1); PG8_BAR;
	s_setprio 1
	v_mfma_f32_16x16x32_bf16 v[44:47], v[210:213], v[170:173], 0
	v_mfma_f32_16x16x32_bf16 v[36:39], v[218:221], v[170:173], 0
	v_mfma_f32_16x16x32_bf16 v[28:31], v[210:213], v[178:181], 0
	v_mfma_f32_16x16x32_bf16 v[20:23], v[218:221], v[178:181], 0
	v_mfma_f32_16x16x32_bf16 v[12:15], v[210:213], v[194:197], 0
	v_mfma_f32_16x16x32_bf16 v[8:11], v[218:221], v[194:197], 0
	v_mfma_f32_16x16x32_bf16 v[4:7], v[210:213], v[202:205], 0
	v_mfma_f32_16x16x32_bf16 v[0:3], v[218:221], v[202:205], 0
	v_mfma_f32_16x16x32_bf16 v[44:47], v[214:217], v[174:177], v[44:47]
	v_mfma_f32_16x16x32_bf16 v[36:39], v[222:225], v[174:177], v[36:39]
	v_mfma_f32_16x16x32_bf16 v[28:31], v[214:217], v[188:191], v[28:31]
	v_mfma_f32_16x16x32_bf16 v[20:23], v[222:225], v[188:191], v[20:23]
	v_mfma_f32_16x16x32_bf16 v[12:15], v[214:217], v[198:201], v[12:15]
	v_mfma_f32_16x16x32_bf16 v[8:11], v[222:225], v[198:201], v[8:11]
	v_mfma_f32_16x16x32_bf16 v[4:7], v[214:217], v[206:209], v[4:7]
	v_mfma_f32_16x16x32_bf16 v[0:3], v[222:225], v[206:209], v[0:3]
	s_setprio 0
	s_barrier
	ds_read_b128 v[150:153], v144
	ds_read_b128 v[154:157], v144 offset:1024
	ds_read_b128 v[162:165], v144 offset:2048
	ds_read_b128 v[166:169], v144 offset:3072
	s_add_u32 s0, s38, 0x160000
	s_addc_u32 s1, s39, 0
	s_mov_b32 m0, s44
	ds_read_b128 v[170:173], v142 offset:32768
	ds_read_b128 v[174:177], v142 offset:33792
	ds_read_b128 v[178:181], v142 offset:34816
	ds_read_b128 v[188:191], v142 offset:35840
	ds_read_b128 v[194:197], v142 offset:36864
	ds_read_b128 v[198:201], v142 offset:37888
	ds_read_b128 v[202:205], v142 offset:38912
	global_load_lds_dwordx4 v130, s[0:1]
	s_mov_b32 m0, s45
	ds_read_b128 v[206:209], v142 offset:39936
	global_load_lds_dwordx4 v128, s[0:1]
	s_waitcnt lgkmcnt(8)
	s_barrier
	s_waitcnt lgkmcnt(0)
	s_setprio 1
	v_mfma_f32_16x16x32_bf16 v[124:127], v[150:153], v[170:173], v[124:127]
	v_mfma_f32_16x16x32_bf16 v[120:123], v[162:165], v[170:173], v[120:123]
	v_mfma_f32_16x16x32_bf16 v[116:119], v[150:153], v[178:181], v[116:119]
	v_mfma_f32_16x16x32_bf16 v[112:115], v[162:165], v[178:181], v[112:115]
	v_mfma_f32_16x16x32_bf16 v[104:107], v[150:153], v[194:197], v[104:107]
	v_mfma_f32_16x16x32_bf16 v[96:99], v[162:165], v[194:197], v[96:99]
	v_mfma_f32_16x16x32_bf16 v[88:91], v[150:153], v[202:205], v[88:91]
	v_mfma_f32_16x16x32_bf16 v[80:83], v[162:165], v[202:205], v[80:83]
	v_mfma_f32_16x16x32_bf16 v[124:127], v[154:157], v[174:177], v[124:127]
	v_mfma_f32_16x16x32_bf16 v[120:123], v[166:169], v[174:177], v[120:123]
	v_mfma_f32_16x16x32_bf16 v[116:119], v[154:157], v[188:191], v[116:119]
	v_mfma_f32_16x16x32_bf16 v[112:115], v[166:169], v[188:191], v[112:115]
	v_mfma_f32_16x16x32_bf16 v[104:107], v[154:157], v[198:201], v[104:107]
	v_mfma_f32_16x16x32_bf16 v[96:99], v[166:169], v[198:201], v[96:99]
	v_mfma_f32_16x16x32_bf16 v[88:91], v[154:157], v[206:209], v[88:91]
	v_mfma_f32_16x16x32_bf16 v[80:83], v[166:169], v[206:209], v[80:83]
	s_setprio 0
	s_barrier
	s_add_i32 s4, 0, 0x1c000
	s_add_i32 s0, s64, s35
	v_add_u32_e32 v145, s4, v140
	s_add_i32 m0, s0, 0xffffff80
	ds_read_b128 v[210:213], v145
	ds_read_b128 v[214:217], v145 offset:1024
	ds_read_b128 v[218:221], v145 offset:2048
	global_load_lds_dwordx4 v130, s[36:37] offset:128
	s_add_i32 m0, s0, 0x1f80
	ds_read_b128 v[222:225], v145 offset:3072
	global_load_lds_dwordx4 v128, s[36:37] offset:128
	s_barrier
	s_waitcnt lgkmcnt(0)
	s_setprio 1
	v_mfma_f32_16x16x32_bf16 v[108:111], v[210:213], v[170:173], v[108:111]
	v_mfma_f32_16x16x32_bf16 v[100:103], v[218:221], v[170:173], v[100:103]
	v_mfma_f32_16x16x32_bf16 v[92:95], v[210:213], v[178:181], v[92:95]
	v_mfma_f32_16x16x32_bf16 v[84:87], v[218:221], v[178:181], v[84:87]
	v_mfma_f32_16x16x32_bf16 v[76:79], v[210:213], v[194:197], v[76:79]
	v_mfma_f32_16x16x32_bf16 v[72:75], v[218:221], v[194:197], v[72:75]
	v_mfma_f32_16x16x32_bf16 v[68:71], v[210:213], v[202:205], v[68:71]
	v_mfma_f32_16x16x32_bf16 v[64:67], v[218:221], v[202:205], v[64:67]
	v_mfma_f32_16x16x32_bf16 v[108:111], v[214:217], v[174:177], v[108:111]
	v_mfma_f32_16x16x32_bf16 v[100:103], v[222:225], v[174:177], v[100:103]
	v_mfma_f32_16x16x32_bf16 v[92:95], v[214:217], v[188:191], v[92:95]
	v_mfma_f32_16x16x32_bf16 v[84:87], v[222:225], v[188:191], v[84:87]
	v_mfma_f32_16x16x32_bf16 v[76:79], v[214:217], v[198:201], v[76:79]
	v_mfma_f32_16x16x32_bf16 v[72:75], v[222:225], v[198:201], v[72:75]
	v_mfma_f32_16x16x32_bf16 v[68:71], v[214:217], v[206:209], v[68:71]
	v_mfma_f32_16x16x32_bf16 v[64:67], v[222:225], v[206:209], v[64:67]
	s_setprio 0
	s_add_i32 m0, s56, 0xffffff80
	s_barrier
	ds_read_b128 v[170:173], v142 offset:49152
	ds_read_b128 v[174:177], v142 offset:50176
	ds_read_b128 v[178:181], v142 offset:51200
	ds_read_b128 v[188:191], v142 offset:52224
	ds_read_b128 v[194:197], v142 offset:53248
	ds_read_b128 v[198:201], v142 offset:54272
	ds_read_b128 v[202:205], v142 offset:55296
	global_load_lds_dwordx4 v130, s[38:39] offset:128
	s_add_i32 m0, s57, 0xffffff80
	ds_read_b128 v[206:209], v142 offset:56320
	global_load_lds_dwordx4 v128, s[38:39] offset:128
	s_barrier
; #define PG8_STAGE(bufoff, gbase, voff) do { _Pragma("unroll") for (int _i = 0; _i < 2; ++_i) \
;         __builtin_amdgcn_global_load_lds((const unsigned*)((const char*)(gbase) + (voff)[_i]), (LAS unsigned*)(lds + (bufoff) + ldsw + _i * 8192), 16, 0, 0); } while (0)
; #define PG8_LDA(dst, b, h) do { _Pragma("unroll") for (int m = 0; m < 4; ++m) _Pragma("unroll") for (int k = 0; k < 2; ++k) dst[m][k] = *(const LAS bf16x8*)(lds + PG8_SA(b, h) + aoff + m * 2048 + k * 1024); } while (0)
; #define PG8_LDB(dst, b, h) do { _Pragma("unroll") for (int n = 0; n < 2; ++n) _Pragma("unroll") for (int k = 0; k < 2; ++k) dst[n][k] = *(const LAS bf16x8*)(lds + PG8_SB(b, h) + boff + n * 2048 + k * 1024); } while (0)
; #define PG8_WAIT_V(n) asm volatile("s_waitcnt vmcnt(" #n ")" ::: "memory")
; #define PG8_WAIT_L(n) asm volatile("s_waitcnt lgkmcnt(" #n ")" ::: "memory")
; #define PG8_BAR __builtin_amdgcn_s_barrier()
; #define PG8_SCHED __builtin_amdgcn_sched_barrier(0)
; template <class Epi, class Sched>
; DI void gemm_phase(LAS unsigned char* lds, const Gemm g, const Sched& S, const Epi& E) {
;     ...
;             PG8_LDB(B0, 0, 0); PG8_SCHED; PG8_LDA(At, 0, 0); PG8_STAGE(PG8_SA(1, 1), a1 + hstep, voffA);
;             PG8_WAIT_L(8); PG8_BAR; PG8_WAIT_L(0); PG8_MMA(0, 0, At, B0); PG8_BAR; PG8_SCHED;
;             PG8_LDB(B1, 0, 1); PG8_STAGE(PG8_SB(0, 0), b2, voffB);
;             PG8_BAR; PG8_WAIT_L(0); PG8_MMA(0, 1, At, B1); PG8_BAR;
;             PG8_LDA(At, 0, 1); PG8_STAGE(PG8_SA(0, 0), a2, voffA);
;             PG8_BAR; PG8_WAIT_L(0); PG8_MMA(1, 0, At, B0); PG8_BAR; PG8_SCHED;
;             PG8_STAGE(PG8_SB(0, 1), b2 + hstep, voffB);
;             PG8_WAIT_V(6); PG8_BAR; PG8_MMA(1, 1, At, B1); PG8_BAR;
;             PG8_LDB(B0, 1, 0); PG8_SCHED; PG8_LDA(At, 1, 0); PG8_STAGE(PG8_SA(0, 1), a2 + hstep, voffA);
;             PG8_WAIT_L(8); PG8_BAR; PG8_WAIT_L(0); PG8_MMA(0, 0, At, B0); PG8_BAR; PG8_SCHED;
;             PG8_LDB(B1, 1, 1); PG8_STAGE(PG8_SB(1, 0), b3, voffB);
;             PG8_BAR; PG8_WAIT_L(0); PG8_MMA(0, 1, At, B1); PG8_BAR;
;             PG8_LDA(At, 1, 1); PG8_STAGE(PG8_SA(1, 0), a3, voffA);
;             PG8_BAR; PG8_WAIT_L(0); PG8_MMA(1, 0, At, B0); PG8_BAR; PG8_SCHED;
;             PG8_STAGE(PG8_SB(1, 1), b3 + hstep, voffB);
;             PG8_WAIT_V(6); PG8_BAR; PG8_MMA(1, 1, At, B1); PG8_BAR;
	s_waitcnt lgkmcnt(0)
	s_setprio 1
	v_mfma_f32_16x16x32_bf16 v[60:63], v[150:153], v[170:173], v[60:63]
	v_mfma_f32_16x16x32_bf16 v[56:59], v[162:165], v[170:173], v[56:59]
	v_mfma_f32_16x16x32_bf16 v[52:55], v[150:153], v[178:181], v[52:55]
	v_mfma_f32_16x16x32_bf16 v[48:51], v[162:165], v[178:181], v[48:51]
	v_mfma_f32_16x16x32_bf16 v[40:43], v[150:153], v[194:197], v[40:43]
	v_mfma_f32_16x16x32_bf16 v[32:35], v[162:165], v[194:197], v[32:35]
	v_mfma_f32_16x16x32_bf16 v[24:27], v[150:153], v[202:205], v[24:27]
	v_mfma_f32_16x16x32_bf16 v[16:19], v[162:165], v[202:205], v[16:19]
	v_mfma_f32_16x16x32_bf16 v[60:63], v[154:157], v[174:177], v[60:63]
	v_mfma_f32_16x16x32_bf16 v[56:59], v[166:169], v[174:177], v[56:59]
	v_mfma_f32_16x16x32_bf16 v[52:55], v[154:157], v[188:191], v[52:55]
	v_mfma_f32_16x16x32_bf16 v[48:51], v[166:169], v[188:191], v[48:51]
	v_mfma_f32_16x16x32_bf16 v[40:43], v[154:157], v[198:201], v[40:43]
	v_mfma_f32_16x16x32_bf16 v[32:35], v[166:169], v[198:201], v[32:35]
	v_mfma_f32_16x16x32_bf16 v[24:27], v[154:157], v[206:209], v[24:27]
	v_mfma_f32_16x16x32_bf16 v[16:19], v[166:169], v[206:209], v[16:19]
	s_setprio 0
	s_barrier
	s_add_u32 s0, s36, 0x160080
	s_addc_u32 s1, s37, 0
	s_add_i32 s4, s4, s35
	s_mov_b32 m0, s4
	s_nop 0
	global_load_lds_dwordx4 v130, s[0:1]
	s_add_i32 m0, s4, 0x2000
	s_nop 0
	global_load_lds_dwordx4 v128, s[0:1]
	s_waitcnt vmcnt(6)
	s_barrier
	s_setprio 1
	v_mfma_f32_16x16x32_bf16 v[44:47], v[210:213], v[170:173], v[44:47]
	v_mfma_f32_16x16x32_bf16 v[36:39], v[218:221], v[170:173], v[36:39]
	v_mfma_f32_16x16x32_bf16 v[28:31], v[210:213], v[178:181], v[28:31]
	v_mfma_f32_16x16x32_bf16 v[20:23], v[218:221], v[178:181], v[20:23]
	v_mfma_f32_16x16x32_bf16 v[12:15], v[210:213], v[194:197], v[12:15]
	v_mfma_f32_16x16x32_bf16 v[8:11], v[218:221], v[194:197], v[8:11]
	v_mfma_f32_16x16x32_bf16 v[4:7], v[210:213], v[202:205], v[4:7]
	v_mfma_f32_16x16x32_bf16 v[0:3], v[218:221], v[202:205], v[0:3]
	v_mfma_f32_16x16x32_bf16 v[44:47], v[214:217], v[174:177], v[44:47]
	v_mfma_f32_16x16x32_bf16 v[36:39], v[222:225], v[174:177], v[36:39]
	v_mfma_f32_16x16x32_bf16 v[28:31], v[214:217], v[188:191], v[28:31]
	v_mfma_f32_16x16x32_bf16 v[20:23], v[222:225], v[188:191], v[20:23]
	v_mfma_f32_16x16x32_bf16 v[12:15], v[214:217], v[198:201], v[12:15]
	v_mfma_f32_16x16x32_bf16 v[8:11], v[222:225], v[198:201], v[8:11]
	v_mfma_f32_16x16x32_bf16 v[4:7], v[214:217], v[206:209], v[4:7]
	v_mfma_f32_16x16x32_bf16 v[0:3], v[222:225], v[206:209], v[0:3]
	s_setprio 0
	s_add_i32 s68, s68, 2
	s_add_u32 s8, s8, 0x100
	s_addc_u32 s9, s9, 0
	s_add_u32 s66, s66, 0x100
	s_addc_u32 s67, s67, 0
	s_cmp_gt_u32 s68, 5
	s_barrier
	s_cbranch_scc0 .LBB0_326
	s_branch .Lpeel_done_326
.LBB0_326:
	ds_read_b128 v[150:153], v141
	ds_read_b128 v[154:157], v141 offset:1024
	ds_read_b128 v[162:165], v141 offset:2048
	ds_read_b128 v[166:169], v141 offset:3072
	s_add_u32 s0, s8, 0xffea0080
	s_addc_u32 s1, s9, -1
	s_cmp_eq_u32 s68, 4
	s_cselect_b32 s39, s15, s1
	s_cselect_b32 s38, s17, s0
	s_cselect_b32 s37, s19, s67
	s_cselect_b32 s36, s18, s66
	s_mov_b32 m0, s58
	ds_read_b128 v[170:173], v142
	ds_read_b128 v[174:177], v142 offset:1024
	ds_read_b128 v[178:181], v142 offset:2048
	ds_read_b128 v[188:191], v142 offset:3072
	ds_read_b128 v[194:197], v142 offset:4096
	ds_read_b128 v[198:201], v142 offset:5120
	ds_read_b128 v[202:205], v142 offset:6144
	global_load_lds_dwordx4 v132, s[8:9]
	s_mov_b32 m0, s59
	ds_read_b128 v[206:209], v142 offset:7168
	global_load_lds_dwordx4 v134, s[8:9]
	s_waitcnt lgkmcnt(8)
	s_barrier
	s_waitcnt lgkmcnt(0)
	s_setprio 1
	v_mfma_f32_16x16x32_bf16 v[124:127], v[150:153], v[170:173], v[124:127]
	v_mfma_f32_16x16x32_bf16 v[120:123], v[162:165], v[170:173], v[120:123]
	v_mfma_f32_16x16x32_bf16 v[116:119], v[150:153], v[178:181], v[116:119]
	v_mfma_f32_16x16x32_bf16 v[112:115], v[162:165], v[178:181], v[112:115]
	v_mfma_f32_16x16x32_bf16 v[104:107], v[150:153], v[194:197], v[104:107]
	v_mfma_f32_16x16x32_bf16 v[96:99], v[162:165], v[194:197], v[96:99]
	v_mfma_f32_16x16x32_bf16 v[88:91], v[150:153], v[202:205], v[88:91]
	v_mfma_f32_16x16x32_bf16 v[80:83], v[162:165], v[202:205], v[80:83]
	v_mfma_f32_16x16x32_bf16 v[124:127], v[154:157], v[174:177], v[124:127]
	v_mfma_f32_16x16x32_bf16 v[120:123], v[166:169], v[174:177], v[120:123]
	v_mfma_f32_16x16x32_bf16 v[116:119], v[154:157], v[188:191], v[116:119]
	v_mfma_f32_16x16x32_bf16 v[112:115], v[166:169], v[188:191], v[112:115]
	v_mfma_f32_16x16x32_bf16 v[104:107], v[154:157], v[198:201], v[104:107]
	v_mfma_f32_16x16x32_bf16 v[96:99], v[166:169], v[198:201], v[96:99]
	v_mfma_f32_16x16x32_bf16 v[88:91], v[154:157], v[206:209], v[88:91]
	v_mfma_f32_16x16x32_bf16 v[80:83], v[166:169], v[206:209], v[80:83]
	s_setprio 0
	s_barrier
	s_mov_b32 m0, s60
	ds_read_b128 v[210:213], v143
	ds_read_b128 v[214:217], v143 offset:1024
	ds_read_b128 v[218:221], v143 offset:2048
	ds_read_b128 v[222:225], v143 offset:3072
	global_load_lds_dwordx4 v130, s[36:37]
	v_lshl_add_u64 v[158:159], s[36:37], 0, v[128:129]
	s_mov_b32 m0, s61
	s_nop 0
	global_load_lds_dwordx4 v128, s[36:37]
	s_barrier
; #define PG8_STAGE(bufoff, gbase, voff) do { _Pragma("unroll") for (int _i = 0; _i < 2; ++_i) \
;         __builtin_amdgcn_global_load_lds((const unsigned*)((const char*)(gbase) + (voff)[_i]), (LAS unsigned*)(lds + (bufoff) + ldsw + _i * 8192), 16, 0, 0); } while (0)
; #define PG8_LDA(dst, b, h) do { _Pragma("unroll") for (int m = 0; m < 4; ++m) _Pragma("unroll") for (int k = 0; k < 2; ++k) dst[m][k] = *(const LAS bf16x8*)(lds + PG8_SA(b, h) + aoff + m * 2048 + k * 1024); } while (0)
; #define PG8_LDB(dst, b, h) do { _Pragma("unroll") for (int n = 0; n < 2; ++n) _Pragma("unroll") for (int k = 0; k < 2; ++k) dst[n][k] = *(const LAS bf16x8*)(lds + PG8_SB(b, h) + boff + n * 2048 + k * 1024); } while (0)
; #define PG8_MMA(ai, bj, At, Bt) do { __builtin_amdgcn_s_setprio(1); _Pragma("unroll") for (int m = 0; m < 4; ++m) _Pragma("unroll") for (int n = 0; n < 2; ++n) _Pragma("unroll") for (int k = 0; k < 2; ++k) \
;         acc[ai][bj][m][n] = __builtin_amdgcn_mfma_f32_16x16x32_bf16(Bt[n][k], At[m][k], acc[ai][bj][m][n], 0, 0, 0); __builtin_amdgcn_s_setprio(0); } while (0)
; #define PG8_WAIT_V(n) asm volatile("s_waitcnt vmcnt(" #n ")" ::: "memory")
; #define PG8_WAIT_L(n) asm volatile("s_waitcnt lgkmcnt(" #n ")" ::: "memory")
; #define PG8_BAR __builtin_amdgcn_s_barrier()
; #define PG8_SCHED __builtin_amdgcn_sched_barrier(0)
; template <class Epi, class Sched>
; DI void gemm_phase(LAS unsigned char* lds, const Gemm g, const Sched& S, const Epi& E) {
;     ...
;             PG8_BAR; PG8_WAIT_L(0); PG8_MMA(0, 1, At, B1); PG8_BAR;
;             PG8_LDA(At, 0, 1); PG8_STAGE(PG8_SA(0, 0), a2, voffA);
;             PG8_BAR; PG8_WAIT_L(0); PG8_MMA(1, 0, At, B0); PG8_BAR; PG8_SCHED;
;             PG8_STAGE(PG8_SB(0, 1), b2 + hstep, voffB);
;             PG8_WAIT_V(6); PG8_BAR; PG8_MMA(1, 1, At, B1); PG8_BAR;
;             PG8_LDB(B0, 1, 0); PG8_SCHED; PG8_LDA(At, 1, 0); PG8_STAGE(PG8_SA(0, 1), a2 + hstep, voffA);
;             PG8_WAIT_L(8); PG8_BAR; PG8_WAIT_L(0); PG8_MMA(0, 0, At, B0); PG8_BAR; PG8_SCHED;
;             PG8_LDB(B1, 1, 1); PG8_STAGE(PG8_SB(1, 0), b3, voffB);
;             PG8_BAR; PG8_WAIT_L(0); PG8_MMA(0, 1, At, B1); PG8_BAR;
;             PG8_LDA(At, 1, 1); PG8_STAGE(PG8_SA(1, 0), a3, voffA);
	s_waitcnt lgkmcnt(0)
	s_setprio 1
	v_mfma_f32_16x16x32_bf16 v[108:111], v[210:213], v[170:173], v[108:111]
	v_mfma_f32_16x16x32_bf16 v[100:103], v[218:221], v[170:173], v[100:103]
	v_mfma_f32_16x16x32_bf16 v[92:95], v[210:213], v[178:181], v[92:95]
	v_mfma_f32_16x16x32_bf16 v[84:87], v[218:221], v[178:181], v[84:87]
	v_mfma_f32_16x16x32_bf16 v[76:79], v[210:213], v[194:197], v[76:79]
	v_mfma_f32_16x16x32_bf16 v[72:75], v[218:221], v[194:197], v[72:75]
	v_mfma_f32_16x16x32_bf16 v[68:71], v[210:213], v[202:205], v[68:71]
	v_mfma_f32_16x16x32_bf16 v[64:67], v[218:221], v[202:205], v[64:67]
	v_mfma_f32_16x16x32_bf16 v[108:111], v[214:217], v[174:177], v[108:111]
	v_mfma_f32_16x16x32_bf16 v[100:103], v[222:225], v[174:177], v[100:103]
	v_mfma_f32_16x16x32_bf16 v[92:95], v[214:217], v[188:191], v[92:95]
	v_mfma_f32_16x16x32_bf16 v[84:87], v[222:225], v[188:191], v[84:87]
	v_mfma_f32_16x16x32_bf16 v[76:79], v[214:217], v[198:201], v[76:79]
	v_mfma_f32_16x16x32_bf16 v[72:75], v[222:225], v[198:201], v[72:75]
	v_mfma_f32_16x16x32_bf16 v[68:71], v[214:217], v[206:209], v[68:71]
	v_mfma_f32_16x16x32_bf16 v[64:67], v[222:225], v[206:209], v[64:67]
	s_setprio 0
	s_mov_b32 m0, s42
	v_lshl_add_u64 v[182:183], s[38:39], 0, v[130:131]
	s_barrier
	ds_read_b128 v[170:173], v142 offset:16384
	ds_read_b128 v[174:177], v142 offset:17408
	ds_read_b128 v[178:181], v142 offset:18432
	ds_read_b128 v[188:191], v142 offset:19456
	ds_read_b128 v[194:197], v142 offset:20480
	ds_read_b128 v[198:201], v142 offset:21504
	ds_read_b128 v[202:205], v142 offset:22528
	ds_read_b128 v[206:209], v142 offset:23552
	global_load_lds_dwordx4 v130, s[38:39]
	v_lshl_add_u64 v[226:227], s[38:39], 0, v[128:129]
	s_mov_b32 m0, s43
	s_nop 0
	global_load_lds_dwordx4 v128, s[38:39]
	s_barrier
	s_waitcnt lgkmcnt(0)
	s_setprio 1
	v_mfma_f32_16x16x32_bf16 v[60:63], v[150:153], v[170:173], v[60:63]
	v_mfma_f32_16x16x32_bf16 v[56:59], v[162:165], v[170:173], v[56:59]
	v_mfma_f32_16x16x32_bf16 v[52:55], v[150:153], v[178:181], v[52:55]
	v_mfma_f32_16x16x32_bf16 v[48:51], v[162:165], v[178:181], v[48:51]
	v_mfma_f32_16x16x32_bf16 v[40:43], v[150:153], v[194:197], v[40:43]
	v_mfma_f32_16x16x32_bf16 v[32:35], v[162:165], v[194:197], v[32:35]
	v_mfma_f32_16x16x32_bf16 v[24:27], v[150:153], v[202:205], v[24:27]
	v_mfma_f32_16x16x32_bf16 v[16:19], v[162:165], v[202:205], v[16:19]
	v_mfma_f32_16x16x32_bf16 v[60:63], v[154:157], v[174:177], v[60:63]
	v_mfma_f32_16x16x32_bf16 v[56:59], v[166:169], v[174:177], v[56:59]
	v_mfma_f32_16x16x32_bf16 v[52:55], v[154:157], v[188:191], v[52:55]
	v_mfma_f32_16x16x32_bf16 v[48:51], v[166:169], v[188:191], v[48:51]
	v_mfma_f32_16x16x32_bf16 v[40:43], v[154:157], v[198:201], v[40:43]
	v_mfma_f32_16x16x32_bf16 v[32:35], v[166:169], v[198:201], v[32:35]
	v_mfma_f32_16x16x32_bf16 v[24:27], v[154:157], v[206:209], v[24:27]
	v_mfma_f32_16x16x32_bf16 v[16:19], v[166:169], v[206:209], v[16:19]
	s_setprio 0
	s_barrier
	s_add_u32 s0, s36, 0x160000
	s_addc_u32 s1, s37, 0
	s_mov_b32 m0, s62
	s_nop 0
	global_load_lds_dwordx4 v130, s[0:1]
	s_mov_b32 m0, s63
	s_nop 0
	global_load_lds_dwordx4 v128, s[0:1]
	s_waitcnt vmcnt(6)
	s_barrier
	s_setprio 1
	v_mfma_f32_16x16x32_bf16 v[44:47], v[210:213], v[170:173], v[44:47]
	v_mfma_f32_16x16x32_bf16 v[36:39], v[218:221], v[170:173], v[36:39]
	v_mfma_f32_16x16x32_bf16 v[28:31], v[210:213], v[178:181], v[28:31]
	v_mfma_f32_16x16x32_bf16 v[20:23], v[218:221], v[178:181], v[20:23]
	v_mfma_f32_16x16x32_bf16 v[12:15], v[210:213], v[194:197], v[12:15]
	v_mfma_f32_16x16x32_bf16 v[8:11], v[218:221], v[194:197], v[8:11]
	v_mfma_f32_16x16x32_bf16 v[4:7], v[210:213], v[202:205], v[4:7]
	v_mfma_f32_16x16x32_bf16 v[0:3], v[218:221], v[202:205], v[0:3]
	v_mfma_f32_16x16x32_bf16 v[44:47], v[214:217], v[174:177], v[44:47]
	v_mfma_f32_16x16x32_bf16 v[36:39], v[222:225], v[174:177], v[36:39]
	v_mfma_f32_16x16x32_bf16 v[28:31], v[214:217], v[188:191], v[28:31]
	v_mfma_f32_16x16x32_bf16 v[20:23], v[222:225], v[188:191], v[20:23]
	v_mfma_f32_16x16x32_bf16 v[12:15], v[214:217], v[198:201], v[12:15]
	v_mfma_f32_16x16x32_bf16 v[8:11], v[222:225], v[198:201], v[8:11]
	v_mfma_f32_16x16x32_bf16 v[4:7], v[214:217], v[206:209], v[4:7]
	v_mfma_f32_16x16x32_bf16 v[0:3], v[222:225], v[206:209], v[0:3]
	s_setprio 0
	s_barrier
	ds_read_b128 v[150:153], v144
	ds_read_b128 v[154:157], v144 offset:1024
	ds_read_b128 v[162:165], v144 offset:2048
	ds_read_b128 v[166:169], v144 offset:3072
	s_add_u32 s0, s38, 0x160000
	s_addc_u32 s1, s39, 0
	s_mov_b32 m0, s44
	ds_read_b128 v[170:173], v142 offset:32768
	ds_read_b128 v[174:177], v142 offset:33792
	ds_read_b128 v[178:181], v142 offset:34816
	ds_read_b128 v[188:191], v142 offset:35840
	ds_read_b128 v[194:197], v142 offset:36864
	ds_read_b128 v[198:201], v142 offset:37888
	ds_read_b128 v[202:205], v142 offset:38912
	global_load_lds_dwordx4 v130, s[0:1]
	s_mov_b32 m0, s45
	ds_read_b128 v[206:209], v142 offset:39936
	global_load_lds_dwordx4 v128, s[0:1]
	s_waitcnt lgkmcnt(8)
	s_barrier
; #define PG8_STAGE(bufoff, gbase, voff) do { _Pragma("unroll") for (int _i = 0; _i < 2; ++_i) \
;         __builtin_amdgcn_global_load_lds((const unsigned*)((const char*)(gbase) + (voff)[_i]), (LAS unsigned*)(lds + (bufoff) + ldsw + _i * 8192), 16, 0, 0); } while (0)
; #define PG8_LDA(dst, b, h) do { _Pragma("unroll") for (int m = 0; m < 4; ++m) _Pragma("unroll") for (int k = 0; k < 2; ++k) dst[m][k] = *(const LAS bf16x8*)(lds + PG8_SA(b, h) + aoff + m * 2048 + k * 1024); } while (0)
; #define PG8_LDB(dst, b, h) do { _Pragma("unroll") for (int n = 0; n < 2; ++n) _Pragma("unroll") for (int k = 0; k < 2; ++k) dst[n][k] = *(const LAS bf16x8*)(lds + PG8_SB(b, h) + boff + n * 2048 + k * 1024); } while (0)
; #define PG8_MMA(ai, bj, At, Bt) do { __builtin_amdgcn_s_setprio(1); _Pragma("unroll") for (int m = 0; m < 4; ++m) _Pragma("unroll") for (int n = 0; n < 2; ++n) _Pragma("unroll") for (int k = 0; k < 2; ++k) \
;         acc[ai][bj][m][n] = __builtin_amdgcn_mfma_f32_16x16x32_bf16(Bt[n][k], At[m][k], acc[ai][bj][m][n], 0, 0, 0); __builtin_amdgcn_s_setprio(0); } while (0)
; #define PG8_WAIT_V(n) asm volatile("s_waitcnt vmcnt(" #n ")" ::: "memory")
; #define PG8_WAIT_L(n) asm volatile("s_waitcnt lgkmcnt(" #n ")" ::: "memory")
; #define PG8_BAR __builtin_amdgcn_s_barrier()
; #define PG8_SCHED __builtin_amdgcn_sched_barrier(0)
; template <class Epi, class Sched>
; DI void gemm_phase(LAS unsigned char* lds, const Gemm g, const Sched& S, const Epi& E) {
;     ...
;             PG8_WAIT_L(8); PG8_BAR; PG8_WAIT_L(0); PG8_MMA(0, 0, At, B0); PG8_BAR; PG8_SCHED;
;             PG8_LDB(B1, 1, 1); PG8_STAGE(PG8_SB(1, 0), b3, voffB);
;             PG8_BAR; PG8_WAIT_L(0); PG8_MMA(0, 1, At, B1); PG8_BAR;
;             PG8_LDA(At, 1, 1); PG8_STAGE(PG8_SA(1, 0), a3, voffA);
;             PG8_BAR; PG8_WAIT_L(0); PG8_MMA(1, 0, At, B0); PG8_BAR; PG8_SCHED;
;             PG8_STAGE(PG8_SB(1, 1), b3 + hstep, voffB);
;             PG8_WAIT_V(6); PG8_BAR; PG8_MMA(1, 1, At, B1); PG8_BAR;
	s_waitcnt lgkmcnt(0)
	s_setprio 1
	v_mfma_f32_16x16x32_bf16 v[124:127], v[150:153], v[170:173], v[124:127]
	v_mfma_f32_16x16x32_bf16 v[120:123], v[162:165], v[170:173], v[120:123]
	v_mfma_f32_16x16x32_bf16 v[116:119], v[150:153], v[178:181], v[116:119]
	v_mfma_f32_16x16x32_bf16 v[112:115], v[162:165], v[178:181], v[112:115]
	v_mfma_f32_16x16x32_bf16 v[104:107], v[150:153], v[194:197], v[104:107]
	v_mfma_f32_16x16x32_bf16 v[96:99], v[162:165], v[194:197], v[96:99]
	v_mfma_f32_16x16x32_bf16 v[88:91], v[150:153], v[202:205], v[88:91]
	v_mfma_f32_16x16x32_bf16 v[80:83], v[162:165], v[202:205], v[80:83]
	v_mfma_f32_16x16x32_bf16 v[124:127], v[154:157], v[174:177], v[124:127]
	v_mfma_f32_16x16x32_bf16 v[120:123], v[166:169], v[174:177], v[120:123]
	v_mfma_f32_16x16x32_bf16 v[116:119], v[154:157], v[188:191], v[116:119]
	v_mfma_f32_16x16x32_bf16 v[112:115], v[166:169], v[188:191], v[112:115]
	v_mfma_f32_16x16x32_bf16 v[104:107], v[154:157], v[198:201], v[104:107]
	v_mfma_f32_16x16x32_bf16 v[96:99], v[166:169], v[198:201], v[96:99]
	v_mfma_f32_16x16x32_bf16 v[88:91], v[154:157], v[206:209], v[88:91]
	v_mfma_f32_16x16x32_bf16 v[80:83], v[166:169], v[206:209], v[80:83]
	s_setprio 0
	s_barrier
	s_add_i32 s4, 0, 0x1c000
	s_add_i32 s0, s64, s35
	v_add_u32_e32 v145, s4, v140
	s_add_i32 m0, s0, 0xffffff80
	ds_read_b128 v[210:213], v145
	ds_read_b128 v[214:217], v145 offset:1024
	ds_read_b128 v[218:221], v145 offset:2048
	global_load_lds_dwordx4 v130, s[36:37] offset:128
	s_add_i32 m0, s0, 0x1f80
	ds_read_b128 v[222:225], v145 offset:3072
	global_load_lds_dwordx4 v128, s[36:37] offset:128
	s_barrier
	s_waitcnt lgkmcnt(0)
	s_setprio 1
	v_mfma_f32_16x16x32_bf16 v[108:111], v[210:213], v[170:173], v[108:111]
	v_mfma_f32_16x16x32_bf16 v[100:103], v[218:221], v[170:173], v[100:103]
	v_mfma_f32_16x16x32_bf16 v[92:95], v[210:213], v[178:181], v[92:95]
	v_mfma_f32_16x16x32_bf16 v[84:87], v[218:221], v[178:181], v[84:87]
	v_mfma_f32_16x16x32_bf16 v[76:79], v[210:213], v[194:197], v[76:79]
	v_mfma_f32_16x16x32_bf16 v[72:75], v[218:221], v[194:197], v[72:75]
	v_mfma_f32_16x16x32_bf16 v[68:71], v[210:213], v[202:205], v[68:71]
	v_mfma_f32_16x16x32_bf16 v[64:67], v[218:221], v[202:205], v[64:67]
	v_mfma_f32_16x16x32_bf16 v[108:111], v[214:217], v[174:177], v[108:111]
	v_mfma_f32_16x16x32_bf16 v[100:103], v[222:225], v[174:177], v[100:103]
	v_mfma_f32_16x16x32_bf16 v[92:95], v[214:217], v[188:191], v[92:95]
	v_mfma_f32_16x16x32_bf16 v[84:87], v[222:225], v[188:191], v[84:87]
	v_mfma_f32_16x16x32_bf16 v[76:79], v[214:217], v[198:201], v[76:79]
	v_mfma_f32_16x16x32_bf16 v[72:75], v[222:225], v[198:201], v[72:75]
	v_mfma_f32_16x16x32_bf16 v[68:71], v[214:217], v[206:209], v[68:71]
	v_mfma_f32_16x16x32_bf16 v[64:67], v[222:225], v[206:209], v[64:67]
	s_setprio 0
	s_add_i32 m0, s56, 0xffffff80
	s_barrier
	ds_read_b128 v[170:173], v142 offset:49152
	ds_read_b128 v[174:177], v142 offset:50176
	ds_read_b128 v[178:181], v142 offset:51200
	ds_read_b128 v[188:191], v142 offset:52224
	ds_read_b128 v[194:197], v142 offset:53248
	ds_read_b128 v[198:201], v142 offset:54272
	ds_read_b128 v[202:205], v142 offset:55296
	global_load_lds_dwordx4 v130, s[38:39] offset:128
	s_add_i32 m0, s57, 0xffffff80
	ds_read_b128 v[206:209], v142 offset:56320
	global_load_lds_dwordx4 v128, s[38:39] offset:128
	s_barrier
	s_waitcnt lgkmcnt(0)
	s_setprio 1
	v_mfma_f32_16x16x32_bf16 v[60:63], v[150:153], v[170:173], v[60:63]
	v_mfma_f32_16x16x32_bf16 v[56:59], v[162:165], v[170:173], v[56:59]
	v_mfma_f32_16x16x32_bf16 v[52:55], v[150:153], v[178:181], v[52:55]
	v_mfma_f32_16x16x32_bf16 v[48:51], v[162:165], v[178:181], v[48:51]
	v_mfma_f32_16x16x32_bf16 v[40:43], v[150:153], v[194:197], v[40:43]
	v_mfma_f32_16x16x32_bf16 v[32:35], v[162:165], v[194:197], v[32:35]
	v_mfma_f32_16x16x32_bf16 v[24:27], v[150:153], v[202:205], v[24:27]
	v_mfma_f32_16x16x32_bf16 v[16:19], v[162:165], v[202:205], v[16:19]
	v_mfma_f32_16x16x32_bf16 v[60:63], v[154:157], v[174:177], v[60:63]
	v_mfma_f32_16x16x32_bf16 v[56:59], v[166:169], v[174:177], v[56:59]
	v_mfma_f32_16x16x32_bf16 v[52:55], v[154:157], v[188:191], v[52:55]
	v_mfma_f32_16x16x32_bf16 v[48:51], v[166:169], v[188:191], v[48:51]
	v_mfma_f32_16x16x32_bf16 v[40:43], v[154:157], v[198:201], v[40:43]
	v_mfma_f32_16x16x32_bf16 v[32:35], v[166:169], v[198:201], v[32:35]
	v_mfma_f32_16x16x32_bf16 v[24:27], v[154:157], v[206:209], v[24:27]
	v_mfma_f32_16x16x32_bf16 v[16:19], v[166:169], v[206:209], v[16:19]
	s_setprio 0
	s_barrier
	s_add_u32 s0, s36, 0x160080
	s_addc_u32 s1, s37, 0
	s_add_i32 s4, s4, s35
	s_mov_b32 m0, s4
	s_nop 0
	global_load_lds_dwordx4 v130, s[0:1]
	s_add_i32 m0, s4, 0x2000
	s_nop 0
	global_load_lds_dwordx4 v128, s[0:1]
	s_waitcnt vmcnt(6)
	s_barrier
	s_setprio 1
	v_mfma_f32_16x16x32_bf16 v[44:47], v[210:213], v[170:173], v[44:47]
	v_mfma_f32_16x16x32_bf16 v[36:39], v[218:221], v[170:173], v[36:39]
	v_mfma_f32_16x16x32_bf16 v[28:31], v[210:213], v[178:181], v[28:31]
	v_mfma_f32_16x16x32_bf16 v[20:23], v[218:221], v[178:181], v[20:23]
	v_mfma_f32_16x16x32_bf16 v[12:15], v[210:213], v[194:197], v[12:15]
	v_mfma_f32_16x16x32_bf16 v[8:11], v[218:221], v[194:197], v[8:11]
	v_mfma_f32_16x16x32_bf16 v[4:7], v[210:213], v[202:205], v[4:7]
	v_mfma_f32_16x16x32_bf16 v[0:3], v[218:221], v[202:205], v[0:3]
	v_mfma_f32_16x16x32_bf16 v[44:47], v[214:217], v[174:177], v[44:47]
	v_mfma_f32_16x16x32_bf16 v[36:39], v[222:225], v[174:177], v[36:39]
	v_mfma_f32_16x16x32_bf16 v[28:31], v[214:217], v[188:191], v[28:31]
	v_mfma_f32_16x16x32_bf16 v[20:23], v[222:225], v[188:191], v[20:23]
	v_mfma_f32_16x16x32_bf16 v[12:15], v[214:217], v[198:201], v[12:15]
	v_mfma_f32_16x16x32_bf16 v[8:11], v[222:225], v[198:201], v[8:11]
	v_mfma_f32_16x16x32_bf16 v[4:7], v[214:217], v[206:209], v[4:7]
	v_mfma_f32_16x16x32_bf16 v[0:3], v[222:225], v[206:209], v[0:3]
	s_setprio 0
	s_add_i32 s68, s68, 2
	s_add_u32 s8, s8, 0x100
	s_addc_u32 s9, s9, 0
	s_add_u32 s66, s66, 0x100
	s_addc_u32 s67, s67, 0
	s_cmp_gt_u32 s68, 5
	s_barrier
	s_cbranch_scc0 .LBB0_326

;     DI size_t aoff(const Unit& u, size_t tstep) const { return (size_t)u.pm * tstep; }
;     DI size_t boff(const Unit& u, size_t tstep) const { return (size_t)u.pn * tstep; }
;     DI bool next(int i, Unit& u) const { const long L = (long)i * G + c; if (L >= np) return false; u.pm = pmv; u.pn = (int)(L % nN); u.ks = (int)(L / nN); return true; }
;     DI size_t aoff(const Unit& u, size_t) const { return (size_t)u.ks * kbytes; }
;     DI size_t boff(const Unit& u, size_t tstep) const { return (size_t)u.pn * tstep + (size_t)u.ks * kbytes; }
;     DI bool next(int i, Unit& u) const { Unit t; if (!S.next(i / 3, t)) return false; u.pm = t.pm; u.pn = t.pn; u.ks = i % 3; return true; }
;     DI size_t aoff(const Unit& u, size_t tstep) const { return (u.ks < 2 ? offU : offOA) + (size_t)u.pm * tstep; }
; #define PG8_WAIT_V(n) asm volatile("s_waitcnt vmcnt(" #n ")" ::: "memory")
; template <class Epi, class Sched>
; DI void gemm_phase(LAS unsigned char* lds, const Gemm g, const Sched& S, const Epi& E) {
;     ...
;         const bool has_next = S.next(ui + 1, nxt);
;         const char* nA = has_next ? (const char*)g.A + S.aoff(nxt, tstep) : cA; const char* nB = has_next ? (const char*)g.Bt + S.boff(nxt, tstep) : cB;
;         for (int t = 0; t < nt; t += 2) {
;             if constexpr (Epi::HAS_MID) { if (t == E.mid_t(nt)) { int fr3 = fr, fq3 = fq; asm volatile("" : "+v"(fr3), "+v"(fq3)); E.mid(acc, cur, wr, wc, fr3, fq3); } }
;             const bool last = (t == nt - 2);
;             const char* a1 = cA + (size_t)(t + 1) * kstep;
;             const char* a2 = last ? nA : cA + (size_t)(t + 2) * kstep; const char* b2 = last ? nB : cB + (size_t)(t + 2) * kstep;
;             const char* a3 = a2 + kstep; const char* b3 = b2 + kstep;
;             PG8_LDB(B0, 0, 0); PG8_SCHED; PG8_LDA(At, 0, 0); PG8_STAGE(PG8_SA(1, 1), a1 + hstep, voffA);
;             PG8_WAIT_L(8); PG8_BAR; PG8_WAIT_L(0); PG8_MMA(0, 0, At, B0); PG8_BAR; PG8_SCHED;
;             PG8_LDB(B1, 0, 1); PG8_STAGE(PG8_SB(0, 0), b2, voffB);
;             PG8_BAR; PG8_WAIT_L(0); PG8_MMA(0, 1, At, B1); PG8_BAR;
;             PG8_LDA(At, 0, 1); PG8_STAGE(PG8_SA(0, 0), a2, voffA);
;             PG8_BAR; PG8_WAIT_L(0); PG8_MMA(1, 0, At, B0); PG8_BAR; PG8_SCHED;
;             PG8_STAGE(PG8_SB(0, 1), b2 + hstep, voffB);
;             PG8_WAIT_V(6); PG8_BAR; PG8_MMA(1, 1, At, B1); PG8_BAR;
.LBB0_526:
	s_ashr_i32 s51, s50, 31
	s_lshl_b64 s[0:1], s[50:51], 20
	s_add_u32 s52, s70, s0
	v_cmp_lt_i64_e32 vcc, s[12:13], v[142:143]
	s_addc_u32 s53, s71, s1
	s_and_b64 s[0:1], vcc, exec
	s_cselect_b32 s14, s53, s9
	s_cselect_b32 s15, s52, s8
	s_ashr_i32 s49, s48, 31
	s_lshl_b64 s[0:1], s[48:49], 20
	s_add_u32 s54, s72, s0
	s_addc_u32 s55, s73, s1
	s_and_b64 s[0:1], vcc, exec
	s_cselect_b32 s16, s55, s11
	s_cselect_b32 s17, s54, s10
	s_add_u32 s8, s8, 0x80080
	s_addc_u32 s9, s9, 0
	s_add_u32 s28, s10, 0x100
	v_mov_b32_e32 v0, 0
	s_addc_u32 s34, s11, 0
	s_mov_b32 s35, -2
	ds_read_b128 v[146:149], v164
	ds_read_b128 v[150:153], v164 offset:1024
	ds_read_b128 v[154:157], v164 offset:2048
	ds_read_b128 v[170:173], v164 offset:3072
	s_add_u32 s0, s8, 0xfff80080
	s_addc_u32 s1, s9, -1
	s_cmp_eq_u32 s35, 28
	s_cselect_b32 s13, s14, s1
	s_cselect_b32 s12, s15, s0
	s_cselect_b32 s11, s16, s34
	s_cselect_b32 s10, s17, s28
	s_add_i32 m0, s59, 0xc000
	ds_read_b128 v[174:177], v165
	ds_read_b128 v[178:181], v165 offset:1024
	ds_read_b128 v[188:191], v165 offset:2048
	ds_read_b128 v[194:197], v165 offset:3072
	ds_read_b128 v[198:201], v165 offset:4096
	ds_read_b128 v[202:205], v165 offset:5120
	ds_read_b128 v[206:209], v165 offset:6144
	global_load_lds_dwordx4 v138, s[8:9]
	s_add_i32 m0, s59, 0xe000
	ds_read_b128 v[210:213], v165 offset:7168
	global_load_lds_dwordx4 v140, s[8:9]
	s_waitcnt lgkmcnt(8)
	s_barrier
	s_waitcnt lgkmcnt(0)
	s_setprio 1
	v_mfma_f32_16x16x32_bf16 v[124:127], v[146:149], v[174:177], 0
	v_mfma_f32_16x16x32_bf16 v[120:123], v[154:157], v[174:177], 0
	v_mfma_f32_16x16x32_bf16 v[108:111], v[146:149], v[188:191], 0
	v_mfma_f32_16x16x32_bf16 v[104:107], v[154:157], v[188:191], 0
	v_mfma_f32_16x16x32_bf16 v[92:95], v[146:149], v[198:201], 0
	v_mfma_f32_16x16x32_bf16 v[88:91], v[154:157], v[198:201], 0
	v_mfma_f32_16x16x32_bf16 v[76:79], v[146:149], v[206:209], 0
	v_mfma_f32_16x16x32_bf16 v[72:75], v[154:157], v[206:209], 0
	v_mfma_f32_16x16x32_bf16 v[124:127], v[150:153], v[178:181], v[124:127]
	v_mfma_f32_16x16x32_bf16 v[120:123], v[170:173], v[178:181], v[120:123]
	v_mfma_f32_16x16x32_bf16 v[108:111], v[150:153], v[194:197], v[108:111]
	v_mfma_f32_16x16x32_bf16 v[104:107], v[170:173], v[194:197], v[104:107]
	v_mfma_f32_16x16x32_bf16 v[92:95], v[150:153], v[202:205], v[92:95]
	v_mfma_f32_16x16x32_bf16 v[88:91], v[170:173], v[202:205], v[88:91]
	v_mfma_f32_16x16x32_bf16 v[76:79], v[150:153], v[210:213], v[76:79]
	v_mfma_f32_16x16x32_bf16 v[72:75], v[170:173], v[210:213], v[72:75]
	s_setprio 0
	s_barrier
	s_add_i32 s0, s47, s74
	s_mov_b32 m0, s0
	ds_read_b128 v[214:217], v166
	ds_read_b128 v[218:221], v166 offset:1024
	ds_read_b128 v[222:225], v166 offset:2048
	ds_read_b128 v[226:229], v166 offset:3072
	global_load_lds_dwordx4 v130, s[10:11]
	v_lshl_add_u64 v[182:183], s[10:11], 0, v[134:135]
	s_add_i32 m0, s0, 0x2000
	s_nop 0
	global_load_lds_dwordx4 v134, s[10:11]
	s_barrier
	s_waitcnt lgkmcnt(0)
	s_setprio 1
	v_mfma_f32_16x16x32_bf16 v[116:119], v[214:217], v[174:177], 0
	v_mfma_f32_16x16x32_bf16 v[112:115], v[222:225], v[174:177], 0
	v_mfma_f32_16x16x32_bf16 v[100:103], v[214:217], v[188:191], 0
	v_mfma_f32_16x16x32_bf16 v[96:99], v[222:225], v[188:191], 0
	v_mfma_f32_16x16x32_bf16 v[84:87], v[214:217], v[198:201], 0
	v_mfma_f32_16x16x32_bf16 v[80:83], v[222:225], v[198:201], 0
	v_mfma_f32_16x16x32_bf16 v[68:71], v[214:217], v[206:209], 0
	v_mfma_f32_16x16x32_bf16 v[64:67], v[222:225], v[206:209], 0
	v_mfma_f32_16x16x32_bf16 v[116:119], v[218:221], v[178:181], v[116:119]
	v_mfma_f32_16x16x32_bf16 v[112:115], v[226:229], v[178:181], v[112:115]
	v_mfma_f32_16x16x32_bf16 v[100:103], v[218:221], v[194:197], v[100:103]
	v_mfma_f32_16x16x32_bf16 v[96:99], v[226:229], v[194:197], v[96:99]
	v_mfma_f32_16x16x32_bf16 v[84:87], v[218:221], v[202:205], v[84:87]
	v_mfma_f32_16x16x32_bf16 v[80:83], v[226:229], v[202:205], v[80:83]
	v_mfma_f32_16x16x32_bf16 v[68:71], v[218:221], v[210:213], v[68:71]
	v_mfma_f32_16x16x32_bf16 v[64:67], v[226:229], v[210:213], v[64:67]
	s_setprio 0
	s_mov_b32 m0, s59
	s_barrier
	ds_read_b128 v[174:177], v165 offset:16384
	ds_read_b128 v[178:181], v165 offset:17408
	ds_read_b128 v[188:191], v165 offset:18432
	ds_read_b128 v[194:197], v165 offset:19456
	ds_read_b128 v[198:201], v165 offset:20480
	ds_read_b128 v[202:205], v165 offset:21504
	ds_read_b128 v[206:209], v165 offset:22528
	ds_read_b128 v[210:213], v165 offset:23552
	global_load_lds_dwordx4 v128, s[12:13]
	v_lshl_add_u64 v[232:233], s[12:13], 0, v[132:133]
	s_mov_b32 m0, s75
	s_nop 0
	global_load_lds_dwordx4 v132, s[12:13]
	s_barrier
	s_waitcnt lgkmcnt(0)
	s_setprio 1
	v_mfma_f32_16x16x32_bf16 v[60:63], v[146:149], v[174:177], 0
	v_mfma_f32_16x16x32_bf16 v[56:59], v[154:157], v[174:177], 0
	v_mfma_f32_16x16x32_bf16 v[44:47], v[146:149], v[188:191], 0
	v_mfma_f32_16x16x32_bf16 v[40:43], v[154:157], v[188:191], 0
	v_mfma_f32_16x16x32_bf16 v[28:31], v[146:149], v[198:201], 0
	v_mfma_f32_16x16x32_bf16 v[24:27], v[154:157], v[198:201], 0
	v_mfma_f32_16x16x32_bf16 v[12:15], v[146:149], v[206:209], 0
	v_mfma_f32_16x16x32_bf16 v[8:11], v[154:157], v[206:209], 0
	v_mfma_f32_16x16x32_bf16 v[60:63], v[150:153], v[178:181], v[60:63]
	v_mfma_f32_16x16x32_bf16 v[56:59], v[170:173], v[178:181], v[56:59]
	v_mfma_f32_16x16x32_bf16 v[44:47], v[150:153], v[194:197], v[44:47]
	v_mfma_f32_16x16x32_bf16 v[40:43], v[170:173], v[194:197], v[40:43]
	v_mfma_f32_16x16x32_bf16 v[28:31], v[150:153], v[202:205], v[28:31]
	v_mfma_f32_16x16x32_bf16 v[24:27], v[170:173], v[202:205], v[24:27]
	v_mfma_f32_16x16x32_bf16 v[12:15], v[150:153], v[210:213], v[12:15]
	v_mfma_f32_16x16x32_bf16 v[8:11], v[170:173], v[210:213], v[8:11]
	s_setprio 0
	s_barrier
; #define PG8_STAGE(bufoff, gbase, voff) do { _Pragma("unroll") for (int _i = 0; _i < 2; ++_i) \
;         __builtin_amdgcn_global_load_lds((const unsigned*)((const char*)(gbase) + (voff)[_i]), (LAS unsigned*)(lds + (bufoff) + ldsw + _i * 8192), 16, 0, 0); } while (0)
; #define PG8_LDA(dst, b, h) do { _Pragma("unroll") for (int m = 0; m < 4; ++m) _Pragma("unroll") for (int k = 0; k < 2; ++k) dst[m][k] = *(const LAS bf16x8*)(lds + PG8_SA(b, h) + aoff + m * 2048 + k * 1024); } while (0)
; #define PG8_LDB(dst, b, h) do { _Pragma("unroll") for (int n = 0; n < 2; ++n) _Pragma("unroll") for (int k = 0; k < 2; ++k) dst[n][k] = *(const LAS bf16x8*)(lds + PG8_SB(b, h) + boff + n * 2048 + k * 1024); } while (0)
; #define PG8_MMA(ai, bj, At, Bt) do { __builtin_amdgcn_s_setprio(1); _Pragma("unroll") for (int m = 0; m < 4; ++m) _Pragma("unroll") for (int n = 0; n < 2; ++n) _Pragma("unroll") for (int k = 0; k < 2; ++k) \
;         acc[ai][bj][m][n] = __builtin_amdgcn_mfma_f32_16x16x32_bf16(Bt[n][k], At[m][k], acc[ai][bj][m][n], 0, 0, 0); __builtin_amdgcn_s_setprio(0); } while (0)
; #define PG8_WAIT_V(n) asm volatile("s_waitcnt vmcnt(" #n ")" ::: "memory")
; #define PG8_WAIT_L(n) asm volatile("s_waitcnt lgkmcnt(" #n ")" ::: "memory")
; #define PG8_BAR __builtin_amdgcn_s_barrier()
; #define PG8_SCHED __builtin_amdgcn_sched_barrier(0)
; template <class Epi, class Sched>
; DI void gemm_phase(LAS unsigned char* lds, const Gemm g, const Sched& S, const Epi& E) {
;     ...
;             PG8_STAGE(PG8_SB(0, 1), b2 + hstep, voffB);
;             PG8_WAIT_V(6); PG8_BAR; PG8_MMA(1, 1, At, B1); PG8_BAR;
;             PG8_LDB(B0, 1, 0); PG8_SCHED; PG8_LDA(At, 1, 0); PG8_STAGE(PG8_SA(0, 1), a2 + hstep, voffA);
;             PG8_WAIT_L(8); PG8_BAR; PG8_WAIT_L(0); PG8_MMA(0, 0, At, B0); PG8_BAR; PG8_SCHED;
;             PG8_LDB(B1, 1, 1); PG8_STAGE(PG8_SB(1, 0), b3, voffB);
;             PG8_BAR; PG8_WAIT_L(0); PG8_MMA(0, 1, At, B1); PG8_BAR;
;             PG8_LDA(At, 1, 1); PG8_STAGE(PG8_SA(1, 0), a3, voffA);
;             PG8_BAR; PG8_WAIT_L(0); PG8_MMA(1, 0, At, B0); PG8_BAR; PG8_SCHED;
;             PG8_STAGE(PG8_SB(1, 1), b3 + hstep, voffB);
	s_add_u32 s0, s10, 0x80000
	s_addc_u32 s1, s11, 0
	s_add_i32 s4, s87, s74
	s_mov_b32 m0, s4
	s_nop 0
	global_load_lds_dwordx4 v130, s[0:1]
	s_add_i32 m0, s4, 0x2000
	s_nop 0
	global_load_lds_dwordx4 v134, s[0:1]
	s_waitcnt vmcnt(6)
	s_barrier
	s_setprio 1
	v_mfma_f32_16x16x32_bf16 v[52:55], v[214:217], v[174:177], 0
	v_mfma_f32_16x16x32_bf16 v[48:51], v[222:225], v[174:177], 0
	v_mfma_f32_16x16x32_bf16 v[36:39], v[214:217], v[188:191], 0
	v_mfma_f32_16x16x32_bf16 v[32:35], v[222:225], v[188:191], 0
	v_mfma_f32_16x16x32_bf16 v[20:23], v[214:217], v[198:201], 0
	v_mfma_f32_16x16x32_bf16 v[16:19], v[222:225], v[198:201], 0
	v_mfma_f32_16x16x32_bf16 v[4:7], v[214:217], v[206:209], 0
	v_mfma_f32_16x16x32_bf16 v[0:3], v[222:225], v[206:209], 0
	v_mfma_f32_16x16x32_bf16 v[52:55], v[218:221], v[178:181], v[52:55]
	v_mfma_f32_16x16x32_bf16 v[48:51], v[226:229], v[178:181], v[48:51]
	v_mfma_f32_16x16x32_bf16 v[36:39], v[218:221], v[194:197], v[36:39]
	v_mfma_f32_16x16x32_bf16 v[32:35], v[226:229], v[194:197], v[32:35]
	v_mfma_f32_16x16x32_bf16 v[20:23], v[218:221], v[202:205], v[20:23]
	v_mfma_f32_16x16x32_bf16 v[16:19], v[226:229], v[202:205], v[16:19]
	v_mfma_f32_16x16x32_bf16 v[4:7], v[218:221], v[210:213], v[4:7]
	v_mfma_f32_16x16x32_bf16 v[0:3], v[226:229], v[210:213], v[0:3]
	s_setprio 0
	s_add_i32 s4, 0, 0x18000
	v_add_u32_e32 v137, s4, v163
	s_barrier
	ds_read_b128 v[146:149], v137
	ds_read_b128 v[150:153], v137 offset:1024
	ds_read_b128 v[154:157], v137 offset:2048
	ds_read_b128 v[170:173], v137 offset:3072
	s_add_u32 s0, s12, 0x80000
	s_addc_u32 s1, s13, 0
	s_mov_b32 m0, s76
	ds_read_b128 v[174:177], v165 offset:32768
	ds_read_b128 v[178:181], v165 offset:33792
	ds_read_b128 v[188:191], v165 offset:34816
	ds_read_b128 v[194:197], v165 offset:35840
	ds_read_b128 v[198:201], v165 offset:36864
	ds_read_b128 v[202:205], v165 offset:37888
	ds_read_b128 v[206:209], v165 offset:38912
	global_load_lds_dwordx4 v128, s[0:1]
	s_mov_b32 m0, s77
	ds_read_b128 v[210:213], v165 offset:39936
	global_load_lds_dwordx4 v132, s[0:1]
	s_waitcnt lgkmcnt(8)
	s_barrier
	s_waitcnt lgkmcnt(0)
	s_setprio 1
	v_mfma_f32_16x16x32_bf16 v[124:127], v[146:149], v[174:177], v[124:127]
	v_mfma_f32_16x16x32_bf16 v[120:123], v[154:157], v[174:177], v[120:123]
	v_mfma_f32_16x16x32_bf16 v[108:111], v[146:149], v[188:191], v[108:111]
	v_mfma_f32_16x16x32_bf16 v[104:107], v[154:157], v[188:191], v[104:107]
	v_mfma_f32_16x16x32_bf16 v[92:95], v[146:149], v[198:201], v[92:95]
	v_mfma_f32_16x16x32_bf16 v[88:91], v[154:157], v[198:201], v[88:91]
	v_mfma_f32_16x16x32_bf16 v[76:79], v[146:149], v[206:209], v[76:79]
	v_mfma_f32_16x16x32_bf16 v[72:75], v[154:157], v[206:209], v[72:75]
	v_mfma_f32_16x16x32_bf16 v[124:127], v[150:153], v[178:181], v[124:127]
	v_mfma_f32_16x16x32_bf16 v[120:123], v[170:173], v[178:181], v[120:123]
	v_mfma_f32_16x16x32_bf16 v[108:111], v[150:153], v[194:197], v[108:111]
	v_mfma_f32_16x16x32_bf16 v[104:107], v[170:173], v[194:197], v[104:107]
	v_mfma_f32_16x16x32_bf16 v[92:95], v[150:153], v[202:205], v[92:95]
	v_mfma_f32_16x16x32_bf16 v[88:91], v[170:173], v[202:205], v[88:91]
	v_mfma_f32_16x16x32_bf16 v[76:79], v[150:153], v[210:213], v[76:79]
	v_mfma_f32_16x16x32_bf16 v[72:75], v[170:173], v[210:213], v[72:75]
	s_setprio 0
	s_barrier
	s_add_i32 s5, 0, 0x1c000
	s_add_i32 s0, s4, s74
	v_add_u32_e32 v137, s5, v163
	s_add_i32 m0, s0, 0xffffff80
	ds_read_b128 v[214:217], v137
	ds_read_b128 v[218:221], v137 offset:1024
	ds_read_b128 v[222:225], v137 offset:2048
	global_load_lds_dwordx4 v130, s[10:11] offset:128
	s_add_i32 m0, s0, 0x1f80
	ds_read_b128 v[226:229], v137 offset:3072
	global_load_lds_dwordx4 v134, s[10:11] offset:128
	s_barrier
	s_waitcnt lgkmcnt(0)
	s_setprio 1
	v_mfma_f32_16x16x32_bf16 v[116:119], v[214:217], v[174:177], v[116:119]
	v_mfma_f32_16x16x32_bf16 v[112:115], v[222:225], v[174:177], v[112:115]
	v_mfma_f32_16x16x32_bf16 v[100:103], v[214:217], v[188:191], v[100:103]
	v_mfma_f32_16x16x32_bf16 v[96:99], v[222:225], v[188:191], v[96:99]
	v_mfma_f32_16x16x32_bf16 v[84:87], v[214:217], v[198:201], v[84:87]
	v_mfma_f32_16x16x32_bf16 v[80:83], v[222:225], v[198:201], v[80:83]
	v_mfma_f32_16x16x32_bf16 v[68:71], v[214:217], v[206:209], v[68:71]
	v_mfma_f32_16x16x32_bf16 v[64:67], v[222:225], v[206:209], v[64:67]
	v_mfma_f32_16x16x32_bf16 v[116:119], v[218:221], v[178:181], v[116:119]
	v_mfma_f32_16x16x32_bf16 v[112:115], v[226:229], v[178:181], v[112:115]
	v_mfma_f32_16x16x32_bf16 v[100:103], v[218:221], v[194:197], v[100:103]
	v_mfma_f32_16x16x32_bf16 v[96:99], v[226:229], v[194:197], v[96:99]
	v_mfma_f32_16x16x32_bf16 v[84:87], v[218:221], v[202:205], v[84:87]
	v_mfma_f32_16x16x32_bf16 v[80:83], v[226:229], v[202:205], v[80:83]
	v_mfma_f32_16x16x32_bf16 v[68:71], v[218:221], v[210:213], v[68:71]
	v_mfma_f32_16x16x32_bf16 v[64:67], v[226:229], v[210:213], v[64:67]
	s_setprio 0
	s_add_i32 m0, s97, 0xffffff80
	s_barrier
	ds_read_b128 v[174:177], v165 offset:49152
	ds_read_b128 v[178:181], v165 offset:50176
	ds_read_b128 v[188:191], v165 offset:51200
	ds_read_b128 v[194:197], v165 offset:52224
	ds_read_b128 v[198:201], v165 offset:53248
	ds_read_b128 v[202:205], v165 offset:54272
	ds_read_b128 v[206:209], v165 offset:55296
	ds_read_b128 v[210:213], v165 offset:56320
	global_load_lds_dwordx4 v128, s[12:13] offset:128
	v_lshl_add_u64 v[158:159], v[232:233], 0, s[40:41]
	s_add_i32 m0, s84, 0xffffff80
	s_nop 0
	global_load_lds_dwordx4 v132, s[12:13] offset:128
	s_barrier
; #define PG8_STAGE(bufoff, gbase, voff) do { _Pragma("unroll") for (int _i = 0; _i < 2; ++_i) \
;         __builtin_amdgcn_global_load_lds((const unsigned*)((const char*)(gbase) + (voff)[_i]), (LAS unsigned*)(lds + (bufoff) + ldsw + _i * 8192), 16, 0, 0); } while (0)
; #define PG8_LDA(dst, b, h) do { _Pragma("unroll") for (int m = 0; m < 4; ++m) _Pragma("unroll") for (int k = 0; k < 2; ++k) dst[m][k] = *(const LAS bf16x8*)(lds + PG8_SA(b, h) + aoff + m * 2048 + k * 1024); } while (0)
; #define PG8_LDB(dst, b, h) do { _Pragma("unroll") for (int n = 0; n < 2; ++n) _Pragma("unroll") for (int k = 0; k < 2; ++k) dst[n][k] = *(const LAS bf16x8*)(lds + PG8_SB(b, h) + boff + n * 2048 + k * 1024); } while (0)
; #define PG8_WAIT_V(n) asm volatile("s_waitcnt vmcnt(" #n ")" ::: "memory")
; #define PG8_WAIT_L(n) asm volatile("s_waitcnt lgkmcnt(" #n ")" ::: "memory")
; #define PG8_BAR __builtin_amdgcn_s_barrier()
; #define PG8_SCHED __builtin_amdgcn_sched_barrier(0)
; template <class Epi, class Sched>
; DI void gemm_phase(LAS unsigned char* lds, const Gemm g, const Sched& S, const Epi& E) {
;     ...
;             PG8_LDB(B0, 0, 0); PG8_SCHED; PG8_LDA(At, 0, 0); PG8_STAGE(PG8_SA(1, 1), a1 + hstep, voffA);
;             PG8_WAIT_L(8); PG8_BAR; PG8_WAIT_L(0); PG8_MMA(0, 0, At, B0); PG8_BAR; PG8_SCHED;
;             PG8_LDB(B1, 0, 1); PG8_STAGE(PG8_SB(0, 0), b2, voffB);
;             PG8_BAR; PG8_WAIT_L(0); PG8_MMA(0, 1, At, B1); PG8_BAR;
;             PG8_LDA(At, 0, 1); PG8_STAGE(PG8_SA(0, 0), a2, voffA);
;             PG8_BAR; PG8_WAIT_L(0); PG8_MMA(1, 0, At, B0); PG8_BAR; PG8_SCHED;
;             PG8_STAGE(PG8_SB(0, 1), b2 + hstep, voffB);
;             PG8_WAIT_V(6); PG8_BAR; PG8_MMA(1, 1, At, B1); PG8_BAR;
;             PG8_LDB(B0, 1, 0); PG8_SCHED; PG8_LDA(At, 1, 0); PG8_STAGE(PG8_SA(0, 1), a2 + hstep, voffA);
;             PG8_WAIT_L(8); PG8_BAR; PG8_WAIT_L(0); PG8_MMA(0, 0, At, B0); PG8_BAR; PG8_SCHED;
;             PG8_LDB(B1, 1, 1); PG8_STAGE(PG8_SB(1, 0), b3, voffB);
;             PG8_BAR; PG8_WAIT_L(0); PG8_MMA(0, 1, At, B1); PG8_BAR;
;             PG8_LDA(At, 1, 1); PG8_STAGE(PG8_SA(1, 0), a3, voffA);
;             PG8_BAR; PG8_WAIT_L(0); PG8_MMA(1, 0, At, B0); PG8_BAR; PG8_SCHED;
;             PG8_STAGE(PG8_SB(1, 1), b3 + hstep, voffB);
;             PG8_WAIT_V(6); PG8_BAR; PG8_MMA(1, 1, At, B1); PG8_BAR;
	s_waitcnt lgkmcnt(0)
	s_setprio 1
	v_mfma_f32_16x16x32_bf16 v[60:63], v[146:149], v[174:177], v[60:63]
	v_mfma_f32_16x16x32_bf16 v[56:59], v[154:157], v[174:177], v[56:59]
	v_mfma_f32_16x16x32_bf16 v[44:47], v[146:149], v[188:191], v[44:47]
	v_mfma_f32_16x16x32_bf16 v[40:43], v[154:157], v[188:191], v[40:43]
	v_mfma_f32_16x16x32_bf16 v[28:31], v[146:149], v[198:201], v[28:31]
	v_mfma_f32_16x16x32_bf16 v[24:27], v[154:157], v[198:201], v[24:27]
	v_mfma_f32_16x16x32_bf16 v[12:15], v[146:149], v[206:209], v[12:15]
	v_mfma_f32_16x16x32_bf16 v[8:11], v[154:157], v[206:209], v[8:11]
	v_mfma_f32_16x16x32_bf16 v[60:63], v[150:153], v[178:181], v[60:63]
	v_mfma_f32_16x16x32_bf16 v[56:59], v[170:173], v[178:181], v[56:59]
	v_mfma_f32_16x16x32_bf16 v[44:47], v[150:153], v[194:197], v[44:47]
	v_mfma_f32_16x16x32_bf16 v[40:43], v[170:173], v[194:197], v[40:43]
	v_mfma_f32_16x16x32_bf16 v[28:31], v[150:153], v[202:205], v[28:31]
	v_mfma_f32_16x16x32_bf16 v[24:27], v[170:173], v[202:205], v[24:27]
	v_mfma_f32_16x16x32_bf16 v[12:15], v[150:153], v[210:213], v[12:15]
	v_mfma_f32_16x16x32_bf16 v[8:11], v[170:173], v[210:213], v[8:11]
	s_setprio 0
	s_barrier
	s_add_u32 s0, s10, 0x80080
	s_addc_u32 s1, s11, 0
	s_add_i32 s4, s5, s74
	s_mov_b32 m0, s4
	s_nop 0
	global_load_lds_dwordx4 v130, s[0:1]
	v_lshl_add_u64 v[146:147], s[0:1], 0, v[134:135]
	s_add_i32 m0, s4, 0x2000
	s_nop 0
	global_load_lds_dwordx4 v134, s[0:1]
	s_waitcnt vmcnt(6)
	s_barrier
	s_setprio 1
	v_mfma_f32_16x16x32_bf16 v[52:55], v[214:217], v[174:177], v[52:55]
	v_mfma_f32_16x16x32_bf16 v[48:51], v[222:225], v[174:177], v[48:51]
	v_mfma_f32_16x16x32_bf16 v[36:39], v[214:217], v[188:191], v[36:39]
	v_mfma_f32_16x16x32_bf16 v[32:35], v[222:225], v[188:191], v[32:35]
	v_mfma_f32_16x16x32_bf16 v[20:23], v[214:217], v[198:201], v[20:23]
	v_mfma_f32_16x16x32_bf16 v[16:19], v[222:225], v[198:201], v[16:19]
	v_mfma_f32_16x16x32_bf16 v[4:7], v[214:217], v[206:209], v[4:7]
	v_mfma_f32_16x16x32_bf16 v[0:3], v[222:225], v[206:209], v[0:3]
	v_mfma_f32_16x16x32_bf16 v[52:55], v[218:221], v[178:181], v[52:55]
	v_mfma_f32_16x16x32_bf16 v[48:51], v[226:229], v[178:181], v[48:51]
	v_mfma_f32_16x16x32_bf16 v[36:39], v[218:221], v[194:197], v[36:39]
	v_mfma_f32_16x16x32_bf16 v[32:35], v[226:229], v[194:197], v[32:35]
	v_mfma_f32_16x16x32_bf16 v[20:23], v[218:221], v[202:205], v[20:23]
	v_mfma_f32_16x16x32_bf16 v[16:19], v[226:229], v[202:205], v[16:19]
	v_mfma_f32_16x16x32_bf16 v[4:7], v[218:221], v[210:213], v[4:7]
	v_mfma_f32_16x16x32_bf16 v[0:3], v[226:229], v[210:213], v[0:3]
	s_setprio 0
	s_add_i32 s35, s35, 2
	s_add_u32 s8, s8, 0x100
	s_addc_u32 s9, s9, 0
	s_add_u32 s28, s28, 0x100
	s_addc_u32 s34, s34, 0
	s_cmp_gt_u32 s35, 29
	s_barrier
	s_cbranch_scc0 .LBB0_527
	s_branch .Lpeel_done_527
.LBB0_527:
	ds_read_b128 v[146:149], v164
	ds_read_b128 v[150:153], v164 offset:1024
	ds_read_b128 v[154:157], v164 offset:2048
	ds_read_b128 v[170:173], v164 offset:3072
	s_add_u32 s0, s8, 0xfff80080
	s_addc_u32 s1, s9, -1
	s_cmp_eq_u32 s35, 28
	s_cselect_b32 s13, s14, s1
	s_cselect_b32 s12, s15, s0
	s_cselect_b32 s11, s16, s34
	s_cselect_b32 s10, s17, s28
	s_add_i32 m0, s59, 0xc000
	ds_read_b128 v[174:177], v165
	ds_read_b128 v[178:181], v165 offset:1024
	ds_read_b128 v[188:191], v165 offset:2048
	ds_read_b128 v[194:197], v165 offset:3072
	ds_read_b128 v[198:201], v165 offset:4096
	ds_read_b128 v[202:205], v165 offset:5120
	ds_read_b128 v[206:209], v165 offset:6144
	global_load_lds_dwordx4 v138, s[8:9]
	s_add_i32 m0, s59, 0xe000
	ds_read_b128 v[210:213], v165 offset:7168
	global_load_lds_dwordx4 v140, s[8:9]
	s_waitcnt lgkmcnt(8)
	s_barrier
	s_waitcnt lgkmcnt(0)
	s_setprio 1
	v_mfma_f32_16x16x32_bf16 v[124:127], v[146:149], v[174:177], v[124:127]
	v_mfma_f32_16x16x32_bf16 v[120:123], v[154:157], v[174:177], v[120:123]
	v_mfma_f32_16x16x32_bf16 v[108:111], v[146:149], v[188:191], v[108:111]
	v_mfma_f32_16x16x32_bf16 v[104:107], v[154:157], v[188:191], v[104:107]
	v_mfma_f32_16x16x32_bf16 v[92:95], v[146:149], v[198:201], v[92:95]
	v_mfma_f32_16x16x32_bf16 v[88:91], v[154:157], v[198:201], v[88:91]
	v_mfma_f32_16x16x32_bf16 v[76:79], v[146:149], v[206:209], v[76:79]
	v_mfma_f32_16x16x32_bf16 v[72:75], v[154:157], v[206:209], v[72:75]
	v_mfma_f32_16x16x32_bf16 v[124:127], v[150:153], v[178:181], v[124:127]
	v_mfma_f32_16x16x32_bf16 v[120:123], v[170:173], v[178:181], v[120:123]
	v_mfma_f32_16x16x32_bf16 v[108:111], v[150:153], v[194:197], v[108:111]
	v_mfma_f32_16x16x32_bf16 v[104:107], v[170:173], v[194:197], v[104:107]
	v_mfma_f32_16x16x32_bf16 v[92:95], v[150:153], v[202:205], v[92:95]
	v_mfma_f32_16x16x32_bf16 v[88:91], v[170:173], v[202:205], v[88:91]
	v_mfma_f32_16x16x32_bf16 v[76:79], v[150:153], v[210:213], v[76:79]
	v_mfma_f32_16x16x32_bf16 v[72:75], v[170:173], v[210:213], v[72:75]
	s_setprio 0
	s_barrier
	s_add_i32 s0, s47, s74
	s_mov_b32 m0, s0
	ds_read_b128 v[214:217], v166
	ds_read_b128 v[218:221], v166 offset:1024
	ds_read_b128 v[222:225], v166 offset:2048
	ds_read_b128 v[226:229], v166 offset:3072
	global_load_lds_dwordx4 v130, s[10:11]
	v_lshl_add_u64 v[182:183], s[10:11], 0, v[134:135]
	s_add_i32 m0, s0, 0x2000
	s_nop 0
	global_load_lds_dwordx4 v134, s[10:11]
	s_barrier
; #define PG8_STAGE(bufoff, gbase, voff) do { _Pragma("unroll") for (int _i = 0; _i < 2; ++_i) \
;         __builtin_amdgcn_global_load_lds((const unsigned*)((const char*)(gbase) + (voff)[_i]), (LAS unsigned*)(lds + (bufoff) + ldsw + _i * 8192), 16, 0, 0); } while (0)
; #define PG8_LDA(dst, b, h) do { _Pragma("unroll") for (int m = 0; m < 4; ++m) _Pragma("unroll") for (int k = 0; k < 2; ++k) dst[m][k] = *(const LAS bf16x8*)(lds + PG8_SA(b, h) + aoff + m * 2048 + k * 1024); } while (0)
; #define PG8_LDB(dst, b, h) do { _Pragma("unroll") for (int n = 0; n < 2; ++n) _Pragma("unroll") for (int k = 0; k < 2; ++k) dst[n][k] = *(const LAS bf16x8*)(lds + PG8_SB(b, h) + boff + n * 2048 + k * 1024); } while (0)
; #define PG8_MMA(ai, bj, At, Bt) do { __builtin_amdgcn_s_setprio(1); _Pragma("unroll") for (int m = 0; m < 4; ++m) _Pragma("unroll") for (int n = 0; n < 2; ++n) _Pragma("unroll") for (int k = 0; k < 2; ++k) \
;         acc[ai][bj][m][n] = __builtin_amdgcn_mfma_f32_16x16x32_bf16(Bt[n][k], At[m][k], acc[ai][bj][m][n], 0, 0, 0); __builtin_amdgcn_s_setprio(0); } while (0)
; #define PG8_WAIT_V(n) asm volatile("s_waitcnt vmcnt(" #n ")" ::: "memory")
; #define PG8_WAIT_L(n) asm volatile("s_waitcnt lgkmcnt(" #n ")" ::: "memory")
; #define PG8_BAR __builtin_amdgcn_s_barrier()
; #define PG8_SCHED __builtin_amdgcn_sched_barrier(0)
; template <class Epi, class Sched>
; DI void gemm_phase(LAS unsigned char* lds, const Gemm g, const Sched& S, const Epi& E) {
;     ...
;             PG8_BAR; PG8_WAIT_L(0); PG8_MMA(0, 1, At, B1); PG8_BAR;
;             PG8_LDA(At, 0, 1); PG8_STAGE(PG8_SA(0, 0), a2, voffA);
;             PG8_BAR; PG8_WAIT_L(0); PG8_MMA(1, 0, At, B0); PG8_BAR; PG8_SCHED;
;             PG8_STAGE(PG8_SB(0, 1), b2 + hstep, voffB);
;             PG8_WAIT_V(6); PG8_BAR; PG8_MMA(1, 1, At, B1); PG8_BAR;
;             PG8_LDB(B0, 1, 0); PG8_SCHED; PG8_LDA(At, 1, 0); PG8_STAGE(PG8_SA(0, 1), a2 + hstep, voffA);
;             PG8_WAIT_L(8); PG8_BAR; PG8_WAIT_L(0); PG8_MMA(0, 0, At, B0); PG8_BAR; PG8_SCHED;
;             PG8_LDB(B1, 1, 1); PG8_STAGE(PG8_SB(1, 0), b3, voffB);
;             PG8_BAR; PG8_WAIT_L(0); PG8_MMA(0, 1, At, B1); PG8_BAR;
;             PG8_LDA(At, 1, 1); PG8_STAGE(PG8_SA(1, 0), a3, voffA);
	s_waitcnt lgkmcnt(0)
	s_setprio 1
	v_mfma_f32_16x16x32_bf16 v[116:119], v[214:217], v[174:177], v[116:119]
	v_mfma_f32_16x16x32_bf16 v[112:115], v[222:225], v[174:177], v[112:115]
	v_mfma_f32_16x16x32_bf16 v[100:103], v[214:217], v[188:191], v[100:103]
	v_mfma_f32_16x16x32_bf16 v[96:99], v[222:225], v[188:191], v[96:99]
	v_mfma_f32_16x16x32_bf16 v[84:87], v[214:217], v[198:201], v[84:87]
	v_mfma_f32_16x16x32_bf16 v[80:83], v[222:225], v[198:201], v[80:83]
	v_mfma_f32_16x16x32_bf16 v[68:71], v[214:217], v[206:209], v[68:71]
	v_mfma_f32_16x16x32_bf16 v[64:67], v[222:225], v[206:209], v[64:67]
	v_mfma_f32_16x16x32_bf16 v[116:119], v[218:221], v[178:181], v[116:119]
	v_mfma_f32_16x16x32_bf16 v[112:115], v[226:229], v[178:181], v[112:115]
	v_mfma_f32_16x16x32_bf16 v[100:103], v[218:221], v[194:197], v[100:103]
	v_mfma_f32_16x16x32_bf16 v[96:99], v[226:229], v[194:197], v[96:99]
	v_mfma_f32_16x16x32_bf16 v[84:87], v[218:221], v[202:205], v[84:87]
	v_mfma_f32_16x16x32_bf16 v[80:83], v[226:229], v[202:205], v[80:83]
	v_mfma_f32_16x16x32_bf16 v[68:71], v[218:221], v[210:213], v[68:71]
	v_mfma_f32_16x16x32_bf16 v[64:67], v[226:229], v[210:213], v[64:67]
	s_setprio 0
	s_mov_b32 m0, s59
	s_barrier
	ds_read_b128 v[174:177], v165 offset:16384
	ds_read_b128 v[178:181], v165 offset:17408
	ds_read_b128 v[188:191], v165 offset:18432
	ds_read_b128 v[194:197], v165 offset:19456
	ds_read_b128 v[198:201], v165 offset:20480
	ds_read_b128 v[202:205], v165 offset:21504
	ds_read_b128 v[206:209], v165 offset:22528
	ds_read_b128 v[210:213], v165 offset:23552
	global_load_lds_dwordx4 v128, s[12:13]
	v_lshl_add_u64 v[232:233], s[12:13], 0, v[132:133]
	s_mov_b32 m0, s75
	s_nop 0
	global_load_lds_dwordx4 v132, s[12:13]
	s_barrier
	s_waitcnt lgkmcnt(0)
	s_setprio 1
	v_mfma_f32_16x16x32_bf16 v[60:63], v[146:149], v[174:177], v[60:63]
	v_mfma_f32_16x16x32_bf16 v[56:59], v[154:157], v[174:177], v[56:59]
	v_mfma_f32_16x16x32_bf16 v[44:47], v[146:149], v[188:191], v[44:47]
	v_mfma_f32_16x16x32_bf16 v[40:43], v[154:157], v[188:191], v[40:43]
	v_mfma_f32_16x16x32_bf16 v[28:31], v[146:149], v[198:201], v[28:31]
	v_mfma_f32_16x16x32_bf16 v[24:27], v[154:157], v[198:201], v[24:27]
	v_mfma_f32_16x16x32_bf16 v[12:15], v[146:149], v[206:209], v[12:15]
	v_mfma_f32_16x16x32_bf16 v[8:11], v[154:157], v[206:209], v[8:11]
	v_mfma_f32_16x16x32_bf16 v[60:63], v[150:153], v[178:181], v[60:63]
	v_mfma_f32_16x16x32_bf16 v[56:59], v[170:173], v[178:181], v[56:59]
	v_mfma_f32_16x16x32_bf16 v[44:47], v[150:153], v[194:197], v[44:47]
	v_mfma_f32_16x16x32_bf16 v[40:43], v[170:173], v[194:197], v[40:43]
	v_mfma_f32_16x16x32_bf16 v[28:31], v[150:153], v[202:205], v[28:31]
	v_mfma_f32_16x16x32_bf16 v[24:27], v[170:173], v[202:205], v[24:27]
	v_mfma_f32_16x16x32_bf16 v[12:15], v[150:153], v[210:213], v[12:15]
	v_mfma_f32_16x16x32_bf16 v[8:11], v[170:173], v[210:213], v[8:11]
	s_setprio 0
	s_barrier
	s_add_u32 s0, s10, 0x80000
	s_addc_u32 s1, s11, 0
	s_add_i32 s4, s87, s74
	s_mov_b32 m0, s4
	s_nop 0
	global_load_lds_dwordx4 v130, s[0:1]
	s_add_i32 m0, s4, 0x2000
	s_nop 0
	global_load_lds_dwordx4 v134, s[0:1]
	s_waitcnt vmcnt(6)
	s_barrier
	s_setprio 1
	v_mfma_f32_16x16x32_bf16 v[52:55], v[214:217], v[174:177], v[52:55]
	v_mfma_f32_16x16x32_bf16 v[48:51], v[222:225], v[174:177], v[48:51]
	v_mfma_f32_16x16x32_bf16 v[36:39], v[214:217], v[188:191], v[36:39]
	v_mfma_f32_16x16x32_bf16 v[32:35], v[222:225], v[188:191], v[32:35]
	v_mfma_f32_16x16x32_bf16 v[20:23], v[214:217], v[198:201], v[20:23]
	v_mfma_f32_16x16x32_bf16 v[16:19], v[222:225], v[198:201], v[16:19]
	v_mfma_f32_16x16x32_bf16 v[4:7], v[214:217], v[206:209], v[4:7]
	v_mfma_f32_16x16x32_bf16 v[0:3], v[222:225], v[206:209], v[0:3]
	v_mfma_f32_16x16x32_bf16 v[52:55], v[218:221], v[178:181], v[52:55]
	v_mfma_f32_16x16x32_bf16 v[48:51], v[226:229], v[178:181], v[48:51]
	v_mfma_f32_16x16x32_bf16 v[36:39], v[218:221], v[194:197], v[36:39]
	v_mfma_f32_16x16x32_bf16 v[32:35], v[226:229], v[194:197], v[32:35]
	v_mfma_f32_16x16x32_bf16 v[20:23], v[218:221], v[202:205], v[20:23]
	v_mfma_f32_16x16x32_bf16 v[16:19], v[226:229], v[202:205], v[16:19]
	v_mfma_f32_16x16x32_bf16 v[4:7], v[218:221], v[210:213], v[4:7]
	v_mfma_f32_16x16x32_bf16 v[0:3], v[226:229], v[210:213], v[0:3]
	s_setprio 0
	s_add_i32 s4, 0, 0x18000
	v_add_u32_e32 v137, s4, v163
	s_barrier
	ds_read_b128 v[146:149], v137
	ds_read_b128 v[150:153], v137 offset:1024
	ds_read_b128 v[154:157], v137 offset:2048
	ds_read_b128 v[170:173], v137 offset:3072
	s_add_u32 s0, s12, 0x80000
	s_addc_u32 s1, s13, 0
	s_mov_b32 m0, s76
	ds_read_b128 v[174:177], v165 offset:32768
	ds_read_b128 v[178:181], v165 offset:33792
	ds_read_b128 v[188:191], v165 offset:34816
	ds_read_b128 v[194:197], v165 offset:35840
	ds_read_b128 v[198:201], v165 offset:36864
	ds_read_b128 v[202:205], v165 offset:37888
	ds_read_b128 v[206:209], v165 offset:38912
	global_load_lds_dwordx4 v128, s[0:1]
	s_mov_b32 m0, s77
	ds_read_b128 v[210:213], v165 offset:39936
	global_load_lds_dwordx4 v132, s[0:1]
	s_waitcnt lgkmcnt(8)
	s_barrier
; #define PG8_STAGE(bufoff, gbase, voff) do { _Pragma("unroll") for (int _i = 0; _i < 2; ++_i) \
;         __builtin_amdgcn_global_load_lds((const unsigned*)((const char*)(gbase) + (voff)[_i]), (LAS unsigned*)(lds + (bufoff) + ldsw + _i * 8192), 16, 0, 0); } while (0)
; #define PG8_LDA(dst, b, h) do { _Pragma("unroll") for (int m = 0; m < 4; ++m) _Pragma("unroll") for (int k = 0; k < 2; ++k) dst[m][k] = *(const LAS bf16x8*)(lds + PG8_SA(b, h) + aoff + m * 2048 + k * 1024); } while (0)
; #define PG8_LDB(dst, b, h) do { _Pragma("unroll") for (int n = 0; n < 2; ++n) _Pragma("unroll") for (int k = 0; k < 2; ++k) dst[n][k] = *(const LAS bf16x8*)(lds + PG8_SB(b, h) + boff + n * 2048 + k * 1024); } while (0)
; #define PG8_MMA(ai, bj, At, Bt) do { __builtin_amdgcn_s_setprio(1); _Pragma("unroll") for (int m = 0; m < 4; ++m) _Pragma("unroll") for (int n = 0; n < 2; ++n) _Pragma("unroll") for (int k = 0; k < 2; ++k) \
;         acc[ai][bj][m][n] = __builtin_amdgcn_mfma_f32_16x16x32_bf16(Bt[n][k], At[m][k], acc[ai][bj][m][n], 0, 0, 0); __builtin_amdgcn_s_setprio(0); } while (0)
; #define PG8_WAIT_V(n) asm volatile("s_waitcnt vmcnt(" #n ")" ::: "memory")
; #define PG8_WAIT_L(n) asm volatile("s_waitcnt lgkmcnt(" #n ")" ::: "memory")
; #define PG8_BAR __builtin_amdgcn_s_barrier()
; #define PG8_SCHED __builtin_amdgcn_sched_barrier(0)
; template <class Epi, class Sched>
; DI void gemm_phase(LAS unsigned char* lds, const Gemm g, const Sched& S, const Epi& E) {
;     ...
;             PG8_WAIT_L(8); PG8_BAR; PG8_WAIT_L(0); PG8_MMA(0, 0, At, B0); PG8_BAR; PG8_SCHED;
;             PG8_LDB(B1, 1, 1); PG8_STAGE(PG8_SB(1, 0), b3, voffB);
;             PG8_BAR; PG8_WAIT_L(0); PG8_MMA(0, 1, At, B1); PG8_BAR;
;             PG8_LDA(At, 1, 1); PG8_STAGE(PG8_SA(1, 0), a3, voffA);
;             PG8_BAR; PG8_WAIT_L(0); PG8_MMA(1, 0, At, B0); PG8_BAR; PG8_SCHED;
;             PG8_STAGE(PG8_SB(1, 1), b3 + hstep, voffB);
;             PG8_WAIT_V(6); PG8_BAR; PG8_MMA(1, 1, At, B1); PG8_BAR;
	s_waitcnt lgkmcnt(0)
	s_setprio 1
	v_mfma_f32_16x16x32_bf16 v[124:127], v[146:149], v[174:177], v[124:127]
	v_mfma_f32_16x16x32_bf16 v[120:123], v[154:157], v[174:177], v[120:123]
	v_mfma_f32_16x16x32_bf16 v[108:111], v[146:149], v[188:191], v[108:111]
	v_mfma_f32_16x16x32_bf16 v[104:107], v[154:157], v[188:191], v[104:107]
	v_mfma_f32_16x16x32_bf16 v[92:95], v[146:149], v[198:201], v[92:95]
	v_mfma_f32_16x16x32_bf16 v[88:91], v[154:157], v[198:201], v[88:91]
	v_mfma_f32_16x16x32_bf16 v[76:79], v[146:149], v[206:209], v[76:79]
	v_mfma_f32_16x16x32_bf16 v[72:75], v[154:157], v[206:209], v[72:75]
	v_mfma_f32_16x16x32_bf16 v[124:127], v[150:153], v[178:181], v[124:127]
	v_mfma_f32_16x16x32_bf16 v[120:123], v[170:173], v[178:181], v[120:123]
	v_mfma_f32_16x16x32_bf16 v[108:111], v[150:153], v[194:197], v[108:111]
	v_mfma_f32_16x16x32_bf16 v[104:107], v[170:173], v[194:197], v[104:107]
	v_mfma_f32_16x16x32_bf16 v[92:95], v[150:153], v[202:205], v[92:95]
	v_mfma_f32_16x16x32_bf16 v[88:91], v[170:173], v[202:205], v[88:91]
	v_mfma_f32_16x16x32_bf16 v[76:79], v[150:153], v[210:213], v[76:79]
	v_mfma_f32_16x16x32_bf16 v[72:75], v[170:173], v[210:213], v[72:75]
	s_setprio 0
	s_barrier
	s_add_i32 s5, 0, 0x1c000
	s_add_i32 s0, s4, s74
	v_add_u32_e32 v137, s5, v163
	s_add_i32 m0, s0, 0xffffff80
	ds_read_b128 v[214:217], v137
	ds_read_b128 v[218:221], v137 offset:1024
	ds_read_b128 v[222:225], v137 offset:2048
	global_load_lds_dwordx4 v130, s[10:11] offset:128
	s_add_i32 m0, s0, 0x1f80
	ds_read_b128 v[226:229], v137 offset:3072
	global_load_lds_dwordx4 v134, s[10:11] offset:128
	s_barrier
	s_waitcnt lgkmcnt(0)
	s_setprio 1
	v_mfma_f32_16x16x32_bf16 v[116:119], v[214:217], v[174:177], v[116:119]
	v_mfma_f32_16x16x32_bf16 v[112:115], v[222:225], v[174:177], v[112:115]
	v_mfma_f32_16x16x32_bf16 v[100:103], v[214:217], v[188:191], v[100:103]
	v_mfma_f32_16x16x32_bf16 v[96:99], v[222:225], v[188:191], v[96:99]
	v_mfma_f32_16x16x32_bf16 v[84:87], v[214:217], v[198:201], v[84:87]
	v_mfma_f32_16x16x32_bf16 v[80:83], v[222:225], v[198:201], v[80:83]
	v_mfma_f32_16x16x32_bf16 v[68:71], v[214:217], v[206:209], v[68:71]
	v_mfma_f32_16x16x32_bf16 v[64:67], v[222:225], v[206:209], v[64:67]
	v_mfma_f32_16x16x32_bf16 v[116:119], v[218:221], v[178:181], v[116:119]
	v_mfma_f32_16x16x32_bf16 v[112:115], v[226:229], v[178:181], v[112:115]
	v_mfma_f32_16x16x32_bf16 v[100:103], v[218:221], v[194:197], v[100:103]
	v_mfma_f32_16x16x32_bf16 v[96:99], v[226:229], v[194:197], v[96:99]
	v_mfma_f32_16x16x32_bf16 v[84:87], v[218:221], v[202:205], v[84:87]
	v_mfma_f32_16x16x32_bf16 v[80:83], v[226:229], v[202:205], v[80:83]
	v_mfma_f32_16x16x32_bf16 v[68:71], v[218:221], v[210:213], v[68:71]
	v_mfma_f32_16x16x32_bf16 v[64:67], v[226:229], v[210:213], v[64:67]
	s_setprio 0
	s_add_i32 m0, s97, 0xffffff80
	s_barrier
	ds_read_b128 v[174:177], v165 offset:49152
	ds_read_b128 v[178:181], v165 offset:50176
	ds_read_b128 v[188:191], v165 offset:51200
	ds_read_b128 v[194:197], v165 offset:52224
	ds_read_b128 v[198:201], v165 offset:53248
	ds_read_b128 v[202:205], v165 offset:54272
	ds_read_b128 v[206:209], v165 offset:55296
	ds_read_b128 v[210:213], v165 offset:56320
	global_load_lds_dwordx4 v128, s[12:13] offset:128
	v_lshl_add_u64 v[158:159], v[232:233], 0, s[40:41]
	s_add_i32 m0, s84, 0xffffff80
	s_nop 0
	global_load_lds_dwordx4 v132, s[12:13] offset:128
	s_barrier
	s_waitcnt lgkmcnt(0)
	s_setprio 1
	v_mfma_f32_16x16x32_bf16 v[60:63], v[146:149], v[174:177], v[60:63]
	v_mfma_f32_16x16x32_bf16 v[56:59], v[154:157], v[174:177], v[56:59]
	v_mfma_f32_16x16x32_bf16 v[44:47], v[146:149], v[188:191], v[44:47]
	v_mfma_f32_16x16x32_bf16 v[40:43], v[154:157], v[188:191], v[40:43]
	v_mfma_f32_16x16x32_bf16 v[28:31], v[146:149], v[198:201], v[28:31]
	v_mfma_f32_16x16x32_bf16 v[24:27], v[154:157], v[198:201], v[24:27]
	v_mfma_f32_16x16x32_bf16 v[12:15], v[146:149], v[206:209], v[12:15]
	v_mfma_f32_16x16x32_bf16 v[8:11], v[154:157], v[206:209], v[8:11]
	v_mfma_f32_16x16x32_bf16 v[60:63], v[150:153], v[178:181], v[60:63]
	v_mfma_f32_16x16x32_bf16 v[56:59], v[170:173], v[178:181], v[56:59]
	v_mfma_f32_16x16x32_bf16 v[44:47], v[150:153], v[194:197], v[44:47]
	v_mfma_f32_16x16x32_bf16 v[40:43], v[170:173], v[194:197], v[40:43]
	v_mfma_f32_16x16x32_bf16 v[28:31], v[150:153], v[202:205], v[28:31]
	v_mfma_f32_16x16x32_bf16 v[24:27], v[170:173], v[202:205], v[24:27]
	v_mfma_f32_16x16x32_bf16 v[12:15], v[150:153], v[210:213], v[12:15]
	v_mfma_f32_16x16x32_bf16 v[8:11], v[170:173], v[210:213], v[8:11]
	s_setprio 0
	s_barrier
	s_add_u32 s0, s10, 0x80080
	s_addc_u32 s1, s11, 0
	s_add_i32 s4, s5, s74
	s_mov_b32 m0, s4
	s_nop 0
	global_load_lds_dwordx4 v130, s[0:1]
	v_lshl_add_u64 v[146:147], s[0:1], 0, v[134:135]
	s_add_i32 m0, s4, 0x2000
	s_nop 0
	global_load_lds_dwordx4 v134, s[0:1]
	s_waitcnt vmcnt(6)
	s_barrier
	s_setprio 1
	v_mfma_f32_16x16x32_bf16 v[52:55], v[214:217], v[174:177], v[52:55]
	v_mfma_f32_16x16x32_bf16 v[48:51], v[222:225], v[174:177], v[48:51]
	v_mfma_f32_16x16x32_bf16 v[36:39], v[214:217], v[188:191], v[36:39]
	v_mfma_f32_16x16x32_bf16 v[32:35], v[222:225], v[188:191], v[32:35]
	v_mfma_f32_16x16x32_bf16 v[20:23], v[214:217], v[198:201], v[20:23]
	v_mfma_f32_16x16x32_bf16 v[16:19], v[222:225], v[198:201], v[16:19]
	v_mfma_f32_16x16x32_bf16 v[4:7], v[214:217], v[206:209], v[4:7]
	v_mfma_f32_16x16x32_bf16 v[0:3], v[222:225], v[206:209], v[0:3]
	v_mfma_f32_16x16x32_bf16 v[52:55], v[218:221], v[178:181], v[52:55]
	v_mfma_f32_16x16x32_bf16 v[48:51], v[226:229], v[178:181], v[48:51]
	v_mfma_f32_16x16x32_bf16 v[36:39], v[218:221], v[194:197], v[36:39]
	v_mfma_f32_16x16x32_bf16 v[32:35], v[226:229], v[194:197], v[32:35]
	v_mfma_f32_16x16x32_bf16 v[20:23], v[218:221], v[202:205], v[20:23]
	v_mfma_f32_16x16x32_bf16 v[16:19], v[226:229], v[202:205], v[16:19]
	v_mfma_f32_16x16x32_bf16 v[4:7], v[218:221], v[210:213], v[4:7]
	v_mfma_f32_16x16x32_bf16 v[0:3], v[226:229], v[210:213], v[0:3]
	s_setprio 0
	s_add_i32 s35, s35, 2
	s_add_u32 s8, s8, 0x100
	s_addc_u32 s9, s9, 0
	s_add_u32 s28, s28, 0x100
	s_addc_u32 s34, s34, 0
	s_cmp_gt_u32 s35, 29
	s_barrier
	s_cbranch_scc0 .LBB0_527

;     DI size_t aoff(const Unit& u, size_t tstep) const { return (size_t)u.pm * tstep; }
;     DI size_t boff(const Unit& u, size_t tstep) const { return (size_t)u.pn * tstep; }
;     DI bool next(int i, Unit& u) const { const long L = (long)i * G + c; if (L >= np) return false; u.pm = pmv; u.pn = (int)(L % nN); u.ks = (int)(L / nN); return true; }
;     DI size_t aoff(const Unit& u, size_t) const { return (size_t)u.ks * kbytes; }
;     DI size_t boff(const Unit& u, size_t tstep) const { return (size_t)u.pn * tstep + (size_t)u.ks * kbytes; }
;     DI bool next(int i, Unit& u) const { Unit t; if (!S.next(i / 3, t)) return false; u.pm = t.pm; u.pn = t.pn; u.ks = i % 3; return true; }
;     DI size_t aoff(const Unit& u, size_t tstep) const { return (u.ks < 2 ? offU : offOA) + (size_t)u.pm * tstep; }
; #define PG8_WAIT_V(n) asm volatile("s_waitcnt vmcnt(" #n ")" ::: "memory")
; template <class Epi, class Sched>
; DI void gemm_phase(LAS unsigned char* lds, const Gemm g, const Sched& S, const Epi& E) {
;     ...
;         const bool has_next = S.next(ui + 1, nxt);
;         const char* nA = has_next ? (const char*)g.A + S.aoff(nxt, tstep) : cA; const char* nB = has_next ? (const char*)g.Bt + S.boff(nxt, tstep) : cB;
;         for (int t = 0; t < nt; t += 2) {
;             if constexpr (Epi::HAS_MID) { if (t == E.mid_t(nt)) { int fr3 = fr, fq3 = fq; asm volatile("" : "+v"(fr3), "+v"(fq3)); E.mid(acc, cur, wr, wc, fr3, fq3); } }
;             const bool last = (t == nt - 2);
;             const char* a1 = cA + (size_t)(t + 1) * kstep;
;             const char* a2 = last ? nA : cA + (size_t)(t + 2) * kstep; const char* b2 = last ? nB : cB + (size_t)(t + 2) * kstep;
;             const char* a3 = a2 + kstep; const char* b3 = b2 + kstep;
;             PG8_LDB(B0, 0, 0); PG8_SCHED; PG8_LDA(At, 0, 0); PG8_STAGE(PG8_SA(1, 1), a1 + hstep, voffA);
;             PG8_WAIT_L(8); PG8_BAR; PG8_WAIT_L(0); PG8_MMA(0, 0, At, B0); PG8_BAR; PG8_SCHED;
;             PG8_LDB(B1, 0, 1); PG8_STAGE(PG8_SB(0, 0), b2, voffB);
;             PG8_BAR; PG8_WAIT_L(0); PG8_MMA(0, 1, At, B1); PG8_BAR;
;             PG8_LDA(At, 0, 1); PG8_STAGE(PG8_SA(0, 0), a2, voffA);
;             PG8_BAR; PG8_WAIT_L(0); PG8_MMA(1, 0, At, B0); PG8_BAR; PG8_SCHED;
;             PG8_STAGE(PG8_SB(0, 1), b2 + hstep, voffB);
;             PG8_WAIT_V(6); PG8_BAR; PG8_MMA(1, 1, At, B1); PG8_BAR;
.LBB0_937:
	s_add_u32 s8, s38, 0x30080
	s_addc_u32 s9, s39, 0
	s_add_u32 s35, s36, 0x100
	v_mov_b32_e32 v0, 0
	s_addc_u32 s40, s37, 0
	s_mov_b32 s41, -2
	ds_read_b128 v[144:147], v165
	ds_read_b128 v[168:171], v165 offset:1024
	ds_read_b128 v[172:175], v165 offset:2048
	ds_read_b128 v[176:179], v165 offset:3072
	s_add_u32 s0, s8, 0xfffd0080
	s_addc_u32 s1, s9, -1
	s_cmp_eq_u32 s41, 8
	s_cselect_b32 s39, s31, s1
	s_cselect_b32 s38, s30, s0
	s_cselect_b32 s37, s11, s40
	s_cselect_b32 s36, s10, s35
	s_add_i32 m0, s51, 0xc000
	ds_read_b128 v[180:183], v166
	ds_read_b128 v[188:191], v166 offset:1024
	ds_read_b128 v[194:197], v166 offset:2048
	ds_read_b128 v[198:201], v166 offset:3072
	ds_read_b128 v[202:205], v166 offset:4096
	ds_read_b128 v[206:209], v166 offset:5120
	ds_read_b128 v[210:213], v166 offset:6144
	global_load_lds_dwordx4 v136, s[8:9]
	s_add_i32 m0, s51, 0xe000
	ds_read_b128 v[214:217], v166 offset:7168
	global_load_lds_dwordx4 v138, s[8:9]
	s_waitcnt lgkmcnt(8)
	s_barrier
	s_waitcnt lgkmcnt(0)
	s_setprio 1
	v_mfma_f32_16x16x32_bf16 v[124:127], v[144:147], v[180:183], 0
	v_mfma_f32_16x16x32_bf16 v[120:123], v[172:175], v[180:183], 0
	v_mfma_f32_16x16x32_bf16 v[108:111], v[144:147], v[194:197], 0
	v_mfma_f32_16x16x32_bf16 v[104:107], v[172:175], v[194:197], 0
	v_mfma_f32_16x16x32_bf16 v[92:95], v[144:147], v[202:205], 0
	v_mfma_f32_16x16x32_bf16 v[88:91], v[172:175], v[202:205], 0
	v_mfma_f32_16x16x32_bf16 v[76:79], v[144:147], v[210:213], 0
	v_mfma_f32_16x16x32_bf16 v[72:75], v[172:175], v[210:213], 0
	v_mfma_f32_16x16x32_bf16 v[124:127], v[168:171], v[188:191], v[124:127]
	v_mfma_f32_16x16x32_bf16 v[120:123], v[176:179], v[188:191], v[120:123]
	v_mfma_f32_16x16x32_bf16 v[108:111], v[168:171], v[198:201], v[108:111]
	v_mfma_f32_16x16x32_bf16 v[104:107], v[176:179], v[198:201], v[104:107]
	v_mfma_f32_16x16x32_bf16 v[92:95], v[168:171], v[206:209], v[92:95]
	v_mfma_f32_16x16x32_bf16 v[88:91], v[176:179], v[206:209], v[88:91]
	v_mfma_f32_16x16x32_bf16 v[76:79], v[168:171], v[214:217], v[76:79]
	v_mfma_f32_16x16x32_bf16 v[72:75], v[176:179], v[214:217], v[72:75]
	s_setprio 0
	s_barrier
	s_add_i32 s0, s61, s50
	s_mov_b32 m0, s0
	ds_read_b128 v[218:221], v167
	ds_read_b128 v[222:225], v167 offset:1024
	ds_read_b128 v[226:229], v167 offset:2048
	global_load_lds_dwordx4 v130, s[36:37]
	s_add_i32 m0, s0, 0x2000
	ds_read_b128 v[230:233], v167 offset:3072
	global_load_lds_dwordx4 v134, s[36:37]
	s_barrier
	s_waitcnt lgkmcnt(0)
	s_setprio 1
	v_mfma_f32_16x16x32_bf16 v[116:119], v[218:221], v[180:183], 0
	v_mfma_f32_16x16x32_bf16 v[112:115], v[226:229], v[180:183], 0
	v_mfma_f32_16x16x32_bf16 v[100:103], v[218:221], v[194:197], 0
	v_mfma_f32_16x16x32_bf16 v[96:99], v[226:229], v[194:197], 0
	v_mfma_f32_16x16x32_bf16 v[84:87], v[218:221], v[202:205], 0
	v_mfma_f32_16x16x32_bf16 v[80:83], v[226:229], v[202:205], 0
	v_mfma_f32_16x16x32_bf16 v[68:71], v[218:221], v[210:213], 0
	v_mfma_f32_16x16x32_bf16 v[64:67], v[226:229], v[210:213], 0
	v_mfma_f32_16x16x32_bf16 v[116:119], v[222:225], v[188:191], v[116:119]
	v_mfma_f32_16x16x32_bf16 v[112:115], v[230:233], v[188:191], v[112:115]
	v_mfma_f32_16x16x32_bf16 v[100:103], v[222:225], v[198:201], v[100:103]
	v_mfma_f32_16x16x32_bf16 v[96:99], v[230:233], v[198:201], v[96:99]
	v_mfma_f32_16x16x32_bf16 v[84:87], v[222:225], v[206:209], v[84:87]
	v_mfma_f32_16x16x32_bf16 v[80:83], v[230:233], v[206:209], v[80:83]
	v_mfma_f32_16x16x32_bf16 v[68:71], v[222:225], v[214:217], v[68:71]
	v_mfma_f32_16x16x32_bf16 v[64:67], v[230:233], v[214:217], v[64:67]
	s_setprio 0
	s_mov_b32 m0, s51
	s_barrier
	ds_read_b128 v[180:183], v166 offset:16384
	ds_read_b128 v[188:191], v166 offset:17408
	ds_read_b128 v[194:197], v166 offset:18432
	ds_read_b128 v[198:201], v166 offset:19456
	ds_read_b128 v[202:205], v166 offset:20480
	ds_read_b128 v[206:209], v166 offset:21504
	ds_read_b128 v[210:213], v166 offset:22528
	global_load_lds_dwordx4 v128, s[38:39]
	s_mov_b32 m0, s52
	ds_read_b128 v[214:217], v166 offset:23552
	global_load_lds_dwordx4 v132, s[38:39]
	s_barrier
	s_waitcnt lgkmcnt(0)
	s_setprio 1
	v_mfma_f32_16x16x32_bf16 v[60:63], v[144:147], v[180:183], 0
	v_mfma_f32_16x16x32_bf16 v[56:59], v[172:175], v[180:183], 0
	v_mfma_f32_16x16x32_bf16 v[44:47], v[144:147], v[194:197], 0
	v_mfma_f32_16x16x32_bf16 v[40:43], v[172:175], v[194:197], 0
	v_mfma_f32_16x16x32_bf16 v[28:31], v[144:147], v[202:205], 0
	v_mfma_f32_16x16x32_bf16 v[24:27], v[172:175], v[202:205], 0
	v_mfma_f32_16x16x32_bf16 v[12:15], v[144:147], v[210:213], 0
	v_mfma_f32_16x16x32_bf16 v[8:11], v[172:175], v[210:213], 0
	v_mfma_f32_16x16x32_bf16 v[60:63], v[168:171], v[188:191], v[60:63]
	v_mfma_f32_16x16x32_bf16 v[56:59], v[176:179], v[188:191], v[56:59]
	v_mfma_f32_16x16x32_bf16 v[44:47], v[168:171], v[198:201], v[44:47]
	v_mfma_f32_16x16x32_bf16 v[40:43], v[176:179], v[198:201], v[40:43]
	v_mfma_f32_16x16x32_bf16 v[28:31], v[168:171], v[206:209], v[28:31]
	v_mfma_f32_16x16x32_bf16 v[24:27], v[176:179], v[206:209], v[24:27]
	v_mfma_f32_16x16x32_bf16 v[12:15], v[168:171], v[214:217], v[12:15]
	v_mfma_f32_16x16x32_bf16 v[8:11], v[176:179], v[214:217], v[8:11]
	s_setprio 0
	s_barrier
	s_add_u32 s0, s36, 0x30000
	s_addc_u32 s1, s37, 0
	s_add_i32 s4, s62, s50
	s_mov_b32 m0, s4
	s_nop 0
	global_load_lds_dwordx4 v130, s[0:1]
	s_add_i32 m0, s4, 0x2000
	s_nop 0
	global_load_lds_dwordx4 v134, s[0:1]
	s_waitcnt vmcnt(6)
	s_barrier
; #define PG8_STAGE(bufoff, gbase, voff) do { _Pragma("unroll") for (int _i = 0; _i < 2; ++_i) \
;         __builtin_amdgcn_global_load_lds((const unsigned*)((const char*)(gbase) + (voff)[_i]), (LAS unsigned*)(lds + (bufoff) + ldsw + _i * 8192), 16, 0, 0); } while (0)
; #define PG8_LDA(dst, b, h) do { _Pragma("unroll") for (int m = 0; m < 4; ++m) _Pragma("unroll") for (int k = 0; k < 2; ++k) dst[m][k] = *(const LAS bf16x8*)(lds + PG8_SA(b, h) + aoff + m * 2048 + k * 1024); } while (0)
; #define PG8_LDB(dst, b, h) do { _Pragma("unroll") for (int n = 0; n < 2; ++n) _Pragma("unroll") for (int k = 0; k < 2; ++k) dst[n][k] = *(const LAS bf16x8*)(lds + PG8_SB(b, h) + boff + n * 2048 + k * 1024); } while (0)
; #define PG8_MMA(ai, bj, At, Bt) do { __builtin_amdgcn_s_setprio(1); _Pragma("unroll") for (int m = 0; m < 4; ++m) _Pragma("unroll") for (int n = 0; n < 2; ++n) _Pragma("unroll") for (int k = 0; k < 2; ++k) \
;         acc[ai][bj][m][n] = __builtin_amdgcn_mfma_f32_16x16x32_bf16(Bt[n][k], At[m][k], acc[ai][bj][m][n], 0, 0, 0); __builtin_amdgcn_s_setprio(0); } while (0)
; #define PG8_WAIT_V(n) asm volatile("s_waitcnt vmcnt(" #n ")" ::: "memory")
; #define PG8_WAIT_L(n) asm volatile("s_waitcnt lgkmcnt(" #n ")" ::: "memory")
; #define PG8_BAR __builtin_amdgcn_s_barrier()
; #define PG8_SCHED __builtin_amdgcn_sched_barrier(0)
; template <class Epi, class Sched>
; DI void gemm_phase(LAS unsigned char* lds, const Gemm g, const Sched& S, const Epi& E) {
;     ...
;             PG8_WAIT_V(6); PG8_BAR; PG8_MMA(1, 1, At, B1); PG8_BAR;
;             PG8_LDB(B0, 1, 0); PG8_SCHED; PG8_LDA(At, 1, 0); PG8_STAGE(PG8_SA(0, 1), a2 + hstep, voffA);
;             PG8_WAIT_L(8); PG8_BAR; PG8_WAIT_L(0); PG8_MMA(0, 0, At, B0); PG8_BAR; PG8_SCHED;
;             PG8_LDB(B1, 1, 1); PG8_STAGE(PG8_SB(1, 0), b3, voffB);
;             PG8_BAR; PG8_WAIT_L(0); PG8_MMA(0, 1, At, B1); PG8_BAR;
;             PG8_LDA(At, 1, 1); PG8_STAGE(PG8_SA(1, 0), a3, voffA);
;             PG8_BAR; PG8_WAIT_L(0); PG8_MMA(1, 0, At, B0); PG8_BAR; PG8_SCHED;
;             PG8_STAGE(PG8_SB(1, 1), b3 + hstep, voffB);
;             PG8_WAIT_V(6); PG8_BAR; PG8_MMA(1, 1, At, B1); PG8_BAR;
	s_setprio 1
	v_mfma_f32_16x16x32_bf16 v[52:55], v[218:221], v[180:183], 0
	v_mfma_f32_16x16x32_bf16 v[48:51], v[226:229], v[180:183], 0
	v_mfma_f32_16x16x32_bf16 v[36:39], v[218:221], v[194:197], 0
	v_mfma_f32_16x16x32_bf16 v[32:35], v[226:229], v[194:197], 0
	v_mfma_f32_16x16x32_bf16 v[20:23], v[218:221], v[202:205], 0
	v_mfma_f32_16x16x32_bf16 v[16:19], v[226:229], v[202:205], 0
	v_mfma_f32_16x16x32_bf16 v[4:7], v[218:221], v[210:213], 0
	v_mfma_f32_16x16x32_bf16 v[0:3], v[226:229], v[210:213], 0
	v_mfma_f32_16x16x32_bf16 v[52:55], v[222:225], v[188:191], v[52:55]
	v_mfma_f32_16x16x32_bf16 v[48:51], v[230:233], v[188:191], v[48:51]
	v_mfma_f32_16x16x32_bf16 v[36:39], v[222:225], v[198:201], v[36:39]
	v_mfma_f32_16x16x32_bf16 v[32:35], v[230:233], v[198:201], v[32:35]
	v_mfma_f32_16x16x32_bf16 v[20:23], v[222:225], v[206:209], v[20:23]
	v_mfma_f32_16x16x32_bf16 v[16:19], v[230:233], v[206:209], v[16:19]
	v_mfma_f32_16x16x32_bf16 v[4:7], v[222:225], v[214:217], v[4:7]
	v_mfma_f32_16x16x32_bf16 v[0:3], v[230:233], v[214:217], v[0:3]
	s_setprio 0
	s_add_i32 s4, 0, 0x18000
	v_add_u32_e32 v150, s4, v164
	s_barrier
	ds_read_b128 v[144:147], v150
	ds_read_b128 v[168:171], v150 offset:1024
	ds_read_b128 v[172:175], v150 offset:2048
	ds_read_b128 v[176:179], v150 offset:3072
	s_add_u32 s0, s38, 0x30000
	s_addc_u32 s1, s39, 0
	s_mov_b32 m0, s53
	ds_read_b128 v[180:183], v166 offset:32768
	ds_read_b128 v[188:191], v166 offset:33792
	ds_read_b128 v[194:197], v166 offset:34816
	ds_read_b128 v[198:201], v166 offset:35840
	ds_read_b128 v[202:205], v166 offset:36864
	ds_read_b128 v[206:209], v166 offset:37888
	ds_read_b128 v[210:213], v166 offset:38912
	global_load_lds_dwordx4 v128, s[0:1]
	s_mov_b32 m0, s54
	ds_read_b128 v[214:217], v166 offset:39936
	global_load_lds_dwordx4 v132, s[0:1]
	s_waitcnt lgkmcnt(8)
	s_barrier
	s_waitcnt lgkmcnt(0)
	s_setprio 1
	v_mfma_f32_16x16x32_bf16 v[124:127], v[144:147], v[180:183], v[124:127]
	v_mfma_f32_16x16x32_bf16 v[120:123], v[172:175], v[180:183], v[120:123]
	v_mfma_f32_16x16x32_bf16 v[108:111], v[144:147], v[194:197], v[108:111]
	v_mfma_f32_16x16x32_bf16 v[104:107], v[172:175], v[194:197], v[104:107]
	v_mfma_f32_16x16x32_bf16 v[92:95], v[144:147], v[202:205], v[92:95]
	v_mfma_f32_16x16x32_bf16 v[88:91], v[172:175], v[202:205], v[88:91]
	v_mfma_f32_16x16x32_bf16 v[76:79], v[144:147], v[210:213], v[76:79]
	v_mfma_f32_16x16x32_bf16 v[72:75], v[172:175], v[210:213], v[72:75]
	v_mfma_f32_16x16x32_bf16 v[124:127], v[168:171], v[188:191], v[124:127]
	v_mfma_f32_16x16x32_bf16 v[120:123], v[176:179], v[188:191], v[120:123]
	v_mfma_f32_16x16x32_bf16 v[108:111], v[168:171], v[198:201], v[108:111]
	v_mfma_f32_16x16x32_bf16 v[104:107], v[176:179], v[198:201], v[104:107]
	v_mfma_f32_16x16x32_bf16 v[92:95], v[168:171], v[206:209], v[92:95]
	v_mfma_f32_16x16x32_bf16 v[88:91], v[176:179], v[206:209], v[88:91]
	v_mfma_f32_16x16x32_bf16 v[76:79], v[168:171], v[214:217], v[76:79]
	v_mfma_f32_16x16x32_bf16 v[72:75], v[176:179], v[214:217], v[72:75]
	s_setprio 0
	s_barrier
	s_add_i32 s5, 0, 0x1c000
	s_add_i32 s0, s4, s50
	v_add_u32_e32 v150, s5, v164
	s_add_i32 m0, s0, 0xffffff80
	ds_read_b128 v[218:221], v150
	ds_read_b128 v[222:225], v150 offset:1024
	ds_read_b128 v[226:229], v150 offset:2048
	global_load_lds_dwordx4 v130, s[36:37] offset:128
	s_add_i32 m0, s0, 0x1f80
	ds_read_b128 v[230:233], v150 offset:3072
	global_load_lds_dwordx4 v134, s[36:37] offset:128
	s_barrier
	s_waitcnt lgkmcnt(0)
	s_setprio 1
	v_mfma_f32_16x16x32_bf16 v[116:119], v[218:221], v[180:183], v[116:119]
	v_mfma_f32_16x16x32_bf16 v[112:115], v[226:229], v[180:183], v[112:115]
	v_mfma_f32_16x16x32_bf16 v[100:103], v[218:221], v[194:197], v[100:103]
	v_mfma_f32_16x16x32_bf16 v[96:99], v[226:229], v[194:197], v[96:99]
	v_mfma_f32_16x16x32_bf16 v[84:87], v[218:221], v[202:205], v[84:87]
	v_mfma_f32_16x16x32_bf16 v[80:83], v[226:229], v[202:205], v[80:83]
	v_mfma_f32_16x16x32_bf16 v[68:71], v[218:221], v[210:213], v[68:71]
	v_mfma_f32_16x16x32_bf16 v[64:67], v[226:229], v[210:213], v[64:67]
	v_mfma_f32_16x16x32_bf16 v[116:119], v[222:225], v[188:191], v[116:119]
	v_mfma_f32_16x16x32_bf16 v[112:115], v[230:233], v[188:191], v[112:115]
	v_mfma_f32_16x16x32_bf16 v[100:103], v[222:225], v[198:201], v[100:103]
	v_mfma_f32_16x16x32_bf16 v[96:99], v[230:233], v[198:201], v[96:99]
	v_mfma_f32_16x16x32_bf16 v[84:87], v[222:225], v[206:209], v[84:87]
	v_mfma_f32_16x16x32_bf16 v[80:83], v[230:233], v[206:209], v[80:83]
	v_mfma_f32_16x16x32_bf16 v[68:71], v[222:225], v[214:217], v[68:71]
	v_mfma_f32_16x16x32_bf16 v[64:67], v[230:233], v[214:217], v[64:67]
	s_setprio 0
	s_add_i32 m0, s57, 0xffffff80
	s_barrier
	ds_read_b128 v[180:183], v166 offset:49152
	ds_read_b128 v[188:191], v166 offset:50176
	ds_read_b128 v[194:197], v166 offset:51200
	ds_read_b128 v[198:201], v166 offset:52224
	ds_read_b128 v[202:205], v166 offset:53248
	ds_read_b128 v[206:209], v166 offset:54272
	ds_read_b128 v[210:213], v166 offset:55296
	global_load_lds_dwordx4 v128, s[38:39] offset:128
	s_add_i32 m0, s58, 0xffffff80
	ds_read_b128 v[214:217], v166 offset:56320
	global_load_lds_dwordx4 v132, s[38:39] offset:128
	s_barrier
; #define PG8_STAGE(bufoff, gbase, voff) do { _Pragma("unroll") for (int _i = 0; _i < 2; ++_i) \
;         __builtin_amdgcn_global_load_lds((const unsigned*)((const char*)(gbase) + (voff)[_i]), (LAS unsigned*)(lds + (bufoff) + ldsw + _i * 8192), 16, 0, 0); } while (0)
; #define PG8_LDA(dst, b, h) do { _Pragma("unroll") for (int m = 0; m < 4; ++m) _Pragma("unroll") for (int k = 0; k < 2; ++k) dst[m][k] = *(const LAS bf16x8*)(lds + PG8_SA(b, h) + aoff + m * 2048 + k * 1024); } while (0)
; #define PG8_LDB(dst, b, h) do { _Pragma("unroll") for (int n = 0; n < 2; ++n) _Pragma("unroll") for (int k = 0; k < 2; ++k) dst[n][k] = *(const LAS bf16x8*)(lds + PG8_SB(b, h) + boff + n * 2048 + k * 1024); } while (0)
; #define PG8_WAIT_V(n) asm volatile("s_waitcnt vmcnt(" #n ")" ::: "memory")
; #define PG8_WAIT_L(n) asm volatile("s_waitcnt lgkmcnt(" #n ")" ::: "memory")
; #define PG8_BAR __builtin_amdgcn_s_barrier()
; #define PG8_SCHED __builtin_amdgcn_sched_barrier(0)
; template <class Epi, class Sched>
; DI void gemm_phase(LAS unsigned char* lds, const Gemm g, const Sched& S, const Epi& E) {
;     ...
;             PG8_LDB(B0, 0, 0); PG8_SCHED; PG8_LDA(At, 0, 0); PG8_STAGE(PG8_SA(1, 1), a1 + hstep, voffA);
;             PG8_WAIT_L(8); PG8_BAR; PG8_WAIT_L(0); PG8_MMA(0, 0, At, B0); PG8_BAR; PG8_SCHED;
;             PG8_LDB(B1, 0, 1); PG8_STAGE(PG8_SB(0, 0), b2, voffB);
;             PG8_BAR; PG8_WAIT_L(0); PG8_MMA(0, 1, At, B1); PG8_BAR;
;             PG8_LDA(At, 0, 1); PG8_STAGE(PG8_SA(0, 0), a2, voffA);
;             PG8_BAR; PG8_WAIT_L(0); PG8_MMA(1, 0, At, B0); PG8_BAR; PG8_SCHED;
;             PG8_STAGE(PG8_SB(0, 1), b2 + hstep, voffB);
;             PG8_WAIT_V(6); PG8_BAR; PG8_MMA(1, 1, At, B1); PG8_BAR;
;             PG8_LDB(B0, 1, 0); PG8_SCHED; PG8_LDA(At, 1, 0); PG8_STAGE(PG8_SA(0, 1), a2 + hstep, voffA);
;             PG8_WAIT_L(8); PG8_BAR; PG8_WAIT_L(0); PG8_MMA(0, 0, At, B0); PG8_BAR; PG8_SCHED;
;             PG8_LDB(B1, 1, 1); PG8_STAGE(PG8_SB(1, 0), b3, voffB);
;             PG8_BAR; PG8_WAIT_L(0); PG8_MMA(0, 1, At, B1); PG8_BAR;
;             PG8_LDA(At, 1, 1); PG8_STAGE(PG8_SA(1, 0), a3, voffA);
;             PG8_BAR; PG8_WAIT_L(0); PG8_MMA(1, 0, At, B0); PG8_BAR; PG8_SCHED;
;             PG8_STAGE(PG8_SB(1, 1), b3 + hstep, voffB);
;             PG8_WAIT_V(6); PG8_BAR; PG8_MMA(1, 1, At, B1); PG8_BAR;
	s_waitcnt lgkmcnt(0)
	s_setprio 1
	v_mfma_f32_16x16x32_bf16 v[60:63], v[144:147], v[180:183], v[60:63]
	v_mfma_f32_16x16x32_bf16 v[56:59], v[172:175], v[180:183], v[56:59]
	v_mfma_f32_16x16x32_bf16 v[44:47], v[144:147], v[194:197], v[44:47]
	v_mfma_f32_16x16x32_bf16 v[40:43], v[172:175], v[194:197], v[40:43]
	v_mfma_f32_16x16x32_bf16 v[28:31], v[144:147], v[202:205], v[28:31]
	v_mfma_f32_16x16x32_bf16 v[24:27], v[172:175], v[202:205], v[24:27]
	v_mfma_f32_16x16x32_bf16 v[12:15], v[144:147], v[210:213], v[12:15]
	v_mfma_f32_16x16x32_bf16 v[8:11], v[172:175], v[210:213], v[8:11]
	v_mfma_f32_16x16x32_bf16 v[60:63], v[168:171], v[188:191], v[60:63]
	v_mfma_f32_16x16x32_bf16 v[56:59], v[176:179], v[188:191], v[56:59]
	v_mfma_f32_16x16x32_bf16 v[44:47], v[168:171], v[198:201], v[44:47]
	v_mfma_f32_16x16x32_bf16 v[40:43], v[176:179], v[198:201], v[40:43]
	v_mfma_f32_16x16x32_bf16 v[28:31], v[168:171], v[206:209], v[28:31]
	v_mfma_f32_16x16x32_bf16 v[24:27], v[176:179], v[206:209], v[24:27]
	v_mfma_f32_16x16x32_bf16 v[12:15], v[168:171], v[214:217], v[12:15]
	v_mfma_f32_16x16x32_bf16 v[8:11], v[176:179], v[214:217], v[8:11]
	s_setprio 0
	s_barrier
	s_add_u32 s0, s36, 0x30080
	s_addc_u32 s1, s37, 0
	s_add_i32 s4, s5, s50
	s_mov_b32 m0, s4
	s_nop 0
	global_load_lds_dwordx4 v130, s[0:1]
	s_add_i32 m0, s4, 0x2000
	s_nop 0
	global_load_lds_dwordx4 v134, s[0:1]
	s_waitcnt vmcnt(6)
	s_barrier
	s_setprio 1
	v_mfma_f32_16x16x32_bf16 v[52:55], v[218:221], v[180:183], v[52:55]
	v_mfma_f32_16x16x32_bf16 v[48:51], v[226:229], v[180:183], v[48:51]
	v_mfma_f32_16x16x32_bf16 v[36:39], v[218:221], v[194:197], v[36:39]
	v_mfma_f32_16x16x32_bf16 v[32:35], v[226:229], v[194:197], v[32:35]
	v_mfma_f32_16x16x32_bf16 v[20:23], v[218:221], v[202:205], v[20:23]
	v_mfma_f32_16x16x32_bf16 v[16:19], v[226:229], v[202:205], v[16:19]
	v_mfma_f32_16x16x32_bf16 v[4:7], v[218:221], v[210:213], v[4:7]
	v_mfma_f32_16x16x32_bf16 v[0:3], v[226:229], v[210:213], v[0:3]
	v_mfma_f32_16x16x32_bf16 v[52:55], v[222:225], v[188:191], v[52:55]
	v_mfma_f32_16x16x32_bf16 v[48:51], v[230:233], v[188:191], v[48:51]
	v_mfma_f32_16x16x32_bf16 v[36:39], v[222:225], v[198:201], v[36:39]
	v_mfma_f32_16x16x32_bf16 v[32:35], v[230:233], v[198:201], v[32:35]
	v_mfma_f32_16x16x32_bf16 v[20:23], v[222:225], v[206:209], v[20:23]
	v_mfma_f32_16x16x32_bf16 v[16:19], v[230:233], v[206:209], v[16:19]
	v_mfma_f32_16x16x32_bf16 v[4:7], v[222:225], v[214:217], v[4:7]
	v_mfma_f32_16x16x32_bf16 v[0:3], v[230:233], v[214:217], v[0:3]
	s_setprio 0
	s_add_i32 s41, s41, 2
	s_add_u32 s8, s8, 0x100
	s_addc_u32 s9, s9, 0
	s_add_u32 s35, s35, 0x100
	s_addc_u32 s40, s40, 0
	s_cmp_gt_u32 s41, 9
	s_barrier
	s_cbranch_scc0 .LBB0_938
	s_branch .Lpeel_done_938
.LBB0_938:
	ds_read_b128 v[144:147], v165
	ds_read_b128 v[168:171], v165 offset:1024
	ds_read_b128 v[172:175], v165 offset:2048
	ds_read_b128 v[176:179], v165 offset:3072
	s_add_u32 s0, s8, 0xfffd0080
	s_addc_u32 s1, s9, -1
	s_cmp_eq_u32 s41, 8
	s_cselect_b32 s39, s31, s1
	s_cselect_b32 s38, s30, s0
	s_cselect_b32 s37, s11, s40
	s_cselect_b32 s36, s10, s35
	s_add_i32 m0, s51, 0xc000
	ds_read_b128 v[180:183], v166
	ds_read_b128 v[188:191], v166 offset:1024
	ds_read_b128 v[194:197], v166 offset:2048
	ds_read_b128 v[198:201], v166 offset:3072
	ds_read_b128 v[202:205], v166 offset:4096
	ds_read_b128 v[206:209], v166 offset:5120
	ds_read_b128 v[210:213], v166 offset:6144
	global_load_lds_dwordx4 v136, s[8:9]
	s_add_i32 m0, s51, 0xe000
	ds_read_b128 v[214:217], v166 offset:7168
	global_load_lds_dwordx4 v138, s[8:9]
	s_waitcnt lgkmcnt(8)
	s_barrier
	s_waitcnt lgkmcnt(0)
	s_setprio 1
	v_mfma_f32_16x16x32_bf16 v[124:127], v[144:147], v[180:183], v[124:127]
	v_mfma_f32_16x16x32_bf16 v[120:123], v[172:175], v[180:183], v[120:123]
	v_mfma_f32_16x16x32_bf16 v[108:111], v[144:147], v[194:197], v[108:111]
	v_mfma_f32_16x16x32_bf16 v[104:107], v[172:175], v[194:197], v[104:107]
	v_mfma_f32_16x16x32_bf16 v[92:95], v[144:147], v[202:205], v[92:95]
	v_mfma_f32_16x16x32_bf16 v[88:91], v[172:175], v[202:205], v[88:91]
	v_mfma_f32_16x16x32_bf16 v[76:79], v[144:147], v[210:213], v[76:79]
	v_mfma_f32_16x16x32_bf16 v[72:75], v[172:175], v[210:213], v[72:75]
	v_mfma_f32_16x16x32_bf16 v[124:127], v[168:171], v[188:191], v[124:127]
	v_mfma_f32_16x16x32_bf16 v[120:123], v[176:179], v[188:191], v[120:123]
	v_mfma_f32_16x16x32_bf16 v[108:111], v[168:171], v[198:201], v[108:111]
	v_mfma_f32_16x16x32_bf16 v[104:107], v[176:179], v[198:201], v[104:107]
	v_mfma_f32_16x16x32_bf16 v[92:95], v[168:171], v[206:209], v[92:95]
	v_mfma_f32_16x16x32_bf16 v[88:91], v[176:179], v[206:209], v[88:91]
	v_mfma_f32_16x16x32_bf16 v[76:79], v[168:171], v[214:217], v[76:79]
	v_mfma_f32_16x16x32_bf16 v[72:75], v[176:179], v[214:217], v[72:75]
	s_setprio 0
	s_barrier
	s_add_i32 s0, s61, s50
	s_mov_b32 m0, s0
	ds_read_b128 v[218:221], v167
	ds_read_b128 v[222:225], v167 offset:1024
	ds_read_b128 v[226:229], v167 offset:2048
	global_load_lds_dwordx4 v130, s[36:37]
	s_add_i32 m0, s0, 0x2000
	ds_read_b128 v[230:233], v167 offset:3072
	global_load_lds_dwordx4 v134, s[36:37]
	s_barrier
; #define PG8_STAGE(bufoff, gbase, voff) do { _Pragma("unroll") for (int _i = 0; _i < 2; ++_i) \
;         __builtin_amdgcn_global_load_lds((const unsigned*)((const char*)(gbase) + (voff)[_i]), (LAS unsigned*)(lds + (bufoff) + ldsw + _i * 8192), 16, 0, 0); } while (0)
; #define PG8_LDA(dst, b, h) do { _Pragma("unroll") for (int m = 0; m < 4; ++m) _Pragma("unroll") for (int k = 0; k < 2; ++k) dst[m][k] = *(const LAS bf16x8*)(lds + PG8_SA(b, h) + aoff + m * 2048 + k * 1024); } while (0)
; #define PG8_LDB(dst, b, h) do { _Pragma("unroll") for (int n = 0; n < 2; ++n) _Pragma("unroll") for (int k = 0; k < 2; ++k) dst[n][k] = *(const LAS bf16x8*)(lds + PG8_SB(b, h) + boff + n * 2048 + k * 1024); } while (0)
; #define PG8_MMA(ai, bj, At, Bt) do { __builtin_amdgcn_s_setprio(1); _Pragma("unroll") for (int m = 0; m < 4; ++m) _Pragma("unroll") for (int n = 0; n < 2; ++n) _Pragma("unroll") for (int k = 0; k < 2; ++k) \
;         acc[ai][bj][m][n] = __builtin_amdgcn_mfma_f32_16x16x32_bf16(Bt[n][k], At[m][k], acc[ai][bj][m][n], 0, 0, 0); __builtin_amdgcn_s_setprio(0); } while (0)
; #define PG8_WAIT_V(n) asm volatile("s_waitcnt vmcnt(" #n ")" ::: "memory")
; #define PG8_WAIT_L(n) asm volatile("s_waitcnt lgkmcnt(" #n ")" ::: "memory")
; #define PG8_BAR __builtin_amdgcn_s_barrier()
; #define PG8_SCHED __builtin_amdgcn_sched_barrier(0)
; template <class Epi, class Sched>
; DI void gemm_phase(LAS unsigned char* lds, const Gemm g, const Sched& S, const Epi& E) {
;     ...
;             PG8_BAR; PG8_WAIT_L(0); PG8_MMA(0, 1, At, B1); PG8_BAR;
;             PG8_LDA(At, 0, 1); PG8_STAGE(PG8_SA(0, 0), a2, voffA);
;             PG8_BAR; PG8_WAIT_L(0); PG8_MMA(1, 0, At, B0); PG8_BAR; PG8_SCHED;
;             PG8_STAGE(PG8_SB(0, 1), b2 + hstep, voffB);
;             PG8_WAIT_V(6); PG8_BAR; PG8_MMA(1, 1, At, B1); PG8_BAR;
;             PG8_LDB(B0, 1, 0); PG8_SCHED; PG8_LDA(At, 1, 0); PG8_STAGE(PG8_SA(0, 1), a2 + hstep, voffA);
;             PG8_WAIT_L(8); PG8_BAR; PG8_WAIT_L(0); PG8_MMA(0, 0, At, B0); PG8_BAR; PG8_SCHED;
;             PG8_LDB(B1, 1, 1); PG8_STAGE(PG8_SB(1, 0), b3, voffB);
;             PG8_BAR; PG8_WAIT_L(0); PG8_MMA(0, 1, At, B1); PG8_BAR;
;             PG8_LDA(At, 1, 1); PG8_STAGE(PG8_SA(1, 0), a3, voffA);
	s_waitcnt lgkmcnt(0)
	s_setprio 1
	v_mfma_f32_16x16x32_bf16 v[116:119], v[218:221], v[180:183], v[116:119]
	v_mfma_f32_16x16x32_bf16 v[112:115], v[226:229], v[180:183], v[112:115]
	v_mfma_f32_16x16x32_bf16 v[100:103], v[218:221], v[194:197], v[100:103]
	v_mfma_f32_16x16x32_bf16 v[96:99], v[226:229], v[194:197], v[96:99]
	v_mfma_f32_16x16x32_bf16 v[84:87], v[218:221], v[202:205], v[84:87]
	v_mfma_f32_16x16x32_bf16 v[80:83], v[226:229], v[202:205], v[80:83]
	v_mfma_f32_16x16x32_bf16 v[68:71], v[218:221], v[210:213], v[68:71]
	v_mfma_f32_16x16x32_bf16 v[64:67], v[226:229], v[210:213], v[64:67]
	v_mfma_f32_16x16x32_bf16 v[116:119], v[222:225], v[188:191], v[116:119]
	v_mfma_f32_16x16x32_bf16 v[112:115], v[230:233], v[188:191], v[112:115]
	v_mfma_f32_16x16x32_bf16 v[100:103], v[222:225], v[198:201], v[100:103]
	v_mfma_f32_16x16x32_bf16 v[96:99], v[230:233], v[198:201], v[96:99]
	v_mfma_f32_16x16x32_bf16 v[84:87], v[222:225], v[206:209], v[84:87]
	v_mfma_f32_16x16x32_bf16 v[80:83], v[230:233], v[206:209], v[80:83]
	v_mfma_f32_16x16x32_bf16 v[68:71], v[222:225], v[214:217], v[68:71]
	v_mfma_f32_16x16x32_bf16 v[64:67], v[230:233], v[214:217], v[64:67]
	s_setprio 0
	s_mov_b32 m0, s51
	s_barrier
	ds_read_b128 v[180:183], v166 offset:16384
	ds_read_b128 v[188:191], v166 offset:17408
	ds_read_b128 v[194:197], v166 offset:18432
	ds_read_b128 v[198:201], v166 offset:19456
	ds_read_b128 v[202:205], v166 offset:20480
	ds_read_b128 v[206:209], v166 offset:21504
	ds_read_b128 v[210:213], v166 offset:22528
	global_load_lds_dwordx4 v128, s[38:39]
	s_mov_b32 m0, s52
	ds_read_b128 v[214:217], v166 offset:23552
	global_load_lds_dwordx4 v132, s[38:39]
	s_barrier
	s_waitcnt lgkmcnt(0)
	s_setprio 1
	v_mfma_f32_16x16x32_bf16 v[60:63], v[144:147], v[180:183], v[60:63]
	v_mfma_f32_16x16x32_bf16 v[56:59], v[172:175], v[180:183], v[56:59]
	v_mfma_f32_16x16x32_bf16 v[44:47], v[144:147], v[194:197], v[44:47]
	v_mfma_f32_16x16x32_bf16 v[40:43], v[172:175], v[194:197], v[40:43]
	v_mfma_f32_16x16x32_bf16 v[28:31], v[144:147], v[202:205], v[28:31]
	v_mfma_f32_16x16x32_bf16 v[24:27], v[172:175], v[202:205], v[24:27]
	v_mfma_f32_16x16x32_bf16 v[12:15], v[144:147], v[210:213], v[12:15]
	v_mfma_f32_16x16x32_bf16 v[8:11], v[172:175], v[210:213], v[8:11]
	v_mfma_f32_16x16x32_bf16 v[60:63], v[168:171], v[188:191], v[60:63]
	v_mfma_f32_16x16x32_bf16 v[56:59], v[176:179], v[188:191], v[56:59]
	v_mfma_f32_16x16x32_bf16 v[44:47], v[168:171], v[198:201], v[44:47]
	v_mfma_f32_16x16x32_bf16 v[40:43], v[176:179], v[198:201], v[40:43]
	v_mfma_f32_16x16x32_bf16 v[28:31], v[168:171], v[206:209], v[28:31]
	v_mfma_f32_16x16x32_bf16 v[24:27], v[176:179], v[206:209], v[24:27]
	v_mfma_f32_16x16x32_bf16 v[12:15], v[168:171], v[214:217], v[12:15]
	v_mfma_f32_16x16x32_bf16 v[8:11], v[176:179], v[214:217], v[8:11]
	s_setprio 0
	s_barrier
	s_add_u32 s0, s36, 0x30000
	s_addc_u32 s1, s37, 0
	s_add_i32 s4, s62, s50
	s_mov_b32 m0, s4
	s_nop 0
	global_load_lds_dwordx4 v130, s[0:1]
	s_add_i32 m0, s4, 0x2000
	s_nop 0
	global_load_lds_dwordx4 v134, s[0:1]
	s_waitcnt vmcnt(6)
	s_barrier
	s_setprio 1
	v_mfma_f32_16x16x32_bf16 v[52:55], v[218:221], v[180:183], v[52:55]
	v_mfma_f32_16x16x32_bf16 v[48:51], v[226:229], v[180:183], v[48:51]
	v_mfma_f32_16x16x32_bf16 v[36:39], v[218:221], v[194:197], v[36:39]
	v_mfma_f32_16x16x32_bf16 v[32:35], v[226:229], v[194:197], v[32:35]
	v_mfma_f32_16x16x32_bf16 v[20:23], v[218:221], v[202:205], v[20:23]
	v_mfma_f32_16x16x32_bf16 v[16:19], v[226:229], v[202:205], v[16:19]
	v_mfma_f32_16x16x32_bf16 v[4:7], v[218:221], v[210:213], v[4:7]
	v_mfma_f32_16x16x32_bf16 v[0:3], v[226:229], v[210:213], v[0:3]
	v_mfma_f32_16x16x32_bf16 v[52:55], v[222:225], v[188:191], v[52:55]
	v_mfma_f32_16x16x32_bf16 v[48:51], v[230:233], v[188:191], v[48:51]
	v_mfma_f32_16x16x32_bf16 v[36:39], v[222:225], v[198:201], v[36:39]
	v_mfma_f32_16x16x32_bf16 v[32:35], v[230:233], v[198:201], v[32:35]
	v_mfma_f32_16x16x32_bf16 v[20:23], v[222:225], v[206:209], v[20:23]
	v_mfma_f32_16x16x32_bf16 v[16:19], v[230:233], v[206:209], v[16:19]
	v_mfma_f32_16x16x32_bf16 v[4:7], v[222:225], v[214:217], v[4:7]
	v_mfma_f32_16x16x32_bf16 v[0:3], v[230:233], v[214:217], v[0:3]
	s_setprio 0
	s_add_i32 s4, 0, 0x18000
	v_add_u32_e32 v150, s4, v164
	s_barrier
	ds_read_b128 v[144:147], v150
	ds_read_b128 v[168:171], v150 offset:1024
	ds_read_b128 v[172:175], v150 offset:2048
	ds_read_b128 v[176:179], v150 offset:3072
	s_add_u32 s0, s38, 0x30000
	s_addc_u32 s1, s39, 0
	s_mov_b32 m0, s53
	ds_read_b128 v[180:183], v166 offset:32768
	ds_read_b128 v[188:191], v166 offset:33792
	ds_read_b128 v[194:197], v166 offset:34816
	ds_read_b128 v[198:201], v166 offset:35840
	ds_read_b128 v[202:205], v166 offset:36864
	ds_read_b128 v[206:209], v166 offset:37888
	ds_read_b128 v[210:213], v166 offset:38912
	global_load_lds_dwordx4 v128, s[0:1]
	s_mov_b32 m0, s54
	ds_read_b128 v[214:217], v166 offset:39936
	global_load_lds_dwordx4 v132, s[0:1]
	s_waitcnt lgkmcnt(8)
	s_barrier
; #define PG8_STAGE(bufoff, gbase, voff) do { _Pragma("unroll") for (int _i = 0; _i < 2; ++_i) \
;         __builtin_amdgcn_global_load_lds((const unsigned*)((const char*)(gbase) + (voff)[_i]), (LAS unsigned*)(lds + (bufoff) + ldsw + _i * 8192), 16, 0, 0); } while (0)
; #define PG8_LDA(dst, b, h) do { _Pragma("unroll") for (int m = 0; m < 4; ++m) _Pragma("unroll") for (int k = 0; k < 2; ++k) dst[m][k] = *(const LAS bf16x8*)(lds + PG8_SA(b, h) + aoff + m * 2048 + k * 1024); } while (0)
; #define PG8_LDB(dst, b, h) do { _Pragma("unroll") for (int n = 0; n < 2; ++n) _Pragma("unroll") for (int k = 0; k < 2; ++k) dst[n][k] = *(const LAS bf16x8*)(lds + PG8_SB(b, h) + boff + n * 2048 + k * 1024); } while (0)
; #define PG8_MMA(ai, bj, At, Bt) do { __builtin_amdgcn_s_setprio(1); _Pragma("unroll") for (int m = 0; m < 4; ++m) _Pragma("unroll") for (int n = 0; n < 2; ++n) _Pragma("unroll") for (int k = 0; k < 2; ++k) \
;         acc[ai][bj][m][n] = __builtin_amdgcn_mfma_f32_16x16x32_bf16(Bt[n][k], At[m][k], acc[ai][bj][m][n], 0, 0, 0); __builtin_amdgcn_s_setprio(0); } while (0)
; #define PG8_WAIT_V(n) asm volatile("s_waitcnt vmcnt(" #n ")" ::: "memory")
; #define PG8_WAIT_L(n) asm volatile("s_waitcnt lgkmcnt(" #n ")" ::: "memory")
; #define PG8_BAR __builtin_amdgcn_s_barrier()
; #define PG8_SCHED __builtin_amdgcn_sched_barrier(0)
; template <class Epi, class Sched>
; DI void gemm_phase(LAS unsigned char* lds, const Gemm g, const Sched& S, const Epi& E) {
;     ...
;             PG8_WAIT_L(8); PG8_BAR; PG8_WAIT_L(0); PG8_MMA(0, 0, At, B0); PG8_BAR; PG8_SCHED;
;             PG8_LDB(B1, 1, 1); PG8_STAGE(PG8_SB(1, 0), b3, voffB);
;             PG8_BAR; PG8_WAIT_L(0); PG8_MMA(0, 1, At, B1); PG8_BAR;
;             PG8_LDA(At, 1, 1); PG8_STAGE(PG8_SA(1, 0), a3, voffA);
;             PG8_BAR; PG8_WAIT_L(0); PG8_MMA(1, 0, At, B0); PG8_BAR; PG8_SCHED;
;             PG8_STAGE(PG8_SB(1, 1), b3 + hstep, voffB);
;             PG8_WAIT_V(6); PG8_BAR; PG8_MMA(1, 1, At, B1); PG8_BAR;
	s_waitcnt lgkmcnt(0)
	s_setprio 1
	v_mfma_f32_16x16x32_bf16 v[124:127], v[144:147], v[180:183], v[124:127]
	v_mfma_f32_16x16x32_bf16 v[120:123], v[172:175], v[180:183], v[120:123]
	v_mfma_f32_16x16x32_bf16 v[108:111], v[144:147], v[194:197], v[108:111]
	v_mfma_f32_16x16x32_bf16 v[104:107], v[172:175], v[194:197], v[104:107]
	v_mfma_f32_16x16x32_bf16 v[92:95], v[144:147], v[202:205], v[92:95]
	v_mfma_f32_16x16x32_bf16 v[88:91], v[172:175], v[202:205], v[88:91]
	v_mfma_f32_16x16x32_bf16 v[76:79], v[144:147], v[210:213], v[76:79]
	v_mfma_f32_16x16x32_bf16 v[72:75], v[172:175], v[210:213], v[72:75]
	v_mfma_f32_16x16x32_bf16 v[124:127], v[168:171], v[188:191], v[124:127]
	v_mfma_f32_16x16x32_bf16 v[120:123], v[176:179], v[188:191], v[120:123]
	v_mfma_f32_16x16x32_bf16 v[108:111], v[168:171], v[198:201], v[108:111]
	v_mfma_f32_16x16x32_bf16 v[104:107], v[176:179], v[198:201], v[104:107]
	v_mfma_f32_16x16x32_bf16 v[92:95], v[168:171], v[206:209], v[92:95]
	v_mfma_f32_16x16x32_bf16 v[88:91], v[176:179], v[206:209], v[88:91]
	v_mfma_f32_16x16x32_bf16 v[76:79], v[168:171], v[214:217], v[76:79]
	v_mfma_f32_16x16x32_bf16 v[72:75], v[176:179], v[214:217], v[72:75]
	s_setprio 0
	s_barrier
	s_add_i32 s5, 0, 0x1c000
	s_add_i32 s0, s4, s50
	v_add_u32_e32 v150, s5, v164
	s_add_i32 m0, s0, 0xffffff80
	ds_read_b128 v[218:221], v150
	ds_read_b128 v[222:225], v150 offset:1024
	ds_read_b128 v[226:229], v150 offset:2048
	global_load_lds_dwordx4 v130, s[36:37] offset:128
	s_add_i32 m0, s0, 0x1f80
	ds_read_b128 v[230:233], v150 offset:3072
	global_load_lds_dwordx4 v134, s[36:37] offset:128
	s_barrier
	s_waitcnt lgkmcnt(0)
	s_setprio 1
	v_mfma_f32_16x16x32_bf16 v[116:119], v[218:221], v[180:183], v[116:119]
	v_mfma_f32_16x16x32_bf16 v[112:115], v[226:229], v[180:183], v[112:115]
	v_mfma_f32_16x16x32_bf16 v[100:103], v[218:221], v[194:197], v[100:103]
	v_mfma_f32_16x16x32_bf16 v[96:99], v[226:229], v[194:197], v[96:99]
	v_mfma_f32_16x16x32_bf16 v[84:87], v[218:221], v[202:205], v[84:87]
	v_mfma_f32_16x16x32_bf16 v[80:83], v[226:229], v[202:205], v[80:83]
	v_mfma_f32_16x16x32_bf16 v[68:71], v[218:221], v[210:213], v[68:71]
	v_mfma_f32_16x16x32_bf16 v[64:67], v[226:229], v[210:213], v[64:67]
	v_mfma_f32_16x16x32_bf16 v[116:119], v[222:225], v[188:191], v[116:119]
	v_mfma_f32_16x16x32_bf16 v[112:115], v[230:233], v[188:191], v[112:115]
	v_mfma_f32_16x16x32_bf16 v[100:103], v[222:225], v[198:201], v[100:103]
	v_mfma_f32_16x16x32_bf16 v[96:99], v[230:233], v[198:201], v[96:99]
	v_mfma_f32_16x16x32_bf16 v[84:87], v[222:225], v[206:209], v[84:87]
	v_mfma_f32_16x16x32_bf16 v[80:83], v[230:233], v[206:209], v[80:83]
	v_mfma_f32_16x16x32_bf16 v[68:71], v[222:225], v[214:217], v[68:71]
	v_mfma_f32_16x16x32_bf16 v[64:67], v[230:233], v[214:217], v[64:67]
	s_setprio 0
	s_add_i32 m0, s57, 0xffffff80
	s_barrier
	ds_read_b128 v[180:183], v166 offset:49152
	ds_read_b128 v[188:191], v166 offset:50176
	ds_read_b128 v[194:197], v166 offset:51200
	ds_read_b128 v[198:201], v166 offset:52224
	ds_read_b128 v[202:205], v166 offset:53248
	ds_read_b128 v[206:209], v166 offset:54272
	ds_read_b128 v[210:213], v166 offset:55296
	global_load_lds_dwordx4 v128, s[38:39] offset:128
	s_add_i32 m0, s58, 0xffffff80
	ds_read_b128 v[214:217], v166 offset:56320
	global_load_lds_dwordx4 v132, s[38:39] offset:128
	s_barrier
	s_waitcnt lgkmcnt(0)
	s_setprio 1
	v_mfma_f32_16x16x32_bf16 v[60:63], v[144:147], v[180:183], v[60:63]
	v_mfma_f32_16x16x32_bf16 v[56:59], v[172:175], v[180:183], v[56:59]
	v_mfma_f32_16x16x32_bf16 v[44:47], v[144:147], v[194:197], v[44:47]
	v_mfma_f32_16x16x32_bf16 v[40:43], v[172:175], v[194:197], v[40:43]
	v_mfma_f32_16x16x32_bf16 v[28:31], v[144:147], v[202:205], v[28:31]
	v_mfma_f32_16x16x32_bf16 v[24:27], v[172:175], v[202:205], v[24:27]
	v_mfma_f32_16x16x32_bf16 v[12:15], v[144:147], v[210:213], v[12:15]
	v_mfma_f32_16x16x32_bf16 v[8:11], v[172:175], v[210:213], v[8:11]
	v_mfma_f32_16x16x32_bf16 v[60:63], v[168:171], v[188:191], v[60:63]
	v_mfma_f32_16x16x32_bf16 v[56:59], v[176:179], v[188:191], v[56:59]
	v_mfma_f32_16x16x32_bf16 v[44:47], v[168:171], v[198:201], v[44:47]
	v_mfma_f32_16x16x32_bf16 v[40:43], v[176:179], v[198:201], v[40:43]
	v_mfma_f32_16x16x32_bf16 v[28:31], v[168:171], v[206:209], v[28:31]
	v_mfma_f32_16x16x32_bf16 v[24:27], v[176:179], v[206:209], v[24:27]
	v_mfma_f32_16x16x32_bf16 v[12:15], v[168:171], v[214:217], v[12:15]
	v_mfma_f32_16x16x32_bf16 v[8:11], v[176:179], v[214:217], v[8:11]
	s_setprio 0
	s_barrier
	s_add_u32 s0, s36, 0x30080
	s_addc_u32 s1, s37, 0
	s_add_i32 s4, s5, s50
	s_mov_b32 m0, s4
	s_nop 0
	global_load_lds_dwordx4 v130, s[0:1]
	s_add_i32 m0, s4, 0x2000
	s_nop 0
	global_load_lds_dwordx4 v134, s[0:1]
	s_waitcnt vmcnt(6)
	s_barrier
	s_setprio 1
	v_mfma_f32_16x16x32_bf16 v[52:55], v[218:221], v[180:183], v[52:55]
	v_mfma_f32_16x16x32_bf16 v[48:51], v[226:229], v[180:183], v[48:51]
	v_mfma_f32_16x16x32_bf16 v[36:39], v[218:221], v[194:197], v[36:39]
	v_mfma_f32_16x16x32_bf16 v[32:35], v[226:229], v[194:197], v[32:35]
	v_mfma_f32_16x16x32_bf16 v[20:23], v[218:221], v[202:205], v[20:23]
	v_mfma_f32_16x16x32_bf16 v[16:19], v[226:229], v[202:205], v[16:19]
	v_mfma_f32_16x16x32_bf16 v[4:7], v[218:221], v[210:213], v[4:7]
	v_mfma_f32_16x16x32_bf16 v[0:3], v[226:229], v[210:213], v[0:3]
	v_mfma_f32_16x16x32_bf16 v[52:55], v[222:225], v[188:191], v[52:55]
	v_mfma_f32_16x16x32_bf16 v[48:51], v[230:233], v[188:191], v[48:51]
	v_mfma_f32_16x16x32_bf16 v[36:39], v[222:225], v[198:201], v[36:39]
	v_mfma_f32_16x16x32_bf16 v[32:35], v[230:233], v[198:201], v[32:35]
	v_mfma_f32_16x16x32_bf16 v[20:23], v[222:225], v[206:209], v[20:23]
	v_mfma_f32_16x16x32_bf16 v[16:19], v[230:233], v[206:209], v[16:19]
	v_mfma_f32_16x16x32_bf16 v[4:7], v[222:225], v[214:217], v[4:7]
	v_mfma_f32_16x16x32_bf16 v[0:3], v[230:233], v[214:217], v[0:3]
	s_setprio 0
	s_add_i32 s41, s41, 2
	s_add_u32 s8, s8, 0x100
	s_addc_u32 s9, s9, 0
	s_add_u32 s35, s35, 0x100
	s_addc_u32 s40, s40, 0
	s_cmp_gt_u32 s41, 9
	s_barrier
	s_cbranch_scc0 .LBB0_938

;     DI size_t aoff(const Unit& u, size_t tstep) const { return (size_t)u.pm * tstep; }
;     DI size_t boff(const Unit& u, size_t tstep) const { return (size_t)u.pn * tstep; }
;     DI bool next(int i, Unit& u) const { const long L = (long)i * G + c; if (L >= np) return false; u.pm = pmv; u.pn = (int)(L % nN); u.ks = (int)(L / nN); return true; }
;     DI size_t aoff(const Unit& u, size_t) const { return (size_t)u.ks * kbytes; }
;     DI size_t boff(const Unit& u, size_t tstep) const { return (size_t)u.pn * tstep + (size_t)u.ks * kbytes; }
;     DI bool next(int i, Unit& u) const { Unit t; if (!S.next(i / 3, t)) return false; u.pm = t.pm; u.pn = t.pn; u.ks = i % 3; return true; }
;     DI size_t aoff(const Unit& u, size_t tstep) const { return (u.ks < 2 ? offU : offOA) + (size_t)u.pm * tstep; }
; #define PG8_LDA(dst, b, h) do { _Pragma("unroll") for (int m = 0; m < 4; ++m) _Pragma("unroll") for (int k = 0; k < 2; ++k) dst[m][k] = *(const LAS bf16x8*)(lds + PG8_SA(b, h) + aoff + m * 2048 + k * 1024); } while (0)
; template <class Epi, class Sched>
; DI void gemm_phase(LAS unsigned char* lds, const Gemm g, const Sched& S, const Epi& E) {
;     ...
;         const bool has_next = S.next(ui + 1, nxt);
;         const char* nA = has_next ? (const char*)g.A + S.aoff(nxt, tstep) : cA; const char* nB = has_next ? (const char*)g.Bt + S.boff(nxt, tstep) : cB;
;         for (int t = 0; t < nt; t += 2) {
;             if constexpr (Epi::HAS_MID) { if (t == E.mid_t(nt)) { int fr3 = fr, fq3 = fq; asm volatile("" : "+v"(fr3), "+v"(fq3)); E.mid(acc, cur, wr, wc, fr3, fq3); } }
;             const bool last = (t == nt - 2);
;             const char* a1 = cA + (size_t)(t + 1) * kstep;
;             const char* a2 = last ? nA : cA + (size_t)(t + 2) * kstep; const char* b2 = last ? nB : cB + (size_t)(t + 2) * kstep;
;             const char* a3 = a2 + kstep; const char* b3 = b2 + kstep;
;             PG8_LDB(B0, 0, 0); PG8_SCHED; PG8_LDA(At, 0, 0); PG8_STAGE(PG8_SA(1, 1), a1 + hstep, voffA);
;             PG8_WAIT_L(8); PG8_BAR; PG8_WAIT_L(0); PG8_MMA(0, 0, At, B0); PG8_BAR; PG8_SCHED;
;             PG8_LDB(B1, 0, 1); PG8_STAGE(PG8_SB(0, 0), b2, voffB);
;             PG8_BAR; PG8_WAIT_L(0); PG8_MMA(0, 1, At, B1); PG8_BAR;
;             PG8_LDA(At, 0, 1); PG8_STAGE(PG8_SA(0, 0), a2, voffA);
;             PG8_BAR; PG8_WAIT_L(0); PG8_MMA(1, 0, At, B0); PG8_BAR; PG8_SCHED;
.LBB0_983:
	s_ashr_i32 s31, s30, 31
	s_lshl_b64 s[0:1], s[30:31], 18
	v_cmp_lt_i64_e32 vcc, s[36:37], v[142:143]
	s_add_u32 s36, s51, s0
	s_addc_u32 s37, s52, s1
	s_and_b64 s[0:1], vcc, exec
	s_cselect_b32 s9, s37, s43
	s_cselect_b32 s31, s36, s42
	s_ashr_i32 s29, s28, 31
	s_lshl_b64 s[0:1], s[28:29], 18
	s_add_u32 s38, s53, s0
	s_addc_u32 s39, s54, s1
	s_and_b64 s[0:1], vcc, exec
	s_cselect_b32 s29, s39, s45
	s_cselect_b32 s34, s38, s44
	s_add_u32 s42, s42, 0x20080
	s_addc_u32 s43, s43, 0
	s_add_u32 s35, s44, 0x100
	v_mov_b32_e32 v0, 0
	s_addc_u32 s41, s45, 0
	s_mov_b32 s79, -2
	ds_read_b128 v[146:149], v156
	ds_read_b128 v[150:153], v156 offset:1024
	ds_read_b128 v[160:163], v156 offset:2048
	ds_read_b128 v[164:167], v156 offset:3072
	s_add_u32 s0, s42, 0xfffe0080
	s_addc_u32 s1, s43, -1
	s_cmp_eq_u32 s79, 4
	s_cselect_b32 s47, s9, s1
	s_cselect_b32 s46, s31, s0
	s_cselect_b32 s45, s29, s41
	s_cselect_b32 s44, s34, s35
	s_add_i32 m0, s55, 0xc000
	ds_read_b128 v[168:171], v158
	ds_read_b128 v[172:175], v158 offset:1024
	ds_read_b128 v[176:179], v158 offset:2048
	ds_read_b128 v[180:183], v158 offset:3072
	ds_read_b128 v[188:191], v158 offset:4096
	ds_read_b128 v[194:197], v158 offset:5120
	ds_read_b128 v[198:201], v158 offset:6144
	global_load_lds_dwordx4 v138, s[42:43]
	s_add_i32 m0, s55, 0xe000
	ds_read_b128 v[202:205], v158 offset:7168
	global_load_lds_dwordx4 v140, s[42:43]
	s_waitcnt lgkmcnt(8)
	s_barrier
	s_waitcnt lgkmcnt(0)
	s_setprio 1
	v_mfma_f32_16x16x32_bf16 v[124:127], v[146:149], v[168:171], 0
	v_mfma_f32_16x16x32_bf16 v[120:123], v[160:163], v[168:171], 0
	v_mfma_f32_16x16x32_bf16 v[108:111], v[146:149], v[176:179], 0
	v_mfma_f32_16x16x32_bf16 v[104:107], v[160:163], v[176:179], 0
	v_mfma_f32_16x16x32_bf16 v[92:95], v[146:149], v[188:191], 0
	v_mfma_f32_16x16x32_bf16 v[88:91], v[160:163], v[188:191], 0
	v_mfma_f32_16x16x32_bf16 v[76:79], v[146:149], v[198:201], 0
	v_mfma_f32_16x16x32_bf16 v[72:75], v[160:163], v[198:201], 0
	v_mfma_f32_16x16x32_bf16 v[124:127], v[150:153], v[172:175], v[124:127]
	v_mfma_f32_16x16x32_bf16 v[120:123], v[164:167], v[172:175], v[120:123]
	v_mfma_f32_16x16x32_bf16 v[108:111], v[150:153], v[180:183], v[108:111]
	v_mfma_f32_16x16x32_bf16 v[104:107], v[164:167], v[180:183], v[104:107]
	v_mfma_f32_16x16x32_bf16 v[92:95], v[150:153], v[194:197], v[92:95]
	v_mfma_f32_16x16x32_bf16 v[88:91], v[164:167], v[194:197], v[88:91]
	v_mfma_f32_16x16x32_bf16 v[76:79], v[150:153], v[202:205], v[76:79]
	v_mfma_f32_16x16x32_bf16 v[72:75], v[164:167], v[202:205], v[72:75]
	s_setprio 0
	s_barrier
	s_add_i32 s0, s66, s50
	s_mov_b32 m0, s0
	ds_read_b128 v[206:209], v159
	ds_read_b128 v[210:213], v159 offset:1024
	ds_read_b128 v[214:217], v159 offset:2048
	global_load_lds_dwordx4 v130, s[44:45]
	s_add_i32 m0, s0, 0x2000
	ds_read_b128 v[218:221], v159 offset:3072
	global_load_lds_dwordx4 v134, s[44:45]
	s_barrier
	s_waitcnt lgkmcnt(0)
	s_setprio 1
	v_mfma_f32_16x16x32_bf16 v[116:119], v[206:209], v[168:171], 0
	v_mfma_f32_16x16x32_bf16 v[112:115], v[214:217], v[168:171], 0
	v_mfma_f32_16x16x32_bf16 v[100:103], v[206:209], v[176:179], 0
	v_mfma_f32_16x16x32_bf16 v[96:99], v[214:217], v[176:179], 0
	v_mfma_f32_16x16x32_bf16 v[84:87], v[206:209], v[188:191], 0
	v_mfma_f32_16x16x32_bf16 v[80:83], v[214:217], v[188:191], 0
	v_mfma_f32_16x16x32_bf16 v[68:71], v[206:209], v[198:201], 0
	v_mfma_f32_16x16x32_bf16 v[64:67], v[214:217], v[198:201], 0
	v_mfma_f32_16x16x32_bf16 v[116:119], v[210:213], v[172:175], v[116:119]
	v_mfma_f32_16x16x32_bf16 v[112:115], v[218:221], v[172:175], v[112:115]
	v_mfma_f32_16x16x32_bf16 v[100:103], v[210:213], v[180:183], v[100:103]
	v_mfma_f32_16x16x32_bf16 v[96:99], v[218:221], v[180:183], v[96:99]
	v_mfma_f32_16x16x32_bf16 v[84:87], v[210:213], v[194:197], v[84:87]
	v_mfma_f32_16x16x32_bf16 v[80:83], v[218:221], v[194:197], v[80:83]
	v_mfma_f32_16x16x32_bf16 v[68:71], v[210:213], v[202:205], v[68:71]
	v_mfma_f32_16x16x32_bf16 v[64:67], v[218:221], v[202:205], v[64:67]
	s_setprio 0
	s_mov_b32 m0, s55
	s_barrier
	ds_read_b128 v[168:171], v158 offset:16384
	ds_read_b128 v[172:175], v158 offset:17408
	ds_read_b128 v[176:179], v158 offset:18432
	ds_read_b128 v[180:183], v158 offset:19456
	ds_read_b128 v[188:191], v158 offset:20480
	ds_read_b128 v[194:197], v158 offset:21504
	ds_read_b128 v[198:201], v158 offset:22528
	global_load_lds_dwordx4 v128, s[46:47]
	s_mov_b32 m0, s56
	ds_read_b128 v[202:205], v158 offset:23552
	global_load_lds_dwordx4 v132, s[46:47]
	s_barrier
	s_waitcnt lgkmcnt(0)
	s_setprio 1
	v_mfma_f32_16x16x32_bf16 v[60:63], v[146:149], v[168:171], 0
	v_mfma_f32_16x16x32_bf16 v[56:59], v[160:163], v[168:171], 0
	v_mfma_f32_16x16x32_bf16 v[44:47], v[146:149], v[176:179], 0
	v_mfma_f32_16x16x32_bf16 v[40:43], v[160:163], v[176:179], 0
	v_mfma_f32_16x16x32_bf16 v[28:31], v[146:149], v[188:191], 0
	v_mfma_f32_16x16x32_bf16 v[24:27], v[160:163], v[188:191], 0
	v_mfma_f32_16x16x32_bf16 v[12:15], v[146:149], v[198:201], 0
	v_mfma_f32_16x16x32_bf16 v[8:11], v[160:163], v[198:201], 0
	v_mfma_f32_16x16x32_bf16 v[60:63], v[150:153], v[172:175], v[60:63]
	v_mfma_f32_16x16x32_bf16 v[56:59], v[164:167], v[172:175], v[56:59]
	v_mfma_f32_16x16x32_bf16 v[44:47], v[150:153], v[180:183], v[44:47]
	v_mfma_f32_16x16x32_bf16 v[40:43], v[164:167], v[180:183], v[40:43]
	v_mfma_f32_16x16x32_bf16 v[28:31], v[150:153], v[194:197], v[28:31]
	v_mfma_f32_16x16x32_bf16 v[24:27], v[164:167], v[194:197], v[24:27]
	v_mfma_f32_16x16x32_bf16 v[12:15], v[150:153], v[202:205], v[12:15]
	v_mfma_f32_16x16x32_bf16 v[8:11], v[164:167], v[202:205], v[8:11]
	s_setprio 0
	s_barrier
; #define PG8_STAGE(bufoff, gbase, voff) do { _Pragma("unroll") for (int _i = 0; _i < 2; ++_i) \
;         __builtin_amdgcn_global_load_lds((const unsigned*)((const char*)(gbase) + (voff)[_i]), (LAS unsigned*)(lds + (bufoff) + ldsw + _i * 8192), 16, 0, 0); } while (0)
; #define PG8_LDA(dst, b, h) do { _Pragma("unroll") for (int m = 0; m < 4; ++m) _Pragma("unroll") for (int k = 0; k < 2; ++k) dst[m][k] = *(const LAS bf16x8*)(lds + PG8_SA(b, h) + aoff + m * 2048 + k * 1024); } while (0)
; #define PG8_LDB(dst, b, h) do { _Pragma("unroll") for (int n = 0; n < 2; ++n) _Pragma("unroll") for (int k = 0; k < 2; ++k) dst[n][k] = *(const LAS bf16x8*)(lds + PG8_SB(b, h) + boff + n * 2048 + k * 1024); } while (0)
; #define PG8_MMA(ai, bj, At, Bt) do { __builtin_amdgcn_s_setprio(1); _Pragma("unroll") for (int m = 0; m < 4; ++m) _Pragma("unroll") for (int n = 0; n < 2; ++n) _Pragma("unroll") for (int k = 0; k < 2; ++k) \
;         acc[ai][bj][m][n] = __builtin_amdgcn_mfma_f32_16x16x32_bf16(Bt[n][k], At[m][k], acc[ai][bj][m][n], 0, 0, 0); __builtin_amdgcn_s_setprio(0); } while (0)
; #define PG8_WAIT_V(n) asm volatile("s_waitcnt vmcnt(" #n ")" ::: "memory")
; #define PG8_WAIT_L(n) asm volatile("s_waitcnt lgkmcnt(" #n ")" ::: "memory")
; #define PG8_BAR __builtin_amdgcn_s_barrier()
; #define PG8_SCHED __builtin_amdgcn_sched_barrier(0)
; template <class Epi, class Sched>
; DI void gemm_phase(LAS unsigned char* lds, const Gemm g, const Sched& S, const Epi& E) {
;     ...
;             PG8_STAGE(PG8_SB(0, 1), b2 + hstep, voffB);
;             PG8_WAIT_V(6); PG8_BAR; PG8_MMA(1, 1, At, B1); PG8_BAR;
;             PG8_LDB(B0, 1, 0); PG8_SCHED; PG8_LDA(At, 1, 0); PG8_STAGE(PG8_SA(0, 1), a2 + hstep, voffA);
;             PG8_WAIT_L(8); PG8_BAR; PG8_WAIT_L(0); PG8_MMA(0, 0, At, B0); PG8_BAR; PG8_SCHED;
;             PG8_LDB(B1, 1, 1); PG8_STAGE(PG8_SB(1, 0), b3, voffB);
;             PG8_BAR; PG8_WAIT_L(0); PG8_MMA(0, 1, At, B1); PG8_BAR;
;             PG8_LDA(At, 1, 1); PG8_STAGE(PG8_SA(1, 0), a3, voffA);
;             PG8_BAR; PG8_WAIT_L(0); PG8_MMA(1, 0, At, B0); PG8_BAR; PG8_SCHED;
	s_add_u32 s0, s44, 0x20000
	s_addc_u32 s1, s45, 0
	s_add_i32 s4, s67, s50
	s_mov_b32 m0, s4
	s_nop 0
	global_load_lds_dwordx4 v130, s[0:1]
	s_add_i32 m0, s4, 0x2000
	s_nop 0
	global_load_lds_dwordx4 v134, s[0:1]
	s_waitcnt vmcnt(6)
	s_barrier
	s_setprio 1
	v_mfma_f32_16x16x32_bf16 v[52:55], v[206:209], v[168:171], 0
	v_mfma_f32_16x16x32_bf16 v[48:51], v[214:217], v[168:171], 0
	v_mfma_f32_16x16x32_bf16 v[36:39], v[206:209], v[176:179], 0
	v_mfma_f32_16x16x32_bf16 v[32:35], v[214:217], v[176:179], 0
	v_mfma_f32_16x16x32_bf16 v[20:23], v[206:209], v[188:191], 0
	v_mfma_f32_16x16x32_bf16 v[16:19], v[214:217], v[188:191], 0
	v_mfma_f32_16x16x32_bf16 v[4:7], v[206:209], v[198:201], 0
	v_mfma_f32_16x16x32_bf16 v[0:3], v[214:217], v[198:201], 0
	v_mfma_f32_16x16x32_bf16 v[52:55], v[210:213], v[172:175], v[52:55]
	v_mfma_f32_16x16x32_bf16 v[48:51], v[218:221], v[172:175], v[48:51]
	v_mfma_f32_16x16x32_bf16 v[36:39], v[210:213], v[180:183], v[36:39]
	v_mfma_f32_16x16x32_bf16 v[32:35], v[218:221], v[180:183], v[32:35]
	v_mfma_f32_16x16x32_bf16 v[20:23], v[210:213], v[194:197], v[20:23]
	v_mfma_f32_16x16x32_bf16 v[16:19], v[218:221], v[194:197], v[16:19]
	v_mfma_f32_16x16x32_bf16 v[4:7], v[210:213], v[202:205], v[4:7]
	v_mfma_f32_16x16x32_bf16 v[0:3], v[218:221], v[202:205], v[0:3]
	s_setprio 0
	s_add_i32 s4, 0, 0x18000
	v_add_u32_e32 v136, s4, v157
	s_barrier
	ds_read_b128 v[146:149], v136
	ds_read_b128 v[150:153], v136 offset:1024
	ds_read_b128 v[160:163], v136 offset:2048
	ds_read_b128 v[164:167], v136 offset:3072
	s_add_u32 s0, s46, 0x20000
	s_addc_u32 s1, s47, 0
	s_mov_b32 m0, s57
	ds_read_b128 v[168:171], v158 offset:32768
	ds_read_b128 v[172:175], v158 offset:33792
	ds_read_b128 v[176:179], v158 offset:34816
	ds_read_b128 v[180:183], v158 offset:35840
	ds_read_b128 v[188:191], v158 offset:36864
	ds_read_b128 v[194:197], v158 offset:37888
	ds_read_b128 v[198:201], v158 offset:38912
	global_load_lds_dwordx4 v128, s[0:1]
	s_mov_b32 m0, s58
	ds_read_b128 v[202:205], v158 offset:39936
	global_load_lds_dwordx4 v132, s[0:1]
	s_waitcnt lgkmcnt(8)
	s_barrier
	s_waitcnt lgkmcnt(0)
	s_setprio 1
	v_mfma_f32_16x16x32_bf16 v[124:127], v[146:149], v[168:171], v[124:127]
	v_mfma_f32_16x16x32_bf16 v[120:123], v[160:163], v[168:171], v[120:123]
	v_mfma_f32_16x16x32_bf16 v[108:111], v[146:149], v[176:179], v[108:111]
	v_mfma_f32_16x16x32_bf16 v[104:107], v[160:163], v[176:179], v[104:107]
	v_mfma_f32_16x16x32_bf16 v[92:95], v[146:149], v[188:191], v[92:95]
	v_mfma_f32_16x16x32_bf16 v[88:91], v[160:163], v[188:191], v[88:91]
	v_mfma_f32_16x16x32_bf16 v[76:79], v[146:149], v[198:201], v[76:79]
	v_mfma_f32_16x16x32_bf16 v[72:75], v[160:163], v[198:201], v[72:75]
	v_mfma_f32_16x16x32_bf16 v[124:127], v[150:153], v[172:175], v[124:127]
	v_mfma_f32_16x16x32_bf16 v[120:123], v[164:167], v[172:175], v[120:123]
	v_mfma_f32_16x16x32_bf16 v[108:111], v[150:153], v[180:183], v[108:111]
	v_mfma_f32_16x16x32_bf16 v[104:107], v[164:167], v[180:183], v[104:107]
	v_mfma_f32_16x16x32_bf16 v[92:95], v[150:153], v[194:197], v[92:95]
	v_mfma_f32_16x16x32_bf16 v[88:91], v[164:167], v[194:197], v[88:91]
	v_mfma_f32_16x16x32_bf16 v[76:79], v[150:153], v[202:205], v[76:79]
	v_mfma_f32_16x16x32_bf16 v[72:75], v[164:167], v[202:205], v[72:75]
	s_setprio 0
	s_barrier
	s_add_i32 s5, 0, 0x1c000
	s_add_i32 s0, s4, s50
	v_add_u32_e32 v136, s5, v157
	s_add_i32 m0, s0, 0xffffff80
	ds_read_b128 v[206:209], v136
	ds_read_b128 v[210:213], v136 offset:1024
	ds_read_b128 v[214:217], v136 offset:2048
	global_load_lds_dwordx4 v130, s[44:45] offset:128
	s_add_i32 m0, s0, 0x1f80
	ds_read_b128 v[218:221], v136 offset:3072
	global_load_lds_dwordx4 v134, s[44:45] offset:128
	s_barrier
	s_waitcnt lgkmcnt(0)
	s_setprio 1
	v_mfma_f32_16x16x32_bf16 v[116:119], v[206:209], v[168:171], v[116:119]
	v_mfma_f32_16x16x32_bf16 v[112:115], v[214:217], v[168:171], v[112:115]
	v_mfma_f32_16x16x32_bf16 v[100:103], v[206:209], v[176:179], v[100:103]
	v_mfma_f32_16x16x32_bf16 v[96:99], v[214:217], v[176:179], v[96:99]
	v_mfma_f32_16x16x32_bf16 v[84:87], v[206:209], v[188:191], v[84:87]
	v_mfma_f32_16x16x32_bf16 v[80:83], v[214:217], v[188:191], v[80:83]
	v_mfma_f32_16x16x32_bf16 v[68:71], v[206:209], v[198:201], v[68:71]
	v_mfma_f32_16x16x32_bf16 v[64:67], v[214:217], v[198:201], v[64:67]
	v_mfma_f32_16x16x32_bf16 v[116:119], v[210:213], v[172:175], v[116:119]
	v_mfma_f32_16x16x32_bf16 v[112:115], v[218:221], v[172:175], v[112:115]
	v_mfma_f32_16x16x32_bf16 v[100:103], v[210:213], v[180:183], v[100:103]
	v_mfma_f32_16x16x32_bf16 v[96:99], v[218:221], v[180:183], v[96:99]
	v_mfma_f32_16x16x32_bf16 v[84:87], v[210:213], v[194:197], v[84:87]
	v_mfma_f32_16x16x32_bf16 v[80:83], v[218:221], v[194:197], v[80:83]
	v_mfma_f32_16x16x32_bf16 v[68:71], v[210:213], v[202:205], v[68:71]
	v_mfma_f32_16x16x32_bf16 v[64:67], v[218:221], v[202:205], v[64:67]
	s_setprio 0
	s_add_i32 m0, s62, 0xffffff80
	s_barrier
	ds_read_b128 v[168:171], v158 offset:49152
	ds_read_b128 v[172:175], v158 offset:50176
	ds_read_b128 v[176:179], v158 offset:51200
	ds_read_b128 v[180:183], v158 offset:52224
	ds_read_b128 v[188:191], v158 offset:53248
	ds_read_b128 v[194:197], v158 offset:54272
	ds_read_b128 v[198:201], v158 offset:55296
	global_load_lds_dwordx4 v128, s[46:47] offset:128
	s_add_i32 m0, s63, 0xffffff80
	ds_read_b128 v[202:205], v158 offset:56320
	global_load_lds_dwordx4 v132, s[46:47] offset:128
	s_barrier
; #define PG8_STAGE(bufoff, gbase, voff) do { _Pragma("unroll") for (int _i = 0; _i < 2; ++_i) \
;         __builtin_amdgcn_global_load_lds((const unsigned*)((const char*)(gbase) + (voff)[_i]), (LAS unsigned*)(lds + (bufoff) + ldsw + _i * 8192), 16, 0, 0); } while (0)
; #define PG8_LDA(dst, b, h) do { _Pragma("unroll") for (int m = 0; m < 4; ++m) _Pragma("unroll") for (int k = 0; k < 2; ++k) dst[m][k] = *(const LAS bf16x8*)(lds + PG8_SA(b, h) + aoff + m * 2048 + k * 1024); } while (0)
; #define PG8_LDB(dst, b, h) do { _Pragma("unroll") for (int n = 0; n < 2; ++n) _Pragma("unroll") for (int k = 0; k < 2; ++k) dst[n][k] = *(const LAS bf16x8*)(lds + PG8_SB(b, h) + boff + n * 2048 + k * 1024); } while (0)
; #define PG8_WAIT_V(n) asm volatile("s_waitcnt vmcnt(" #n ")" ::: "memory")
; #define PG8_WAIT_L(n) asm volatile("s_waitcnt lgkmcnt(" #n ")" ::: "memory")
; #define PG8_BAR __builtin_amdgcn_s_barrier()
; #define PG8_SCHED __builtin_amdgcn_sched_barrier(0)
; template <class Epi, class Sched>
; DI void gemm_phase(LAS unsigned char* lds, const Gemm g, const Sched& S, const Epi& E) {
;     ...
;             PG8_LDB(B0, 0, 0); PG8_SCHED; PG8_LDA(At, 0, 0); PG8_STAGE(PG8_SA(1, 1), a1 + hstep, voffA);
;             PG8_WAIT_L(8); PG8_BAR; PG8_WAIT_L(0); PG8_MMA(0, 0, At, B0); PG8_BAR; PG8_SCHED;
;             PG8_LDB(B1, 0, 1); PG8_STAGE(PG8_SB(0, 0), b2, voffB);
;             PG8_BAR; PG8_WAIT_L(0); PG8_MMA(0, 1, At, B1); PG8_BAR;
;             PG8_LDA(At, 0, 1); PG8_STAGE(PG8_SA(0, 0), a2, voffA);
;             PG8_BAR; PG8_WAIT_L(0); PG8_MMA(1, 0, At, B0); PG8_BAR; PG8_SCHED;
;             PG8_STAGE(PG8_SB(0, 1), b2 + hstep, voffB);
;             PG8_WAIT_V(6); PG8_BAR; PG8_MMA(1, 1, At, B1); PG8_BAR;
;             PG8_LDB(B0, 1, 0); PG8_SCHED; PG8_LDA(At, 1, 0); PG8_STAGE(PG8_SA(0, 1), a2 + hstep, voffA);
;             PG8_WAIT_L(8); PG8_BAR; PG8_WAIT_L(0); PG8_MMA(0, 0, At, B0); PG8_BAR; PG8_SCHED;
;             PG8_LDB(B1, 1, 1); PG8_STAGE(PG8_SB(1, 0), b3, voffB);
;             PG8_BAR; PG8_WAIT_L(0); PG8_MMA(0, 1, At, B1); PG8_BAR;
;             PG8_LDA(At, 1, 1); PG8_STAGE(PG8_SA(1, 0), a3, voffA);
;             PG8_BAR; PG8_WAIT_L(0); PG8_MMA(1, 0, At, B0); PG8_BAR; PG8_SCHED;
;             PG8_STAGE(PG8_SB(1, 1), b3 + hstep, voffB);
;             PG8_WAIT_V(6); PG8_BAR; PG8_MMA(1, 1, At, B1); PG8_BAR;
	s_waitcnt lgkmcnt(0)
	s_setprio 1
	v_mfma_f32_16x16x32_bf16 v[60:63], v[146:149], v[168:171], v[60:63]
	v_mfma_f32_16x16x32_bf16 v[56:59], v[160:163], v[168:171], v[56:59]
	v_mfma_f32_16x16x32_bf16 v[44:47], v[146:149], v[176:179], v[44:47]
	v_mfma_f32_16x16x32_bf16 v[40:43], v[160:163], v[176:179], v[40:43]
	v_mfma_f32_16x16x32_bf16 v[28:31], v[146:149], v[188:191], v[28:31]
	v_mfma_f32_16x16x32_bf16 v[24:27], v[160:163], v[188:191], v[24:27]
	v_mfma_f32_16x16x32_bf16 v[12:15], v[146:149], v[198:201], v[12:15]
	v_mfma_f32_16x16x32_bf16 v[8:11], v[160:163], v[198:201], v[8:11]
	v_mfma_f32_16x16x32_bf16 v[60:63], v[150:153], v[172:175], v[60:63]
	v_mfma_f32_16x16x32_bf16 v[56:59], v[164:167], v[172:175], v[56:59]
	v_mfma_f32_16x16x32_bf16 v[44:47], v[150:153], v[180:183], v[44:47]
	v_mfma_f32_16x16x32_bf16 v[40:43], v[164:167], v[180:183], v[40:43]
	v_mfma_f32_16x16x32_bf16 v[28:31], v[150:153], v[194:197], v[28:31]
	v_mfma_f32_16x16x32_bf16 v[24:27], v[164:167], v[194:197], v[24:27]
	v_mfma_f32_16x16x32_bf16 v[12:15], v[150:153], v[202:205], v[12:15]
	v_mfma_f32_16x16x32_bf16 v[8:11], v[164:167], v[202:205], v[8:11]
	s_setprio 0
	s_barrier
	s_add_u32 s0, s44, 0x20080
	s_addc_u32 s1, s45, 0
	s_add_i32 s4, s5, s50
	s_mov_b32 m0, s4
	s_nop 0
	global_load_lds_dwordx4 v130, s[0:1]
	v_lshl_add_u64 v[146:147], s[0:1], 0, v[134:135]
	s_add_i32 m0, s4, 0x2000
	s_nop 0
	global_load_lds_dwordx4 v134, s[0:1]
	s_waitcnt vmcnt(6)
	s_barrier
	s_setprio 1
	v_mfma_f32_16x16x32_bf16 v[52:55], v[206:209], v[168:171], v[52:55]
	v_mfma_f32_16x16x32_bf16 v[48:51], v[214:217], v[168:171], v[48:51]
	v_mfma_f32_16x16x32_bf16 v[36:39], v[206:209], v[176:179], v[36:39]
	v_mfma_f32_16x16x32_bf16 v[32:35], v[214:217], v[176:179], v[32:35]
	v_mfma_f32_16x16x32_bf16 v[20:23], v[206:209], v[188:191], v[20:23]
	v_mfma_f32_16x16x32_bf16 v[16:19], v[214:217], v[188:191], v[16:19]
	v_mfma_f32_16x16x32_bf16 v[4:7], v[206:209], v[198:201], v[4:7]
	v_mfma_f32_16x16x32_bf16 v[0:3], v[214:217], v[198:201], v[0:3]
	v_mfma_f32_16x16x32_bf16 v[52:55], v[210:213], v[172:175], v[52:55]
	v_mfma_f32_16x16x32_bf16 v[48:51], v[218:221], v[172:175], v[48:51]
	v_mfma_f32_16x16x32_bf16 v[36:39], v[210:213], v[180:183], v[36:39]
	v_mfma_f32_16x16x32_bf16 v[32:35], v[218:221], v[180:183], v[32:35]
	v_mfma_f32_16x16x32_bf16 v[20:23], v[210:213], v[194:197], v[20:23]
	v_mfma_f32_16x16x32_bf16 v[16:19], v[218:221], v[194:197], v[16:19]
	v_mfma_f32_16x16x32_bf16 v[4:7], v[210:213], v[202:205], v[4:7]
	v_mfma_f32_16x16x32_bf16 v[0:3], v[218:221], v[202:205], v[0:3]
	s_setprio 0
	s_add_i32 s79, s79, 2
	s_add_u32 s42, s42, 0x100
	s_addc_u32 s43, s43, 0
	s_add_u32 s35, s35, 0x100
	s_addc_u32 s41, s41, 0
	s_cmp_gt_u32 s79, 5
	s_barrier
	s_cbranch_scc0 .LBB0_984
	s_branch .Lpeel_done_984
.LBB0_984:
	ds_read_b128 v[146:149], v156
	ds_read_b128 v[150:153], v156 offset:1024
	ds_read_b128 v[160:163], v156 offset:2048
	ds_read_b128 v[164:167], v156 offset:3072
	s_add_u32 s0, s42, 0xfffe0080
	s_addc_u32 s1, s43, -1
	s_cmp_eq_u32 s79, 4
	s_cselect_b32 s47, s9, s1
	s_cselect_b32 s46, s31, s0
	s_cselect_b32 s45, s29, s41
	s_cselect_b32 s44, s34, s35
	s_add_i32 m0, s55, 0xc000
	ds_read_b128 v[168:171], v158
	ds_read_b128 v[172:175], v158 offset:1024
	ds_read_b128 v[176:179], v158 offset:2048
	ds_read_b128 v[180:183], v158 offset:3072
	ds_read_b128 v[188:191], v158 offset:4096
	ds_read_b128 v[194:197], v158 offset:5120
	ds_read_b128 v[198:201], v158 offset:6144
	global_load_lds_dwordx4 v138, s[42:43]
	s_add_i32 m0, s55, 0xe000
	ds_read_b128 v[202:205], v158 offset:7168
	global_load_lds_dwordx4 v140, s[42:43]
	s_waitcnt lgkmcnt(8)
	s_barrier
	s_waitcnt lgkmcnt(0)
	s_setprio 1
	v_mfma_f32_16x16x32_bf16 v[124:127], v[146:149], v[168:171], v[124:127]
	v_mfma_f32_16x16x32_bf16 v[120:123], v[160:163], v[168:171], v[120:123]
	v_mfma_f32_16x16x32_bf16 v[108:111], v[146:149], v[176:179], v[108:111]
	v_mfma_f32_16x16x32_bf16 v[104:107], v[160:163], v[176:179], v[104:107]
	v_mfma_f32_16x16x32_bf16 v[92:95], v[146:149], v[188:191], v[92:95]
	v_mfma_f32_16x16x32_bf16 v[88:91], v[160:163], v[188:191], v[88:91]
	v_mfma_f32_16x16x32_bf16 v[76:79], v[146:149], v[198:201], v[76:79]
	v_mfma_f32_16x16x32_bf16 v[72:75], v[160:163], v[198:201], v[72:75]
	v_mfma_f32_16x16x32_bf16 v[124:127], v[150:153], v[172:175], v[124:127]
	v_mfma_f32_16x16x32_bf16 v[120:123], v[164:167], v[172:175], v[120:123]
	v_mfma_f32_16x16x32_bf16 v[108:111], v[150:153], v[180:183], v[108:111]
	v_mfma_f32_16x16x32_bf16 v[104:107], v[164:167], v[180:183], v[104:107]
	v_mfma_f32_16x16x32_bf16 v[92:95], v[150:153], v[194:197], v[92:95]
	v_mfma_f32_16x16x32_bf16 v[88:91], v[164:167], v[194:197], v[88:91]
	v_mfma_f32_16x16x32_bf16 v[76:79], v[150:153], v[202:205], v[76:79]
	v_mfma_f32_16x16x32_bf16 v[72:75], v[164:167], v[202:205], v[72:75]
	s_setprio 0
	s_barrier
	s_add_i32 s0, s66, s50
	s_mov_b32 m0, s0
	ds_read_b128 v[206:209], v159
	ds_read_b128 v[210:213], v159 offset:1024
	ds_read_b128 v[214:217], v159 offset:2048
	global_load_lds_dwordx4 v130, s[44:45]
	s_add_i32 m0, s0, 0x2000
	ds_read_b128 v[218:221], v159 offset:3072
	global_load_lds_dwordx4 v134, s[44:45]
	s_barrier
; #define PG8_STAGE(bufoff, gbase, voff) do { _Pragma("unroll") for (int _i = 0; _i < 2; ++_i) \
;         __builtin_amdgcn_global_load_lds((const unsigned*)((const char*)(gbase) + (voff)[_i]), (LAS unsigned*)(lds + (bufoff) + ldsw + _i * 8192), 16, 0, 0); } while (0)
; #define PG8_LDA(dst, b, h) do { _Pragma("unroll") for (int m = 0; m < 4; ++m) _Pragma("unroll") for (int k = 0; k < 2; ++k) dst[m][k] = *(const LAS bf16x8*)(lds + PG8_SA(b, h) + aoff + m * 2048 + k * 1024); } while (0)
; #define PG8_LDB(dst, b, h) do { _Pragma("unroll") for (int n = 0; n < 2; ++n) _Pragma("unroll") for (int k = 0; k < 2; ++k) dst[n][k] = *(const LAS bf16x8*)(lds + PG8_SB(b, h) + boff + n * 2048 + k * 1024); } while (0)
; #define PG8_MMA(ai, bj, At, Bt) do { __builtin_amdgcn_s_setprio(1); _Pragma("unroll") for (int m = 0; m < 4; ++m) _Pragma("unroll") for (int n = 0; n < 2; ++n) _Pragma("unroll") for (int k = 0; k < 2; ++k) \
;         acc[ai][bj][m][n] = __builtin_amdgcn_mfma_f32_16x16x32_bf16(Bt[n][k], At[m][k], acc[ai][bj][m][n], 0, 0, 0); __builtin_amdgcn_s_setprio(0); } while (0)
; #define PG8_WAIT_V(n) asm volatile("s_waitcnt vmcnt(" #n ")" ::: "memory")
; #define PG8_WAIT_L(n) asm volatile("s_waitcnt lgkmcnt(" #n ")" ::: "memory")
; #define PG8_BAR __builtin_amdgcn_s_barrier()
; #define PG8_SCHED __builtin_amdgcn_sched_barrier(0)
; template <class Epi, class Sched>
; DI void gemm_phase(LAS unsigned char* lds, const Gemm g, const Sched& S, const Epi& E) {
;     ...
;             PG8_BAR; PG8_WAIT_L(0); PG8_MMA(0, 1, At, B1); PG8_BAR;
;             PG8_LDA(At, 0, 1); PG8_STAGE(PG8_SA(0, 0), a2, voffA);
;             PG8_BAR; PG8_WAIT_L(0); PG8_MMA(1, 0, At, B0); PG8_BAR; PG8_SCHED;
;             PG8_STAGE(PG8_SB(0, 1), b2 + hstep, voffB);
;             PG8_WAIT_V(6); PG8_BAR; PG8_MMA(1, 1, At, B1); PG8_BAR;
;             PG8_LDB(B0, 1, 0); PG8_SCHED; PG8_LDA(At, 1, 0); PG8_STAGE(PG8_SA(0, 1), a2 + hstep, voffA);
;             PG8_WAIT_L(8); PG8_BAR; PG8_WAIT_L(0); PG8_MMA(0, 0, At, B0); PG8_BAR; PG8_SCHED;
;             PG8_LDB(B1, 1, 1); PG8_STAGE(PG8_SB(1, 0), b3, voffB);
;             PG8_BAR; PG8_WAIT_L(0); PG8_MMA(0, 1, At, B1); PG8_BAR;
;             PG8_LDA(At, 1, 1); PG8_STAGE(PG8_SA(1, 0), a3, voffA);
	s_waitcnt lgkmcnt(0)
	s_setprio 1
	v_mfma_f32_16x16x32_bf16 v[116:119], v[206:209], v[168:171], v[116:119]
	v_mfma_f32_16x16x32_bf16 v[112:115], v[214:217], v[168:171], v[112:115]
	v_mfma_f32_16x16x32_bf16 v[100:103], v[206:209], v[176:179], v[100:103]
	v_mfma_f32_16x16x32_bf16 v[96:99], v[214:217], v[176:179], v[96:99]
	v_mfma_f32_16x16x32_bf16 v[84:87], v[206:209], v[188:191], v[84:87]
	v_mfma_f32_16x16x32_bf16 v[80:83], v[214:217], v[188:191], v[80:83]
	v_mfma_f32_16x16x32_bf16 v[68:71], v[206:209], v[198:201], v[68:71]
	v_mfma_f32_16x16x32_bf16 v[64:67], v[214:217], v[198:201], v[64:67]
	v_mfma_f32_16x16x32_bf16 v[116:119], v[210:213], v[172:175], v[116:119]
	v_mfma_f32_16x16x32_bf16 v[112:115], v[218:221], v[172:175], v[112:115]
	v_mfma_f32_16x16x32_bf16 v[100:103], v[210:213], v[180:183], v[100:103]
	v_mfma_f32_16x16x32_bf16 v[96:99], v[218:221], v[180:183], v[96:99]
	v_mfma_f32_16x16x32_bf16 v[84:87], v[210:213], v[194:197], v[84:87]
	v_mfma_f32_16x16x32_bf16 v[80:83], v[218:221], v[194:197], v[80:83]
	v_mfma_f32_16x16x32_bf16 v[68:71], v[210:213], v[202:205], v[68:71]
	v_mfma_f32_16x16x32_bf16 v[64:67], v[218:221], v[202:205], v[64:67]
	s_setprio 0
	s_mov_b32 m0, s55
	s_barrier
	ds_read_b128 v[168:171], v158 offset:16384
	ds_read_b128 v[172:175], v158 offset:17408
	ds_read_b128 v[176:179], v158 offset:18432
	ds_read_b128 v[180:183], v158 offset:19456
	ds_read_b128 v[188:191], v158 offset:20480
	ds_read_b128 v[194:197], v158 offset:21504
	ds_read_b128 v[198:201], v158 offset:22528
	global_load_lds_dwordx4 v128, s[46:47]
	s_mov_b32 m0, s56
	ds_read_b128 v[202:205], v158 offset:23552
	global_load_lds_dwordx4 v132, s[46:47]
	s_barrier
	s_waitcnt lgkmcnt(0)
	s_setprio 1
	v_mfma_f32_16x16x32_bf16 v[60:63], v[146:149], v[168:171], v[60:63]
	v_mfma_f32_16x16x32_bf16 v[56:59], v[160:163], v[168:171], v[56:59]
	v_mfma_f32_16x16x32_bf16 v[44:47], v[146:149], v[176:179], v[44:47]
	v_mfma_f32_16x16x32_bf16 v[40:43], v[160:163], v[176:179], v[40:43]
	v_mfma_f32_16x16x32_bf16 v[28:31], v[146:149], v[188:191], v[28:31]
	v_mfma_f32_16x16x32_bf16 v[24:27], v[160:163], v[188:191], v[24:27]
	v_mfma_f32_16x16x32_bf16 v[12:15], v[146:149], v[198:201], v[12:15]
	v_mfma_f32_16x16x32_bf16 v[8:11], v[160:163], v[198:201], v[8:11]
	v_mfma_f32_16x16x32_bf16 v[60:63], v[150:153], v[172:175], v[60:63]
	v_mfma_f32_16x16x32_bf16 v[56:59], v[164:167], v[172:175], v[56:59]
	v_mfma_f32_16x16x32_bf16 v[44:47], v[150:153], v[180:183], v[44:47]
	v_mfma_f32_16x16x32_bf16 v[40:43], v[164:167], v[180:183], v[40:43]
	v_mfma_f32_16x16x32_bf16 v[28:31], v[150:153], v[194:197], v[28:31]
	v_mfma_f32_16x16x32_bf16 v[24:27], v[164:167], v[194:197], v[24:27]
	v_mfma_f32_16x16x32_bf16 v[12:15], v[150:153], v[202:205], v[12:15]
	v_mfma_f32_16x16x32_bf16 v[8:11], v[164:167], v[202:205], v[8:11]
	s_setprio 0
	s_barrier
	s_add_u32 s0, s44, 0x20000
	s_addc_u32 s1, s45, 0
	s_add_i32 s4, s67, s50
	s_mov_b32 m0, s4
	s_nop 0
	global_load_lds_dwordx4 v130, s[0:1]
	s_add_i32 m0, s4, 0x2000
	s_nop 0
	global_load_lds_dwordx4 v134, s[0:1]
	s_waitcnt vmcnt(6)
	s_barrier
	s_setprio 1
	v_mfma_f32_16x16x32_bf16 v[52:55], v[206:209], v[168:171], v[52:55]
	v_mfma_f32_16x16x32_bf16 v[48:51], v[214:217], v[168:171], v[48:51]
	v_mfma_f32_16x16x32_bf16 v[36:39], v[206:209], v[176:179], v[36:39]
	v_mfma_f32_16x16x32_bf16 v[32:35], v[214:217], v[176:179], v[32:35]
	v_mfma_f32_16x16x32_bf16 v[20:23], v[206:209], v[188:191], v[20:23]
	v_mfma_f32_16x16x32_bf16 v[16:19], v[214:217], v[188:191], v[16:19]
	v_mfma_f32_16x16x32_bf16 v[4:7], v[206:209], v[198:201], v[4:7]
	v_mfma_f32_16x16x32_bf16 v[0:3], v[214:217], v[198:201], v[0:3]
	v_mfma_f32_16x16x32_bf16 v[52:55], v[210:213], v[172:175], v[52:55]
	v_mfma_f32_16x16x32_bf16 v[48:51], v[218:221], v[172:175], v[48:51]
	v_mfma_f32_16x16x32_bf16 v[36:39], v[210:213], v[180:183], v[36:39]
	v_mfma_f32_16x16x32_bf16 v[32:35], v[218:221], v[180:183], v[32:35]
	v_mfma_f32_16x16x32_bf16 v[20:23], v[210:213], v[194:197], v[20:23]
	v_mfma_f32_16x16x32_bf16 v[16:19], v[218:221], v[194:197], v[16:19]
	v_mfma_f32_16x16x32_bf16 v[4:7], v[210:213], v[202:205], v[4:7]
	v_mfma_f32_16x16x32_bf16 v[0:3], v[218:221], v[202:205], v[0:3]
	s_setprio 0
	s_add_i32 s4, 0, 0x18000
	v_add_u32_e32 v136, s4, v157
	s_barrier
	ds_read_b128 v[146:149], v136
	ds_read_b128 v[150:153], v136 offset:1024
	ds_read_b128 v[160:163], v136 offset:2048
	ds_read_b128 v[164:167], v136 offset:3072
	s_add_u32 s0, s46, 0x20000
	s_addc_u32 s1, s47, 0
	s_mov_b32 m0, s57
	ds_read_b128 v[168:171], v158 offset:32768
	ds_read_b128 v[172:175], v158 offset:33792
	ds_read_b128 v[176:179], v158 offset:34816
	ds_read_b128 v[180:183], v158 offset:35840
	ds_read_b128 v[188:191], v158 offset:36864
	ds_read_b128 v[194:197], v158 offset:37888
	ds_read_b128 v[198:201], v158 offset:38912
	global_load_lds_dwordx4 v128, s[0:1]
	s_mov_b32 m0, s58
	ds_read_b128 v[202:205], v158 offset:39936
	global_load_lds_dwordx4 v132, s[0:1]
	s_waitcnt lgkmcnt(8)
	s_barrier
; #define PG8_STAGE(bufoff, gbase, voff) do { _Pragma("unroll") for (int _i = 0; _i < 2; ++_i) \
;         __builtin_amdgcn_global_load_lds((const unsigned*)((const char*)(gbase) + (voff)[_i]), (LAS unsigned*)(lds + (bufoff) + ldsw + _i * 8192), 16, 0, 0); } while (0)
; #define PG8_LDA(dst, b, h) do { _Pragma("unroll") for (int m = 0; m < 4; ++m) _Pragma("unroll") for (int k = 0; k < 2; ++k) dst[m][k] = *(const LAS bf16x8*)(lds + PG8_SA(b, h) + aoff + m * 2048 + k * 1024); } while (0)
; #define PG8_LDB(dst, b, h) do { _Pragma("unroll") for (int n = 0; n < 2; ++n) _Pragma("unroll") for (int k = 0; k < 2; ++k) dst[n][k] = *(const LAS bf16x8*)(lds + PG8_SB(b, h) + boff + n * 2048 + k * 1024); } while (0)
; #define PG8_MMA(ai, bj, At, Bt) do { __builtin_amdgcn_s_setprio(1); _Pragma("unroll") for (int m = 0; m < 4; ++m) _Pragma("unroll") for (int n = 0; n < 2; ++n) _Pragma("unroll") for (int k = 0; k < 2; ++k) \
;         acc[ai][bj][m][n] = __builtin_amdgcn_mfma_f32_16x16x32_bf16(Bt[n][k], At[m][k], acc[ai][bj][m][n], 0, 0, 0); __builtin_amdgcn_s_setprio(0); } while (0)
; #define PG8_WAIT_V(n) asm volatile("s_waitcnt vmcnt(" #n ")" ::: "memory")
; #define PG8_WAIT_L(n) asm volatile("s_waitcnt lgkmcnt(" #n ")" ::: "memory")
; #define PG8_BAR __builtin_amdgcn_s_barrier()
; #define PG8_SCHED __builtin_amdgcn_sched_barrier(0)
; template <class Epi, class Sched>
; DI void gemm_phase(LAS unsigned char* lds, const Gemm g, const Sched& S, const Epi& E) {
;     ...
;             PG8_WAIT_L(8); PG8_BAR; PG8_WAIT_L(0); PG8_MMA(0, 0, At, B0); PG8_BAR; PG8_SCHED;
;             PG8_LDB(B1, 1, 1); PG8_STAGE(PG8_SB(1, 0), b3, voffB);
;             PG8_BAR; PG8_WAIT_L(0); PG8_MMA(0, 1, At, B1); PG8_BAR;
;             PG8_LDA(At, 1, 1); PG8_STAGE(PG8_SA(1, 0), a3, voffA);
;             PG8_BAR; PG8_WAIT_L(0); PG8_MMA(1, 0, At, B0); PG8_BAR; PG8_SCHED;
;             PG8_STAGE(PG8_SB(1, 1), b3 + hstep, voffB);
;             PG8_WAIT_V(6); PG8_BAR; PG8_MMA(1, 1, At, B1); PG8_BAR;
	s_waitcnt lgkmcnt(0)
	s_setprio 1
	v_mfma_f32_16x16x32_bf16 v[124:127], v[146:149], v[168:171], v[124:127]
	v_mfma_f32_16x16x32_bf16 v[120:123], v[160:163], v[168:171], v[120:123]
	v_mfma_f32_16x16x32_bf16 v[108:111], v[146:149], v[176:179], v[108:111]
	v_mfma_f32_16x16x32_bf16 v[104:107], v[160:163], v[176:179], v[104:107]
	v_mfma_f32_16x16x32_bf16 v[92:95], v[146:149], v[188:191], v[92:95]
	v_mfma_f32_16x16x32_bf16 v[88:91], v[160:163], v[188:191], v[88:91]
	v_mfma_f32_16x16x32_bf16 v[76:79], v[146:149], v[198:201], v[76:79]
	v_mfma_f32_16x16x32_bf16 v[72:75], v[160:163], v[198:201], v[72:75]
	v_mfma_f32_16x16x32_bf16 v[124:127], v[150:153], v[172:175], v[124:127]
	v_mfma_f32_16x16x32_bf16 v[120:123], v[164:167], v[172:175], v[120:123]
	v_mfma_f32_16x16x32_bf16 v[108:111], v[150:153], v[180:183], v[108:111]
	v_mfma_f32_16x16x32_bf16 v[104:107], v[164:167], v[180:183], v[104:107]
	v_mfma_f32_16x16x32_bf16 v[92:95], v[150:153], v[194:197], v[92:95]
	v_mfma_f32_16x16x32_bf16 v[88:91], v[164:167], v[194:197], v[88:91]
	v_mfma_f32_16x16x32_bf16 v[76:79], v[150:153], v[202:205], v[76:79]
	v_mfma_f32_16x16x32_bf16 v[72:75], v[164:167], v[202:205], v[72:75]
	s_setprio 0
	s_barrier
	s_add_i32 s5, 0, 0x1c000
	s_add_i32 s0, s4, s50
	v_add_u32_e32 v136, s5, v157
	s_add_i32 m0, s0, 0xffffff80
	ds_read_b128 v[206:209], v136
	ds_read_b128 v[210:213], v136 offset:1024
	ds_read_b128 v[214:217], v136 offset:2048
	global_load_lds_dwordx4 v130, s[44:45] offset:128
	s_add_i32 m0, s0, 0x1f80
	ds_read_b128 v[218:221], v136 offset:3072
	global_load_lds_dwordx4 v134, s[44:45] offset:128
	s_barrier
	s_waitcnt lgkmcnt(0)
	s_setprio 1
	v_mfma_f32_16x16x32_bf16 v[116:119], v[206:209], v[168:171], v[116:119]
	v_mfma_f32_16x16x32_bf16 v[112:115], v[214:217], v[168:171], v[112:115]
	v_mfma_f32_16x16x32_bf16 v[100:103], v[206:209], v[176:179], v[100:103]
	v_mfma_f32_16x16x32_bf16 v[96:99], v[214:217], v[176:179], v[96:99]
	v_mfma_f32_16x16x32_bf16 v[84:87], v[206:209], v[188:191], v[84:87]
	v_mfma_f32_16x16x32_bf16 v[80:83], v[214:217], v[188:191], v[80:83]
	v_mfma_f32_16x16x32_bf16 v[68:71], v[206:209], v[198:201], v[68:71]
	v_mfma_f32_16x16x32_bf16 v[64:67], v[214:217], v[198:201], v[64:67]
	v_mfma_f32_16x16x32_bf16 v[116:119], v[210:213], v[172:175], v[116:119]
	v_mfma_f32_16x16x32_bf16 v[112:115], v[218:221], v[172:175], v[112:115]
	v_mfma_f32_16x16x32_bf16 v[100:103], v[210:213], v[180:183], v[100:103]
	v_mfma_f32_16x16x32_bf16 v[96:99], v[218:221], v[180:183], v[96:99]
	v_mfma_f32_16x16x32_bf16 v[84:87], v[210:213], v[194:197], v[84:87]
	v_mfma_f32_16x16x32_bf16 v[80:83], v[218:221], v[194:197], v[80:83]
	v_mfma_f32_16x16x32_bf16 v[68:71], v[210:213], v[202:205], v[68:71]
	v_mfma_f32_16x16x32_bf16 v[64:67], v[218:221], v[202:205], v[64:67]
	s_setprio 0
	s_add_i32 m0, s62, 0xffffff80
	s_barrier
	ds_read_b128 v[168:171], v158 offset:49152
	ds_read_b128 v[172:175], v158 offset:50176
	ds_read_b128 v[176:179], v158 offset:51200
	ds_read_b128 v[180:183], v158 offset:52224
	ds_read_b128 v[188:191], v158 offset:53248
	ds_read_b128 v[194:197], v158 offset:54272
	ds_read_b128 v[198:201], v158 offset:55296
	global_load_lds_dwordx4 v128, s[46:47] offset:128
	s_add_i32 m0, s63, 0xffffff80
	ds_read_b128 v[202:205], v158 offset:56320
	global_load_lds_dwordx4 v132, s[46:47] offset:128
	s_barrier
	s_waitcnt lgkmcnt(0)
	s_setprio 1
	v_mfma_f32_16x16x32_bf16 v[60:63], v[146:149], v[168:171], v[60:63]
	v_mfma_f32_16x16x32_bf16 v[56:59], v[160:163], v[168:171], v[56:59]
	v_mfma_f32_16x16x32_bf16 v[44:47], v[146:149], v[176:179], v[44:47]
	v_mfma_f32_16x16x32_bf16 v[40:43], v[160:163], v[176:179], v[40:43]
	v_mfma_f32_16x16x32_bf16 v[28:31], v[146:149], v[188:191], v[28:31]
	v_mfma_f32_16x16x32_bf16 v[24:27], v[160:163], v[188:191], v[24:27]
	v_mfma_f32_16x16x32_bf16 v[12:15], v[146:149], v[198:201], v[12:15]
	v_mfma_f32_16x16x32_bf16 v[8:11], v[160:163], v[198:201], v[8:11]
	v_mfma_f32_16x16x32_bf16 v[60:63], v[150:153], v[172:175], v[60:63]
	v_mfma_f32_16x16x32_bf16 v[56:59], v[164:167], v[172:175], v[56:59]
	v_mfma_f32_16x16x32_bf16 v[44:47], v[150:153], v[180:183], v[44:47]
	v_mfma_f32_16x16x32_bf16 v[40:43], v[164:167], v[180:183], v[40:43]
	v_mfma_f32_16x16x32_bf16 v[28:31], v[150:153], v[194:197], v[28:31]
	v_mfma_f32_16x16x32_bf16 v[24:27], v[164:167], v[194:197], v[24:27]
	v_mfma_f32_16x16x32_bf16 v[12:15], v[150:153], v[202:205], v[12:15]
	v_mfma_f32_16x16x32_bf16 v[8:11], v[164:167], v[202:205], v[8:11]
	s_setprio 0
	s_barrier
	s_add_u32 s0, s44, 0x20080
	s_addc_u32 s1, s45, 0
	s_add_i32 s4, s5, s50
	s_mov_b32 m0, s4
	s_nop 0
	global_load_lds_dwordx4 v130, s[0:1]
	v_lshl_add_u64 v[146:147], s[0:1], 0, v[134:135]
	s_add_i32 m0, s4, 0x2000
	s_nop 0
	global_load_lds_dwordx4 v134, s[0:1]
	s_waitcnt vmcnt(6)
	s_barrier
	s_setprio 1
	v_mfma_f32_16x16x32_bf16 v[52:55], v[206:209], v[168:171], v[52:55]
	v_mfma_f32_16x16x32_bf16 v[48:51], v[214:217], v[168:171], v[48:51]
	v_mfma_f32_16x16x32_bf16 v[36:39], v[206:209], v[176:179], v[36:39]
	v_mfma_f32_16x16x32_bf16 v[32:35], v[214:217], v[176:179], v[32:35]
	v_mfma_f32_16x16x32_bf16 v[20:23], v[206:209], v[188:191], v[20:23]
	v_mfma_f32_16x16x32_bf16 v[16:19], v[214:217], v[188:191], v[16:19]
	v_mfma_f32_16x16x32_bf16 v[4:7], v[206:209], v[198:201], v[4:7]
	v_mfma_f32_16x16x32_bf16 v[0:3], v[214:217], v[198:201], v[0:3]
	v_mfma_f32_16x16x32_bf16 v[52:55], v[210:213], v[172:175], v[52:55]
	v_mfma_f32_16x16x32_bf16 v[48:51], v[218:221], v[172:175], v[48:51]
	v_mfma_f32_16x16x32_bf16 v[36:39], v[210:213], v[180:183], v[36:39]
	v_mfma_f32_16x16x32_bf16 v[32:35], v[218:221], v[180:183], v[32:35]
	v_mfma_f32_16x16x32_bf16 v[20:23], v[210:213], v[194:197], v[20:23]
	v_mfma_f32_16x16x32_bf16 v[16:19], v[218:221], v[194:197], v[16:19]
	v_mfma_f32_16x16x32_bf16 v[4:7], v[210:213], v[202:205], v[4:7]
	v_mfma_f32_16x16x32_bf16 v[0:3], v[218:221], v[202:205], v[0:3]
	s_setprio 0
	s_add_i32 s79, s79, 2
	s_add_u32 s42, s42, 0x100
	s_addc_u32 s43, s43, 0
	s_add_u32 s35, s35, 0x100
	s_addc_u32 s41, s41, 0
	s_cmp_gt_u32 s79, 5
	s_barrier
	s_cbranch_scc0 .LBB0_984

; #define PG8_STAGE(bufoff, gbase, voff) do { _Pragma("unroll") for (int _i = 0; _i < 2; ++_i) \
;         __builtin_amdgcn_global_load_lds((const unsigned*)((const char*)(gbase) + (voff)[_i]), (LAS unsigned*)(lds + (bufoff) + ldsw + _i * 8192), 16, 0, 0); } while (0)
; #define PG8_LDA(dst, b, h) do { _Pragma("unroll") for (int m = 0; m < 4; ++m) _Pragma("unroll") for (int k = 0; k < 2; ++k) dst[m][k] = *(const LAS bf16x8*)(lds + PG8_SA(b, h) + aoff + m * 2048 + k * 1024); } while (0)
; #define PG8_LDB(dst, b, h) do { _Pragma("unroll") for (int n = 0; n < 2; ++n) _Pragma("unroll") for (int k = 0; k < 2; ++k) dst[n][k] = *(const LAS bf16x8*)(lds + PG8_SB(b, h) + boff + n * 2048 + k * 1024); } while (0)
; #define PG8_MMA(ai, bj, At, Bt) do { __builtin_amdgcn_s_setprio(1); _Pragma("unroll") for (int m = 0; m < 4; ++m) _Pragma("unroll") for (int n = 0; n < 2; ++n) _Pragma("unroll") for (int k = 0; k < 2; ++k) \
;         acc[ai][bj][m][n] = __builtin_amdgcn_mfma_f32_16x16x32_bf16(Bt[n][k], At[m][k], acc[ai][bj][m][n], 0, 0, 0); __builtin_amdgcn_s_setprio(0); } while (0)
; #define PG8_WAIT_L(n) asm volatile("s_waitcnt lgkmcnt(" #n ")" ::: "memory")
; #define PG8_BAR __builtin_amdgcn_s_barrier()
; #define PG8_SCHED __builtin_amdgcn_sched_barrier(0)
; template <class Epi, class Sched>
; DI void gemm_phase(LAS unsigned char* lds, const Gemm g, const Sched& S, const Epi& E) {
;     ...
;             const bool last = (t == nt - 2);
;             const char* a1 = cA + (size_t)(t + 1) * kstep;
;             const char* a2 = last ? nA : cA + (size_t)(t + 2) * kstep; const char* b2 = last ? nB : cB + (size_t)(t + 2) * kstep;
;             const char* a3 = a2 + kstep; const char* b3 = b2 + kstep;
;             PG8_LDB(B0, 0, 0); PG8_SCHED; PG8_LDA(At, 0, 0); PG8_STAGE(PG8_SA(1, 1), a1 + hstep, voffA);
;             PG8_WAIT_L(8); PG8_BAR; PG8_WAIT_L(0); PG8_MMA(0, 0, At, B0); PG8_BAR; PG8_SCHED;
;             PG8_LDB(B1, 0, 1); PG8_STAGE(PG8_SB(0, 0), b2, voffB);
;             PG8_BAR; PG8_WAIT_L(0); PG8_MMA(0, 1, At, B1); PG8_BAR;
;             PG8_LDA(At, 0, 1); PG8_STAGE(PG8_SA(0, 0), a2, voffA);
;             PG8_BAR; PG8_WAIT_L(0); PG8_MMA(1, 0, At, B0); PG8_BAR; PG8_SCHED;
.LBB0_1347:
	v_add_u32_e32 v1, s63, v202
	s_add_u32 s0, s40, s44
	ds_read_b128 v[132:135], v1
	ds_read_b128 v[136:139], v1 offset:1024
	ds_read_b128 v[140:143], v1 offset:2048
	ds_read_b128 v[144:147], v1 offset:3072
	s_addc_u32 s1, s41, s45
	s_add_u32 s0, s0, 0x100
	s_addc_u32 s1, s1, 0
	s_add_u32 s4, s79, s44
	s_addc_u32 s5, s80, s45
	s_cmpk_eq_i32 s44, 0xf00
	s_cselect_b32 s49, s70, s1
	s_cselect_b32 s48, s71, s0
	s_cselect_b32 s47, s37, s5
	s_cselect_b32 s46, s36, s4
	v_lshl_add_u64 v[2:3], v[188:189], 0, s[44:45]
	s_add_i32 m0, s53, 0xc000
	ds_read_b128 v[148:151], v203
	ds_read_b128 v[152:155], v203 offset:1024
	ds_read_b128 v[156:159], v203 offset:2048
	ds_read_b128 v[160:163], v203 offset:3072
	ds_read_b128 v[164:167], v203 offset:4096
	ds_read_b128 v[208:211], v203 offset:5120
	ds_read_b128 v[212:215], v203 offset:6144
	ds_read_b128 v[216:219], v203 offset:7168
	global_load_lds_dwordx4 v[2:3], off
	v_lshl_add_u64 v[2:3], v[190:191], 0, s[44:45]
	s_add_i32 m0, s53, 0xe000
	s_nop 0
	global_load_lds_dwordx4 v[2:3], off
	s_waitcnt lgkmcnt(8)
	s_barrier
	s_waitcnt lgkmcnt(0)
	s_setprio 1
	v_mfma_f32_16x16x32_bf16 v[128:131], v[132:135], v[148:151], v[128:131]
	v_mfma_f32_16x16x32_bf16 v[124:127], v[140:143], v[148:151], v[124:127]
	v_mfma_f32_16x16x32_bf16 v[112:115], v[132:135], v[156:159], v[112:115]
	v_mfma_f32_16x16x32_bf16 v[108:111], v[140:143], v[156:159], v[108:111]
	v_mfma_f32_16x16x32_bf16 v[96:99], v[132:135], v[164:167], v[96:99]
	v_mfma_f32_16x16x32_bf16 v[92:95], v[140:143], v[164:167], v[92:95]
	v_mfma_f32_16x16x32_bf16 v[80:83], v[132:135], v[212:215], v[80:83]
	v_mfma_f32_16x16x32_bf16 v[76:79], v[140:143], v[212:215], v[76:79]
	v_mfma_f32_16x16x32_bf16 v[128:131], v[136:139], v[152:155], v[128:131]
	v_mfma_f32_16x16x32_bf16 v[124:127], v[144:147], v[152:155], v[124:127]
	v_mfma_f32_16x16x32_bf16 v[112:115], v[136:139], v[160:163], v[112:115]
	v_mfma_f32_16x16x32_bf16 v[108:111], v[144:147], v[160:163], v[108:111]
	v_mfma_f32_16x16x32_bf16 v[96:99], v[136:139], v[208:211], v[96:99]
	v_mfma_f32_16x16x32_bf16 v[92:95], v[144:147], v[208:211], v[92:95]
	v_mfma_f32_16x16x32_bf16 v[80:83], v[136:139], v[216:219], v[80:83]
	v_mfma_f32_16x16x32_bf16 v[76:79], v[144:147], v[216:219], v[76:79]
	s_setprio 0
	s_barrier
	s_add_i32 s0, s63, s51
	v_add_u32_e32 v1, s64, v202
	s_mov_b32 m0, s0
	ds_read_b128 v[220:223], v1
	ds_read_b128 v[224:227], v1 offset:1024
	ds_read_b128 v[228:231], v1 offset:2048
	global_load_lds_dwordx4 v172, s[46:47]
	s_add_i32 m0, s0, 0x2000
	ds_read_b128 v[232:235], v1 offset:3072
	global_load_lds_dwordx4 v174, s[46:47]
	s_barrier
	s_waitcnt lgkmcnt(0)
	s_setprio 1
	v_mfma_f32_16x16x32_bf16 v[120:123], v[220:223], v[148:151], v[120:123]
	v_mfma_f32_16x16x32_bf16 v[116:119], v[228:231], v[148:151], v[116:119]
	v_mfma_f32_16x16x32_bf16 v[104:107], v[220:223], v[156:159], v[104:107]
	v_mfma_f32_16x16x32_bf16 v[100:103], v[228:231], v[156:159], v[100:103]
	v_mfma_f32_16x16x32_bf16 v[88:91], v[220:223], v[164:167], v[88:91]
	v_mfma_f32_16x16x32_bf16 v[84:87], v[228:231], v[164:167], v[84:87]
	v_mfma_f32_16x16x32_bf16 v[72:75], v[220:223], v[212:215], v[72:75]
	v_mfma_f32_16x16x32_bf16 v[68:71], v[228:231], v[212:215], v[68:71]
	v_mfma_f32_16x16x32_bf16 v[120:123], v[224:227], v[152:155], v[120:123]
	v_mfma_f32_16x16x32_bf16 v[116:119], v[232:235], v[152:155], v[116:119]
	v_mfma_f32_16x16x32_bf16 v[104:107], v[224:227], v[160:163], v[104:107]
	v_mfma_f32_16x16x32_bf16 v[100:103], v[232:235], v[160:163], v[100:103]
	v_mfma_f32_16x16x32_bf16 v[88:91], v[224:227], v[208:211], v[88:91]
	v_mfma_f32_16x16x32_bf16 v[84:87], v[232:235], v[208:211], v[84:87]
	v_mfma_f32_16x16x32_bf16 v[72:75], v[224:227], v[216:219], v[72:75]
	v_mfma_f32_16x16x32_bf16 v[68:71], v[232:235], v[216:219], v[68:71]
	s_setprio 0
	s_mov_b32 m0, s53
	s_barrier
	ds_read_b128 v[148:151], v203 offset:16384
	ds_read_b128 v[152:155], v203 offset:17408
	ds_read_b128 v[156:159], v203 offset:18432
	ds_read_b128 v[160:163], v203 offset:19456
	ds_read_b128 v[164:167], v203 offset:20480
	ds_read_b128 v[208:211], v203 offset:21504
	ds_read_b128 v[212:215], v203 offset:22528
	global_load_lds_dwordx4 v168, s[48:49]
	s_mov_b32 m0, s54
	ds_read_b128 v[216:219], v203 offset:23552
	global_load_lds_dwordx4 v170, s[48:49]
	s_barrier
	s_waitcnt lgkmcnt(0)
	s_setprio 1
	v_mfma_f32_16x16x32_bf16 v[64:67], v[132:135], v[148:151], v[64:67]
	v_mfma_f32_16x16x32_bf16 v[60:63], v[140:143], v[148:151], v[60:63]
	v_mfma_f32_16x16x32_bf16 v[48:51], v[132:135], v[156:159], v[48:51]
	v_mfma_f32_16x16x32_bf16 v[44:47], v[140:143], v[156:159], v[44:47]
	v_mfma_f32_16x16x32_bf16 v[32:35], v[132:135], v[164:167], v[32:35]
	v_mfma_f32_16x16x32_bf16 v[28:31], v[140:143], v[164:167], v[28:31]
	v_mfma_f32_16x16x32_bf16 v[16:19], v[132:135], v[212:215], v[16:19]
	v_mfma_f32_16x16x32_bf16 v[12:15], v[140:143], v[212:215], v[12:15]
	v_mfma_f32_16x16x32_bf16 v[64:67], v[136:139], v[152:155], v[64:67]
	v_mfma_f32_16x16x32_bf16 v[60:63], v[144:147], v[152:155], v[60:63]
	v_mfma_f32_16x16x32_bf16 v[48:51], v[136:139], v[160:163], v[48:51]
	v_mfma_f32_16x16x32_bf16 v[44:47], v[144:147], v[160:163], v[44:47]
	v_mfma_f32_16x16x32_bf16 v[32:35], v[136:139], v[208:211], v[32:35]
	v_mfma_f32_16x16x32_bf16 v[28:31], v[144:147], v[208:211], v[28:31]
	v_mfma_f32_16x16x32_bf16 v[16:19], v[136:139], v[216:219], v[16:19]
	v_mfma_f32_16x16x32_bf16 v[12:15], v[144:147], v[216:219], v[12:15]
	s_setprio 0
	s_barrier
	s_add_u32 s0, s46, 0x80000
	s_addc_u32 s1, s47, 0
	s_add_i32 s4, s64, s51
	s_mov_b32 m0, s4
	s_nop 0
	global_load_lds_dwordx4 v172, s[0:1]
	s_add_i32 m0, s4, 0x2000
	s_nop 0
	global_load_lds_dwordx4 v174, s[0:1]
	s_waitcnt vmcnt(6)
	s_barrier
; #define PG8_STAGE(bufoff, gbase, voff) do { _Pragma("unroll") for (int _i = 0; _i < 2; ++_i) \
;         __builtin_amdgcn_global_load_lds((const unsigned*)((const char*)(gbase) + (voff)[_i]), (LAS unsigned*)(lds + (bufoff) + ldsw + _i * 8192), 16, 0, 0); } while (0)
; #define PG8_LDA(dst, b, h) do { _Pragma("unroll") for (int m = 0; m < 4; ++m) _Pragma("unroll") for (int k = 0; k < 2; ++k) dst[m][k] = *(const LAS bf16x8*)(lds + PG8_SA(b, h) + aoff + m * 2048 + k * 1024); } while (0)
; #define PG8_LDB(dst, b, h) do { _Pragma("unroll") for (int n = 0; n < 2; ++n) _Pragma("unroll") for (int k = 0; k < 2; ++k) dst[n][k] = *(const LAS bf16x8*)(lds + PG8_SB(b, h) + boff + n * 2048 + k * 1024); } while (0)
; #define PG8_MMA(ai, bj, At, Bt) do { __builtin_amdgcn_s_setprio(1); _Pragma("unroll") for (int m = 0; m < 4; ++m) _Pragma("unroll") for (int n = 0; n < 2; ++n) _Pragma("unroll") for (int k = 0; k < 2; ++k) \
;         acc[ai][bj][m][n] = __builtin_amdgcn_mfma_f32_16x16x32_bf16(Bt[n][k], At[m][k], acc[ai][bj][m][n], 0, 0, 0); __builtin_amdgcn_s_setprio(0); } while (0)
; #define PG8_WAIT_V(n) asm volatile("s_waitcnt vmcnt(" #n ")" ::: "memory")
; #define PG8_WAIT_L(n) asm volatile("s_waitcnt lgkmcnt(" #n ")" ::: "memory")
; #define PG8_BAR __builtin_amdgcn_s_barrier()
; #define PG8_SCHED __builtin_amdgcn_sched_barrier(0)
; template <class Epi, class Sched>
; DI void gemm_phase(LAS unsigned char* lds, const Gemm g, const Sched& S, const Epi& E) {
;     ...
;             PG8_WAIT_V(6); PG8_BAR; PG8_MMA(1, 1, At, B1); PG8_BAR;
;             PG8_LDB(B0, 1, 0); PG8_SCHED; PG8_LDA(At, 1, 0); PG8_STAGE(PG8_SA(0, 1), a2 + hstep, voffA);
;             PG8_WAIT_L(8); PG8_BAR; PG8_WAIT_L(0); PG8_MMA(0, 0, At, B0); PG8_BAR; PG8_SCHED;
;             PG8_LDB(B1, 1, 1); PG8_STAGE(PG8_SB(1, 0), b3, voffB);
;             PG8_BAR; PG8_WAIT_L(0); PG8_MMA(0, 1, At, B1); PG8_BAR;
;             PG8_LDA(At, 1, 1); PG8_STAGE(PG8_SA(1, 0), a3, voffA);
;             PG8_BAR; PG8_WAIT_L(0); PG8_MMA(1, 0, At, B0); PG8_BAR; PG8_SCHED;
	s_setprio 1
	v_mfma_f32_16x16x32_bf16 v[56:59], v[220:223], v[148:151], v[56:59]
	v_mfma_f32_16x16x32_bf16 v[52:55], v[228:231], v[148:151], v[52:55]
	v_mfma_f32_16x16x32_bf16 v[40:43], v[220:223], v[156:159], v[40:43]
	v_mfma_f32_16x16x32_bf16 v[36:39], v[228:231], v[156:159], v[36:39]
	v_mfma_f32_16x16x32_bf16 v[24:27], v[220:223], v[164:167], v[24:27]
	v_mfma_f32_16x16x32_bf16 v[20:23], v[228:231], v[164:167], v[20:23]
	v_mfma_f32_16x16x32_bf16 v[8:11], v[220:223], v[212:215], v[8:11]
	v_mfma_f32_16x16x32_bf16 v[2:5], v[228:231], v[212:215], v[4:7]
	v_mfma_f32_16x16x32_bf16 v[56:59], v[224:227], v[152:155], v[56:59]
	v_mfma_f32_16x16x32_bf16 v[52:55], v[232:235], v[152:155], v[52:55]
	v_mfma_f32_16x16x32_bf16 v[40:43], v[224:227], v[160:163], v[40:43]
	v_mfma_f32_16x16x32_bf16 v[36:39], v[232:235], v[160:163], v[36:39]
	v_mfma_f32_16x16x32_bf16 v[24:27], v[224:227], v[208:211], v[24:27]
	v_mfma_f32_16x16x32_bf16 v[20:23], v[232:235], v[208:211], v[20:23]
	v_mfma_f32_16x16x32_bf16 v[8:11], v[224:227], v[216:219], v[8:11]
	v_mfma_f32_16x16x32_bf16 v[2:5], v[232:235], v[216:219], v[2:5]
	s_setprio 0
	s_add_i32 s4, 0, 0x18000
	v_add_u32_e32 v1, s4, v202
	s_barrier
	ds_read_b128 v[132:135], v1
	ds_read_b128 v[136:139], v1 offset:1024
	ds_read_b128 v[140:143], v1 offset:2048
	ds_read_b128 v[144:147], v1 offset:3072
	s_add_u32 s0, s48, 0x80000
	s_addc_u32 s1, s49, 0
	s_mov_b32 m0, s55
	ds_read_b128 v[148:151], v203 offset:32768
	ds_read_b128 v[152:155], v203 offset:33792
	ds_read_b128 v[156:159], v203 offset:34816
	ds_read_b128 v[160:163], v203 offset:35840
	ds_read_b128 v[164:167], v203 offset:36864
	ds_read_b128 v[208:211], v203 offset:37888
	ds_read_b128 v[212:215], v203 offset:38912
	global_load_lds_dwordx4 v168, s[0:1]
	s_mov_b32 m0, s56
	ds_read_b128 v[216:219], v203 offset:39936
	global_load_lds_dwordx4 v170, s[0:1]
	s_waitcnt lgkmcnt(8)
	s_barrier
	s_waitcnt lgkmcnt(0)
	s_setprio 1
	v_mfma_f32_16x16x32_bf16 v[128:131], v[132:135], v[148:151], v[128:131]
	v_mfma_f32_16x16x32_bf16 v[124:127], v[140:143], v[148:151], v[124:127]
	v_mfma_f32_16x16x32_bf16 v[112:115], v[132:135], v[156:159], v[112:115]
	v_mfma_f32_16x16x32_bf16 v[108:111], v[140:143], v[156:159], v[108:111]
	v_mfma_f32_16x16x32_bf16 v[96:99], v[132:135], v[164:167], v[96:99]
	v_mfma_f32_16x16x32_bf16 v[92:95], v[140:143], v[164:167], v[92:95]
	v_mfma_f32_16x16x32_bf16 v[80:83], v[132:135], v[212:215], v[80:83]
	v_mfma_f32_16x16x32_bf16 v[76:79], v[140:143], v[212:215], v[76:79]
	v_mfma_f32_16x16x32_bf16 v[128:131], v[136:139], v[152:155], v[128:131]
	v_mfma_f32_16x16x32_bf16 v[124:127], v[144:147], v[152:155], v[124:127]
	v_mfma_f32_16x16x32_bf16 v[112:115], v[136:139], v[160:163], v[112:115]
	v_mfma_f32_16x16x32_bf16 v[108:111], v[144:147], v[160:163], v[108:111]
	v_mfma_f32_16x16x32_bf16 v[96:99], v[136:139], v[208:211], v[96:99]
	v_mfma_f32_16x16x32_bf16 v[92:95], v[144:147], v[208:211], v[92:95]
	v_mfma_f32_16x16x32_bf16 v[80:83], v[136:139], v[216:219], v[80:83]
	v_mfma_f32_16x16x32_bf16 v[76:79], v[144:147], v[216:219], v[76:79]
	s_setprio 0
	s_barrier
	s_add_i32 s5, 0, 0x1c000
	s_add_i32 s0, s4, s51
	v_add_u32_e32 v1, s5, v202
	s_add_i32 m0, s0, 0xffffff80
	ds_read_b128 v[220:223], v1
	ds_read_b128 v[224:227], v1 offset:1024
	ds_read_b128 v[228:231], v1 offset:2048
	global_load_lds_dwordx4 v172, s[46:47] offset:128
	s_add_i32 m0, s0, 0x1f80
	ds_read_b128 v[232:235], v1 offset:3072
	global_load_lds_dwordx4 v174, s[46:47] offset:128
	s_barrier
; #define PG8_STAGE(bufoff, gbase, voff) do { _Pragma("unroll") for (int _i = 0; _i < 2; ++_i) \
;         __builtin_amdgcn_global_load_lds((const unsigned*)((const char*)(gbase) + (voff)[_i]), (LAS unsigned*)(lds + (bufoff) + ldsw + _i * 8192), 16, 0, 0); } while (0)
; #define PG8_MMA(ai, bj, At, Bt) do { __builtin_amdgcn_s_setprio(1); _Pragma("unroll") for (int m = 0; m < 4; ++m) _Pragma("unroll") for (int n = 0; n < 2; ++n) _Pragma("unroll") for (int k = 0; k < 2; ++k) \
;         acc[ai][bj][m][n] = __builtin_amdgcn_mfma_f32_16x16x32_bf16(Bt[n][k], At[m][k], acc[ai][bj][m][n], 0, 0, 0); __builtin_amdgcn_s_setprio(0); } while (0)
; #define PG8_WAIT_V(n) asm volatile("s_waitcnt vmcnt(" #n ")" ::: "memory")
; #define PG8_WAIT_L(n) asm volatile("s_waitcnt lgkmcnt(" #n ")" ::: "memory")
; #define PG8_BAR __builtin_amdgcn_s_barrier()
; #define PG8_SCHED __builtin_amdgcn_sched_barrier(0)
; template <class Epi, class Sched>
; DI void gemm_phase(LAS unsigned char* lds, const Gemm g, const Sched& S, const Epi& E) {
;     ...
;             PG8_BAR; PG8_WAIT_L(0); PG8_MMA(1, 0, At, B0); PG8_BAR; PG8_SCHED;
;             PG8_STAGE(PG8_SB(1, 1), b3 + hstep, voffB);
;             PG8_WAIT_V(6); PG8_BAR; PG8_MMA(1, 1, At, B1); PG8_BAR;
	s_waitcnt lgkmcnt(0)
	s_setprio 1
	v_mfma_f32_16x16x32_bf16 v[120:123], v[220:223], v[148:151], v[120:123]
	v_mfma_f32_16x16x32_bf16 v[116:119], v[228:231], v[148:151], v[116:119]
	v_mfma_f32_16x16x32_bf16 v[104:107], v[220:223], v[156:159], v[104:107]
	v_mfma_f32_16x16x32_bf16 v[100:103], v[228:231], v[156:159], v[100:103]
	v_mfma_f32_16x16x32_bf16 v[88:91], v[220:223], v[164:167], v[88:91]
	v_mfma_f32_16x16x32_bf16 v[84:87], v[228:231], v[164:167], v[84:87]
	v_mfma_f32_16x16x32_bf16 v[72:75], v[220:223], v[212:215], v[72:75]
	v_mfma_f32_16x16x32_bf16 v[68:71], v[228:231], v[212:215], v[68:71]
	v_mfma_f32_16x16x32_bf16 v[120:123], v[224:227], v[152:155], v[120:123]
	v_mfma_f32_16x16x32_bf16 v[116:119], v[232:235], v[152:155], v[116:119]
	v_mfma_f32_16x16x32_bf16 v[104:107], v[224:227], v[160:163], v[104:107]
	v_mfma_f32_16x16x32_bf16 v[100:103], v[232:235], v[160:163], v[100:103]
	v_mfma_f32_16x16x32_bf16 v[88:91], v[224:227], v[208:211], v[88:91]
	v_mfma_f32_16x16x32_bf16 v[84:87], v[232:235], v[208:211], v[84:87]
	v_mfma_f32_16x16x32_bf16 v[72:75], v[224:227], v[216:219], v[72:75]
	v_mfma_f32_16x16x32_bf16 v[68:71], v[232:235], v[216:219], v[68:71]
	s_setprio 0
	s_add_i32 m0, s59, 0xffffff80
	s_barrier
	ds_read_b128 v[148:151], v203 offset:49152
	ds_read_b128 v[152:155], v203 offset:50176
	ds_read_b128 v[156:159], v203 offset:51200
	ds_read_b128 v[160:163], v203 offset:52224
	ds_read_b128 v[164:167], v203 offset:53248
	ds_read_b128 v[208:211], v203 offset:54272
	ds_read_b128 v[212:215], v203 offset:55296
	global_load_lds_dwordx4 v168, s[48:49] offset:128
	s_add_i32 m0, s60, 0xffffff80
	ds_read_b128 v[216:219], v203 offset:56320
	global_load_lds_dwordx4 v170, s[48:49] offset:128
	s_barrier
	s_waitcnt lgkmcnt(0)
	s_setprio 1
	v_mfma_f32_16x16x32_bf16 v[64:67], v[132:135], v[148:151], v[64:67]
	v_mfma_f32_16x16x32_bf16 v[60:63], v[140:143], v[148:151], v[60:63]
	v_mfma_f32_16x16x32_bf16 v[48:51], v[132:135], v[156:159], v[48:51]
	v_mfma_f32_16x16x32_bf16 v[44:47], v[140:143], v[156:159], v[44:47]
	v_mfma_f32_16x16x32_bf16 v[32:35], v[132:135], v[164:167], v[32:35]
	v_mfma_f32_16x16x32_bf16 v[28:31], v[140:143], v[164:167], v[28:31]
	v_mfma_f32_16x16x32_bf16 v[16:19], v[132:135], v[212:215], v[16:19]
	v_mfma_f32_16x16x32_bf16 v[12:15], v[140:143], v[212:215], v[12:15]
	v_mfma_f32_16x16x32_bf16 v[64:67], v[136:139], v[152:155], v[64:67]
	v_mfma_f32_16x16x32_bf16 v[60:63], v[144:147], v[152:155], v[60:63]
	v_mfma_f32_16x16x32_bf16 v[48:51], v[136:139], v[160:163], v[48:51]
	v_mfma_f32_16x16x32_bf16 v[44:47], v[144:147], v[160:163], v[44:47]
	v_mfma_f32_16x16x32_bf16 v[32:35], v[136:139], v[208:211], v[32:35]
	v_mfma_f32_16x16x32_bf16 v[28:31], v[144:147], v[208:211], v[28:31]
	v_mfma_f32_16x16x32_bf16 v[16:19], v[136:139], v[216:219], v[16:19]
	v_mfma_f32_16x16x32_bf16 v[12:15], v[144:147], v[216:219], v[12:15]
	s_setprio 0
	s_barrier
	s_add_u32 s0, s46, 0x80080
	s_addc_u32 s1, s47, 0
	s_add_i32 s4, s5, s51
	s_mov_b32 m0, s4
	s_nop 0
	global_load_lds_dwordx4 v172, s[0:1]
	s_add_i32 m0, s4, 0x2000
	s_nop 0
	global_load_lds_dwordx4 v174, s[0:1]
	s_waitcnt vmcnt(6)
	s_barrier
	s_setprio 1
	v_mfma_f32_16x16x32_bf16 v[56:59], v[220:223], v[148:151], v[56:59]
	v_mfma_f32_16x16x32_bf16 v[52:55], v[228:231], v[148:151], v[52:55]
	v_mfma_f32_16x16x32_bf16 v[40:43], v[220:223], v[156:159], v[40:43]
	v_mfma_f32_16x16x32_bf16 v[36:39], v[228:231], v[156:159], v[36:39]
	v_mfma_f32_16x16x32_bf16 v[24:27], v[220:223], v[164:167], v[24:27]
	v_mfma_f32_16x16x32_bf16 v[20:23], v[228:231], v[164:167], v[20:23]
	v_mfma_f32_16x16x32_bf16 v[6:9], v[220:223], v[212:215], v[8:11]
	v_mfma_f32_16x16x32_bf16 v[2:5], v[228:231], v[212:215], v[2:5]
	v_mfma_f32_16x16x32_bf16 v[56:59], v[224:227], v[152:155], v[56:59]
	v_mfma_f32_16x16x32_bf16 v[52:55], v[232:235], v[152:155], v[52:55]
	v_mfma_f32_16x16x32_bf16 v[40:43], v[224:227], v[160:163], v[40:43]
	v_mfma_f32_16x16x32_bf16 v[36:39], v[232:235], v[160:163], v[36:39]
	v_mfma_f32_16x16x32_bf16 v[24:27], v[224:227], v[208:211], v[24:27]
	v_mfma_f32_16x16x32_bf16 v[20:23], v[232:235], v[208:211], v[20:23]
	v_mfma_f32_16x16x32_bf16 v[8:11], v[224:227], v[216:219], v[6:9]
	v_mfma_f32_16x16x32_bf16 v[4:7], v[232:235], v[216:219], v[2:5]
	s_setprio 0
	s_add_i32 s81, s81, 2
	s_add_u32 s44, s44, 0x100
	s_addc_u32 s45, s45, 0
	s_cmp_gt_u32 s81, 29
	s_barrier
	s_cbranch_scc1 .LBB0_1351

;     DI size_t aoff(const Unit& u, size_t tstep) const { return (size_t)u.pm * tstep; }
;     DI size_t boff(const Unit& u, size_t tstep) const { return (size_t)u.pn * tstep; }
;     DI size_t aoff(const Unit& u, size_t) const { return (size_t)u.ks * kbytes; }
;     DI size_t boff(const Unit& u, size_t tstep) const { return (size_t)u.pn * tstep + (size_t)u.ks * kbytes; }
;     DI size_t aoff(const Unit& u, size_t tstep) const { return (u.ks < 2 ? offU : offOA) + (size_t)u.pm * tstep; }
; #define PG8_STAGE(bufoff, gbase, voff) do { _Pragma("unroll") for (int _i = 0; _i < 2; ++_i) \
;         __builtin_amdgcn_global_load_lds((const unsigned*)((const char*)(gbase) + (voff)[_i]), (LAS unsigned*)(lds + (bufoff) + ldsw + _i * 8192), 16, 0, 0); } while (0)
; #define PG8_LDA(dst, b, h) do { _Pragma("unroll") for (int m = 0; m < 4; ++m) _Pragma("unroll") for (int k = 0; k < 2; ++k) dst[m][k] = *(const LAS bf16x8*)(lds + PG8_SA(b, h) + aoff + m * 2048 + k * 1024); } while (0)
; #define PG8_WAIT_L(n) asm volatile("s_waitcnt lgkmcnt(" #n ")" ::: "memory")
; template <class Epi, class Sched>
; DI void gemm_phase(LAS unsigned char* lds, const Gemm g, const Sched& S, const Epi& E) {
;     ...
;         const char* nA = has_next ? (const char*)g.A + S.aoff(nxt, tstep) : cA; const char* nB = has_next ? (const char*)g.Bt + S.boff(nxt, tstep) : cB;
;         for (int t = 0; t < nt; t += 2) {
;             if constexpr (Epi::HAS_MID) { if (t == E.mid_t(nt)) { int fr3 = fr, fq3 = fq; asm volatile("" : "+v"(fr3), "+v"(fq3)); E.mid(acc, cur, wr, wc, fr3, fq3); } }
;             const bool last = (t == nt - 2);
;             const char* a1 = cA + (size_t)(t + 1) * kstep;
;             const char* a2 = last ? nA : cA + (size_t)(t + 2) * kstep; const char* b2 = last ? nB : cB + (size_t)(t + 2) * kstep;
;             const char* a3 = a2 + kstep; const char* b3 = b2 + kstep;
;             PG8_LDB(B0, 0, 0); PG8_SCHED; PG8_LDA(At, 0, 0); PG8_STAGE(PG8_SA(1, 1), a1 + hstep, voffA);
;             PG8_WAIT_L(8); PG8_BAR; PG8_WAIT_L(0); PG8_MMA(0, 0, At, B0); PG8_BAR; PG8_SCHED;
;             PG8_LDB(B1, 0, 1); PG8_STAGE(PG8_SB(0, 0), b2, voffB);
;             PG8_BAR; PG8_WAIT_L(0); PG8_MMA(0, 1, At, B1); PG8_BAR;
;             PG8_LDA(At, 0, 1); PG8_STAGE(PG8_SA(0, 0), a2, voffA);
;             PG8_BAR; PG8_WAIT_L(0); PG8_MMA(1, 0, At, B0); PG8_BAR; PG8_SCHED;
.LBB0_1365:
	s_add_u32 s33, s30, s0
	s_addc_u32 s39, s31, 0
	s_add_u32 s1, s33, 0x100
	s_addc_u32 s50, s39, 0
	s_and_b64 s[4:5], s[48:49], exec
	s_cselect_b32 s55, s19, s50
	s_cselect_b32 s54, s37, s1
	s_add_u32 s0, s28, s0
	s_addc_u32 s1, s29, 0
	s_add_u32 s4, s0, 0x100
	s_addc_u32 s5, s1, 0
	s_and_b64 s[0:1], s[48:49], exec
	s_cselect_b32 s57, s45, s5
	s_cselect_b32 s56, s44, s4
	s_add_u32 s58, s33, 0x80080
	s_addc_u32 s59, s39, 0
	s_add_i32 s82, s75, s61
	s_add_i32 s81, s82, 0x2000
	s_add_u32 s52, s56, 0x80000
	s_addc_u32 s53, s57, 0
	s_add_i32 s39, s76, s61
	ds_read_b128 v[132:135], v129
	ds_read_b128 v[136:139], v129 offset:1024
	ds_read_b128 v[140:143], v129 offset:2048
	ds_read_b128 v[144:147], v129 offset:3072
	s_add_i32 s33, s39, 0x2000
	s_add_i32 s5, 0, 0x18000
	s_add_u32 s50, s54, 0x80000
	s_addc_u32 s51, s55, 0
	s_add_i32 s4, s5, s61
	s_add_i32 s1, 0, 0x1c000
	s_add_i32 s0, s4, 0x2000
	s_add_u32 s48, s56, 0x80080
	s_addc_u32 s49, s57, 0
	s_add_i32 s80, s1, s61
	s_add_i32 s79, s80, 0x2000
	s_mov_b32 m0, s77
	ds_read_b128 v[148:151], v130
	ds_read_b128 v[152:155], v130 offset:1024
	ds_read_b128 v[156:159], v130 offset:2048
	ds_read_b128 v[160:163], v130 offset:3072
	ds_read_b128 v[164:167], v130 offset:4096
	ds_read_b128 v[172:175], v130 offset:5120
	ds_read_b128 v[176:179], v130 offset:6144
	global_load_lds_dwordx4 v168, s[58:59]
	s_mov_b32 m0, s78
	ds_read_b128 v[180:183], v130 offset:7168
	global_load_lds_dwordx4 v170, s[58:59]
	s_waitcnt lgkmcnt(8)
	s_barrier
	s_waitcnt lgkmcnt(0)
	s_setprio 1
	v_mfma_f32_16x16x32_bf16 v[124:127], v[132:135], v[148:151], v[124:127]
	v_mfma_f32_16x16x32_bf16 v[120:123], v[140:143], v[148:151], v[120:123]
	v_mfma_f32_16x16x32_bf16 v[116:119], v[132:135], v[156:159], v[116:119]
	v_mfma_f32_16x16x32_bf16 v[112:115], v[140:143], v[156:159], v[112:115]
	v_mfma_f32_16x16x32_bf16 v[104:107], v[132:135], v[164:167], v[104:107]
	v_mfma_f32_16x16x32_bf16 v[96:99], v[140:143], v[164:167], v[96:99]
	v_mfma_f32_16x16x32_bf16 v[88:91], v[132:135], v[176:179], v[88:91]
	v_mfma_f32_16x16x32_bf16 v[80:83], v[140:143], v[176:179], v[80:83]
	v_mfma_f32_16x16x32_bf16 v[124:127], v[136:139], v[152:155], v[124:127]
	v_mfma_f32_16x16x32_bf16 v[120:123], v[144:147], v[152:155], v[120:123]
	v_mfma_f32_16x16x32_bf16 v[116:119], v[136:139], v[160:163], v[116:119]
	v_mfma_f32_16x16x32_bf16 v[112:115], v[144:147], v[160:163], v[112:115]
	v_mfma_f32_16x16x32_bf16 v[104:107], v[136:139], v[172:175], v[104:107]
	v_mfma_f32_16x16x32_bf16 v[96:99], v[144:147], v[172:175], v[96:99]
	v_mfma_f32_16x16x32_bf16 v[88:91], v[136:139], v[180:183], v[88:91]
	v_mfma_f32_16x16x32_bf16 v[80:83], v[144:147], v[180:183], v[80:83]
	s_setprio 0
	s_barrier
	s_mov_b32 m0, s82
	ds_read_b128 v[188:191], v131
	ds_read_b128 v[206:209], v131 offset:1024
	ds_read_b128 v[210:213], v131 offset:2048
	global_load_lds_dwordx4 v168, s[56:57]
	s_mov_b32 m0, s81
	ds_read_b128 v[214:217], v131 offset:3072
	global_load_lds_dwordx4 v170, s[56:57]
	s_barrier
	s_waitcnt lgkmcnt(0)
	s_setprio 1
	v_mfma_f32_16x16x32_bf16 v[108:111], v[188:191], v[148:151], v[108:111]
	v_mfma_f32_16x16x32_bf16 v[100:103], v[210:213], v[148:151], v[100:103]
	v_mfma_f32_16x16x32_bf16 v[92:95], v[188:191], v[156:159], v[92:95]
	v_mfma_f32_16x16x32_bf16 v[84:87], v[210:213], v[156:159], v[84:87]
	v_mfma_f32_16x16x32_bf16 v[76:79], v[188:191], v[164:167], v[76:79]
	v_mfma_f32_16x16x32_bf16 v[72:75], v[210:213], v[164:167], v[72:75]
	v_mfma_f32_16x16x32_bf16 v[68:71], v[188:191], v[176:179], v[68:71]
	v_mfma_f32_16x16x32_bf16 v[64:67], v[210:213], v[176:179], v[64:67]
	v_mfma_f32_16x16x32_bf16 v[108:111], v[206:209], v[152:155], v[108:111]
	v_mfma_f32_16x16x32_bf16 v[100:103], v[214:217], v[152:155], v[100:103]
	v_mfma_f32_16x16x32_bf16 v[92:95], v[206:209], v[160:163], v[92:95]
	v_mfma_f32_16x16x32_bf16 v[84:87], v[214:217], v[160:163], v[84:87]
	v_mfma_f32_16x16x32_bf16 v[76:79], v[206:209], v[172:175], v[76:79]
	v_mfma_f32_16x16x32_bf16 v[72:75], v[214:217], v[172:175], v[72:75]
	v_mfma_f32_16x16x32_bf16 v[68:71], v[206:209], v[180:183], v[68:71]
	v_mfma_f32_16x16x32_bf16 v[64:67], v[214:217], v[180:183], v[64:67]
	s_setprio 0
	s_mov_b32 m0, s17
	s_barrier
	ds_read_b128 v[148:151], v130 offset:16384
	ds_read_b128 v[152:155], v130 offset:17408
	ds_read_b128 v[156:159], v130 offset:18432
	ds_read_b128 v[160:163], v130 offset:19456
	ds_read_b128 v[164:167], v130 offset:20480
	ds_read_b128 v[172:175], v130 offset:21504
	ds_read_b128 v[176:179], v130 offset:22528
	global_load_lds_dwordx4 v168, s[54:55]
	s_mov_b32 m0, s67
	ds_read_b128 v[180:183], v130 offset:23552
	global_load_lds_dwordx4 v170, s[54:55]
	s_barrier
	s_waitcnt lgkmcnt(0)
	s_setprio 1
	v_mfma_f32_16x16x32_bf16 v[60:63], v[132:135], v[148:151], v[60:63]
	v_mfma_f32_16x16x32_bf16 v[56:59], v[140:143], v[148:151], v[56:59]
	v_mfma_f32_16x16x32_bf16 v[52:55], v[132:135], v[156:159], v[52:55]
	v_mfma_f32_16x16x32_bf16 v[48:51], v[140:143], v[156:159], v[48:51]
	v_mfma_f32_16x16x32_bf16 v[40:43], v[132:135], v[164:167], v[40:43]
	v_mfma_f32_16x16x32_bf16 v[32:35], v[140:143], v[164:167], v[32:35]
	v_mfma_f32_16x16x32_bf16 v[24:27], v[132:135], v[176:179], v[24:27]
	v_mfma_f32_16x16x32_bf16 v[16:19], v[140:143], v[176:179], v[16:19]
	v_mfma_f32_16x16x32_bf16 v[60:63], v[136:139], v[152:155], v[60:63]
	v_mfma_f32_16x16x32_bf16 v[56:59], v[144:147], v[152:155], v[56:59]
	v_mfma_f32_16x16x32_bf16 v[52:55], v[136:139], v[160:163], v[52:55]
	v_mfma_f32_16x16x32_bf16 v[48:51], v[144:147], v[160:163], v[48:51]
	v_mfma_f32_16x16x32_bf16 v[40:43], v[136:139], v[172:175], v[40:43]
	v_mfma_f32_16x16x32_bf16 v[32:35], v[144:147], v[172:175], v[32:35]
	v_mfma_f32_16x16x32_bf16 v[24:27], v[136:139], v[180:183], v[24:27]
	v_mfma_f32_16x16x32_bf16 v[16:19], v[144:147], v[180:183], v[16:19]
	s_setprio 0
	s_barrier
; #define PG8_STAGE(bufoff, gbase, voff) do { _Pragma("unroll") for (int _i = 0; _i < 2; ++_i) \
;         __builtin_amdgcn_global_load_lds((const unsigned*)((const char*)(gbase) + (voff)[_i]), (LAS unsigned*)(lds + (bufoff) + ldsw + _i * 8192), 16, 0, 0); } while (0)
; #define PG8_LDA(dst, b, h) do { _Pragma("unroll") for (int m = 0; m < 4; ++m) _Pragma("unroll") for (int k = 0; k < 2; ++k) dst[m][k] = *(const LAS bf16x8*)(lds + PG8_SA(b, h) + aoff + m * 2048 + k * 1024); } while (0)
; #define PG8_LDB(dst, b, h) do { _Pragma("unroll") for (int n = 0; n < 2; ++n) _Pragma("unroll") for (int k = 0; k < 2; ++k) dst[n][k] = *(const LAS bf16x8*)(lds + PG8_SB(b, h) + boff + n * 2048 + k * 1024); } while (0)
; #define PG8_MMA(ai, bj, At, Bt) do { __builtin_amdgcn_s_setprio(1); _Pragma("unroll") for (int m = 0; m < 4; ++m) _Pragma("unroll") for (int n = 0; n < 2; ++n) _Pragma("unroll") for (int k = 0; k < 2; ++k) \
;         acc[ai][bj][m][n] = __builtin_amdgcn_mfma_f32_16x16x32_bf16(Bt[n][k], At[m][k], acc[ai][bj][m][n], 0, 0, 0); __builtin_amdgcn_s_setprio(0); } while (0)
; #define PG8_WAIT_V(n) asm volatile("s_waitcnt vmcnt(" #n ")" ::: "memory")
; #define PG8_WAIT_L(n) asm volatile("s_waitcnt lgkmcnt(" #n ")" ::: "memory")
; #define PG8_BAR __builtin_amdgcn_s_barrier()
; #define PG8_SCHED __builtin_amdgcn_sched_barrier(0)
; template <class Epi, class Sched>
; DI void gemm_phase(LAS unsigned char* lds, const Gemm g, const Sched& S, const Epi& E) {
;     ...
;             PG8_STAGE(PG8_SB(0, 1), b2 + hstep, voffB);
;             PG8_WAIT_V(6); PG8_BAR; PG8_MMA(1, 1, At, B1); PG8_BAR;
;             PG8_LDB(B0, 1, 0); PG8_SCHED; PG8_LDA(At, 1, 0); PG8_STAGE(PG8_SA(0, 1), a2 + hstep, voffA);
;             PG8_WAIT_L(8); PG8_BAR; PG8_WAIT_L(0); PG8_MMA(0, 0, At, B0); PG8_BAR; PG8_SCHED;
;             PG8_LDB(B1, 1, 1); PG8_STAGE(PG8_SB(1, 0), b3, voffB);
;             PG8_BAR; PG8_WAIT_L(0); PG8_MMA(0, 1, At, B1); PG8_BAR;
;             PG8_LDA(At, 1, 1); PG8_STAGE(PG8_SA(1, 0), a3, voffA);
;             PG8_BAR; PG8_WAIT_L(0); PG8_MMA(1, 0, At, B0); PG8_BAR; PG8_SCHED;
	s_mov_b32 m0, s39
	s_nop 0
	global_load_lds_dwordx4 v168, s[52:53]
	s_mov_b32 m0, s33
	s_nop 0
	global_load_lds_dwordx4 v170, s[52:53]
	s_waitcnt vmcnt(6)
	s_barrier
	s_setprio 1
	v_mfma_f32_16x16x32_bf16 v[44:47], v[188:191], v[148:151], v[44:47]
	v_mfma_f32_16x16x32_bf16 v[36:39], v[210:213], v[148:151], v[36:39]
	v_mfma_f32_16x16x32_bf16 v[28:31], v[188:191], v[156:159], v[28:31]
	v_mfma_f32_16x16x32_bf16 v[20:23], v[210:213], v[156:159], v[20:23]
	v_mfma_f32_16x16x32_bf16 v[12:15], v[188:191], v[164:167], v[12:15]
	v_mfma_f32_16x16x32_bf16 v[8:11], v[210:213], v[164:167], v[8:11]
	v_mfma_f32_16x16x32_bf16 v[4:7], v[188:191], v[176:179], v[4:7]
	v_mfma_f32_16x16x32_bf16 v[0:3], v[210:213], v[176:179], v[0:3]
	v_mfma_f32_16x16x32_bf16 v[44:47], v[206:209], v[152:155], v[44:47]
	v_mfma_f32_16x16x32_bf16 v[36:39], v[214:217], v[152:155], v[36:39]
	v_mfma_f32_16x16x32_bf16 v[28:31], v[206:209], v[160:163], v[28:31]
	v_mfma_f32_16x16x32_bf16 v[20:23], v[214:217], v[160:163], v[20:23]
	v_mfma_f32_16x16x32_bf16 v[12:15], v[206:209], v[172:175], v[12:15]
	v_mfma_f32_16x16x32_bf16 v[8:11], v[214:217], v[172:175], v[8:11]
	v_mfma_f32_16x16x32_bf16 v[4:7], v[206:209], v[180:183], v[4:7]
	v_mfma_f32_16x16x32_bf16 v[0:3], v[214:217], v[180:183], v[0:3]
	s_setprio 0
	v_add_u32_e32 v144, s5, v128
	s_barrier
	ds_read_b128 v[132:135], v144
	ds_read_b128 v[136:139], v144 offset:1024
	ds_read_b128 v[140:143], v144 offset:2048
	ds_read_b128 v[144:147], v144 offset:3072
	s_mov_b32 m0, s68
	ds_read_b128 v[148:151], v130 offset:32768
	ds_read_b128 v[152:155], v130 offset:33792
	ds_read_b128 v[156:159], v130 offset:34816
	ds_read_b128 v[160:163], v130 offset:35840
	ds_read_b128 v[164:167], v130 offset:36864
	ds_read_b128 v[172:175], v130 offset:37888
	ds_read_b128 v[176:179], v130 offset:38912
	global_load_lds_dwordx4 v168, s[50:51]
	s_mov_b32 m0, s69
	ds_read_b128 v[180:183], v130 offset:39936
	global_load_lds_dwordx4 v170, s[50:51]
	s_waitcnt lgkmcnt(8)
	s_barrier
	s_waitcnt lgkmcnt(0)
	s_setprio 1
	v_mfma_f32_16x16x32_bf16 v[124:127], v[132:135], v[148:151], v[124:127]
	v_mfma_f32_16x16x32_bf16 v[120:123], v[140:143], v[148:151], v[120:123]
	v_mfma_f32_16x16x32_bf16 v[116:119], v[132:135], v[156:159], v[116:119]
	v_mfma_f32_16x16x32_bf16 v[112:115], v[140:143], v[156:159], v[112:115]
	v_mfma_f32_16x16x32_bf16 v[104:107], v[132:135], v[164:167], v[104:107]
	v_mfma_f32_16x16x32_bf16 v[96:99], v[140:143], v[164:167], v[96:99]
	v_mfma_f32_16x16x32_bf16 v[88:91], v[132:135], v[176:179], v[88:91]
	v_mfma_f32_16x16x32_bf16 v[80:83], v[140:143], v[176:179], v[80:83]
	v_mfma_f32_16x16x32_bf16 v[124:127], v[136:139], v[152:155], v[124:127]
	v_mfma_f32_16x16x32_bf16 v[120:123], v[144:147], v[152:155], v[120:123]
	v_mfma_f32_16x16x32_bf16 v[116:119], v[136:139], v[160:163], v[116:119]
	v_mfma_f32_16x16x32_bf16 v[112:115], v[144:147], v[160:163], v[112:115]
	v_mfma_f32_16x16x32_bf16 v[104:107], v[136:139], v[172:175], v[104:107]
	v_mfma_f32_16x16x32_bf16 v[96:99], v[144:147], v[172:175], v[96:99]
	v_mfma_f32_16x16x32_bf16 v[88:91], v[136:139], v[180:183], v[88:91]
	v_mfma_f32_16x16x32_bf16 v[80:83], v[144:147], v[180:183], v[80:83]
	s_setprio 0
	s_barrier
	s_add_i32 m0, s4, 0xffffff80
	v_add_u32_e32 v205, s1, v128
	ds_read_b128 v[188:191], v205
	ds_read_b128 v[206:209], v205 offset:1024
	ds_read_b128 v[210:213], v205 offset:2048
	global_load_lds_dwordx4 v168, s[56:57] offset:128
	s_add_i32 m0, s0, 0xffffff80
	ds_read_b128 v[214:217], v205 offset:3072
	global_load_lds_dwordx4 v170, s[56:57] offset:128
	s_barrier
	s_waitcnt lgkmcnt(0)
	s_setprio 1
	v_mfma_f32_16x16x32_bf16 v[108:111], v[188:191], v[148:151], v[108:111]
	v_mfma_f32_16x16x32_bf16 v[100:103], v[210:213], v[148:151], v[100:103]
	v_mfma_f32_16x16x32_bf16 v[92:95], v[188:191], v[156:159], v[92:95]
	v_mfma_f32_16x16x32_bf16 v[84:87], v[210:213], v[156:159], v[84:87]
	v_mfma_f32_16x16x32_bf16 v[76:79], v[188:191], v[164:167], v[76:79]
	v_mfma_f32_16x16x32_bf16 v[72:75], v[210:213], v[164:167], v[72:75]
	v_mfma_f32_16x16x32_bf16 v[68:71], v[188:191], v[176:179], v[68:71]
	v_mfma_f32_16x16x32_bf16 v[64:67], v[210:213], v[176:179], v[64:67]
	v_mfma_f32_16x16x32_bf16 v[108:111], v[206:209], v[152:155], v[108:111]
	v_mfma_f32_16x16x32_bf16 v[100:103], v[214:217], v[152:155], v[100:103]
	v_mfma_f32_16x16x32_bf16 v[92:95], v[206:209], v[160:163], v[92:95]
	v_mfma_f32_16x16x32_bf16 v[84:87], v[214:217], v[160:163], v[84:87]
	v_mfma_f32_16x16x32_bf16 v[76:79], v[206:209], v[172:175], v[76:79]
	v_mfma_f32_16x16x32_bf16 v[72:75], v[214:217], v[172:175], v[72:75]
	v_mfma_f32_16x16x32_bf16 v[68:71], v[206:209], v[180:183], v[68:71]
	v_mfma_f32_16x16x32_bf16 v[64:67], v[214:217], v[180:183], v[64:67]
	s_setprio 0
	s_add_i32 m0, s72, 0xffffff80
	s_barrier
	ds_read_b128 v[148:151], v130 offset:49152
	ds_read_b128 v[152:155], v130 offset:50176
	ds_read_b128 v[156:159], v130 offset:51200
	ds_read_b128 v[160:163], v130 offset:52224
	ds_read_b128 v[164:167], v130 offset:53248
	ds_read_b128 v[172:175], v130 offset:54272
	ds_read_b128 v[176:179], v130 offset:55296
	global_load_lds_dwordx4 v168, s[54:55] offset:128
	s_add_i32 m0, s73, 0xffffff80
	ds_read_b128 v[180:183], v130 offset:56320
	global_load_lds_dwordx4 v170, s[54:55] offset:128
	s_barrier
; #define PG8_STAGE(bufoff, gbase, voff) do { _Pragma("unroll") for (int _i = 0; _i < 2; ++_i) \
;         __builtin_amdgcn_global_load_lds((const unsigned*)((const char*)(gbase) + (voff)[_i]), (LAS unsigned*)(lds + (bufoff) + ldsw + _i * 8192), 16, 0, 0); } while (0)
; #define PG8_MMA(ai, bj, At, Bt) do { __builtin_amdgcn_s_setprio(1); _Pragma("unroll") for (int m = 0; m < 4; ++m) _Pragma("unroll") for (int n = 0; n < 2; ++n) _Pragma("unroll") for (int k = 0; k < 2; ++k) \
;         acc[ai][bj][m][n] = __builtin_amdgcn_mfma_f32_16x16x32_bf16(Bt[n][k], At[m][k], acc[ai][bj][m][n], 0, 0, 0); __builtin_amdgcn_s_setprio(0); } while (0)
; #define PG8_WAIT_V(n) asm volatile("s_waitcnt vmcnt(" #n ")" ::: "memory")
; #define PG8_WAIT_L(n) asm volatile("s_waitcnt lgkmcnt(" #n ")" ::: "memory")
; #define PG8_BAR __builtin_amdgcn_s_barrier()
; #define PG8_SCHED __builtin_amdgcn_sched_barrier(0)
; template <class Epi, class Sched>
; DI void gemm_phase(LAS unsigned char* lds, const Gemm g, const Sched& S, const Epi& E) {
;     ...
;             PG8_BAR; PG8_WAIT_L(0); PG8_MMA(1, 0, At, B0); PG8_BAR; PG8_SCHED;
;             PG8_STAGE(PG8_SB(1, 1), b3 + hstep, voffB);
;             PG8_WAIT_V(6); PG8_BAR; PG8_MMA(1, 1, At, B1); PG8_BAR;
;         }
;         { int fr2 = fr, fq2 = fq; asm volatile("" : "+v"(fr2), "+v"(fq2)); E(acc, cur, wr, wc, fr2, fq2); }
;     DI void operator()(AccRef acc, const Unit& u, int wr, int wc, int fr, int fq) const {
;         float* base = P + (size_t)slot0 * 256 * DM + (size_t)u.ks * 256 * ld; const int col0 = u.pn * 256 + wc * 32 + 4 * fq;
; #pragma unroll
;         for (int ai = 0; ai < 2; ++ai)
; #pragma unroll
;             for (int m = 0; m < 4; ++m) { const size_t off = (size_t)(ai * 128 + wr * 64 + m * 16 + fr) * ld + col0;
; #pragma unroll
;                 for (int bj = 0; bj < 2; ++bj)
; #pragma unroll
;                     for (int n = 0; n < 2; ++n) *(f32x4*)(base + off + bj * 128 + n * 16) = acc[ai][bj][m][n]; }
;     }
	s_waitcnt lgkmcnt(0)
	s_setprio 1
	v_mfma_f32_16x16x32_bf16 v[60:63], v[132:135], v[148:151], v[60:63]
	v_mfma_f32_16x16x32_bf16 v[56:59], v[140:143], v[148:151], v[56:59]
	v_mfma_f32_16x16x32_bf16 v[52:55], v[132:135], v[156:159], v[52:55]
	v_mfma_f32_16x16x32_bf16 v[48:51], v[140:143], v[156:159], v[48:51]
	v_mfma_f32_16x16x32_bf16 v[40:43], v[132:135], v[164:167], v[40:43]
	v_mfma_f32_16x16x32_bf16 v[32:35], v[140:143], v[164:167], v[32:35]
	v_mfma_f32_16x16x32_bf16 v[24:27], v[132:135], v[176:179], v[24:27]
	v_mfma_f32_16x16x32_bf16 v[16:19], v[140:143], v[176:179], v[16:19]
	v_mfma_f32_16x16x32_bf16 v[60:63], v[136:139], v[152:155], v[60:63]
	v_mfma_f32_16x16x32_bf16 v[56:59], v[144:147], v[152:155], v[56:59]
	v_mfma_f32_16x16x32_bf16 v[52:55], v[136:139], v[160:163], v[52:55]
	v_mfma_f32_16x16x32_bf16 v[48:51], v[144:147], v[160:163], v[48:51]
	v_mfma_f32_16x16x32_bf16 v[40:43], v[136:139], v[172:175], v[40:43]
	v_mfma_f32_16x16x32_bf16 v[32:35], v[144:147], v[172:175], v[32:35]
	v_mfma_f32_16x16x32_bf16 v[24:27], v[136:139], v[180:183], v[24:27]
	v_mfma_f32_16x16x32_bf16 v[16:19], v[144:147], v[180:183], v[16:19]
	s_setprio 0
	s_barrier
	s_mov_b32 m0, s80
	s_nop 0
	global_load_lds_dwordx4 v168, s[48:49]
	s_mov_b32 m0, s79
	s_nop 0
	global_load_lds_dwordx4 v170, s[48:49]
	s_waitcnt vmcnt(6)
	s_barrier
	s_setprio 1
	v_mfma_f32_16x16x32_bf16 v[44:47], v[188:191], v[148:151], v[44:47]
	v_mfma_f32_16x16x32_bf16 v[36:39], v[210:213], v[148:151], v[36:39]
	v_mfma_f32_16x16x32_bf16 v[28:31], v[188:191], v[156:159], v[28:31]
	v_mfma_f32_16x16x32_bf16 v[20:23], v[210:213], v[156:159], v[20:23]
	v_mfma_f32_16x16x32_bf16 v[12:15], v[188:191], v[164:167], v[12:15]
	v_mfma_f32_16x16x32_bf16 v[8:11], v[210:213], v[164:167], v[8:11]
	v_mfma_f32_16x16x32_bf16 v[4:7], v[188:191], v[176:179], v[4:7]
	v_mfma_f32_16x16x32_bf16 v[0:3], v[210:213], v[176:179], v[0:3]
	v_mfma_f32_16x16x32_bf16 v[44:47], v[206:209], v[152:155], v[44:47]
	v_mfma_f32_16x16x32_bf16 v[36:39], v[214:217], v[152:155], v[36:39]
	v_mfma_f32_16x16x32_bf16 v[28:31], v[206:209], v[160:163], v[28:31]
	v_mfma_f32_16x16x32_bf16 v[20:23], v[214:217], v[160:163], v[20:23]
	v_mfma_f32_16x16x32_bf16 v[12:15], v[206:209], v[172:175], v[12:15]
	v_mfma_f32_16x16x32_bf16 v[8:11], v[214:217], v[172:175], v[8:11]
	v_mfma_f32_16x16x32_bf16 v[4:7], v[206:209], v[180:183], v[4:7]
	v_mfma_f32_16x16x32_bf16 v[0:3], v[214:217], v[180:183], v[0:3]
	s_setprio 0
	s_movk_i32 s0, 0x100
	s_andn2_b64 vcc, exec, s[46:47]
	s_mov_b64 s[48:49], -1
	s_mov_b64 s[46:47], 0
	s_barrier
	s_cbranch_vccz .LBB0_1365
	s_ashr_i32 s19, s18, 31
	s_lshl_b64 s[0:1], s[18:19], 21
	s_add_u32 s0, s8, s0
	v_mov_b32_e32 v133, v194
	v_mov_b32_e32 v132, v192
	s_addc_u32 s1, s9, s1
	s_lshl_b32 s4, s16, 8
	s_or_b32 s4, s4, s71
	v_lshl_add_u32 v132, v132, 2, s4
	v_add_u32_e32 v134, s70, v133
	v_ashrrev_i32_e32 v133, 31, v132
	v_ashrrev_i32_e32 v135, 31, v134
	v_lshl_add_u64 v[132:133], v[132:133], 2, s[0:1]
	v_lshlrev_b64 v[136:137], 13, v[134:135]
	v_lshl_add_u64 v[136:137], v[132:133], 0, v[136:137]
	global_store_dwordx4 v[136:137], v[124:127], off
	global_store_dwordx4 v[136:137], v[120:123], off offset:64
	global_store_dwordx4 v[136:137], v[108:111], off offset:512
	global_store_dwordx4 v[136:137], v[100:103], off offset:576
	s_and_b64 vcc, exec, s[40:41]
	s_mov_b32 s18, s36
	v_add_u32_e32 v100, 16, v134
	v_ashrrev_i32_e32 v101, 31, v100
	v_lshlrev_b64 v[100:101], 13, v[100:101]
	v_lshl_add_u64 v[100:101], v[132:133], 0, v[100:101]
	global_store_dwordx4 v[100:101], v[116:119], off
	global_store_dwordx4 v[100:101], v[112:115], off offset:64
	global_store_dwordx4 v[100:101], v[92:95], off offset:512
	global_store_dwordx4 v[100:101], v[84:87], off offset:576
	s_mov_b32 s16, s38
	s_mov_b64 s[28:29], s[44:45]
	v_add_u32_e32 v84, 32, v134
	v_ashrrev_i32_e32 v85, 31, v84
	v_lshlrev_b64 v[84:85], 13, v[84:85]
	v_lshl_add_u64 v[84:85], v[132:133], 0, v[84:85]
	global_store_dwordx4 v[84:85], v[104:107], off
	global_store_dwordx4 v[84:85], v[96:99], off offset:64
	global_store_dwordx4 v[84:85], v[76:79], off offset:512
	global_store_dwordx4 v[84:85], v[72:75], off offset:576
	s_mov_b64 s[30:31], s[42:43]
	s_nop 0
	v_add_u32_e32 v72, 48, v134
	v_ashrrev_i32_e32 v73, 31, v72
	v_lshlrev_b64 v[72:73], 13, v[72:73]
	v_lshl_add_u64 v[72:73], v[132:133], 0, v[72:73]
	global_store_dwordx4 v[72:73], v[88:91], off
	global_store_dwordx4 v[72:73], v[80:83], off offset:64
	global_store_dwordx4 v[72:73], v[68:71], off offset:512
	global_store_dwordx4 v[72:73], v[64:67], off offset:576
	s_nop 1
	v_add_u32_e32 v64, 0x80, v134
	v_ashrrev_i32_e32 v65, 31, v64
	v_lshlrev_b64 v[64:65], 13, v[64:65]
	v_lshl_add_u64 v[64:65], v[132:133], 0, v[64:65]
	global_store_dwordx4 v[64:65], v[60:63], off
	global_store_dwordx4 v[64:65], v[56:59], off offset:64
	global_store_dwordx4 v[64:65], v[44:47], off offset:512
	global_store_dwordx4 v[64:65], v[36:39], off offset:576
	s_nop 1
	v_add_u32_e32 v36, 0x90, v134
	v_ashrrev_i32_e32 v37, 31, v36
	v_lshlrev_b64 v[36:37], 13, v[36:37]
	v_lshl_add_u64 v[36:37], v[132:133], 0, v[36:37]
	global_store_dwordx4 v[36:37], v[52:55], off
	global_store_dwordx4 v[36:37], v[48:51], off offset:64
	global_store_dwordx4 v[36:37], v[28:31], off offset:512
	global_store_dwordx4 v[36:37], v[20:23], off offset:576
	s_nop 1
	v_add_u32_e32 v20, 0xa0, v134
	v_ashrrev_i32_e32 v21, 31, v20
	v_lshlrev_b64 v[20:21], 13, v[20:21]
	v_lshl_add_u64 v[20:21], v[132:133], 0, v[20:21]
	global_store_dwordx4 v[20:21], v[40:43], off
	global_store_dwordx4 v[20:21], v[32:35], off offset:64
	global_store_dwordx4 v[20:21], v[12:15], off offset:512
	global_store_dwordx4 v[20:21], v[8:11], off offset:576
	s_nop 1
	v_add_u32_e32 v8, 0xb0, v134
	v_ashrrev_i32_e32 v9, 31, v8
	v_lshlrev_b64 v[8:9], 13, v[8:9]
	v_lshl_add_u64 v[8:9], v[132:133], 0, v[8:9]
	global_store_dwordx4 v[8:9], v[24:27], off
	global_store_dwordx4 v[8:9], v[16:19], off offset:64
	global_store_dwordx4 v[8:9], v[4:7], off offset:512
	global_store_dwordx4 v[8:9], v[0:3], off offset:576
	s_cbranch_vccz .LBB0_1362
	s_waitcnt vmcnt(0)
	s_cmpk_gt_u32 s60, 0xff
	s_cbranch_scc1 .LBB0_1369
	s_barrier

;     DI size_t aoff(const Unit& u, size_t tstep) const { return (size_t)u.pm * tstep; }
;     DI size_t boff(const Unit& u, size_t tstep) const { return (size_t)u.pn * tstep; }
;     DI size_t aoff(const Unit& u, size_t) const { return (size_t)u.ks * kbytes; }
;     DI size_t boff(const Unit& u, size_t tstep) const { return (size_t)u.pn * tstep + (size_t)u.ks * kbytes; }
;     DI size_t aoff(const Unit& u, size_t tstep) const { return (u.ks < 2 ? offU : offOA) + (size_t)u.pm * tstep; }
; #define PG8_STAGE(bufoff, gbase, voff) do { _Pragma("unroll") for (int _i = 0; _i < 2; ++_i) \
;         __builtin_amdgcn_global_load_lds((const unsigned*)((const char*)(gbase) + (voff)[_i]), (LAS unsigned*)(lds + (bufoff) + ldsw + _i * 8192), 16, 0, 0); } while (0)
; #define PG8_LDA(dst, b, h) do { _Pragma("unroll") for (int m = 0; m < 4; ++m) _Pragma("unroll") for (int k = 0; k < 2; ++k) dst[m][k] = *(const LAS bf16x8*)(lds + PG8_SA(b, h) + aoff + m * 2048 + k * 1024); } while (0)
; #define PG8_WAIT_L(n) asm volatile("s_waitcnt lgkmcnt(" #n ")" ::: "memory")
; template <class Epi, class Sched>
; DI void gemm_phase(LAS unsigned char* lds, const Gemm g, const Sched& S, const Epi& E) {
;     ...
;         const char* nA = has_next ? (const char*)g.A + S.aoff(nxt, tstep) : cA; const char* nB = has_next ? (const char*)g.Bt + S.boff(nxt, tstep) : cB;
;         for (int t = 0; t < nt; t += 2) {
;             if constexpr (Epi::HAS_MID) { if (t == E.mid_t(nt)) { int fr3 = fr, fq3 = fq; asm volatile("" : "+v"(fr3), "+v"(fq3)); E.mid(acc, cur, wr, wc, fr3, fq3); } }
;             const bool last = (t == nt - 2);
;             const char* a1 = cA + (size_t)(t + 1) * kstep;
;             const char* a2 = last ? nA : cA + (size_t)(t + 2) * kstep; const char* b2 = last ? nB : cB + (size_t)(t + 2) * kstep;
;             const char* a3 = a2 + kstep; const char* b3 = b2 + kstep;
;             PG8_LDB(B0, 0, 0); PG8_SCHED; PG8_LDA(At, 0, 0); PG8_STAGE(PG8_SA(1, 1), a1 + hstep, voffA);
;             PG8_WAIT_L(8); PG8_BAR; PG8_WAIT_L(0); PG8_MMA(0, 0, At, B0); PG8_BAR; PG8_SCHED;
;             PG8_LDB(B1, 0, 1); PG8_STAGE(PG8_SB(0, 0), b2, voffB);
;             PG8_BAR; PG8_WAIT_L(0); PG8_MMA(0, 1, At, B1); PG8_BAR;
;             PG8_LDA(At, 0, 1); PG8_STAGE(PG8_SA(0, 0), a2, voffA);
;             PG8_BAR; PG8_WAIT_L(0); PG8_MMA(1, 0, At, B0); PG8_BAR; PG8_SCHED;
.LBB0_1377:
	s_add_u32 s33, s38, s0
	s_addc_u32 s43, s39, 0
	s_add_u32 s1, s33, 0x100
	s_addc_u32 s52, s43, 0
	s_and_b64 s[4:5], s[50:51], exec
	s_cselect_b32 s57, s31, s52
	s_cselect_b32 s56, s41, s1
	s_add_u32 s0, s36, s0
	s_addc_u32 s1, s37, 0
	s_add_u32 s4, s0, 0x100
	s_addc_u32 s5, s1, 0
	s_and_b64 s[0:1], s[50:51], exec
	s_cselect_b32 s59, s47, s5
	s_cselect_b32 s58, s46, s4
	s_add_u32 s60, s33, 0x80080
	s_addc_u32 s61, s43, 0
	s_add_u32 s54, s58, 0x80000
	s_addc_u32 s55, s59, 0
	s_add_i32 s43, s76, s62
	ds_read_b128 v[136:139], v133
	ds_read_b128 v[140:143], v133 offset:1024
	ds_read_b128 v[144:147], v133 offset:2048
	ds_read_b128 v[148:151], v133 offset:3072
	s_add_i32 s33, s43, 0x2000
	s_add_i32 s5, 0, 0x18000
	s_add_u32 s52, s56, 0x80000
	s_addc_u32 s53, s57, 0
	s_add_i32 s4, s5, s62
	s_add_i32 s1, 0, 0x1c000
	s_add_i32 s0, s4, 0x2000
	s_add_u32 s50, s58, 0x80080
	s_addc_u32 s51, s59, 0
	s_add_i32 s82, s1, s62
	s_add_i32 s81, s82, 0x2000
	s_mov_b32 m0, s77
	ds_read_b128 v[152:155], v134
	ds_read_b128 v[156:159], v134 offset:1024
	ds_read_b128 v[160:163], v134 offset:2048
	ds_read_b128 v[164:167], v134 offset:3072
	ds_read_b128 v[172:175], v134 offset:4096
	ds_read_b128 v[176:179], v134 offset:5120
	ds_read_b128 v[180:183], v134 offset:6144
	global_load_lds_dwordx4 v168, s[60:61]
	s_mov_b32 m0, s78
	ds_read_b128 v[188:191], v134 offset:7168
	global_load_lds_dwordx4 v170, s[60:61]
	s_waitcnt lgkmcnt(8)
	s_barrier
	s_waitcnt lgkmcnt(0)
	s_setprio 1
	v_mfma_f32_16x16x32_bf16 v[124:127], v[136:139], v[152:155], v[124:127]
	v_mfma_f32_16x16x32_bf16 v[120:123], v[144:147], v[152:155], v[120:123]
	v_mfma_f32_16x16x32_bf16 v[116:119], v[136:139], v[160:163], v[116:119]
	v_mfma_f32_16x16x32_bf16 v[112:115], v[144:147], v[160:163], v[112:115]
	v_mfma_f32_16x16x32_bf16 v[104:107], v[136:139], v[172:175], v[104:107]
	v_mfma_f32_16x16x32_bf16 v[96:99], v[144:147], v[172:175], v[96:99]
	v_mfma_f32_16x16x32_bf16 v[88:91], v[136:139], v[180:183], v[88:91]
	v_mfma_f32_16x16x32_bf16 v[80:83], v[144:147], v[180:183], v[80:83]
	v_mfma_f32_16x16x32_bf16 v[124:127], v[140:143], v[156:159], v[124:127]
	v_mfma_f32_16x16x32_bf16 v[120:123], v[148:151], v[156:159], v[120:123]
	v_mfma_f32_16x16x32_bf16 v[116:119], v[140:143], v[164:167], v[116:119]
	v_mfma_f32_16x16x32_bf16 v[112:115], v[148:151], v[164:167], v[112:115]
	v_mfma_f32_16x16x32_bf16 v[104:107], v[140:143], v[176:179], v[104:107]
	v_mfma_f32_16x16x32_bf16 v[96:99], v[148:151], v[176:179], v[96:99]
	v_mfma_f32_16x16x32_bf16 v[88:91], v[140:143], v[188:191], v[88:91]
	v_mfma_f32_16x16x32_bf16 v[80:83], v[148:151], v[188:191], v[80:83]
	s_setprio 0
	s_barrier
	s_mov_b32 m0, s79
	ds_read_b128 v[206:209], v135
	ds_read_b128 v[210:213], v135 offset:1024
	ds_read_b128 v[214:217], v135 offset:2048
	global_load_lds_dwordx4 v168, s[58:59]
	s_mov_b32 m0, s80
	ds_read_b128 v[218:221], v135 offset:3072
	global_load_lds_dwordx4 v170, s[58:59]
	s_barrier
	s_waitcnt lgkmcnt(0)
	s_setprio 1
	v_mfma_f32_16x16x32_bf16 v[108:111], v[206:209], v[152:155], v[108:111]
	v_mfma_f32_16x16x32_bf16 v[100:103], v[214:217], v[152:155], v[100:103]
	v_mfma_f32_16x16x32_bf16 v[92:95], v[206:209], v[160:163], v[92:95]
	v_mfma_f32_16x16x32_bf16 v[84:87], v[214:217], v[160:163], v[84:87]
	v_mfma_f32_16x16x32_bf16 v[76:79], v[206:209], v[172:175], v[76:79]
	v_mfma_f32_16x16x32_bf16 v[72:75], v[214:217], v[172:175], v[72:75]
	v_mfma_f32_16x16x32_bf16 v[68:71], v[206:209], v[180:183], v[68:71]
	v_mfma_f32_16x16x32_bf16 v[64:67], v[214:217], v[180:183], v[64:67]
	v_mfma_f32_16x16x32_bf16 v[108:111], v[210:213], v[156:159], v[108:111]
	v_mfma_f32_16x16x32_bf16 v[100:103], v[218:221], v[156:159], v[100:103]
	v_mfma_f32_16x16x32_bf16 v[92:95], v[210:213], v[164:167], v[92:95]
	v_mfma_f32_16x16x32_bf16 v[84:87], v[218:221], v[164:167], v[84:87]
	v_mfma_f32_16x16x32_bf16 v[76:79], v[210:213], v[176:179], v[76:79]
	v_mfma_f32_16x16x32_bf16 v[72:75], v[218:221], v[176:179], v[72:75]
	v_mfma_f32_16x16x32_bf16 v[68:71], v[210:213], v[188:191], v[68:71]
	v_mfma_f32_16x16x32_bf16 v[64:67], v[218:221], v[188:191], v[64:67]
	s_setprio 0
	s_mov_b32 m0, s29
	s_barrier
	ds_read_b128 v[152:155], v134 offset:16384
	ds_read_b128 v[156:159], v134 offset:17408
	ds_read_b128 v[160:163], v134 offset:18432
	ds_read_b128 v[164:167], v134 offset:19456
	ds_read_b128 v[172:175], v134 offset:20480
	ds_read_b128 v[176:179], v134 offset:21504
	ds_read_b128 v[180:183], v134 offset:22528
	global_load_lds_dwordx4 v168, s[56:57]
	s_mov_b32 m0, s68
	ds_read_b128 v[188:191], v134 offset:23552
	global_load_lds_dwordx4 v170, s[56:57]
	s_barrier
	s_waitcnt lgkmcnt(0)
	s_setprio 1
	v_mfma_f32_16x16x32_bf16 v[60:63], v[136:139], v[152:155], v[60:63]
	v_mfma_f32_16x16x32_bf16 v[56:59], v[144:147], v[152:155], v[56:59]
	v_mfma_f32_16x16x32_bf16 v[52:55], v[136:139], v[160:163], v[52:55]
	v_mfma_f32_16x16x32_bf16 v[48:51], v[144:147], v[160:163], v[48:51]
	v_mfma_f32_16x16x32_bf16 v[40:43], v[136:139], v[172:175], v[40:43]
	v_mfma_f32_16x16x32_bf16 v[32:35], v[144:147], v[172:175], v[32:35]
	v_mfma_f32_16x16x32_bf16 v[24:27], v[136:139], v[180:183], v[24:27]
	v_mfma_f32_16x16x32_bf16 v[16:19], v[144:147], v[180:183], v[16:19]
	v_mfma_f32_16x16x32_bf16 v[60:63], v[140:143], v[156:159], v[60:63]
	v_mfma_f32_16x16x32_bf16 v[56:59], v[148:151], v[156:159], v[56:59]
	v_mfma_f32_16x16x32_bf16 v[52:55], v[140:143], v[164:167], v[52:55]
	v_mfma_f32_16x16x32_bf16 v[48:51], v[148:151], v[164:167], v[48:51]
	v_mfma_f32_16x16x32_bf16 v[40:43], v[140:143], v[176:179], v[40:43]
	v_mfma_f32_16x16x32_bf16 v[32:35], v[148:151], v[176:179], v[32:35]
	v_mfma_f32_16x16x32_bf16 v[24:27], v[140:143], v[188:191], v[24:27]
	v_mfma_f32_16x16x32_bf16 v[16:19], v[148:151], v[188:191], v[16:19]
	s_setprio 0
	s_barrier
; #define PG8_STAGE(bufoff, gbase, voff) do { _Pragma("unroll") for (int _i = 0; _i < 2; ++_i) \
;         __builtin_amdgcn_global_load_lds((const unsigned*)((const char*)(gbase) + (voff)[_i]), (LAS unsigned*)(lds + (bufoff) + ldsw + _i * 8192), 16, 0, 0); } while (0)
; #define PG8_LDA(dst, b, h) do { _Pragma("unroll") for (int m = 0; m < 4; ++m) _Pragma("unroll") for (int k = 0; k < 2; ++k) dst[m][k] = *(const LAS bf16x8*)(lds + PG8_SA(b, h) + aoff + m * 2048 + k * 1024); } while (0)
; #define PG8_LDB(dst, b, h) do { _Pragma("unroll") for (int n = 0; n < 2; ++n) _Pragma("unroll") for (int k = 0; k < 2; ++k) dst[n][k] = *(const LAS bf16x8*)(lds + PG8_SB(b, h) + boff + n * 2048 + k * 1024); } while (0)
; #define PG8_MMA(ai, bj, At, Bt) do { __builtin_amdgcn_s_setprio(1); _Pragma("unroll") for (int m = 0; m < 4; ++m) _Pragma("unroll") for (int n = 0; n < 2; ++n) _Pragma("unroll") for (int k = 0; k < 2; ++k) \
;         acc[ai][bj][m][n] = __builtin_amdgcn_mfma_f32_16x16x32_bf16(Bt[n][k], At[m][k], acc[ai][bj][m][n], 0, 0, 0); __builtin_amdgcn_s_setprio(0); } while (0)
; #define PG8_WAIT_V(n) asm volatile("s_waitcnt vmcnt(" #n ")" ::: "memory")
; #define PG8_WAIT_L(n) asm volatile("s_waitcnt lgkmcnt(" #n ")" ::: "memory")
; #define PG8_BAR __builtin_amdgcn_s_barrier()
; #define PG8_SCHED __builtin_amdgcn_sched_barrier(0)
; template <class Epi, class Sched>
; DI void gemm_phase(LAS unsigned char* lds, const Gemm g, const Sched& S, const Epi& E) {
;     ...
;             PG8_STAGE(PG8_SB(0, 1), b2 + hstep, voffB);
;             PG8_WAIT_V(6); PG8_BAR; PG8_MMA(1, 1, At, B1); PG8_BAR;
;             PG8_LDB(B0, 1, 0); PG8_SCHED; PG8_LDA(At, 1, 0); PG8_STAGE(PG8_SA(0, 1), a2 + hstep, voffA);
;             PG8_WAIT_L(8); PG8_BAR; PG8_WAIT_L(0); PG8_MMA(0, 0, At, B0); PG8_BAR; PG8_SCHED;
;             PG8_LDB(B1, 1, 1); PG8_STAGE(PG8_SB(1, 0), b3, voffB);
;             PG8_BAR; PG8_WAIT_L(0); PG8_MMA(0, 1, At, B1); PG8_BAR;
;             PG8_LDA(At, 1, 1); PG8_STAGE(PG8_SA(1, 0), a3, voffA);
;             PG8_BAR; PG8_WAIT_L(0); PG8_MMA(1, 0, At, B0); PG8_BAR; PG8_SCHED;
	s_mov_b32 m0, s43
	s_nop 0
	global_load_lds_dwordx4 v168, s[54:55]
	s_mov_b32 m0, s33
	s_nop 0
	global_load_lds_dwordx4 v170, s[54:55]
	s_waitcnt vmcnt(6)
	s_barrier
	s_setprio 1
	v_mfma_f32_16x16x32_bf16 v[44:47], v[206:209], v[152:155], v[44:47]
	v_mfma_f32_16x16x32_bf16 v[36:39], v[214:217], v[152:155], v[36:39]
	v_mfma_f32_16x16x32_bf16 v[28:31], v[206:209], v[160:163], v[28:31]
	v_mfma_f32_16x16x32_bf16 v[20:23], v[214:217], v[160:163], v[20:23]
	v_mfma_f32_16x16x32_bf16 v[12:15], v[206:209], v[172:175], v[12:15]
	v_mfma_f32_16x16x32_bf16 v[8:11], v[214:217], v[172:175], v[8:11]
	v_mfma_f32_16x16x32_bf16 v[4:7], v[206:209], v[180:183], v[4:7]
	v_mfma_f32_16x16x32_bf16 v[0:3], v[214:217], v[180:183], v[0:3]
	v_mfma_f32_16x16x32_bf16 v[44:47], v[210:213], v[156:159], v[44:47]
	v_mfma_f32_16x16x32_bf16 v[36:39], v[218:221], v[156:159], v[36:39]
	v_mfma_f32_16x16x32_bf16 v[28:31], v[210:213], v[164:167], v[28:31]
	v_mfma_f32_16x16x32_bf16 v[20:23], v[218:221], v[164:167], v[20:23]
	v_mfma_f32_16x16x32_bf16 v[12:15], v[210:213], v[176:179], v[12:15]
	v_mfma_f32_16x16x32_bf16 v[8:11], v[218:221], v[176:179], v[8:11]
	v_mfma_f32_16x16x32_bf16 v[4:7], v[210:213], v[188:191], v[4:7]
	v_mfma_f32_16x16x32_bf16 v[0:3], v[218:221], v[188:191], v[0:3]
	s_setprio 0
	v_add_u32_e32 v148, s5, v132
	s_barrier
	ds_read_b128 v[136:139], v148
	ds_read_b128 v[140:143], v148 offset:1024
	ds_read_b128 v[144:147], v148 offset:2048
	ds_read_b128 v[148:151], v148 offset:3072
	s_mov_b32 m0, s69
	ds_read_b128 v[152:155], v134 offset:32768
	ds_read_b128 v[156:159], v134 offset:33792
	ds_read_b128 v[160:163], v134 offset:34816
	ds_read_b128 v[164:167], v134 offset:35840
	ds_read_b128 v[172:175], v134 offset:36864
	ds_read_b128 v[176:179], v134 offset:37888
	ds_read_b128 v[180:183], v134 offset:38912
	global_load_lds_dwordx4 v168, s[52:53]
	s_mov_b32 m0, s70
	ds_read_b128 v[188:191], v134 offset:39936
	global_load_lds_dwordx4 v170, s[52:53]
	s_waitcnt lgkmcnt(8)
	s_barrier
	s_waitcnt lgkmcnt(0)
	s_setprio 1
	v_mfma_f32_16x16x32_bf16 v[124:127], v[136:139], v[152:155], v[124:127]
	v_mfma_f32_16x16x32_bf16 v[120:123], v[144:147], v[152:155], v[120:123]
	v_mfma_f32_16x16x32_bf16 v[116:119], v[136:139], v[160:163], v[116:119]
	v_mfma_f32_16x16x32_bf16 v[112:115], v[144:147], v[160:163], v[112:115]
	v_mfma_f32_16x16x32_bf16 v[104:107], v[136:139], v[172:175], v[104:107]
	v_mfma_f32_16x16x32_bf16 v[96:99], v[144:147], v[172:175], v[96:99]
	v_mfma_f32_16x16x32_bf16 v[88:91], v[136:139], v[180:183], v[88:91]
	v_mfma_f32_16x16x32_bf16 v[80:83], v[144:147], v[180:183], v[80:83]
	v_mfma_f32_16x16x32_bf16 v[124:127], v[140:143], v[156:159], v[124:127]
	v_mfma_f32_16x16x32_bf16 v[120:123], v[148:151], v[156:159], v[120:123]
	v_mfma_f32_16x16x32_bf16 v[116:119], v[140:143], v[164:167], v[116:119]
	v_mfma_f32_16x16x32_bf16 v[112:115], v[148:151], v[164:167], v[112:115]
	v_mfma_f32_16x16x32_bf16 v[104:107], v[140:143], v[176:179], v[104:107]
	v_mfma_f32_16x16x32_bf16 v[96:99], v[148:151], v[176:179], v[96:99]
	v_mfma_f32_16x16x32_bf16 v[88:91], v[140:143], v[188:191], v[88:91]
	v_mfma_f32_16x16x32_bf16 v[80:83], v[148:151], v[188:191], v[80:83]
	s_setprio 0
	s_barrier
	s_add_i32 m0, s4, 0xffffff80
	v_add_u32_e32 v201, s1, v132
	ds_read_b128 v[206:209], v201
	ds_read_b128 v[210:213], v201 offset:1024
	ds_read_b128 v[214:217], v201 offset:2048
	global_load_lds_dwordx4 v168, s[58:59] offset:128
	s_add_i32 m0, s0, 0xffffff80
	ds_read_b128 v[218:221], v201 offset:3072
	global_load_lds_dwordx4 v170, s[58:59] offset:128
	s_barrier
	s_waitcnt lgkmcnt(0)
	s_setprio 1
	v_mfma_f32_16x16x32_bf16 v[108:111], v[206:209], v[152:155], v[108:111]
	v_mfma_f32_16x16x32_bf16 v[100:103], v[214:217], v[152:155], v[100:103]
	v_mfma_f32_16x16x32_bf16 v[92:95], v[206:209], v[160:163], v[92:95]
	v_mfma_f32_16x16x32_bf16 v[84:87], v[214:217], v[160:163], v[84:87]
	v_mfma_f32_16x16x32_bf16 v[76:79], v[206:209], v[172:175], v[76:79]
	v_mfma_f32_16x16x32_bf16 v[72:75], v[214:217], v[172:175], v[72:75]
	v_mfma_f32_16x16x32_bf16 v[68:71], v[206:209], v[180:183], v[68:71]
	v_mfma_f32_16x16x32_bf16 v[64:67], v[214:217], v[180:183], v[64:67]
	v_mfma_f32_16x16x32_bf16 v[108:111], v[210:213], v[156:159], v[108:111]
	v_mfma_f32_16x16x32_bf16 v[100:103], v[218:221], v[156:159], v[100:103]
	v_mfma_f32_16x16x32_bf16 v[92:95], v[210:213], v[164:167], v[92:95]
	v_mfma_f32_16x16x32_bf16 v[84:87], v[218:221], v[164:167], v[84:87]
	v_mfma_f32_16x16x32_bf16 v[76:79], v[210:213], v[176:179], v[76:79]
	v_mfma_f32_16x16x32_bf16 v[72:75], v[218:221], v[176:179], v[72:75]
	v_mfma_f32_16x16x32_bf16 v[68:71], v[210:213], v[188:191], v[68:71]
	v_mfma_f32_16x16x32_bf16 v[64:67], v[218:221], v[188:191], v[64:67]
	s_setprio 0
	s_add_i32 m0, s74, 0xffffff80
	s_barrier
	ds_read_b128 v[152:155], v134 offset:49152
	ds_read_b128 v[156:159], v134 offset:50176
	ds_read_b128 v[160:163], v134 offset:51200
	ds_read_b128 v[164:167], v134 offset:52224
	ds_read_b128 v[172:175], v134 offset:53248
	ds_read_b128 v[176:179], v134 offset:54272
	ds_read_b128 v[180:183], v134 offset:55296
	global_load_lds_dwordx4 v168, s[56:57] offset:128
	s_add_i32 m0, s75, 0xffffff80
	ds_read_b128 v[188:191], v134 offset:56320
	global_load_lds_dwordx4 v170, s[56:57] offset:128
	s_barrier
; #define PG8_STAGE(bufoff, gbase, voff) do { _Pragma("unroll") for (int _i = 0; _i < 2; ++_i) \
;         __builtin_amdgcn_global_load_lds((const unsigned*)((const char*)(gbase) + (voff)[_i]), (LAS unsigned*)(lds + (bufoff) + ldsw + _i * 8192), 16, 0, 0); } while (0)
; #define PG8_MMA(ai, bj, At, Bt) do { __builtin_amdgcn_s_setprio(1); _Pragma("unroll") for (int m = 0; m < 4; ++m) _Pragma("unroll") for (int n = 0; n < 2; ++n) _Pragma("unroll") for (int k = 0; k < 2; ++k) \
;         acc[ai][bj][m][n] = __builtin_amdgcn_mfma_f32_16x16x32_bf16(Bt[n][k], At[m][k], acc[ai][bj][m][n], 0, 0, 0); __builtin_amdgcn_s_setprio(0); } while (0)
; #define PG8_WAIT_V(n) asm volatile("s_waitcnt vmcnt(" #n ")" ::: "memory")
; #define PG8_WAIT_L(n) asm volatile("s_waitcnt lgkmcnt(" #n ")" ::: "memory")
; #define PG8_BAR __builtin_amdgcn_s_barrier()
; #define PG8_SCHED __builtin_amdgcn_sched_barrier(0)
; template <class Epi, class Sched>
; DI void gemm_phase(LAS unsigned char* lds, const Gemm g, const Sched& S, const Epi& E) {
;     ...
;             PG8_BAR; PG8_WAIT_L(0); PG8_MMA(1, 0, At, B0); PG8_BAR; PG8_SCHED;
;             PG8_STAGE(PG8_SB(1, 1), b3 + hstep, voffB);
;             PG8_WAIT_V(6); PG8_BAR; PG8_MMA(1, 1, At, B1); PG8_BAR;
;         }
;         { int fr2 = fr, fq2 = fq; asm volatile("" : "+v"(fr2), "+v"(fq2)); E(acc, cur, wr, wc, fr2, fq2); }
;     DI void operator()(AccRef acc, const Unit& u, int wr, int wc, int fr, int fq) const {
;         float* base = P + (size_t)slot0 * 256 * DM + (size_t)u.ks * 256 * ld; const int col0 = u.pn * 256 + wc * 32 + 4 * fq;
; #pragma unroll
;         for (int ai = 0; ai < 2; ++ai)
; #pragma unroll
;             for (int m = 0; m < 4; ++m) { const size_t off = (size_t)(ai * 128 + wr * 64 + m * 16 + fr) * ld + col0;
; #pragma unroll
;                 for (int bj = 0; bj < 2; ++bj)
; #pragma unroll
;                     for (int n = 0; n < 2; ++n) *(f32x4*)(base + off + bj * 128 + n * 16) = acc[ai][bj][m][n]; }
;     }
	s_waitcnt lgkmcnt(0)
	s_setprio 1
	v_mfma_f32_16x16x32_bf16 v[60:63], v[136:139], v[152:155], v[60:63]
	v_mfma_f32_16x16x32_bf16 v[56:59], v[144:147], v[152:155], v[56:59]
	v_mfma_f32_16x16x32_bf16 v[52:55], v[136:139], v[160:163], v[52:55]
	v_mfma_f32_16x16x32_bf16 v[48:51], v[144:147], v[160:163], v[48:51]
	v_mfma_f32_16x16x32_bf16 v[40:43], v[136:139], v[172:175], v[40:43]
	v_mfma_f32_16x16x32_bf16 v[32:35], v[144:147], v[172:175], v[32:35]
	v_mfma_f32_16x16x32_bf16 v[24:27], v[136:139], v[180:183], v[24:27]
	v_mfma_f32_16x16x32_bf16 v[16:19], v[144:147], v[180:183], v[16:19]
	v_mfma_f32_16x16x32_bf16 v[60:63], v[140:143], v[156:159], v[60:63]
	v_mfma_f32_16x16x32_bf16 v[56:59], v[148:151], v[156:159], v[56:59]
	v_mfma_f32_16x16x32_bf16 v[52:55], v[140:143], v[164:167], v[52:55]
	v_mfma_f32_16x16x32_bf16 v[48:51], v[148:151], v[164:167], v[48:51]
	v_mfma_f32_16x16x32_bf16 v[40:43], v[140:143], v[176:179], v[40:43]
	v_mfma_f32_16x16x32_bf16 v[32:35], v[148:151], v[176:179], v[32:35]
	v_mfma_f32_16x16x32_bf16 v[24:27], v[140:143], v[188:191], v[24:27]
	v_mfma_f32_16x16x32_bf16 v[16:19], v[148:151], v[188:191], v[16:19]
	s_setprio 0
	s_barrier
	s_mov_b32 m0, s82
	s_nop 0
	global_load_lds_dwordx4 v168, s[50:51]
	s_mov_b32 m0, s81
	s_nop 0
	global_load_lds_dwordx4 v170, s[50:51]
	s_waitcnt vmcnt(6)
	s_barrier
	s_setprio 1
	v_mfma_f32_16x16x32_bf16 v[44:47], v[206:209], v[152:155], v[44:47]
	v_mfma_f32_16x16x32_bf16 v[36:39], v[214:217], v[152:155], v[36:39]
	v_mfma_f32_16x16x32_bf16 v[28:31], v[206:209], v[160:163], v[28:31]
	v_mfma_f32_16x16x32_bf16 v[20:23], v[214:217], v[160:163], v[20:23]
	v_mfma_f32_16x16x32_bf16 v[12:15], v[206:209], v[172:175], v[12:15]
	v_mfma_f32_16x16x32_bf16 v[8:11], v[214:217], v[172:175], v[8:11]
	v_mfma_f32_16x16x32_bf16 v[4:7], v[206:209], v[180:183], v[4:7]
	v_mfma_f32_16x16x32_bf16 v[0:3], v[214:217], v[180:183], v[0:3]
	v_mfma_f32_16x16x32_bf16 v[44:47], v[210:213], v[156:159], v[44:47]
	v_mfma_f32_16x16x32_bf16 v[36:39], v[218:221], v[156:159], v[36:39]
	v_mfma_f32_16x16x32_bf16 v[28:31], v[210:213], v[164:167], v[28:31]
	v_mfma_f32_16x16x32_bf16 v[20:23], v[218:221], v[164:167], v[20:23]
	v_mfma_f32_16x16x32_bf16 v[12:15], v[210:213], v[176:179], v[12:15]
	v_mfma_f32_16x16x32_bf16 v[8:11], v[218:221], v[176:179], v[8:11]
	v_mfma_f32_16x16x32_bf16 v[4:7], v[210:213], v[188:191], v[4:7]
	v_mfma_f32_16x16x32_bf16 v[0:3], v[218:221], v[188:191], v[0:3]
	s_setprio 0
	s_movk_i32 s0, 0x100
	s_andn2_b64 vcc, exec, s[48:49]
	s_mov_b64 s[50:51], -1
	s_mov_b64 s[48:49], 0
	s_barrier
	s_cbranch_vccz .LBB0_1377
	s_ashr_i32 s31, s30, 31
	s_lshl_b64 s[0:1], s[30:31], 22
	s_add_u32 s0, s18, s0
	v_mov_b32_e32 v137, v194
	v_mov_b32_e32 v136, v192
	s_addc_u32 s1, s19, s1
	s_lshl_b32 s4, s28, 8
	s_or_b32 s4, s4, s73
	v_lshl_add_u32 v136, v136, 2, s4
	v_add_u32_e32 v138, s72, v137
	v_ashrrev_i32_e32 v137, 31, v136
	v_ashrrev_i32_e32 v139, 31, v138
	v_lshl_add_u64 v[136:137], v[136:137], 2, s[0:1]
	v_lshlrev_b64 v[140:141], 14, v[138:139]
	v_lshl_add_u64 v[140:141], v[136:137], 0, v[140:141]
	global_store_dwordx4 v[140:141], v[124:127], off
	global_store_dwordx4 v[140:141], v[120:123], off offset:64
	global_store_dwordx4 v[140:141], v[108:111], off offset:512
	global_store_dwordx4 v[140:141], v[100:103], off offset:576
	s_and_b64 vcc, exec, s[6:7]
	s_mov_b32 s30, s40
	v_add_u32_e32 v100, 16, v138
	v_ashrrev_i32_e32 v101, 31, v100
	v_lshlrev_b64 v[100:101], 14, v[100:101]
	v_lshl_add_u64 v[100:101], v[136:137], 0, v[100:101]
	global_store_dwordx4 v[100:101], v[116:119], off
	global_store_dwordx4 v[100:101], v[112:115], off offset:64
	global_store_dwordx4 v[100:101], v[92:95], off offset:512
	global_store_dwordx4 v[100:101], v[84:87], off offset:576
	s_mov_b32 s28, s42
	s_mov_b64 s[36:37], s[46:47]
	v_add_u32_e32 v84, 32, v138
	v_ashrrev_i32_e32 v85, 31, v84
	v_lshlrev_b64 v[84:85], 14, v[84:85]
	v_lshl_add_u64 v[84:85], v[136:137], 0, v[84:85]
	global_store_dwordx4 v[84:85], v[104:107], off
	global_store_dwordx4 v[84:85], v[96:99], off offset:64
	global_store_dwordx4 v[84:85], v[76:79], off offset:512
	global_store_dwordx4 v[84:85], v[72:75], off offset:576
	s_mov_b64 s[38:39], s[44:45]
	s_nop 0
	v_add_u32_e32 v72, 48, v138
	v_ashrrev_i32_e32 v73, 31, v72
	v_lshlrev_b64 v[72:73], 14, v[72:73]
	v_lshl_add_u64 v[72:73], v[136:137], 0, v[72:73]
	global_store_dwordx4 v[72:73], v[88:91], off
	global_store_dwordx4 v[72:73], v[80:83], off offset:64
	global_store_dwordx4 v[72:73], v[68:71], off offset:512
	global_store_dwordx4 v[72:73], v[64:67], off offset:576
	s_nop 1
	v_add_u32_e32 v64, 0x80, v138
	v_ashrrev_i32_e32 v65, 31, v64
	v_lshlrev_b64 v[64:65], 14, v[64:65]
	v_lshl_add_u64 v[64:65], v[136:137], 0, v[64:65]
	global_store_dwordx4 v[64:65], v[60:63], off
	global_store_dwordx4 v[64:65], v[56:59], off offset:64
	global_store_dwordx4 v[64:65], v[44:47], off offset:512
	global_store_dwordx4 v[64:65], v[36:39], off offset:576
	s_nop 1
	v_add_u32_e32 v36, 0x90, v138
	v_ashrrev_i32_e32 v37, 31, v36
	v_lshlrev_b64 v[36:37], 14, v[36:37]
	v_lshl_add_u64 v[36:37], v[136:137], 0, v[36:37]
	global_store_dwordx4 v[36:37], v[52:55], off
	global_store_dwordx4 v[36:37], v[48:51], off offset:64
	global_store_dwordx4 v[36:37], v[28:31], off offset:512
	global_store_dwordx4 v[36:37], v[20:23], off offset:576
	s_nop 1
	v_add_u32_e32 v20, 0xa0, v138
	v_ashrrev_i32_e32 v21, 31, v20
	v_lshlrev_b64 v[20:21], 14, v[20:21]
	v_lshl_add_u64 v[20:21], v[136:137], 0, v[20:21]
	global_store_dwordx4 v[20:21], v[40:43], off
	global_store_dwordx4 v[20:21], v[32:35], off offset:64
	global_store_dwordx4 v[20:21], v[12:15], off offset:512
	global_store_dwordx4 v[20:21], v[8:11], off offset:576
	s_nop 1
	v_add_u32_e32 v8, 0xb0, v138
	v_ashrrev_i32_e32 v9, 31, v8
	v_lshlrev_b64 v[8:9], 14, v[8:9]
	v_lshl_add_u64 v[8:9], v[136:137], 0, v[8:9]
	global_store_dwordx4 v[8:9], v[24:27], off
	global_store_dwordx4 v[8:9], v[16:19], off offset:64
	global_store_dwordx4 v[8:9], v[4:7], off offset:512
	global_store_dwordx4 v[8:9], v[0:3], off offset:576
	s_cbranch_vccz .LBB0_1374
	s_waitcnt vmcnt(0)
	s_cmpk_gt_u32 s35, 0xff
	s_cbranch_scc1 .LBB0_1381
	s_barrier

;     DI size_t aoff(const Unit& u, size_t tstep) const { return (size_t)u.pm * tstep; }
;     DI size_t boff(const Unit& u, size_t tstep) const { return (size_t)u.pn * tstep; }
;     DI bool next(int i, Unit& u) const { const long L = (long)i * G + c; if (L >= np) return false; u.pm = pmv; u.pn = (int)(L % nN); u.ks = (int)(L / nN); return true; }
;     DI size_t aoff(const Unit& u, size_t) const { return (size_t)u.ks * kbytes; }
;     DI size_t boff(const Unit& u, size_t tstep) const { return (size_t)u.pn * tstep + (size_t)u.ks * kbytes; }
;     DI bool next(int i, Unit& u) const { Unit t; if (!S.next(i / 3, t)) return false; u.pm = t.pm; u.pn = t.pn; u.ks = i % 3; return true; }
;     DI size_t aoff(const Unit& u, size_t tstep) const { return (u.ks < 2 ? offU : offOA) + (size_t)u.pm * tstep; }
; #define PG8_LDA(dst, b, h) do { _Pragma("unroll") for (int m = 0; m < 4; ++m) _Pragma("unroll") for (int k = 0; k < 2; ++k) dst[m][k] = *(const LAS bf16x8*)(lds + PG8_SA(b, h) + aoff + m * 2048 + k * 1024); } while (0)
; template <class Epi, class Sched>
; DI void gemm_phase(LAS unsigned char* lds, const Gemm g, const Sched& S, const Epi& E) {
;     ...
;         const bool has_next = S.next(ui + 1, nxt);
;         const char* nA = has_next ? (const char*)g.A + S.aoff(nxt, tstep) : cA; const char* nB = has_next ? (const char*)g.Bt + S.boff(nxt, tstep) : cB;
;         for (int t = 0; t < nt; t += 2) {
;             if constexpr (Epi::HAS_MID) { if (t == E.mid_t(nt)) { int fr3 = fr, fq3 = fq; asm volatile("" : "+v"(fr3), "+v"(fq3)); E.mid(acc, cur, wr, wc, fr3, fq3); } }
;             const bool last = (t == nt - 2);
;             const char* a1 = cA + (size_t)(t + 1) * kstep;
;             const char* a2 = last ? nA : cA + (size_t)(t + 2) * kstep; const char* b2 = last ? nB : cB + (size_t)(t + 2) * kstep;
;             const char* a3 = a2 + kstep; const char* b3 = b2 + kstep;
;             PG8_LDB(B0, 0, 0); PG8_SCHED; PG8_LDA(At, 0, 0); PG8_STAGE(PG8_SA(1, 1), a1 + hstep, voffA);
;             PG8_WAIT_L(8); PG8_BAR; PG8_WAIT_L(0); PG8_MMA(0, 0, At, B0); PG8_BAR; PG8_SCHED;
;             PG8_LDB(B1, 0, 1); PG8_STAGE(PG8_SB(0, 0), b2, voffB);
;             PG8_BAR; PG8_WAIT_L(0); PG8_MMA(0, 1, At, B1); PG8_BAR;
;             PG8_LDA(At, 0, 1); PG8_STAGE(PG8_SA(0, 0), a2, voffA);
;             PG8_BAR; PG8_WAIT_L(0); PG8_MMA(1, 0, At, B0); PG8_BAR; PG8_SCHED;
.LBB0_1507:
	s_ashr_i32 s37, s36, 31
	s_lshl_b64 s[0:1], s[36:37], 20
	v_cmp_lt_i64_e32 vcc, s[38:39], v[140:141]
	s_add_u32 s38, s13, s0
	s_addc_u32 s39, s50, s1
	s_and_b64 s[0:1], vcc, exec
	s_cselect_b32 s34, s39, s45
	s_cselect_b32 s35, s38, s44
	s_ashr_i32 s31, s30, 31
	s_lshl_b64 s[0:1], s[30:31], 20
	s_add_u32 s40, s55, s0
	s_addc_u32 s41, s56, s1
	s_and_b64 s[0:1], vcc, exec
	s_cselect_b32 s31, s41, s47
	s_cselect_b32 s37, s40, s46
	s_add_u32 s44, s44, 0x80080
	s_addc_u32 s45, s45, 0
	s_add_u32 s43, s46, 0x100
	v_mov_b32_e32 v0, 0
	s_addc_u32 s68, s47, 0
	s_mov_b32 s69, -2
	s_waitcnt lgkmcnt(0)
	ds_read_b128 v[144:147], v150
	ds_read_b128 v[154:157], v150 offset:1024
	ds_read_b128 v[158:161], v150 offset:2048
	ds_read_b128 v[162:165], v150 offset:3072
	s_add_u32 s0, s44, 0xfff80080
	s_addc_u32 s1, s45, -1
	s_cmp_eq_u32 s69, 28
	s_cselect_b32 s49, s34, s1
	s_cselect_b32 s48, s35, s0
	s_cselect_b32 s47, s31, s68
	s_cselect_b32 s46, s37, s43
	s_add_i32 m0, s52, 0xc000
	ds_read_b128 v[166:169], v151
	ds_read_b128 v[170:173], v151 offset:1024
	ds_read_b128 v[174:177], v151 offset:2048
	ds_read_b128 v[178:181], v151 offset:3072
	ds_read_b128 v[188:191], v151 offset:4096
	ds_read_b128 v[206:209], v151 offset:5120
	ds_read_b128 v[210:213], v151 offset:6144
	global_load_lds_dwordx4 v136, s[44:45]
	s_add_i32 m0, s52, 0xe000
	ds_read_b128 v[214:217], v151 offset:7168
	global_load_lds_dwordx4 v138, s[44:45]
	s_waitcnt lgkmcnt(8)
	s_barrier
	s_waitcnt lgkmcnt(0)
	s_setprio 1
	v_mfma_f32_16x16x32_bf16 v[124:127], v[144:147], v[166:169], 0
	v_mfma_f32_16x16x32_bf16 v[120:123], v[158:161], v[166:169], 0
	v_mfma_f32_16x16x32_bf16 v[108:111], v[144:147], v[174:177], 0
	v_mfma_f32_16x16x32_bf16 v[104:107], v[158:161], v[174:177], 0
	v_mfma_f32_16x16x32_bf16 v[92:95], v[144:147], v[188:191], 0
	v_mfma_f32_16x16x32_bf16 v[88:91], v[158:161], v[188:191], 0
	v_mfma_f32_16x16x32_bf16 v[76:79], v[144:147], v[210:213], 0
	v_mfma_f32_16x16x32_bf16 v[72:75], v[158:161], v[210:213], 0
	v_mfma_f32_16x16x32_bf16 v[124:127], v[154:157], v[170:173], v[124:127]
	v_mfma_f32_16x16x32_bf16 v[120:123], v[162:165], v[170:173], v[120:123]
	v_mfma_f32_16x16x32_bf16 v[108:111], v[154:157], v[178:181], v[108:111]
	v_mfma_f32_16x16x32_bf16 v[104:107], v[162:165], v[178:181], v[104:107]
	v_mfma_f32_16x16x32_bf16 v[92:95], v[154:157], v[206:209], v[92:95]
	v_mfma_f32_16x16x32_bf16 v[88:91], v[162:165], v[206:209], v[88:91]
	v_mfma_f32_16x16x32_bf16 v[76:79], v[154:157], v[214:217], v[76:79]
	v_mfma_f32_16x16x32_bf16 v[72:75], v[162:165], v[214:217], v[72:75]
	s_setprio 0
	s_barrier
	s_add_i32 s0, s65, s51
	s_mov_b32 m0, s0
	ds_read_b128 v[218:221], v152
	ds_read_b128 v[222:225], v152 offset:1024
	ds_read_b128 v[226:229], v152 offset:2048
	global_load_lds_dwordx4 v132, s[46:47]
	s_add_i32 m0, s0, 0x2000
	ds_read_b128 v[230:233], v152 offset:3072
	global_load_lds_dwordx4 v134, s[46:47]
	s_barrier
	s_waitcnt lgkmcnt(0)
	s_setprio 1
	v_mfma_f32_16x16x32_bf16 v[116:119], v[218:221], v[166:169], 0
	v_mfma_f32_16x16x32_bf16 v[112:115], v[226:229], v[166:169], 0
	v_mfma_f32_16x16x32_bf16 v[100:103], v[218:221], v[174:177], 0
	v_mfma_f32_16x16x32_bf16 v[96:99], v[226:229], v[174:177], 0
	v_mfma_f32_16x16x32_bf16 v[84:87], v[218:221], v[188:191], 0
	v_mfma_f32_16x16x32_bf16 v[80:83], v[226:229], v[188:191], 0
	v_mfma_f32_16x16x32_bf16 v[68:71], v[218:221], v[210:213], 0
	v_mfma_f32_16x16x32_bf16 v[64:67], v[226:229], v[210:213], 0
	v_mfma_f32_16x16x32_bf16 v[116:119], v[222:225], v[170:173], v[116:119]
	v_mfma_f32_16x16x32_bf16 v[112:115], v[230:233], v[170:173], v[112:115]
	v_mfma_f32_16x16x32_bf16 v[100:103], v[222:225], v[178:181], v[100:103]
	v_mfma_f32_16x16x32_bf16 v[96:99], v[230:233], v[178:181], v[96:99]
	v_mfma_f32_16x16x32_bf16 v[84:87], v[222:225], v[206:209], v[84:87]
	v_mfma_f32_16x16x32_bf16 v[80:83], v[230:233], v[206:209], v[80:83]
	v_mfma_f32_16x16x32_bf16 v[68:71], v[222:225], v[214:217], v[68:71]
	v_mfma_f32_16x16x32_bf16 v[64:67], v[230:233], v[214:217], v[64:67]
	s_setprio 0
	s_mov_b32 m0, s52
	s_barrier
	ds_read_b128 v[166:169], v151 offset:16384
	ds_read_b128 v[170:173], v151 offset:17408
	ds_read_b128 v[174:177], v151 offset:18432
	ds_read_b128 v[178:181], v151 offset:19456
	ds_read_b128 v[188:191], v151 offset:20480
	ds_read_b128 v[206:209], v151 offset:21504
	ds_read_b128 v[210:213], v151 offset:22528
	global_load_lds_dwordx4 v128, s[48:49]
	s_mov_b32 m0, s53
	ds_read_b128 v[214:217], v151 offset:23552
	global_load_lds_dwordx4 v130, s[48:49]
	s_barrier
	s_waitcnt lgkmcnt(0)
	s_setprio 1
	v_mfma_f32_16x16x32_bf16 v[60:63], v[144:147], v[166:169], 0
	v_mfma_f32_16x16x32_bf16 v[56:59], v[158:161], v[166:169], 0
	v_mfma_f32_16x16x32_bf16 v[44:47], v[144:147], v[174:177], 0
	v_mfma_f32_16x16x32_bf16 v[40:43], v[158:161], v[174:177], 0
	v_mfma_f32_16x16x32_bf16 v[28:31], v[144:147], v[188:191], 0
	v_mfma_f32_16x16x32_bf16 v[24:27], v[158:161], v[188:191], 0
	v_mfma_f32_16x16x32_bf16 v[12:15], v[144:147], v[210:213], 0
	v_mfma_f32_16x16x32_bf16 v[8:11], v[158:161], v[210:213], 0
	v_mfma_f32_16x16x32_bf16 v[60:63], v[154:157], v[170:173], v[60:63]
	v_mfma_f32_16x16x32_bf16 v[56:59], v[162:165], v[170:173], v[56:59]
	v_mfma_f32_16x16x32_bf16 v[44:47], v[154:157], v[178:181], v[44:47]
	v_mfma_f32_16x16x32_bf16 v[40:43], v[162:165], v[178:181], v[40:43]
	v_mfma_f32_16x16x32_bf16 v[28:31], v[154:157], v[206:209], v[28:31]
	v_mfma_f32_16x16x32_bf16 v[24:27], v[162:165], v[206:209], v[24:27]
	v_mfma_f32_16x16x32_bf16 v[12:15], v[154:157], v[214:217], v[12:15]
	v_mfma_f32_16x16x32_bf16 v[8:11], v[162:165], v[214:217], v[8:11]
	s_setprio 0
	s_barrier
; #define PG8_STAGE(bufoff, gbase, voff) do { _Pragma("unroll") for (int _i = 0; _i < 2; ++_i) \
;         __builtin_amdgcn_global_load_lds((const unsigned*)((const char*)(gbase) + (voff)[_i]), (LAS unsigned*)(lds + (bufoff) + ldsw + _i * 8192), 16, 0, 0); } while (0)
; #define PG8_LDA(dst, b, h) do { _Pragma("unroll") for (int m = 0; m < 4; ++m) _Pragma("unroll") for (int k = 0; k < 2; ++k) dst[m][k] = *(const LAS bf16x8*)(lds + PG8_SA(b, h) + aoff + m * 2048 + k * 1024); } while (0)
; #define PG8_LDB(dst, b, h) do { _Pragma("unroll") for (int n = 0; n < 2; ++n) _Pragma("unroll") for (int k = 0; k < 2; ++k) dst[n][k] = *(const LAS bf16x8*)(lds + PG8_SB(b, h) + boff + n * 2048 + k * 1024); } while (0)
; #define PG8_MMA(ai, bj, At, Bt) do { __builtin_amdgcn_s_setprio(1); _Pragma("unroll") for (int m = 0; m < 4; ++m) _Pragma("unroll") for (int n = 0; n < 2; ++n) _Pragma("unroll") for (int k = 0; k < 2; ++k) \
;         acc[ai][bj][m][n] = __builtin_amdgcn_mfma_f32_16x16x32_bf16(Bt[n][k], At[m][k], acc[ai][bj][m][n], 0, 0, 0); __builtin_amdgcn_s_setprio(0); } while (0)
; #define PG8_WAIT_V(n) asm volatile("s_waitcnt vmcnt(" #n ")" ::: "memory")
; #define PG8_WAIT_L(n) asm volatile("s_waitcnt lgkmcnt(" #n ")" ::: "memory")
; #define PG8_BAR __builtin_amdgcn_s_barrier()
; #define PG8_SCHED __builtin_amdgcn_sched_barrier(0)
; template <class Epi, class Sched>
; DI void gemm_phase(LAS unsigned char* lds, const Gemm g, const Sched& S, const Epi& E) {
;     ...
;             PG8_STAGE(PG8_SB(0, 1), b2 + hstep, voffB);
;             PG8_WAIT_V(6); PG8_BAR; PG8_MMA(1, 1, At, B1); PG8_BAR;
;             PG8_LDB(B0, 1, 0); PG8_SCHED; PG8_LDA(At, 1, 0); PG8_STAGE(PG8_SA(0, 1), a2 + hstep, voffA);
;             PG8_WAIT_L(8); PG8_BAR; PG8_WAIT_L(0); PG8_MMA(0, 0, At, B0); PG8_BAR; PG8_SCHED;
;             PG8_LDB(B1, 1, 1); PG8_STAGE(PG8_SB(1, 0), b3, voffB);
;             PG8_BAR; PG8_WAIT_L(0); PG8_MMA(0, 1, At, B1); PG8_BAR;
;             PG8_LDA(At, 1, 1); PG8_STAGE(PG8_SA(1, 0), a3, voffA);
;             PG8_BAR; PG8_WAIT_L(0); PG8_MMA(1, 0, At, B0); PG8_BAR; PG8_SCHED;
	s_add_u32 s0, s46, 0x80000
	s_addc_u32 s1, s47, 0
	s_add_i32 s4, s66, s51
	s_mov_b32 m0, s4
	s_nop 0
	global_load_lds_dwordx4 v132, s[0:1]
	s_add_i32 m0, s4, 0x2000
	s_nop 0
	global_load_lds_dwordx4 v134, s[0:1]
	s_waitcnt vmcnt(6)
	s_barrier
	s_setprio 1
	v_mfma_f32_16x16x32_bf16 v[52:55], v[218:221], v[166:169], 0
	v_mfma_f32_16x16x32_bf16 v[48:51], v[226:229], v[166:169], 0
	v_mfma_f32_16x16x32_bf16 v[36:39], v[218:221], v[174:177], 0
	v_mfma_f32_16x16x32_bf16 v[32:35], v[226:229], v[174:177], 0
	v_mfma_f32_16x16x32_bf16 v[20:23], v[218:221], v[188:191], 0
	v_mfma_f32_16x16x32_bf16 v[16:19], v[226:229], v[188:191], 0
	v_mfma_f32_16x16x32_bf16 v[4:7], v[218:221], v[210:213], 0
	v_mfma_f32_16x16x32_bf16 v[0:3], v[226:229], v[210:213], 0
	v_mfma_f32_16x16x32_bf16 v[52:55], v[222:225], v[170:173], v[52:55]
	v_mfma_f32_16x16x32_bf16 v[48:51], v[230:233], v[170:173], v[48:51]
	v_mfma_f32_16x16x32_bf16 v[36:39], v[222:225], v[178:181], v[36:39]
	v_mfma_f32_16x16x32_bf16 v[32:35], v[230:233], v[178:181], v[32:35]
	v_mfma_f32_16x16x32_bf16 v[20:23], v[222:225], v[206:209], v[20:23]
	v_mfma_f32_16x16x32_bf16 v[16:19], v[230:233], v[206:209], v[16:19]
	v_mfma_f32_16x16x32_bf16 v[4:7], v[222:225], v[214:217], v[4:7]
	v_mfma_f32_16x16x32_bf16 v[0:3], v[230:233], v[214:217], v[0:3]
	s_setprio 0
	s_add_i32 s4, 0, 0x18000
	v_add_u32_e32 v162, s4, v149
	s_barrier
	ds_read_b128 v[144:147], v162
	ds_read_b128 v[154:157], v162 offset:1024
	ds_read_b128 v[158:161], v162 offset:2048
	ds_read_b128 v[162:165], v162 offset:3072
	s_add_u32 s0, s48, 0x80000
	s_addc_u32 s1, s49, 0
	s_mov_b32 m0, s58
	ds_read_b128 v[166:169], v151 offset:32768
	ds_read_b128 v[170:173], v151 offset:33792
	ds_read_b128 v[174:177], v151 offset:34816
	ds_read_b128 v[178:181], v151 offset:35840
	ds_read_b128 v[188:191], v151 offset:36864
	ds_read_b128 v[206:209], v151 offset:37888
	ds_read_b128 v[210:213], v151 offset:38912
	global_load_lds_dwordx4 v128, s[0:1]
	s_mov_b32 m0, s59
	ds_read_b128 v[214:217], v151 offset:39936
	global_load_lds_dwordx4 v130, s[0:1]
	s_waitcnt lgkmcnt(8)
	s_barrier
	s_waitcnt lgkmcnt(0)
	s_setprio 1
	v_mfma_f32_16x16x32_bf16 v[124:127], v[144:147], v[166:169], v[124:127]
	v_mfma_f32_16x16x32_bf16 v[120:123], v[158:161], v[166:169], v[120:123]
	v_mfma_f32_16x16x32_bf16 v[108:111], v[144:147], v[174:177], v[108:111]
	v_mfma_f32_16x16x32_bf16 v[104:107], v[158:161], v[174:177], v[104:107]
	v_mfma_f32_16x16x32_bf16 v[92:95], v[144:147], v[188:191], v[92:95]
	v_mfma_f32_16x16x32_bf16 v[88:91], v[158:161], v[188:191], v[88:91]
	v_mfma_f32_16x16x32_bf16 v[76:79], v[144:147], v[210:213], v[76:79]
	v_mfma_f32_16x16x32_bf16 v[72:75], v[158:161], v[210:213], v[72:75]
	v_mfma_f32_16x16x32_bf16 v[124:127], v[154:157], v[170:173], v[124:127]
	v_mfma_f32_16x16x32_bf16 v[120:123], v[162:165], v[170:173], v[120:123]
	v_mfma_f32_16x16x32_bf16 v[108:111], v[154:157], v[178:181], v[108:111]
	v_mfma_f32_16x16x32_bf16 v[104:107], v[162:165], v[178:181], v[104:107]
	v_mfma_f32_16x16x32_bf16 v[92:95], v[154:157], v[206:209], v[92:95]
	v_mfma_f32_16x16x32_bf16 v[88:91], v[162:165], v[206:209], v[88:91]
	v_mfma_f32_16x16x32_bf16 v[76:79], v[154:157], v[214:217], v[76:79]
	v_mfma_f32_16x16x32_bf16 v[72:75], v[162:165], v[214:217], v[72:75]
	s_setprio 0
	s_barrier
	s_add_i32 s5, 0, 0x1c000
	s_add_i32 s0, s4, s51
	v_add_u32_e32 v201, s5, v149
	s_add_i32 m0, s0, 0xffffff80
	ds_read_b128 v[218:221], v201
	ds_read_b128 v[222:225], v201 offset:1024
	ds_read_b128 v[226:229], v201 offset:2048
	global_load_lds_dwordx4 v132, s[46:47] offset:128
	s_add_i32 m0, s0, 0x1f80
	ds_read_b128 v[230:233], v201 offset:3072
	global_load_lds_dwordx4 v134, s[46:47] offset:128
	s_barrier
	s_waitcnt lgkmcnt(0)
	s_setprio 1
	v_mfma_f32_16x16x32_bf16 v[116:119], v[218:221], v[166:169], v[116:119]
	v_mfma_f32_16x16x32_bf16 v[112:115], v[226:229], v[166:169], v[112:115]
	v_mfma_f32_16x16x32_bf16 v[100:103], v[218:221], v[174:177], v[100:103]
	v_mfma_f32_16x16x32_bf16 v[96:99], v[226:229], v[174:177], v[96:99]
	v_mfma_f32_16x16x32_bf16 v[84:87], v[218:221], v[188:191], v[84:87]
	v_mfma_f32_16x16x32_bf16 v[80:83], v[226:229], v[188:191], v[80:83]
	v_mfma_f32_16x16x32_bf16 v[68:71], v[218:221], v[210:213], v[68:71]
	v_mfma_f32_16x16x32_bf16 v[64:67], v[226:229], v[210:213], v[64:67]
	v_mfma_f32_16x16x32_bf16 v[116:119], v[222:225], v[170:173], v[116:119]
	v_mfma_f32_16x16x32_bf16 v[112:115], v[230:233], v[170:173], v[112:115]
	v_mfma_f32_16x16x32_bf16 v[100:103], v[222:225], v[178:181], v[100:103]
	v_mfma_f32_16x16x32_bf16 v[96:99], v[230:233], v[178:181], v[96:99]
	v_mfma_f32_16x16x32_bf16 v[84:87], v[222:225], v[206:209], v[84:87]
	v_mfma_f32_16x16x32_bf16 v[80:83], v[230:233], v[206:209], v[80:83]
	v_mfma_f32_16x16x32_bf16 v[68:71], v[222:225], v[214:217], v[68:71]
	v_mfma_f32_16x16x32_bf16 v[64:67], v[230:233], v[214:217], v[64:67]
	s_setprio 0
	s_add_i32 m0, s63, 0xffffff80
	s_barrier
	ds_read_b128 v[166:169], v151 offset:49152
	ds_read_b128 v[170:173], v151 offset:50176
	ds_read_b128 v[174:177], v151 offset:51200
	ds_read_b128 v[178:181], v151 offset:52224
	ds_read_b128 v[188:191], v151 offset:53248
	ds_read_b128 v[206:209], v151 offset:54272
	ds_read_b128 v[210:213], v151 offset:55296
	global_load_lds_dwordx4 v128, s[48:49] offset:128
	s_add_i32 m0, s64, 0xffffff80
	ds_read_b128 v[214:217], v151 offset:56320
	global_load_lds_dwordx4 v130, s[48:49] offset:128
	s_barrier
; #define PG8_STAGE(bufoff, gbase, voff) do { _Pragma("unroll") for (int _i = 0; _i < 2; ++_i) \
;         __builtin_amdgcn_global_load_lds((const unsigned*)((const char*)(gbase) + (voff)[_i]), (LAS unsigned*)(lds + (bufoff) + ldsw + _i * 8192), 16, 0, 0); } while (0)
; #define PG8_LDA(dst, b, h) do { _Pragma("unroll") for (int m = 0; m < 4; ++m) _Pragma("unroll") for (int k = 0; k < 2; ++k) dst[m][k] = *(const LAS bf16x8*)(lds + PG8_SA(b, h) + aoff + m * 2048 + k * 1024); } while (0)
; #define PG8_LDB(dst, b, h) do { _Pragma("unroll") for (int n = 0; n < 2; ++n) _Pragma("unroll") for (int k = 0; k < 2; ++k) dst[n][k] = *(const LAS bf16x8*)(lds + PG8_SB(b, h) + boff + n * 2048 + k * 1024); } while (0)
; #define PG8_WAIT_V(n) asm volatile("s_waitcnt vmcnt(" #n ")" ::: "memory")
; #define PG8_WAIT_L(n) asm volatile("s_waitcnt lgkmcnt(" #n ")" ::: "memory")
; #define PG8_BAR __builtin_amdgcn_s_barrier()
; #define PG8_SCHED __builtin_amdgcn_sched_barrier(0)
; template <class Epi, class Sched>
; DI void gemm_phase(LAS unsigned char* lds, const Gemm g, const Sched& S, const Epi& E) {
;     ...
;             PG8_LDB(B0, 0, 0); PG8_SCHED; PG8_LDA(At, 0, 0); PG8_STAGE(PG8_SA(1, 1), a1 + hstep, voffA);
;             PG8_WAIT_L(8); PG8_BAR; PG8_WAIT_L(0); PG8_MMA(0, 0, At, B0); PG8_BAR; PG8_SCHED;
;             PG8_LDB(B1, 0, 1); PG8_STAGE(PG8_SB(0, 0), b2, voffB);
;             PG8_BAR; PG8_WAIT_L(0); PG8_MMA(0, 1, At, B1); PG8_BAR;
;             PG8_LDA(At, 0, 1); PG8_STAGE(PG8_SA(0, 0), a2, voffA);
;             PG8_BAR; PG8_WAIT_L(0); PG8_MMA(1, 0, At, B0); PG8_BAR; PG8_SCHED;
;             PG8_STAGE(PG8_SB(0, 1), b2 + hstep, voffB);
;             PG8_WAIT_V(6); PG8_BAR; PG8_MMA(1, 1, At, B1); PG8_BAR;
;             PG8_LDB(B0, 1, 0); PG8_SCHED; PG8_LDA(At, 1, 0); PG8_STAGE(PG8_SA(0, 1), a2 + hstep, voffA);
;             PG8_WAIT_L(8); PG8_BAR; PG8_WAIT_L(0); PG8_MMA(0, 0, At, B0); PG8_BAR; PG8_SCHED;
;             PG8_LDB(B1, 1, 1); PG8_STAGE(PG8_SB(1, 0), b3, voffB);
;             PG8_BAR; PG8_WAIT_L(0); PG8_MMA(0, 1, At, B1); PG8_BAR;
;             PG8_LDA(At, 1, 1); PG8_STAGE(PG8_SA(1, 0), a3, voffA);
;             PG8_BAR; PG8_WAIT_L(0); PG8_MMA(1, 0, At, B0); PG8_BAR; PG8_SCHED;
;             PG8_STAGE(PG8_SB(1, 1), b3 + hstep, voffB);
;             PG8_WAIT_V(6); PG8_BAR; PG8_MMA(1, 1, At, B1); PG8_BAR;
	s_waitcnt lgkmcnt(0)
	s_setprio 1
	v_mfma_f32_16x16x32_bf16 v[60:63], v[144:147], v[166:169], v[60:63]
	v_mfma_f32_16x16x32_bf16 v[56:59], v[158:161], v[166:169], v[56:59]
	v_mfma_f32_16x16x32_bf16 v[44:47], v[144:147], v[174:177], v[44:47]
	v_mfma_f32_16x16x32_bf16 v[40:43], v[158:161], v[174:177], v[40:43]
	v_mfma_f32_16x16x32_bf16 v[28:31], v[144:147], v[188:191], v[28:31]
	v_mfma_f32_16x16x32_bf16 v[24:27], v[158:161], v[188:191], v[24:27]
	v_mfma_f32_16x16x32_bf16 v[12:15], v[144:147], v[210:213], v[12:15]
	v_mfma_f32_16x16x32_bf16 v[8:11], v[158:161], v[210:213], v[8:11]
	v_mfma_f32_16x16x32_bf16 v[60:63], v[154:157], v[170:173], v[60:63]
	v_mfma_f32_16x16x32_bf16 v[56:59], v[162:165], v[170:173], v[56:59]
	v_mfma_f32_16x16x32_bf16 v[44:47], v[154:157], v[178:181], v[44:47]
	v_mfma_f32_16x16x32_bf16 v[40:43], v[162:165], v[178:181], v[40:43]
	v_mfma_f32_16x16x32_bf16 v[28:31], v[154:157], v[206:209], v[28:31]
	v_mfma_f32_16x16x32_bf16 v[24:27], v[162:165], v[206:209], v[24:27]
	v_mfma_f32_16x16x32_bf16 v[12:15], v[154:157], v[214:217], v[12:15]
	v_mfma_f32_16x16x32_bf16 v[8:11], v[162:165], v[214:217], v[8:11]
	s_setprio 0
	s_barrier
	s_add_u32 s0, s46, 0x80080
	s_addc_u32 s1, s47, 0
	s_add_i32 s4, s5, s51
	s_mov_b32 m0, s4
	s_nop 0
	global_load_lds_dwordx4 v132, s[0:1]
	s_add_i32 m0, s4, 0x2000
	s_nop 0
	global_load_lds_dwordx4 v134, s[0:1]
	s_waitcnt vmcnt(6)
	s_barrier
	s_setprio 1
	v_mfma_f32_16x16x32_bf16 v[52:55], v[218:221], v[166:169], v[52:55]
	v_mfma_f32_16x16x32_bf16 v[48:51], v[226:229], v[166:169], v[48:51]
	v_mfma_f32_16x16x32_bf16 v[36:39], v[218:221], v[174:177], v[36:39]
	v_mfma_f32_16x16x32_bf16 v[32:35], v[226:229], v[174:177], v[32:35]
	v_mfma_f32_16x16x32_bf16 v[20:23], v[218:221], v[188:191], v[20:23]
	v_mfma_f32_16x16x32_bf16 v[16:19], v[226:229], v[188:191], v[16:19]
	v_mfma_f32_16x16x32_bf16 v[4:7], v[218:221], v[210:213], v[4:7]
	v_mfma_f32_16x16x32_bf16 v[0:3], v[226:229], v[210:213], v[0:3]
	v_mfma_f32_16x16x32_bf16 v[52:55], v[222:225], v[170:173], v[52:55]
	v_mfma_f32_16x16x32_bf16 v[48:51], v[230:233], v[170:173], v[48:51]
	v_mfma_f32_16x16x32_bf16 v[36:39], v[222:225], v[178:181], v[36:39]
	v_mfma_f32_16x16x32_bf16 v[32:35], v[230:233], v[178:181], v[32:35]
	v_mfma_f32_16x16x32_bf16 v[20:23], v[222:225], v[206:209], v[20:23]
	v_mfma_f32_16x16x32_bf16 v[16:19], v[230:233], v[206:209], v[16:19]
	v_mfma_f32_16x16x32_bf16 v[4:7], v[222:225], v[214:217], v[4:7]
	v_mfma_f32_16x16x32_bf16 v[0:3], v[230:233], v[214:217], v[0:3]
	s_setprio 0
	s_add_i32 s69, s69, 2
	s_add_u32 s44, s44, 0x100
	s_addc_u32 s45, s45, 0
	s_add_u32 s43, s43, 0x100
	s_addc_u32 s68, s68, 0
	s_cmp_gt_u32 s69, 29
	s_barrier
	s_cbranch_scc0 .LBB0_1508
	s_branch .Lpeel_done_1508
.LBB0_1508:
	ds_read_b128 v[144:147], v150
	ds_read_b128 v[154:157], v150 offset:1024
	ds_read_b128 v[158:161], v150 offset:2048
	ds_read_b128 v[162:165], v150 offset:3072
	s_add_u32 s0, s44, 0xfff80080
	s_addc_u32 s1, s45, -1
	s_cmp_eq_u32 s69, 28
	s_cselect_b32 s49, s34, s1
	s_cselect_b32 s48, s35, s0
	s_cselect_b32 s47, s31, s68
	s_cselect_b32 s46, s37, s43
	s_add_i32 m0, s52, 0xc000
	ds_read_b128 v[166:169], v151
	ds_read_b128 v[170:173], v151 offset:1024
	ds_read_b128 v[174:177], v151 offset:2048
	ds_read_b128 v[178:181], v151 offset:3072
	ds_read_b128 v[188:191], v151 offset:4096
	ds_read_b128 v[206:209], v151 offset:5120
	ds_read_b128 v[210:213], v151 offset:6144
	global_load_lds_dwordx4 v136, s[44:45]
	s_add_i32 m0, s52, 0xe000
	ds_read_b128 v[214:217], v151 offset:7168
	global_load_lds_dwordx4 v138, s[44:45]
	s_waitcnt lgkmcnt(8)
	s_barrier
	s_waitcnt lgkmcnt(0)
	s_setprio 1
	v_mfma_f32_16x16x32_bf16 v[124:127], v[144:147], v[166:169], v[124:127]
	v_mfma_f32_16x16x32_bf16 v[120:123], v[158:161], v[166:169], v[120:123]
	v_mfma_f32_16x16x32_bf16 v[108:111], v[144:147], v[174:177], v[108:111]
	v_mfma_f32_16x16x32_bf16 v[104:107], v[158:161], v[174:177], v[104:107]
	v_mfma_f32_16x16x32_bf16 v[92:95], v[144:147], v[188:191], v[92:95]
	v_mfma_f32_16x16x32_bf16 v[88:91], v[158:161], v[188:191], v[88:91]
	v_mfma_f32_16x16x32_bf16 v[76:79], v[144:147], v[210:213], v[76:79]
	v_mfma_f32_16x16x32_bf16 v[72:75], v[158:161], v[210:213], v[72:75]
	v_mfma_f32_16x16x32_bf16 v[124:127], v[154:157], v[170:173], v[124:127]
	v_mfma_f32_16x16x32_bf16 v[120:123], v[162:165], v[170:173], v[120:123]
	v_mfma_f32_16x16x32_bf16 v[108:111], v[154:157], v[178:181], v[108:111]
	v_mfma_f32_16x16x32_bf16 v[104:107], v[162:165], v[178:181], v[104:107]
	v_mfma_f32_16x16x32_bf16 v[92:95], v[154:157], v[206:209], v[92:95]
	v_mfma_f32_16x16x32_bf16 v[88:91], v[162:165], v[206:209], v[88:91]
	v_mfma_f32_16x16x32_bf16 v[76:79], v[154:157], v[214:217], v[76:79]
	v_mfma_f32_16x16x32_bf16 v[72:75], v[162:165], v[214:217], v[72:75]
	s_setprio 0
	s_barrier
	s_add_i32 s0, s65, s51
	s_mov_b32 m0, s0
	ds_read_b128 v[218:221], v152
	ds_read_b128 v[222:225], v152 offset:1024
	ds_read_b128 v[226:229], v152 offset:2048
	global_load_lds_dwordx4 v132, s[46:47]
	s_add_i32 m0, s0, 0x2000
	ds_read_b128 v[230:233], v152 offset:3072
	global_load_lds_dwordx4 v134, s[46:47]
	s_barrier
; #define PG8_STAGE(bufoff, gbase, voff) do { _Pragma("unroll") for (int _i = 0; _i < 2; ++_i) \
;         __builtin_amdgcn_global_load_lds((const unsigned*)((const char*)(gbase) + (voff)[_i]), (LAS unsigned*)(lds + (bufoff) + ldsw + _i * 8192), 16, 0, 0); } while (0)
; #define PG8_LDA(dst, b, h) do { _Pragma("unroll") for (int m = 0; m < 4; ++m) _Pragma("unroll") for (int k = 0; k < 2; ++k) dst[m][k] = *(const LAS bf16x8*)(lds + PG8_SA(b, h) + aoff + m * 2048 + k * 1024); } while (0)
; #define PG8_LDB(dst, b, h) do { _Pragma("unroll") for (int n = 0; n < 2; ++n) _Pragma("unroll") for (int k = 0; k < 2; ++k) dst[n][k] = *(const LAS bf16x8*)(lds + PG8_SB(b, h) + boff + n * 2048 + k * 1024); } while (0)
; #define PG8_MMA(ai, bj, At, Bt) do { __builtin_amdgcn_s_setprio(1); _Pragma("unroll") for (int m = 0; m < 4; ++m) _Pragma("unroll") for (int n = 0; n < 2; ++n) _Pragma("unroll") for (int k = 0; k < 2; ++k) \
;         acc[ai][bj][m][n] = __builtin_amdgcn_mfma_f32_16x16x32_bf16(Bt[n][k], At[m][k], acc[ai][bj][m][n], 0, 0, 0); __builtin_amdgcn_s_setprio(0); } while (0)
; #define PG8_WAIT_V(n) asm volatile("s_waitcnt vmcnt(" #n ")" ::: "memory")
; #define PG8_WAIT_L(n) asm volatile("s_waitcnt lgkmcnt(" #n ")" ::: "memory")
; #define PG8_BAR __builtin_amdgcn_s_barrier()
; #define PG8_SCHED __builtin_amdgcn_sched_barrier(0)
; template <class Epi, class Sched>
; DI void gemm_phase(LAS unsigned char* lds, const Gemm g, const Sched& S, const Epi& E) {
;     ...
;             PG8_BAR; PG8_WAIT_L(0); PG8_MMA(0, 1, At, B1); PG8_BAR;
;             PG8_LDA(At, 0, 1); PG8_STAGE(PG8_SA(0, 0), a2, voffA);
;             PG8_BAR; PG8_WAIT_L(0); PG8_MMA(1, 0, At, B0); PG8_BAR; PG8_SCHED;
;             PG8_STAGE(PG8_SB(0, 1), b2 + hstep, voffB);
;             PG8_WAIT_V(6); PG8_BAR; PG8_MMA(1, 1, At, B1); PG8_BAR;
;             PG8_LDB(B0, 1, 0); PG8_SCHED; PG8_LDA(At, 1, 0); PG8_STAGE(PG8_SA(0, 1), a2 + hstep, voffA);
;             PG8_WAIT_L(8); PG8_BAR; PG8_WAIT_L(0); PG8_MMA(0, 0, At, B0); PG8_BAR; PG8_SCHED;
;             PG8_LDB(B1, 1, 1); PG8_STAGE(PG8_SB(1, 0), b3, voffB);
;             PG8_BAR; PG8_WAIT_L(0); PG8_MMA(0, 1, At, B1); PG8_BAR;
;             PG8_LDA(At, 1, 1); PG8_STAGE(PG8_SA(1, 0), a3, voffA);
	s_waitcnt lgkmcnt(0)
	s_setprio 1
	v_mfma_f32_16x16x32_bf16 v[116:119], v[218:221], v[166:169], v[116:119]
	v_mfma_f32_16x16x32_bf16 v[112:115], v[226:229], v[166:169], v[112:115]
	v_mfma_f32_16x16x32_bf16 v[100:103], v[218:221], v[174:177], v[100:103]
	v_mfma_f32_16x16x32_bf16 v[96:99], v[226:229], v[174:177], v[96:99]
	v_mfma_f32_16x16x32_bf16 v[84:87], v[218:221], v[188:191], v[84:87]
	v_mfma_f32_16x16x32_bf16 v[80:83], v[226:229], v[188:191], v[80:83]
	v_mfma_f32_16x16x32_bf16 v[68:71], v[218:221], v[210:213], v[68:71]
	v_mfma_f32_16x16x32_bf16 v[64:67], v[226:229], v[210:213], v[64:67]
	v_mfma_f32_16x16x32_bf16 v[116:119], v[222:225], v[170:173], v[116:119]
	v_mfma_f32_16x16x32_bf16 v[112:115], v[230:233], v[170:173], v[112:115]
	v_mfma_f32_16x16x32_bf16 v[100:103], v[222:225], v[178:181], v[100:103]
	v_mfma_f32_16x16x32_bf16 v[96:99], v[230:233], v[178:181], v[96:99]
	v_mfma_f32_16x16x32_bf16 v[84:87], v[222:225], v[206:209], v[84:87]
	v_mfma_f32_16x16x32_bf16 v[80:83], v[230:233], v[206:209], v[80:83]
	v_mfma_f32_16x16x32_bf16 v[68:71], v[222:225], v[214:217], v[68:71]
	v_mfma_f32_16x16x32_bf16 v[64:67], v[230:233], v[214:217], v[64:67]
	s_setprio 0
	s_mov_b32 m0, s52
	s_barrier
	ds_read_b128 v[166:169], v151 offset:16384
	ds_read_b128 v[170:173], v151 offset:17408
	ds_read_b128 v[174:177], v151 offset:18432
	ds_read_b128 v[178:181], v151 offset:19456
	ds_read_b128 v[188:191], v151 offset:20480
	ds_read_b128 v[206:209], v151 offset:21504
	ds_read_b128 v[210:213], v151 offset:22528
	global_load_lds_dwordx4 v128, s[48:49]
	s_mov_b32 m0, s53
	ds_read_b128 v[214:217], v151 offset:23552
	global_load_lds_dwordx4 v130, s[48:49]
	s_barrier
	s_waitcnt lgkmcnt(0)
	s_setprio 1
	v_mfma_f32_16x16x32_bf16 v[60:63], v[144:147], v[166:169], v[60:63]
	v_mfma_f32_16x16x32_bf16 v[56:59], v[158:161], v[166:169], v[56:59]
	v_mfma_f32_16x16x32_bf16 v[44:47], v[144:147], v[174:177], v[44:47]
	v_mfma_f32_16x16x32_bf16 v[40:43], v[158:161], v[174:177], v[40:43]
	v_mfma_f32_16x16x32_bf16 v[28:31], v[144:147], v[188:191], v[28:31]
	v_mfma_f32_16x16x32_bf16 v[24:27], v[158:161], v[188:191], v[24:27]
	v_mfma_f32_16x16x32_bf16 v[12:15], v[144:147], v[210:213], v[12:15]
	v_mfma_f32_16x16x32_bf16 v[8:11], v[158:161], v[210:213], v[8:11]
	v_mfma_f32_16x16x32_bf16 v[60:63], v[154:157], v[170:173], v[60:63]
	v_mfma_f32_16x16x32_bf16 v[56:59], v[162:165], v[170:173], v[56:59]
	v_mfma_f32_16x16x32_bf16 v[44:47], v[154:157], v[178:181], v[44:47]
	v_mfma_f32_16x16x32_bf16 v[40:43], v[162:165], v[178:181], v[40:43]
	v_mfma_f32_16x16x32_bf16 v[28:31], v[154:157], v[206:209], v[28:31]
	v_mfma_f32_16x16x32_bf16 v[24:27], v[162:165], v[206:209], v[24:27]
	v_mfma_f32_16x16x32_bf16 v[12:15], v[154:157], v[214:217], v[12:15]
	v_mfma_f32_16x16x32_bf16 v[8:11], v[162:165], v[214:217], v[8:11]
	s_setprio 0
	s_barrier
	s_add_u32 s0, s46, 0x80000
	s_addc_u32 s1, s47, 0
	s_add_i32 s4, s66, s51
	s_mov_b32 m0, s4
	s_nop 0
	global_load_lds_dwordx4 v132, s[0:1]
	s_add_i32 m0, s4, 0x2000
	s_nop 0
	global_load_lds_dwordx4 v134, s[0:1]
	s_waitcnt vmcnt(6)
	s_barrier
	s_setprio 1
	v_mfma_f32_16x16x32_bf16 v[52:55], v[218:221], v[166:169], v[52:55]
	v_mfma_f32_16x16x32_bf16 v[48:51], v[226:229], v[166:169], v[48:51]
	v_mfma_f32_16x16x32_bf16 v[36:39], v[218:221], v[174:177], v[36:39]
	v_mfma_f32_16x16x32_bf16 v[32:35], v[226:229], v[174:177], v[32:35]
	v_mfma_f32_16x16x32_bf16 v[20:23], v[218:221], v[188:191], v[20:23]
	v_mfma_f32_16x16x32_bf16 v[16:19], v[226:229], v[188:191], v[16:19]
	v_mfma_f32_16x16x32_bf16 v[4:7], v[218:221], v[210:213], v[4:7]
	v_mfma_f32_16x16x32_bf16 v[0:3], v[226:229], v[210:213], v[0:3]
	v_mfma_f32_16x16x32_bf16 v[52:55], v[222:225], v[170:173], v[52:55]
	v_mfma_f32_16x16x32_bf16 v[48:51], v[230:233], v[170:173], v[48:51]
	v_mfma_f32_16x16x32_bf16 v[36:39], v[222:225], v[178:181], v[36:39]
	v_mfma_f32_16x16x32_bf16 v[32:35], v[230:233], v[178:181], v[32:35]
	v_mfma_f32_16x16x32_bf16 v[20:23], v[222:225], v[206:209], v[20:23]
	v_mfma_f32_16x16x32_bf16 v[16:19], v[230:233], v[206:209], v[16:19]
	v_mfma_f32_16x16x32_bf16 v[4:7], v[222:225], v[214:217], v[4:7]
	v_mfma_f32_16x16x32_bf16 v[0:3], v[230:233], v[214:217], v[0:3]
	s_setprio 0
	s_add_i32 s4, 0, 0x18000
	v_add_u32_e32 v162, s4, v149
	s_barrier
	ds_read_b128 v[144:147], v162
	ds_read_b128 v[154:157], v162 offset:1024
	ds_read_b128 v[158:161], v162 offset:2048
	ds_read_b128 v[162:165], v162 offset:3072
	s_add_u32 s0, s48, 0x80000
	s_addc_u32 s1, s49, 0
	s_mov_b32 m0, s58
	ds_read_b128 v[166:169], v151 offset:32768
	ds_read_b128 v[170:173], v151 offset:33792
	ds_read_b128 v[174:177], v151 offset:34816
	ds_read_b128 v[178:181], v151 offset:35840
	ds_read_b128 v[188:191], v151 offset:36864
	ds_read_b128 v[206:209], v151 offset:37888
	ds_read_b128 v[210:213], v151 offset:38912
	global_load_lds_dwordx4 v128, s[0:1]
	s_mov_b32 m0, s59
	ds_read_b128 v[214:217], v151 offset:39936
	global_load_lds_dwordx4 v130, s[0:1]
	s_waitcnt lgkmcnt(8)
	s_barrier
; #define PG8_STAGE(bufoff, gbase, voff) do { _Pragma("unroll") for (int _i = 0; _i < 2; ++_i) \
;         __builtin_amdgcn_global_load_lds((const unsigned*)((const char*)(gbase) + (voff)[_i]), (LAS unsigned*)(lds + (bufoff) + ldsw + _i * 8192), 16, 0, 0); } while (0)
; #define PG8_LDA(dst, b, h) do { _Pragma("unroll") for (int m = 0; m < 4; ++m) _Pragma("unroll") for (int k = 0; k < 2; ++k) dst[m][k] = *(const LAS bf16x8*)(lds + PG8_SA(b, h) + aoff + m * 2048 + k * 1024); } while (0)
; #define PG8_LDB(dst, b, h) do { _Pragma("unroll") for (int n = 0; n < 2; ++n) _Pragma("unroll") for (int k = 0; k < 2; ++k) dst[n][k] = *(const LAS bf16x8*)(lds + PG8_SB(b, h) + boff + n * 2048 + k * 1024); } while (0)
; #define PG8_MMA(ai, bj, At, Bt) do { __builtin_amdgcn_s_setprio(1); _Pragma("unroll") for (int m = 0; m < 4; ++m) _Pragma("unroll") for (int n = 0; n < 2; ++n) _Pragma("unroll") for (int k = 0; k < 2; ++k) \
;         acc[ai][bj][m][n] = __builtin_amdgcn_mfma_f32_16x16x32_bf16(Bt[n][k], At[m][k], acc[ai][bj][m][n], 0, 0, 0); __builtin_amdgcn_s_setprio(0); } while (0)
; #define PG8_WAIT_V(n) asm volatile("s_waitcnt vmcnt(" #n ")" ::: "memory")
; #define PG8_WAIT_L(n) asm volatile("s_waitcnt lgkmcnt(" #n ")" ::: "memory")
; #define PG8_BAR __builtin_amdgcn_s_barrier()
; #define PG8_SCHED __builtin_amdgcn_sched_barrier(0)
; template <class Epi, class Sched>
; DI void gemm_phase(LAS unsigned char* lds, const Gemm g, const Sched& S, const Epi& E) {
;     ...
;             PG8_WAIT_L(8); PG8_BAR; PG8_WAIT_L(0); PG8_MMA(0, 0, At, B0); PG8_BAR; PG8_SCHED;
;             PG8_LDB(B1, 1, 1); PG8_STAGE(PG8_SB(1, 0), b3, voffB);
;             PG8_BAR; PG8_WAIT_L(0); PG8_MMA(0, 1, At, B1); PG8_BAR;
;             PG8_LDA(At, 1, 1); PG8_STAGE(PG8_SA(1, 0), a3, voffA);
;             PG8_BAR; PG8_WAIT_L(0); PG8_MMA(1, 0, At, B0); PG8_BAR; PG8_SCHED;
;             PG8_STAGE(PG8_SB(1, 1), b3 + hstep, voffB);
;             PG8_WAIT_V(6); PG8_BAR; PG8_MMA(1, 1, At, B1); PG8_BAR;
	s_waitcnt lgkmcnt(0)
	s_setprio 1
	v_mfma_f32_16x16x32_bf16 v[124:127], v[144:147], v[166:169], v[124:127]
	v_mfma_f32_16x16x32_bf16 v[120:123], v[158:161], v[166:169], v[120:123]
	v_mfma_f32_16x16x32_bf16 v[108:111], v[144:147], v[174:177], v[108:111]
	v_mfma_f32_16x16x32_bf16 v[104:107], v[158:161], v[174:177], v[104:107]
	v_mfma_f32_16x16x32_bf16 v[92:95], v[144:147], v[188:191], v[92:95]
	v_mfma_f32_16x16x32_bf16 v[88:91], v[158:161], v[188:191], v[88:91]
	v_mfma_f32_16x16x32_bf16 v[76:79], v[144:147], v[210:213], v[76:79]
	v_mfma_f32_16x16x32_bf16 v[72:75], v[158:161], v[210:213], v[72:75]
	v_mfma_f32_16x16x32_bf16 v[124:127], v[154:157], v[170:173], v[124:127]
	v_mfma_f32_16x16x32_bf16 v[120:123], v[162:165], v[170:173], v[120:123]
	v_mfma_f32_16x16x32_bf16 v[108:111], v[154:157], v[178:181], v[108:111]
	v_mfma_f32_16x16x32_bf16 v[104:107], v[162:165], v[178:181], v[104:107]
	v_mfma_f32_16x16x32_bf16 v[92:95], v[154:157], v[206:209], v[92:95]
	v_mfma_f32_16x16x32_bf16 v[88:91], v[162:165], v[206:209], v[88:91]
	v_mfma_f32_16x16x32_bf16 v[76:79], v[154:157], v[214:217], v[76:79]
	v_mfma_f32_16x16x32_bf16 v[72:75], v[162:165], v[214:217], v[72:75]
	s_setprio 0
	s_barrier
	s_add_i32 s5, 0, 0x1c000
	s_add_i32 s0, s4, s51
	v_add_u32_e32 v201, s5, v149
	s_add_i32 m0, s0, 0xffffff80
	ds_read_b128 v[218:221], v201
	ds_read_b128 v[222:225], v201 offset:1024
	ds_read_b128 v[226:229], v201 offset:2048
	global_load_lds_dwordx4 v132, s[46:47] offset:128
	s_add_i32 m0, s0, 0x1f80
	ds_read_b128 v[230:233], v201 offset:3072
	global_load_lds_dwordx4 v134, s[46:47] offset:128
	s_barrier
	s_waitcnt lgkmcnt(0)
	s_setprio 1
	v_mfma_f32_16x16x32_bf16 v[116:119], v[218:221], v[166:169], v[116:119]
	v_mfma_f32_16x16x32_bf16 v[112:115], v[226:229], v[166:169], v[112:115]
	v_mfma_f32_16x16x32_bf16 v[100:103], v[218:221], v[174:177], v[100:103]
	v_mfma_f32_16x16x32_bf16 v[96:99], v[226:229], v[174:177], v[96:99]
	v_mfma_f32_16x16x32_bf16 v[84:87], v[218:221], v[188:191], v[84:87]
	v_mfma_f32_16x16x32_bf16 v[80:83], v[226:229], v[188:191], v[80:83]
	v_mfma_f32_16x16x32_bf16 v[68:71], v[218:221], v[210:213], v[68:71]
	v_mfma_f32_16x16x32_bf16 v[64:67], v[226:229], v[210:213], v[64:67]
	v_mfma_f32_16x16x32_bf16 v[116:119], v[222:225], v[170:173], v[116:119]
	v_mfma_f32_16x16x32_bf16 v[112:115], v[230:233], v[170:173], v[112:115]
	v_mfma_f32_16x16x32_bf16 v[100:103], v[222:225], v[178:181], v[100:103]
	v_mfma_f32_16x16x32_bf16 v[96:99], v[230:233], v[178:181], v[96:99]
	v_mfma_f32_16x16x32_bf16 v[84:87], v[222:225], v[206:209], v[84:87]
	v_mfma_f32_16x16x32_bf16 v[80:83], v[230:233], v[206:209], v[80:83]
	v_mfma_f32_16x16x32_bf16 v[68:71], v[222:225], v[214:217], v[68:71]
	v_mfma_f32_16x16x32_bf16 v[64:67], v[230:233], v[214:217], v[64:67]
	s_setprio 0
	s_add_i32 m0, s63, 0xffffff80
	s_barrier
	ds_read_b128 v[166:169], v151 offset:49152
	ds_read_b128 v[170:173], v151 offset:50176
	ds_read_b128 v[174:177], v151 offset:51200
	ds_read_b128 v[178:181], v151 offset:52224
	ds_read_b128 v[188:191], v151 offset:53248
	ds_read_b128 v[206:209], v151 offset:54272
	ds_read_b128 v[210:213], v151 offset:55296
	global_load_lds_dwordx4 v128, s[48:49] offset:128
	s_add_i32 m0, s64, 0xffffff80
	ds_read_b128 v[214:217], v151 offset:56320
	global_load_lds_dwordx4 v130, s[48:49] offset:128
	s_barrier
	s_waitcnt lgkmcnt(0)
	s_setprio 1
	v_mfma_f32_16x16x32_bf16 v[60:63], v[144:147], v[166:169], v[60:63]
	v_mfma_f32_16x16x32_bf16 v[56:59], v[158:161], v[166:169], v[56:59]
	v_mfma_f32_16x16x32_bf16 v[44:47], v[144:147], v[174:177], v[44:47]
	v_mfma_f32_16x16x32_bf16 v[40:43], v[158:161], v[174:177], v[40:43]
	v_mfma_f32_16x16x32_bf16 v[28:31], v[144:147], v[188:191], v[28:31]
	v_mfma_f32_16x16x32_bf16 v[24:27], v[158:161], v[188:191], v[24:27]
	v_mfma_f32_16x16x32_bf16 v[12:15], v[144:147], v[210:213], v[12:15]
	v_mfma_f32_16x16x32_bf16 v[8:11], v[158:161], v[210:213], v[8:11]
	v_mfma_f32_16x16x32_bf16 v[60:63], v[154:157], v[170:173], v[60:63]
	v_mfma_f32_16x16x32_bf16 v[56:59], v[162:165], v[170:173], v[56:59]
	v_mfma_f32_16x16x32_bf16 v[44:47], v[154:157], v[178:181], v[44:47]
	v_mfma_f32_16x16x32_bf16 v[40:43], v[162:165], v[178:181], v[40:43]
	v_mfma_f32_16x16x32_bf16 v[28:31], v[154:157], v[206:209], v[28:31]
	v_mfma_f32_16x16x32_bf16 v[24:27], v[162:165], v[206:209], v[24:27]
	v_mfma_f32_16x16x32_bf16 v[12:15], v[154:157], v[214:217], v[12:15]
	v_mfma_f32_16x16x32_bf16 v[8:11], v[162:165], v[214:217], v[8:11]
	s_setprio 0
	s_barrier
	s_add_u32 s0, s46, 0x80080
	s_addc_u32 s1, s47, 0
	s_add_i32 s4, s5, s51
	s_mov_b32 m0, s4
	s_nop 0
	global_load_lds_dwordx4 v132, s[0:1]
	s_add_i32 m0, s4, 0x2000
	s_nop 0
	global_load_lds_dwordx4 v134, s[0:1]
	s_waitcnt vmcnt(6)
	s_barrier
	s_setprio 1
	v_mfma_f32_16x16x32_bf16 v[52:55], v[218:221], v[166:169], v[52:55]
	v_mfma_f32_16x16x32_bf16 v[48:51], v[226:229], v[166:169], v[48:51]
	v_mfma_f32_16x16x32_bf16 v[36:39], v[218:221], v[174:177], v[36:39]
	v_mfma_f32_16x16x32_bf16 v[32:35], v[226:229], v[174:177], v[32:35]
	v_mfma_f32_16x16x32_bf16 v[20:23], v[218:221], v[188:191], v[20:23]
	v_mfma_f32_16x16x32_bf16 v[16:19], v[226:229], v[188:191], v[16:19]
	v_mfma_f32_16x16x32_bf16 v[4:7], v[218:221], v[210:213], v[4:7]
	v_mfma_f32_16x16x32_bf16 v[0:3], v[226:229], v[210:213], v[0:3]
	v_mfma_f32_16x16x32_bf16 v[52:55], v[222:225], v[170:173], v[52:55]
	v_mfma_f32_16x16x32_bf16 v[48:51], v[230:233], v[170:173], v[48:51]
	v_mfma_f32_16x16x32_bf16 v[36:39], v[222:225], v[178:181], v[36:39]
	v_mfma_f32_16x16x32_bf16 v[32:35], v[230:233], v[178:181], v[32:35]
	v_mfma_f32_16x16x32_bf16 v[20:23], v[222:225], v[206:209], v[20:23]
	v_mfma_f32_16x16x32_bf16 v[16:19], v[230:233], v[206:209], v[16:19]
	v_mfma_f32_16x16x32_bf16 v[4:7], v[222:225], v[214:217], v[4:7]
	v_mfma_f32_16x16x32_bf16 v[0:3], v[230:233], v[214:217], v[0:3]
	s_setprio 0
	s_add_i32 s69, s69, 2
	s_add_u32 s44, s44, 0x100
	s_addc_u32 s45, s45, 0
	s_add_u32 s43, s43, 0x100
	s_addc_u32 s68, s68, 0
	s_cmp_gt_u32 s69, 29
	s_barrier
	s_cbranch_scc0 .LBB0_1508

;     DI size_t aoff(const Unit& u, size_t tstep) const { return (size_t)u.pm * tstep; }
;     DI size_t boff(const Unit& u, size_t tstep) const { return (size_t)u.pn * tstep; }
;     DI size_t aoff(const Unit& u, size_t) const { return (size_t)u.ks * kbytes; }
;     DI size_t boff(const Unit& u, size_t tstep) const { return (size_t)u.pn * tstep + (size_t)u.ks * kbytes; }
;     DI size_t aoff(const Unit& u, size_t tstep) const { return (u.ks < 2 ? offU : offOA) + (size_t)u.pm * tstep; }
; #define PG8_STAGE(bufoff, gbase, voff) do { _Pragma("unroll") for (int _i = 0; _i < 2; ++_i) \
;         __builtin_amdgcn_global_load_lds((const unsigned*)((const char*)(gbase) + (voff)[_i]), (LAS unsigned*)(lds + (bufoff) + ldsw + _i * 8192), 16, 0, 0); } while (0)
; #define PG8_LDA(dst, b, h) do { _Pragma("unroll") for (int m = 0; m < 4; ++m) _Pragma("unroll") for (int k = 0; k < 2; ++k) dst[m][k] = *(const LAS bf16x8*)(lds + PG8_SA(b, h) + aoff + m * 2048 + k * 1024); } while (0)
; #define PG8_WAIT_L(n) asm volatile("s_waitcnt lgkmcnt(" #n ")" ::: "memory")
; template <class Epi, class Sched>
; DI void gemm_phase(LAS unsigned char* lds, const Gemm g, const Sched& S, const Epi& E) {
;     ...
;         const char* nA = has_next ? (const char*)g.A + S.aoff(nxt, tstep) : cA; const char* nB = has_next ? (const char*)g.Bt + S.boff(nxt, tstep) : cB;
;         for (int t = 0; t < nt; t += 2) {
;             if constexpr (Epi::HAS_MID) { if (t == E.mid_t(nt)) { int fr3 = fr, fq3 = fq; asm volatile("" : "+v"(fr3), "+v"(fq3)); E.mid(acc, cur, wr, wc, fr3, fq3); } }
;             const bool last = (t == nt - 2);
;             const char* a1 = cA + (size_t)(t + 1) * kstep;
;             const char* a2 = last ? nA : cA + (size_t)(t + 2) * kstep; const char* b2 = last ? nB : cB + (size_t)(t + 2) * kstep;
;             const char* a3 = a2 + kstep; const char* b3 = b2 + kstep;
;             PG8_LDB(B0, 0, 0); PG8_SCHED; PG8_LDA(At, 0, 0); PG8_STAGE(PG8_SA(1, 1), a1 + hstep, voffA);
;             PG8_WAIT_L(8); PG8_BAR; PG8_WAIT_L(0); PG8_MMA(0, 0, At, B0); PG8_BAR; PG8_SCHED;
;             PG8_LDB(B1, 0, 1); PG8_STAGE(PG8_SB(0, 0), b2, voffB);
;             PG8_BAR; PG8_WAIT_L(0); PG8_MMA(0, 1, At, B1); PG8_BAR;
;             PG8_LDA(At, 0, 1); PG8_STAGE(PG8_SA(0, 0), a2, voffA);
;             PG8_BAR; PG8_WAIT_L(0); PG8_MMA(1, 0, At, B0); PG8_BAR; PG8_SCHED;
.LBB0_1535:
	s_add_u32 s29, s16, s0
	s_addc_u32 s33, s17, 0
	s_add_u32 s1, s29, 0x100
	s_addc_u32 s44, s33, 0
	s_and_b64 s[4:5], s[42:43], exec
	s_cselect_b32 s49, s13, s44
	s_cselect_b32 s48, s19, s1
	s_add_u32 s0, s14, s0
	s_addc_u32 s1, s15, 0
	s_add_u32 s4, s0, 0x100
	s_addc_u32 s5, s1, 0
	s_and_b64 s[0:1], s[42:43], exec
	s_cselect_b32 s51, s39, s5
	s_cselect_b32 s50, s38, s4
	s_add_u32 s52, s29, 0x80080
	s_addc_u32 s53, s33, 0
	s_add_u32 s46, s50, 0x80000
	s_addc_u32 s47, s51, 0
	s_add_i32 s33, s70, s35
	ds_read_b128 v[136:139], v133
	ds_read_b128 v[140:143], v133 offset:1024
	ds_read_b128 v[144:147], v133 offset:2048
	ds_read_b128 v[148:151], v133 offset:3072
	s_add_i32 s29, s33, 0x2000
	s_add_i32 s5, 0, 0x18000
	s_add_u32 s44, s48, 0x80000
	s_addc_u32 s45, s49, 0
	s_add_i32 s4, s5, s35
	s_add_i32 s1, 0, 0x1c000
	s_add_i32 s0, s4, 0x2000
	s_add_u32 s42, s50, 0x80080
	s_addc_u32 s43, s51, 0
	s_add_i32 s76, s1, s35
	s_add_i32 s75, s76, 0x2000
	s_mov_b32 m0, s71
	ds_read_b128 v[152:155], v134
	ds_read_b128 v[156:159], v134 offset:1024
	ds_read_b128 v[160:163], v134 offset:2048
	ds_read_b128 v[164:167], v134 offset:3072
	ds_read_b128 v[168:171], v134 offset:4096
	ds_read_b128 v[172:175], v134 offset:5120
	ds_read_b128 v[176:179], v134 offset:6144
	global_load_lds_dwordx4 v128, s[52:53]
	s_mov_b32 m0, s72
	ds_read_b128 v[180:183], v134 offset:7168
	global_load_lds_dwordx4 v130, s[52:53]
	s_waitcnt lgkmcnt(8)
	s_barrier
	s_waitcnt lgkmcnt(0)
	s_setprio 1
	v_mfma_f32_16x16x32_bf16 v[124:127], v[136:139], v[152:155], v[124:127]
	v_mfma_f32_16x16x32_bf16 v[120:123], v[144:147], v[152:155], v[120:123]
	v_mfma_f32_16x16x32_bf16 v[116:119], v[136:139], v[160:163], v[116:119]
	v_mfma_f32_16x16x32_bf16 v[112:115], v[144:147], v[160:163], v[112:115]
	v_mfma_f32_16x16x32_bf16 v[104:107], v[136:139], v[168:171], v[104:107]
	v_mfma_f32_16x16x32_bf16 v[96:99], v[144:147], v[168:171], v[96:99]
	v_mfma_f32_16x16x32_bf16 v[88:91], v[136:139], v[176:179], v[88:91]
	v_mfma_f32_16x16x32_bf16 v[80:83], v[144:147], v[176:179], v[80:83]
	v_mfma_f32_16x16x32_bf16 v[124:127], v[140:143], v[156:159], v[124:127]
	v_mfma_f32_16x16x32_bf16 v[120:123], v[148:151], v[156:159], v[120:123]
	v_mfma_f32_16x16x32_bf16 v[116:119], v[140:143], v[164:167], v[116:119]
	v_mfma_f32_16x16x32_bf16 v[112:115], v[148:151], v[164:167], v[112:115]
	v_mfma_f32_16x16x32_bf16 v[104:107], v[140:143], v[172:175], v[104:107]
	v_mfma_f32_16x16x32_bf16 v[96:99], v[148:151], v[172:175], v[96:99]
	v_mfma_f32_16x16x32_bf16 v[88:91], v[140:143], v[180:183], v[88:91]
	v_mfma_f32_16x16x32_bf16 v[80:83], v[148:151], v[180:183], v[80:83]
	s_setprio 0
	s_barrier
	s_mov_b32 m0, s73
	ds_read_b128 v[188:191], v135
	ds_read_b128 v[206:209], v135 offset:1024
	ds_read_b128 v[210:213], v135 offset:2048
	global_load_lds_dwordx4 v128, s[50:51]
	s_mov_b32 m0, s74
	ds_read_b128 v[214:217], v135 offset:3072
	global_load_lds_dwordx4 v130, s[50:51]
	s_barrier
	s_waitcnt lgkmcnt(0)
	s_setprio 1
	v_mfma_f32_16x16x32_bf16 v[108:111], v[188:191], v[152:155], v[108:111]
	v_mfma_f32_16x16x32_bf16 v[100:103], v[210:213], v[152:155], v[100:103]
	v_mfma_f32_16x16x32_bf16 v[92:95], v[188:191], v[160:163], v[92:95]
	v_mfma_f32_16x16x32_bf16 v[84:87], v[210:213], v[160:163], v[84:87]
	v_mfma_f32_16x16x32_bf16 v[76:79], v[188:191], v[168:171], v[76:79]
	v_mfma_f32_16x16x32_bf16 v[72:75], v[210:213], v[168:171], v[72:75]
	v_mfma_f32_16x16x32_bf16 v[68:71], v[188:191], v[176:179], v[68:71]
	v_mfma_f32_16x16x32_bf16 v[64:67], v[210:213], v[176:179], v[64:67]
	v_mfma_f32_16x16x32_bf16 v[108:111], v[206:209], v[156:159], v[108:111]
	v_mfma_f32_16x16x32_bf16 v[100:103], v[214:217], v[156:159], v[100:103]
	v_mfma_f32_16x16x32_bf16 v[92:95], v[206:209], v[164:167], v[92:95]
	v_mfma_f32_16x16x32_bf16 v[84:87], v[214:217], v[164:167], v[84:87]
	v_mfma_f32_16x16x32_bf16 v[76:79], v[206:209], v[172:175], v[76:79]
	v_mfma_f32_16x16x32_bf16 v[72:75], v[214:217], v[172:175], v[72:75]
	v_mfma_f32_16x16x32_bf16 v[68:71], v[206:209], v[180:183], v[68:71]
	v_mfma_f32_16x16x32_bf16 v[64:67], v[214:217], v[180:183], v[64:67]
	s_setprio 0
	s_mov_b32 m0, s11
	s_barrier
	ds_read_b128 v[152:155], v134 offset:16384
	ds_read_b128 v[156:159], v134 offset:17408
	ds_read_b128 v[160:163], v134 offset:18432
	ds_read_b128 v[164:167], v134 offset:19456
	ds_read_b128 v[168:171], v134 offset:20480
	ds_read_b128 v[172:175], v134 offset:21504
	ds_read_b128 v[176:179], v134 offset:22528
	global_load_lds_dwordx4 v128, s[48:49]
	s_mov_b32 m0, s60
	ds_read_b128 v[180:183], v134 offset:23552
	global_load_lds_dwordx4 v130, s[48:49]
	s_barrier
	s_waitcnt lgkmcnt(0)
	s_setprio 1
	v_mfma_f32_16x16x32_bf16 v[60:63], v[136:139], v[152:155], v[60:63]
	v_mfma_f32_16x16x32_bf16 v[56:59], v[144:147], v[152:155], v[56:59]
	v_mfma_f32_16x16x32_bf16 v[52:55], v[136:139], v[160:163], v[52:55]
	v_mfma_f32_16x16x32_bf16 v[48:51], v[144:147], v[160:163], v[48:51]
	v_mfma_f32_16x16x32_bf16 v[40:43], v[136:139], v[168:171], v[40:43]
	v_mfma_f32_16x16x32_bf16 v[32:35], v[144:147], v[168:171], v[32:35]
	v_mfma_f32_16x16x32_bf16 v[24:27], v[136:139], v[176:179], v[24:27]
	v_mfma_f32_16x16x32_bf16 v[16:19], v[144:147], v[176:179], v[16:19]
	v_mfma_f32_16x16x32_bf16 v[60:63], v[140:143], v[156:159], v[60:63]
	v_mfma_f32_16x16x32_bf16 v[56:59], v[148:151], v[156:159], v[56:59]
	v_mfma_f32_16x16x32_bf16 v[52:55], v[140:143], v[164:167], v[52:55]
	v_mfma_f32_16x16x32_bf16 v[48:51], v[148:151], v[164:167], v[48:51]
	v_mfma_f32_16x16x32_bf16 v[40:43], v[140:143], v[172:175], v[40:43]
	v_mfma_f32_16x16x32_bf16 v[32:35], v[148:151], v[172:175], v[32:35]
	v_mfma_f32_16x16x32_bf16 v[24:27], v[140:143], v[180:183], v[24:27]
	v_mfma_f32_16x16x32_bf16 v[16:19], v[148:151], v[180:183], v[16:19]
	s_setprio 0
	s_barrier
; #define PG8_STAGE(bufoff, gbase, voff) do { _Pragma("unroll") for (int _i = 0; _i < 2; ++_i) \
;         __builtin_amdgcn_global_load_lds((const unsigned*)((const char*)(gbase) + (voff)[_i]), (LAS unsigned*)(lds + (bufoff) + ldsw + _i * 8192), 16, 0, 0); } while (0)
; #define PG8_LDA(dst, b, h) do { _Pragma("unroll") for (int m = 0; m < 4; ++m) _Pragma("unroll") for (int k = 0; k < 2; ++k) dst[m][k] = *(const LAS bf16x8*)(lds + PG8_SA(b, h) + aoff + m * 2048 + k * 1024); } while (0)
; #define PG8_LDB(dst, b, h) do { _Pragma("unroll") for (int n = 0; n < 2; ++n) _Pragma("unroll") for (int k = 0; k < 2; ++k) dst[n][k] = *(const LAS bf16x8*)(lds + PG8_SB(b, h) + boff + n * 2048 + k * 1024); } while (0)
; #define PG8_MMA(ai, bj, At, Bt) do { __builtin_amdgcn_s_setprio(1); _Pragma("unroll") for (int m = 0; m < 4; ++m) _Pragma("unroll") for (int n = 0; n < 2; ++n) _Pragma("unroll") for (int k = 0; k < 2; ++k) \
;         acc[ai][bj][m][n] = __builtin_amdgcn_mfma_f32_16x16x32_bf16(Bt[n][k], At[m][k], acc[ai][bj][m][n], 0, 0, 0); __builtin_amdgcn_s_setprio(0); } while (0)
; #define PG8_WAIT_V(n) asm volatile("s_waitcnt vmcnt(" #n ")" ::: "memory")
; #define PG8_WAIT_L(n) asm volatile("s_waitcnt lgkmcnt(" #n ")" ::: "memory")
; #define PG8_BAR __builtin_amdgcn_s_barrier()
; #define PG8_SCHED __builtin_amdgcn_sched_barrier(0)
; template <class Epi, class Sched>
; DI void gemm_phase(LAS unsigned char* lds, const Gemm g, const Sched& S, const Epi& E) {
;     ...
;             PG8_STAGE(PG8_SB(0, 1), b2 + hstep, voffB);
;             PG8_WAIT_V(6); PG8_BAR; PG8_MMA(1, 1, At, B1); PG8_BAR;
;             PG8_LDB(B0, 1, 0); PG8_SCHED; PG8_LDA(At, 1, 0); PG8_STAGE(PG8_SA(0, 1), a2 + hstep, voffA);
;             PG8_WAIT_L(8); PG8_BAR; PG8_WAIT_L(0); PG8_MMA(0, 0, At, B0); PG8_BAR; PG8_SCHED;
;             PG8_LDB(B1, 1, 1); PG8_STAGE(PG8_SB(1, 0), b3, voffB);
;             PG8_BAR; PG8_WAIT_L(0); PG8_MMA(0, 1, At, B1); PG8_BAR;
;             PG8_LDA(At, 1, 1); PG8_STAGE(PG8_SA(1, 0), a3, voffA);
;             PG8_BAR; PG8_WAIT_L(0); PG8_MMA(1, 0, At, B0); PG8_BAR; PG8_SCHED;
	s_mov_b32 m0, s33
	s_nop 0
	global_load_lds_dwordx4 v128, s[46:47]
	s_mov_b32 m0, s29
	s_nop 0
	global_load_lds_dwordx4 v130, s[46:47]
	s_waitcnt vmcnt(6)
	s_barrier
	s_setprio 1
	v_mfma_f32_16x16x32_bf16 v[44:47], v[188:191], v[152:155], v[44:47]
	v_mfma_f32_16x16x32_bf16 v[36:39], v[210:213], v[152:155], v[36:39]
	v_mfma_f32_16x16x32_bf16 v[28:31], v[188:191], v[160:163], v[28:31]
	v_mfma_f32_16x16x32_bf16 v[20:23], v[210:213], v[160:163], v[20:23]
	v_mfma_f32_16x16x32_bf16 v[12:15], v[188:191], v[168:171], v[12:15]
	v_mfma_f32_16x16x32_bf16 v[8:11], v[210:213], v[168:171], v[8:11]
	v_mfma_f32_16x16x32_bf16 v[4:7], v[188:191], v[176:179], v[4:7]
	v_mfma_f32_16x16x32_bf16 v[0:3], v[210:213], v[176:179], v[0:3]
	v_mfma_f32_16x16x32_bf16 v[44:47], v[206:209], v[156:159], v[44:47]
	v_mfma_f32_16x16x32_bf16 v[36:39], v[214:217], v[156:159], v[36:39]
	v_mfma_f32_16x16x32_bf16 v[28:31], v[206:209], v[164:167], v[28:31]
	v_mfma_f32_16x16x32_bf16 v[20:23], v[214:217], v[164:167], v[20:23]
	v_mfma_f32_16x16x32_bf16 v[12:15], v[206:209], v[172:175], v[12:15]
	v_mfma_f32_16x16x32_bf16 v[8:11], v[214:217], v[172:175], v[8:11]
	v_mfma_f32_16x16x32_bf16 v[4:7], v[206:209], v[180:183], v[4:7]
	v_mfma_f32_16x16x32_bf16 v[0:3], v[214:217], v[180:183], v[0:3]
	s_setprio 0
	v_add_u32_e32 v148, s5, v132
	s_barrier
	ds_read_b128 v[136:139], v148
	ds_read_b128 v[140:143], v148 offset:1024
	ds_read_b128 v[144:147], v148 offset:2048
	ds_read_b128 v[148:151], v148 offset:3072
	s_mov_b32 m0, s61
	ds_read_b128 v[152:155], v134 offset:32768
	ds_read_b128 v[156:159], v134 offset:33792
	ds_read_b128 v[160:163], v134 offset:34816
	ds_read_b128 v[164:167], v134 offset:35840
	ds_read_b128 v[168:171], v134 offset:36864
	ds_read_b128 v[172:175], v134 offset:37888
	ds_read_b128 v[176:179], v134 offset:38912
	global_load_lds_dwordx4 v128, s[44:45]
	s_mov_b32 m0, s62
	ds_read_b128 v[180:183], v134 offset:39936
	global_load_lds_dwordx4 v130, s[44:45]
	s_waitcnt lgkmcnt(8)
	s_barrier
	s_waitcnt lgkmcnt(0)
	s_setprio 1
	v_mfma_f32_16x16x32_bf16 v[124:127], v[136:139], v[152:155], v[124:127]
	v_mfma_f32_16x16x32_bf16 v[120:123], v[144:147], v[152:155], v[120:123]
	v_mfma_f32_16x16x32_bf16 v[116:119], v[136:139], v[160:163], v[116:119]
	v_mfma_f32_16x16x32_bf16 v[112:115], v[144:147], v[160:163], v[112:115]
	v_mfma_f32_16x16x32_bf16 v[104:107], v[136:139], v[168:171], v[104:107]
	v_mfma_f32_16x16x32_bf16 v[96:99], v[144:147], v[168:171], v[96:99]
	v_mfma_f32_16x16x32_bf16 v[88:91], v[136:139], v[176:179], v[88:91]
	v_mfma_f32_16x16x32_bf16 v[80:83], v[144:147], v[176:179], v[80:83]
	v_mfma_f32_16x16x32_bf16 v[124:127], v[140:143], v[156:159], v[124:127]
	v_mfma_f32_16x16x32_bf16 v[120:123], v[148:151], v[156:159], v[120:123]
	v_mfma_f32_16x16x32_bf16 v[116:119], v[140:143], v[164:167], v[116:119]
	v_mfma_f32_16x16x32_bf16 v[112:115], v[148:151], v[164:167], v[112:115]
	v_mfma_f32_16x16x32_bf16 v[104:107], v[140:143], v[172:175], v[104:107]
	v_mfma_f32_16x16x32_bf16 v[96:99], v[148:151], v[172:175], v[96:99]
	v_mfma_f32_16x16x32_bf16 v[88:91], v[140:143], v[180:183], v[88:91]
	v_mfma_f32_16x16x32_bf16 v[80:83], v[148:151], v[180:183], v[80:83]
	s_setprio 0
	s_barrier
	s_add_i32 m0, s4, 0xffffff80
	v_add_u32_e32 v201, s1, v132
	ds_read_b128 v[188:191], v201
	ds_read_b128 v[206:209], v201 offset:1024
	ds_read_b128 v[210:213], v201 offset:2048
	global_load_lds_dwordx4 v128, s[50:51] offset:128
	s_add_i32 m0, s0, 0xffffff80
	ds_read_b128 v[214:217], v201 offset:3072
	global_load_lds_dwordx4 v130, s[50:51] offset:128
	s_barrier
	s_waitcnt lgkmcnt(0)
	s_setprio 1
	v_mfma_f32_16x16x32_bf16 v[108:111], v[188:191], v[152:155], v[108:111]
	v_mfma_f32_16x16x32_bf16 v[100:103], v[210:213], v[152:155], v[100:103]
	v_mfma_f32_16x16x32_bf16 v[92:95], v[188:191], v[160:163], v[92:95]
	v_mfma_f32_16x16x32_bf16 v[84:87], v[210:213], v[160:163], v[84:87]
	v_mfma_f32_16x16x32_bf16 v[76:79], v[188:191], v[168:171], v[76:79]
	v_mfma_f32_16x16x32_bf16 v[72:75], v[210:213], v[168:171], v[72:75]
	v_mfma_f32_16x16x32_bf16 v[68:71], v[188:191], v[176:179], v[68:71]
	v_mfma_f32_16x16x32_bf16 v[64:67], v[210:213], v[176:179], v[64:67]
	v_mfma_f32_16x16x32_bf16 v[108:111], v[206:209], v[156:159], v[108:111]
	v_mfma_f32_16x16x32_bf16 v[100:103], v[214:217], v[156:159], v[100:103]
	v_mfma_f32_16x16x32_bf16 v[92:95], v[206:209], v[164:167], v[92:95]
	v_mfma_f32_16x16x32_bf16 v[84:87], v[214:217], v[164:167], v[84:87]
	v_mfma_f32_16x16x32_bf16 v[76:79], v[206:209], v[172:175], v[76:79]
	v_mfma_f32_16x16x32_bf16 v[72:75], v[214:217], v[172:175], v[72:75]
	v_mfma_f32_16x16x32_bf16 v[68:71], v[206:209], v[180:183], v[68:71]
	v_mfma_f32_16x16x32_bf16 v[64:67], v[214:217], v[180:183], v[64:67]
	s_setprio 0
	s_add_i32 m0, s68, 0xffffff80
	s_barrier
	ds_read_b128 v[152:155], v134 offset:49152
	ds_read_b128 v[156:159], v134 offset:50176
	ds_read_b128 v[160:163], v134 offset:51200
	ds_read_b128 v[164:167], v134 offset:52224
	ds_read_b128 v[168:171], v134 offset:53248
	ds_read_b128 v[172:175], v134 offset:54272
	ds_read_b128 v[176:179], v134 offset:55296
	global_load_lds_dwordx4 v128, s[48:49] offset:128
	s_add_i32 m0, s69, 0xffffff80
	ds_read_b128 v[180:183], v134 offset:56320
	global_load_lds_dwordx4 v130, s[48:49] offset:128
	s_barrier
; #define PG8_STAGE(bufoff, gbase, voff) do { _Pragma("unroll") for (int _i = 0; _i < 2; ++_i) \
;         __builtin_amdgcn_global_load_lds((const unsigned*)((const char*)(gbase) + (voff)[_i]), (LAS unsigned*)(lds + (bufoff) + ldsw + _i * 8192), 16, 0, 0); } while (0)
; #define PG8_MMA(ai, bj, At, Bt) do { __builtin_amdgcn_s_setprio(1); _Pragma("unroll") for (int m = 0; m < 4; ++m) _Pragma("unroll") for (int n = 0; n < 2; ++n) _Pragma("unroll") for (int k = 0; k < 2; ++k) \
;         acc[ai][bj][m][n] = __builtin_amdgcn_mfma_f32_16x16x32_bf16(Bt[n][k], At[m][k], acc[ai][bj][m][n], 0, 0, 0); __builtin_amdgcn_s_setprio(0); } while (0)
; #define PG8_WAIT_V(n) asm volatile("s_waitcnt vmcnt(" #n ")" ::: "memory")
; #define PG8_WAIT_L(n) asm volatile("s_waitcnt lgkmcnt(" #n ")" ::: "memory")
; #define PG8_BAR __builtin_amdgcn_s_barrier()
; #define PG8_SCHED __builtin_amdgcn_sched_barrier(0)
; template <class Epi, class Sched>
; DI void gemm_phase(LAS unsigned char* lds, const Gemm g, const Sched& S, const Epi& E) {
;     ...
;             PG8_BAR; PG8_WAIT_L(0); PG8_MMA(1, 0, At, B0); PG8_BAR; PG8_SCHED;
;             PG8_STAGE(PG8_SB(1, 1), b3 + hstep, voffB);
;             PG8_WAIT_V(6); PG8_BAR; PG8_MMA(1, 1, At, B1); PG8_BAR;
;         }
;         { int fr2 = fr, fq2 = fq; asm volatile("" : "+v"(fr2), "+v"(fq2)); E(acc, cur, wr, wc, fr2, fq2); }
;     DI void operator()(AccRef acc, const Unit& u, int wr, int wc, int fr, int fq) const {
;         float* base = P + (size_t)slot0 * 256 * DM + (size_t)u.ks * 256 * ld; const int col0 = u.pn * 256 + wc * 32 + 4 * fq;
; #pragma unroll
;         for (int ai = 0; ai < 2; ++ai)
; #pragma unroll
;             for (int m = 0; m < 4; ++m) { const size_t off = (size_t)(ai * 128 + wr * 64 + m * 16 + fr) * ld + col0;
; #pragma unroll
;                 for (int bj = 0; bj < 2; ++bj)
; #pragma unroll
;                     for (int n = 0; n < 2; ++n) *(f32x4*)(base + off + bj * 128 + n * 16) = acc[ai][bj][m][n]; }
;     }
	s_waitcnt lgkmcnt(0)
	s_setprio 1
	v_mfma_f32_16x16x32_bf16 v[60:63], v[136:139], v[152:155], v[60:63]
	v_mfma_f32_16x16x32_bf16 v[56:59], v[144:147], v[152:155], v[56:59]
	v_mfma_f32_16x16x32_bf16 v[52:55], v[136:139], v[160:163], v[52:55]
	v_mfma_f32_16x16x32_bf16 v[48:51], v[144:147], v[160:163], v[48:51]
	v_mfma_f32_16x16x32_bf16 v[40:43], v[136:139], v[168:171], v[40:43]
	v_mfma_f32_16x16x32_bf16 v[32:35], v[144:147], v[168:171], v[32:35]
	v_mfma_f32_16x16x32_bf16 v[24:27], v[136:139], v[176:179], v[24:27]
	v_mfma_f32_16x16x32_bf16 v[16:19], v[144:147], v[176:179], v[16:19]
	v_mfma_f32_16x16x32_bf16 v[60:63], v[140:143], v[156:159], v[60:63]
	v_mfma_f32_16x16x32_bf16 v[56:59], v[148:151], v[156:159], v[56:59]
	v_mfma_f32_16x16x32_bf16 v[52:55], v[140:143], v[164:167], v[52:55]
	v_mfma_f32_16x16x32_bf16 v[48:51], v[148:151], v[164:167], v[48:51]
	v_mfma_f32_16x16x32_bf16 v[40:43], v[140:143], v[172:175], v[40:43]
	v_mfma_f32_16x16x32_bf16 v[32:35], v[148:151], v[172:175], v[32:35]
	v_mfma_f32_16x16x32_bf16 v[24:27], v[140:143], v[180:183], v[24:27]
	v_mfma_f32_16x16x32_bf16 v[16:19], v[148:151], v[180:183], v[16:19]
	s_setprio 0
	s_barrier
	s_mov_b32 m0, s76
	s_nop 0
	global_load_lds_dwordx4 v128, s[42:43]
	s_mov_b32 m0, s75
	s_nop 0
	global_load_lds_dwordx4 v130, s[42:43]
	s_waitcnt vmcnt(6)
	s_barrier
	s_setprio 1
	v_mfma_f32_16x16x32_bf16 v[44:47], v[188:191], v[152:155], v[44:47]
	v_mfma_f32_16x16x32_bf16 v[36:39], v[210:213], v[152:155], v[36:39]
	v_mfma_f32_16x16x32_bf16 v[28:31], v[188:191], v[160:163], v[28:31]
	v_mfma_f32_16x16x32_bf16 v[20:23], v[210:213], v[160:163], v[20:23]
	v_mfma_f32_16x16x32_bf16 v[12:15], v[188:191], v[168:171], v[12:15]
	v_mfma_f32_16x16x32_bf16 v[8:11], v[210:213], v[168:171], v[8:11]
	v_mfma_f32_16x16x32_bf16 v[4:7], v[188:191], v[176:179], v[4:7]
	v_mfma_f32_16x16x32_bf16 v[0:3], v[210:213], v[176:179], v[0:3]
	v_mfma_f32_16x16x32_bf16 v[44:47], v[206:209], v[156:159], v[44:47]
	v_mfma_f32_16x16x32_bf16 v[36:39], v[214:217], v[156:159], v[36:39]
	v_mfma_f32_16x16x32_bf16 v[28:31], v[206:209], v[164:167], v[28:31]
	v_mfma_f32_16x16x32_bf16 v[20:23], v[214:217], v[164:167], v[20:23]
	v_mfma_f32_16x16x32_bf16 v[12:15], v[206:209], v[172:175], v[12:15]
	v_mfma_f32_16x16x32_bf16 v[8:11], v[214:217], v[172:175], v[8:11]
	v_mfma_f32_16x16x32_bf16 v[4:7], v[206:209], v[180:183], v[4:7]
	v_mfma_f32_16x16x32_bf16 v[0:3], v[214:217], v[180:183], v[0:3]
	s_setprio 0
	s_movk_i32 s0, 0x100
	s_andn2_b64 vcc, exec, s[40:41]
	s_mov_b64 s[42:43], -1
	s_mov_b64 s[40:41], 0
	s_barrier
	s_cbranch_vccz .LBB0_1535
	s_ashr_i32 s13, s12, 31
	s_lshl_b64 s[0:1], s[12:13], 21
	s_add_u32 s0, s66, s0
	v_mov_b32_e32 v137, v194
	v_mov_b32_e32 v136, v192
	s_addc_u32 s1, s67, s1
	s_lshl_b32 s4, s10, 8
	s_or_b32 s4, s4, s65
	v_lshl_add_u32 v136, v136, 2, s4
	v_add_u32_e32 v138, s64, v137
	v_ashrrev_i32_e32 v137, 31, v136
	v_ashrrev_i32_e32 v139, 31, v138
	v_lshl_add_u64 v[136:137], v[136:137], 2, s[0:1]
	v_lshlrev_b64 v[140:141], 13, v[138:139]
	v_lshl_add_u64 v[140:141], v[136:137], 0, v[140:141]
	global_store_dwordx4 v[140:141], v[124:127], off
	global_store_dwordx4 v[140:141], v[120:123], off offset:64
	global_store_dwordx4 v[140:141], v[108:111], off offset:512
	global_store_dwordx4 v[140:141], v[100:103], off offset:576
	s_and_b64 vcc, exec, s[30:31]
	s_mov_b32 s12, s18
	v_add_u32_e32 v100, 16, v138
	v_ashrrev_i32_e32 v101, 31, v100
	v_lshlrev_b64 v[100:101], 13, v[100:101]
	v_lshl_add_u64 v[100:101], v[136:137], 0, v[100:101]
	global_store_dwordx4 v[100:101], v[116:119], off
	global_store_dwordx4 v[100:101], v[112:115], off offset:64
	global_store_dwordx4 v[100:101], v[92:95], off offset:512
	global_store_dwordx4 v[100:101], v[84:87], off offset:576
	s_mov_b32 s10, s28
	s_mov_b64 s[14:15], s[38:39]
	v_add_u32_e32 v84, 32, v138
	v_ashrrev_i32_e32 v85, 31, v84
	v_lshlrev_b64 v[84:85], 13, v[84:85]
	v_lshl_add_u64 v[84:85], v[136:137], 0, v[84:85]
	global_store_dwordx4 v[84:85], v[104:107], off
	global_store_dwordx4 v[84:85], v[96:99], off offset:64
	global_store_dwordx4 v[84:85], v[76:79], off offset:512
	global_store_dwordx4 v[84:85], v[72:75], off offset:576
	s_mov_b64 s[16:17], s[36:37]
	s_nop 0
	v_add_u32_e32 v72, 48, v138
	v_ashrrev_i32_e32 v73, 31, v72
	v_lshlrev_b64 v[72:73], 13, v[72:73]
	v_lshl_add_u64 v[72:73], v[136:137], 0, v[72:73]
	global_store_dwordx4 v[72:73], v[88:91], off
	global_store_dwordx4 v[72:73], v[80:83], off offset:64
	global_store_dwordx4 v[72:73], v[68:71], off offset:512
	global_store_dwordx4 v[72:73], v[64:67], off offset:576
	s_nop 1
	v_add_u32_e32 v64, 0x80, v138
	v_ashrrev_i32_e32 v65, 31, v64
	v_lshlrev_b64 v[64:65], 13, v[64:65]
	v_lshl_add_u64 v[64:65], v[136:137], 0, v[64:65]
	global_store_dwordx4 v[64:65], v[60:63], off
	global_store_dwordx4 v[64:65], v[56:59], off offset:64
	global_store_dwordx4 v[64:65], v[44:47], off offset:512
	global_store_dwordx4 v[64:65], v[36:39], off offset:576
	s_nop 1
	v_add_u32_e32 v36, 0x90, v138
	v_ashrrev_i32_e32 v37, 31, v36
	v_lshlrev_b64 v[36:37], 13, v[36:37]
	v_lshl_add_u64 v[36:37], v[136:137], 0, v[36:37]
	global_store_dwordx4 v[36:37], v[52:55], off
	global_store_dwordx4 v[36:37], v[48:51], off offset:64
	global_store_dwordx4 v[36:37], v[28:31], off offset:512
	global_store_dwordx4 v[36:37], v[20:23], off offset:576
	s_nop 1
	v_add_u32_e32 v20, 0xa0, v138
	v_ashrrev_i32_e32 v21, 31, v20
	v_lshlrev_b64 v[20:21], 13, v[20:21]
	v_lshl_add_u64 v[20:21], v[136:137], 0, v[20:21]
	global_store_dwordx4 v[20:21], v[40:43], off
	global_store_dwordx4 v[20:21], v[32:35], off offset:64
	global_store_dwordx4 v[20:21], v[12:15], off offset:512
	global_store_dwordx4 v[20:21], v[8:11], off offset:576
	s_nop 1
	v_add_u32_e32 v8, 0xb0, v138
	v_ashrrev_i32_e32 v9, 31, v8
	v_lshlrev_b64 v[8:9], 13, v[8:9]
	v_lshl_add_u64 v[8:9], v[136:137], 0, v[8:9]
	global_store_dwordx4 v[8:9], v[24:27], off
	global_store_dwordx4 v[8:9], v[16:19], off offset:64
	global_store_dwordx4 v[8:9], v[4:7], off offset:512
	global_store_dwordx4 v[8:9], v[0:3], off offset:576
	s_cbranch_vccz .LBB0_1532
	s_waitcnt vmcnt(0)
	s_cmpk_gt_u32 s34, 0xff
	s_cbranch_scc1 .LBB0_1539
	s_barrier

;     DI size_t aoff(const Unit& u, size_t tstep) const { return (size_t)u.pm * tstep; }
;     DI size_t boff(const Unit& u, size_t tstep) const { return (size_t)u.pn * tstep; }
;     DI bool next(int i, Unit& u) const { const long L = (long)i * G + c; if (L >= np) return false; u.pm = pmv; u.pn = (int)(L % nN); u.ks = (int)(L / nN); return true; }
;     DI size_t aoff(const Unit& u, size_t) const { return (size_t)u.ks * kbytes; }
;     DI size_t boff(const Unit& u, size_t tstep) const { return (size_t)u.pn * tstep + (size_t)u.ks * kbytes; }
;     DI bool next(int i, Unit& u) const { Unit t; if (!S.next(i / 3, t)) return false; u.pm = t.pm; u.pn = t.pn; u.ks = i % 3; return true; }
;     DI size_t aoff(const Unit& u, size_t tstep) const { return (u.ks < 2 ? offU : offOA) + (size_t)u.pm * tstep; }
; #define PG8_WAIT_V(n) asm volatile("s_waitcnt vmcnt(" #n ")" ::: "memory")
; template <class Epi, class Sched>
; DI void gemm_phase(LAS unsigned char* lds, const Gemm g, const Sched& S, const Epi& E) {
;     ...
;     for (;;) {
;         const bool has_next = S.next(ui + 1, nxt);
;         const char* nA = has_next ? (const char*)g.A + S.aoff(nxt, tstep) : cA; const char* nB = has_next ? (const char*)g.Bt + S.boff(nxt, tstep) : cB;
;         for (int t = 0; t < nt; t += 2) {
;             if constexpr (Epi::HAS_MID) { if (t == E.mid_t(nt)) { int fr3 = fr, fq3 = fq; asm volatile("" : "+v"(fr3), "+v"(fq3)); E.mid(acc, cur, wr, wc, fr3, fq3); } }
;             const bool last = (t == nt - 2);
;             const char* a1 = cA + (size_t)(t + 1) * kstep;
;             const char* a2 = last ? nA : cA + (size_t)(t + 2) * kstep; const char* b2 = last ? nB : cB + (size_t)(t + 2) * kstep;
;             const char* a3 = a2 + kstep; const char* b3 = b2 + kstep;
;             PG8_LDB(B0, 0, 0); PG8_SCHED; PG8_LDA(At, 0, 0); PG8_STAGE(PG8_SA(1, 1), a1 + hstep, voffA);
;             PG8_WAIT_L(8); PG8_BAR; PG8_WAIT_L(0); PG8_MMA(0, 0, At, B0); PG8_BAR; PG8_SCHED;
;             PG8_LDB(B1, 0, 1); PG8_STAGE(PG8_SB(0, 0), b2, voffB);
;             PG8_BAR; PG8_WAIT_L(0); PG8_MMA(0, 1, At, B1); PG8_BAR;
;             PG8_LDA(At, 0, 1); PG8_STAGE(PG8_SA(0, 0), a2, voffA);
;             PG8_BAR; PG8_WAIT_L(0); PG8_MMA(1, 0, At, B0); PG8_BAR; PG8_SCHED;
;             PG8_STAGE(PG8_SB(0, 1), b2 + hstep, voffB);
;             PG8_WAIT_V(6); PG8_BAR; PG8_MMA(1, 1, At, B1); PG8_BAR;
.LBB0_1667:
	s_ashr_i32 s29, s28, 31
	s_lshl_b64 s[0:1], s[28:29], 20
	s_add_u32 s30, s45, s0
	v_cmp_lt_i64_e32 vcc, s[8:9], v[140:141]
	s_addc_u32 s31, s46, s1
	s_and_b64 s[0:1], vcc, exec
	s_cselect_b32 s29, s31, s43
	s_cselect_b32 s35, s30, s42
	s_ashr_i32 s19, s18, 31
	s_lshl_b64 s[0:1], s[18:19], 20
	s_add_u32 s36, s47, s0
	s_addc_u32 s37, s48, s1
	s_and_b64 s[0:1], vcc, exec
	s_cselect_b32 s19, s37, s41
	s_cselect_b32 s65, s36, s40
	s_add_u32 s8, s42, 0x80080
	s_addc_u32 s9, s43, 0
	s_add_u32 s66, s40, 0x100
	v_mov_b32_e32 v8, 0
	s_addc_u32 s67, s41, 0
	s_mov_b32 s68, -2
	ds_read_b128 v[144:147], v149
	ds_read_b128 v[156:159], v149 offset:1024
	ds_read_b128 v[160:163], v149 offset:2048
	ds_read_b128 v[164:167], v149 offset:3072
	s_add_u32 s0, s8, 0xfff80080
	s_addc_u32 s1, s9, -1
	s_cmp_eq_u32 s68, 28
	s_cselect_b32 s43, s29, s1
	s_cselect_b32 s42, s35, s0
	s_cselect_b32 s41, s19, s67
	s_cselect_b32 s40, s65, s66
	s_add_i32 m0, s39, 0xc000
	ds_read_b128 v[168:171], v150
	ds_read_b128 v[172:175], v150 offset:1024
	ds_read_b128 v[176:179], v150 offset:2048
	ds_read_b128 v[180:183], v150 offset:3072
	ds_read_b128 v[188:191], v150 offset:4096
	ds_read_b128 v[206:209], v150 offset:5120
	ds_read_b128 v[210:213], v150 offset:6144
	global_load_lds_dwordx4 v136, s[8:9]
	s_add_i32 m0, s39, 0xe000
	ds_read_b128 v[214:217], v150 offset:7168
	global_load_lds_dwordx4 v138, s[8:9]
	s_waitcnt lgkmcnt(8)
	s_barrier
	s_waitcnt lgkmcnt(0)
	s_setprio 1
	v_mfma_f32_16x16x32_bf16 v[116:119], v[144:147], v[168:171], 0
	v_mfma_f32_16x16x32_bf16 v[112:115], v[160:163], v[168:171], 0
	v_mfma_f32_16x16x32_bf16 v[100:103], v[144:147], v[176:179], 0
	v_mfma_f32_16x16x32_bf16 v[96:99], v[160:163], v[176:179], 0
	v_mfma_f32_16x16x32_bf16 v[84:87], v[144:147], v[188:191], 0
	v_mfma_f32_16x16x32_bf16 v[80:83], v[160:163], v[188:191], 0
	v_mfma_f32_16x16x32_bf16 v[68:71], v[144:147], v[210:213], 0
	v_mfma_f32_16x16x32_bf16 v[64:67], v[160:163], v[210:213], 0
	v_mfma_f32_16x16x32_bf16 v[116:119], v[156:159], v[172:175], v[116:119]
	v_mfma_f32_16x16x32_bf16 v[112:115], v[164:167], v[172:175], v[112:115]
	v_mfma_f32_16x16x32_bf16 v[100:103], v[156:159], v[180:183], v[100:103]
	v_mfma_f32_16x16x32_bf16 v[96:99], v[164:167], v[180:183], v[96:99]
	v_mfma_f32_16x16x32_bf16 v[84:87], v[156:159], v[206:209], v[84:87]
	v_mfma_f32_16x16x32_bf16 v[80:83], v[164:167], v[206:209], v[80:83]
	v_mfma_f32_16x16x32_bf16 v[68:71], v[156:159], v[214:217], v[68:71]
	v_mfma_f32_16x16x32_bf16 v[64:67], v[164:167], v[214:217], v[64:67]
	s_setprio 0
	s_barrier
	s_add_i32 s0, s61, s50
	s_mov_b32 m0, s0
	ds_read_b128 v[218:221], v151
	ds_read_b128 v[222:225], v151 offset:1024
	ds_read_b128 v[226:229], v151 offset:2048
	global_load_lds_dwordx4 v130, s[40:41]
	s_add_i32 m0, s0, 0x2000
	ds_read_b128 v[230:233], v151 offset:3072
	global_load_lds_dwordx4 v134, s[40:41]
	s_barrier
	s_waitcnt lgkmcnt(0)
	s_setprio 1
	v_mfma_f32_16x16x32_bf16 v[124:127], v[218:221], v[168:171], 0
	v_mfma_f32_16x16x32_bf16 v[120:123], v[226:229], v[168:171], 0
	v_mfma_f32_16x16x32_bf16 v[108:111], v[218:221], v[176:179], 0
	v_mfma_f32_16x16x32_bf16 v[104:107], v[226:229], v[176:179], 0
	v_mfma_f32_16x16x32_bf16 v[92:95], v[218:221], v[188:191], 0
	v_mfma_f32_16x16x32_bf16 v[88:91], v[226:229], v[188:191], 0
	v_mfma_f32_16x16x32_bf16 v[76:79], v[218:221], v[210:213], 0
	v_mfma_f32_16x16x32_bf16 v[72:75], v[226:229], v[210:213], 0
	v_mfma_f32_16x16x32_bf16 v[124:127], v[222:225], v[172:175], v[124:127]
	v_mfma_f32_16x16x32_bf16 v[120:123], v[230:233], v[172:175], v[120:123]
	v_mfma_f32_16x16x32_bf16 v[108:111], v[222:225], v[180:183], v[108:111]
	v_mfma_f32_16x16x32_bf16 v[104:107], v[230:233], v[180:183], v[104:107]
	v_mfma_f32_16x16x32_bf16 v[92:95], v[222:225], v[206:209], v[92:95]
	v_mfma_f32_16x16x32_bf16 v[88:91], v[230:233], v[206:209], v[88:91]
	v_mfma_f32_16x16x32_bf16 v[76:79], v[222:225], v[214:217], v[76:79]
	v_mfma_f32_16x16x32_bf16 v[72:75], v[230:233], v[214:217], v[72:75]
	s_setprio 0
	s_mov_b32 m0, s39
	s_barrier
	ds_read_b128 v[168:171], v150 offset:16384
	ds_read_b128 v[172:175], v150 offset:17408
	ds_read_b128 v[176:179], v150 offset:18432
	ds_read_b128 v[180:183], v150 offset:19456
	ds_read_b128 v[188:191], v150 offset:20480
	ds_read_b128 v[206:209], v150 offset:21504
	ds_read_b128 v[210:213], v150 offset:22528
	global_load_lds_dwordx4 v128, s[42:43]
	s_mov_b32 m0, s51
	ds_read_b128 v[214:217], v150 offset:23552
	global_load_lds_dwordx4 v132, s[42:43]
	s_barrier
	s_waitcnt lgkmcnt(0)
	s_setprio 1
	v_mfma_f32_16x16x32_bf16 v[52:55], v[144:147], v[168:171], 0
	v_mfma_f32_16x16x32_bf16 v[48:51], v[160:163], v[168:171], 0
	v_mfma_f32_16x16x32_bf16 v[36:39], v[144:147], v[176:179], 0
	v_mfma_f32_16x16x32_bf16 v[32:35], v[160:163], v[176:179], 0
	v_mfma_f32_16x16x32_bf16 v[20:23], v[144:147], v[188:191], 0
	v_mfma_f32_16x16x32_bf16 v[16:19], v[160:163], v[188:191], 0
	v_mfma_f32_16x16x32_bf16 v[4:7], v[144:147], v[210:213], 0
	v_mfma_f32_16x16x32_bf16 v[0:3], v[160:163], v[210:213], 0
	v_mfma_f32_16x16x32_bf16 v[52:55], v[156:159], v[172:175], v[52:55]
	v_mfma_f32_16x16x32_bf16 v[48:51], v[164:167], v[172:175], v[48:51]
	v_mfma_f32_16x16x32_bf16 v[36:39], v[156:159], v[180:183], v[36:39]
	v_mfma_f32_16x16x32_bf16 v[32:35], v[164:167], v[180:183], v[32:35]
	v_mfma_f32_16x16x32_bf16 v[20:23], v[156:159], v[206:209], v[20:23]
	v_mfma_f32_16x16x32_bf16 v[16:19], v[164:167], v[206:209], v[16:19]
	v_mfma_f32_16x16x32_bf16 v[4:7], v[156:159], v[214:217], v[4:7]
	v_mfma_f32_16x16x32_bf16 v[0:3], v[164:167], v[214:217], v[0:3]
	s_setprio 0
	s_barrier
; #define PG8_STAGE(bufoff, gbase, voff) do { _Pragma("unroll") for (int _i = 0; _i < 2; ++_i) \
;         __builtin_amdgcn_global_load_lds((const unsigned*)((const char*)(gbase) + (voff)[_i]), (LAS unsigned*)(lds + (bufoff) + ldsw + _i * 8192), 16, 0, 0); } while (0)
; #define PG8_LDA(dst, b, h) do { _Pragma("unroll") for (int m = 0; m < 4; ++m) _Pragma("unroll") for (int k = 0; k < 2; ++k) dst[m][k] = *(const LAS bf16x8*)(lds + PG8_SA(b, h) + aoff + m * 2048 + k * 1024); } while (0)
; #define PG8_LDB(dst, b, h) do { _Pragma("unroll") for (int n = 0; n < 2; ++n) _Pragma("unroll") for (int k = 0; k < 2; ++k) dst[n][k] = *(const LAS bf16x8*)(lds + PG8_SB(b, h) + boff + n * 2048 + k * 1024); } while (0)
; #define PG8_MMA(ai, bj, At, Bt) do { __builtin_amdgcn_s_setprio(1); _Pragma("unroll") for (int m = 0; m < 4; ++m) _Pragma("unroll") for (int n = 0; n < 2; ++n) _Pragma("unroll") for (int k = 0; k < 2; ++k) \
;         acc[ai][bj][m][n] = __builtin_amdgcn_mfma_f32_16x16x32_bf16(Bt[n][k], At[m][k], acc[ai][bj][m][n], 0, 0, 0); __builtin_amdgcn_s_setprio(0); } while (0)
; #define PG8_WAIT_V(n) asm volatile("s_waitcnt vmcnt(" #n ")" ::: "memory")
; #define PG8_WAIT_L(n) asm volatile("s_waitcnt lgkmcnt(" #n ")" ::: "memory")
; #define PG8_BAR __builtin_amdgcn_s_barrier()
; #define PG8_SCHED __builtin_amdgcn_sched_barrier(0)
; template <class Epi, class Sched>
; DI void gemm_phase(LAS unsigned char* lds, const Gemm g, const Sched& S, const Epi& E) {
;     ...
;             PG8_LDA(At, 0, 1); PG8_STAGE(PG8_SA(0, 0), a2, voffA);
;             PG8_BAR; PG8_WAIT_L(0); PG8_MMA(1, 0, At, B0); PG8_BAR; PG8_SCHED;
;             PG8_STAGE(PG8_SB(0, 1), b2 + hstep, voffB);
;             PG8_WAIT_V(6); PG8_BAR; PG8_MMA(1, 1, At, B1); PG8_BAR;
;             PG8_LDB(B0, 1, 0); PG8_SCHED; PG8_LDA(At, 1, 0); PG8_STAGE(PG8_SA(0, 1), a2 + hstep, voffA);
;             PG8_WAIT_L(8); PG8_BAR; PG8_WAIT_L(0); PG8_MMA(0, 0, At, B0); PG8_BAR; PG8_SCHED;
;             PG8_LDB(B1, 1, 1); PG8_STAGE(PG8_SB(1, 0), b3, voffB);
;             PG8_BAR; PG8_WAIT_L(0); PG8_MMA(0, 1, At, B1); PG8_BAR;
;             PG8_LDA(At, 1, 1); PG8_STAGE(PG8_SA(1, 0), a3, voffA);
;             PG8_BAR; PG8_WAIT_L(0); PG8_MMA(1, 0, At, B0); PG8_BAR; PG8_SCHED;
;             PG8_STAGE(PG8_SB(1, 1), b3 + hstep, voffB);
;             PG8_WAIT_V(6); PG8_BAR; PG8_MMA(1, 1, At, B1); PG8_BAR;
	s_add_u32 s0, s40, 0x80000
	s_addc_u32 s1, s41, 0
	s_add_i32 s4, s62, s50
	s_mov_b32 m0, s4
	s_nop 0
	global_load_lds_dwordx4 v130, s[0:1]
	s_add_i32 m0, s4, 0x2000
	s_nop 0
	global_load_lds_dwordx4 v134, s[0:1]
	s_waitcnt vmcnt(6)
	s_barrier
	s_setprio 1
	v_mfma_f32_16x16x32_bf16 v[60:63], v[218:221], v[168:171], 0
	v_mfma_f32_16x16x32_bf16 v[56:59], v[226:229], v[168:171], 0
	v_mfma_f32_16x16x32_bf16 v[44:47], v[218:221], v[176:179], 0
	v_mfma_f32_16x16x32_bf16 v[40:43], v[226:229], v[176:179], 0
	v_mfma_f32_16x16x32_bf16 v[28:31], v[218:221], v[188:191], 0
	v_mfma_f32_16x16x32_bf16 v[24:27], v[226:229], v[188:191], 0
	v_mfma_f32_16x16x32_bf16 v[12:15], v[218:221], v[210:213], 0
	v_mfma_f32_16x16x32_bf16 v[8:11], v[226:229], v[210:213], 0
	v_mfma_f32_16x16x32_bf16 v[60:63], v[222:225], v[172:175], v[60:63]
	v_mfma_f32_16x16x32_bf16 v[56:59], v[230:233], v[172:175], v[56:59]
	v_mfma_f32_16x16x32_bf16 v[44:47], v[222:225], v[180:183], v[44:47]
	v_mfma_f32_16x16x32_bf16 v[40:43], v[230:233], v[180:183], v[40:43]
	v_mfma_f32_16x16x32_bf16 v[28:31], v[222:225], v[206:209], v[28:31]
	v_mfma_f32_16x16x32_bf16 v[24:27], v[230:233], v[206:209], v[24:27]
	v_mfma_f32_16x16x32_bf16 v[12:15], v[222:225], v[214:217], v[12:15]
	v_mfma_f32_16x16x32_bf16 v[8:11], v[230:233], v[214:217], v[8:11]
	s_setprio 0
	s_add_i32 s4, 0, 0x18000
	v_add_u32_e32 v155, s4, v148
	s_barrier
	ds_read_b128 v[144:147], v155
	ds_read_b128 v[156:159], v155 offset:1024
	ds_read_b128 v[160:163], v155 offset:2048
	ds_read_b128 v[164:167], v155 offset:3072
	s_add_u32 s0, s42, 0x80000
	s_addc_u32 s1, s43, 0
	s_mov_b32 m0, s52
	ds_read_b128 v[168:171], v150 offset:32768
	ds_read_b128 v[172:175], v150 offset:33792
	ds_read_b128 v[176:179], v150 offset:34816
	ds_read_b128 v[180:183], v150 offset:35840
	ds_read_b128 v[188:191], v150 offset:36864
	ds_read_b128 v[206:209], v150 offset:37888
	ds_read_b128 v[210:213], v150 offset:38912
	global_load_lds_dwordx4 v128, s[0:1]
	s_mov_b32 m0, s53
	ds_read_b128 v[214:217], v150 offset:39936
	global_load_lds_dwordx4 v132, s[0:1]
	s_waitcnt lgkmcnt(8)
	s_barrier
	s_waitcnt lgkmcnt(0)
	s_setprio 1
	v_mfma_f32_16x16x32_bf16 v[116:119], v[144:147], v[168:171], v[116:119]
	v_mfma_f32_16x16x32_bf16 v[112:115], v[160:163], v[168:171], v[112:115]
	v_mfma_f32_16x16x32_bf16 v[100:103], v[144:147], v[176:179], v[100:103]
	v_mfma_f32_16x16x32_bf16 v[96:99], v[160:163], v[176:179], v[96:99]
	v_mfma_f32_16x16x32_bf16 v[84:87], v[144:147], v[188:191], v[84:87]
	v_mfma_f32_16x16x32_bf16 v[80:83], v[160:163], v[188:191], v[80:83]
	v_mfma_f32_16x16x32_bf16 v[68:71], v[144:147], v[210:213], v[68:71]
	v_mfma_f32_16x16x32_bf16 v[64:67], v[160:163], v[210:213], v[64:67]
	v_mfma_f32_16x16x32_bf16 v[116:119], v[156:159], v[172:175], v[116:119]
	v_mfma_f32_16x16x32_bf16 v[112:115], v[164:167], v[172:175], v[112:115]
	v_mfma_f32_16x16x32_bf16 v[100:103], v[156:159], v[180:183], v[100:103]
	v_mfma_f32_16x16x32_bf16 v[96:99], v[164:167], v[180:183], v[96:99]
	v_mfma_f32_16x16x32_bf16 v[84:87], v[156:159], v[206:209], v[84:87]
	v_mfma_f32_16x16x32_bf16 v[80:83], v[164:167], v[206:209], v[80:83]
	v_mfma_f32_16x16x32_bf16 v[68:71], v[156:159], v[214:217], v[68:71]
	v_mfma_f32_16x16x32_bf16 v[64:67], v[164:167], v[214:217], v[64:67]
	s_setprio 0
	s_barrier
	s_add_i32 s5, 0, 0x1c000
	s_add_i32 s0, s4, s50
	v_add_u32_e32 v155, s5, v148
	s_add_i32 m0, s0, 0xffffff80
	ds_read_b128 v[218:221], v155
	ds_read_b128 v[222:225], v155 offset:1024
	ds_read_b128 v[226:229], v155 offset:2048
	global_load_lds_dwordx4 v130, s[40:41] offset:128
	s_add_i32 m0, s0, 0x1f80
	ds_read_b128 v[230:233], v155 offset:3072
	global_load_lds_dwordx4 v134, s[40:41] offset:128
	s_barrier
	s_waitcnt lgkmcnt(0)
	s_setprio 1
	v_mfma_f32_16x16x32_bf16 v[124:127], v[218:221], v[168:171], v[124:127]
	v_mfma_f32_16x16x32_bf16 v[120:123], v[226:229], v[168:171], v[120:123]
	v_mfma_f32_16x16x32_bf16 v[108:111], v[218:221], v[176:179], v[108:111]
	v_mfma_f32_16x16x32_bf16 v[104:107], v[226:229], v[176:179], v[104:107]
	v_mfma_f32_16x16x32_bf16 v[92:95], v[218:221], v[188:191], v[92:95]
	v_mfma_f32_16x16x32_bf16 v[88:91], v[226:229], v[188:191], v[88:91]
	v_mfma_f32_16x16x32_bf16 v[76:79], v[218:221], v[210:213], v[76:79]
	v_mfma_f32_16x16x32_bf16 v[72:75], v[226:229], v[210:213], v[72:75]
	v_mfma_f32_16x16x32_bf16 v[124:127], v[222:225], v[172:175], v[124:127]
	v_mfma_f32_16x16x32_bf16 v[120:123], v[230:233], v[172:175], v[120:123]
	v_mfma_f32_16x16x32_bf16 v[108:111], v[222:225], v[180:183], v[108:111]
	v_mfma_f32_16x16x32_bf16 v[104:107], v[230:233], v[180:183], v[104:107]
	v_mfma_f32_16x16x32_bf16 v[92:95], v[222:225], v[206:209], v[92:95]
	v_mfma_f32_16x16x32_bf16 v[88:91], v[230:233], v[206:209], v[88:91]
	v_mfma_f32_16x16x32_bf16 v[76:79], v[222:225], v[214:217], v[76:79]
	v_mfma_f32_16x16x32_bf16 v[72:75], v[230:233], v[214:217], v[72:75]
	s_setprio 0
	s_add_i32 m0, s57, 0xffffff80
	s_barrier
	ds_read_b128 v[168:171], v150 offset:49152
	ds_read_b128 v[172:175], v150 offset:50176
	ds_read_b128 v[176:179], v150 offset:51200
	ds_read_b128 v[180:183], v150 offset:52224
	ds_read_b128 v[188:191], v150 offset:53248
	ds_read_b128 v[206:209], v150 offset:54272
	ds_read_b128 v[210:213], v150 offset:55296
	global_load_lds_dwordx4 v128, s[42:43] offset:128
	s_add_i32 m0, s58, 0xffffff80
	ds_read_b128 v[214:217], v150 offset:56320
	global_load_lds_dwordx4 v132, s[42:43] offset:128
	s_barrier
; #define PG8_STAGE(bufoff, gbase, voff) do { _Pragma("unroll") for (int _i = 0; _i < 2; ++_i) \
;         __builtin_amdgcn_global_load_lds((const unsigned*)((const char*)(gbase) + (voff)[_i]), (LAS unsigned*)(lds + (bufoff) + ldsw + _i * 8192), 16, 0, 0); } while (0)
; #define PG8_LDA(dst, b, h) do { _Pragma("unroll") for (int m = 0; m < 4; ++m) _Pragma("unroll") for (int k = 0; k < 2; ++k) dst[m][k] = *(const LAS bf16x8*)(lds + PG8_SA(b, h) + aoff + m * 2048 + k * 1024); } while (0)
; #define PG8_LDB(dst, b, h) do { _Pragma("unroll") for (int n = 0; n < 2; ++n) _Pragma("unroll") for (int k = 0; k < 2; ++k) dst[n][k] = *(const LAS bf16x8*)(lds + PG8_SB(b, h) + boff + n * 2048 + k * 1024); } while (0)
; #define PG8_MMA(ai, bj, At, Bt) do { __builtin_amdgcn_s_setprio(1); _Pragma("unroll") for (int m = 0; m < 4; ++m) _Pragma("unroll") for (int n = 0; n < 2; ++n) _Pragma("unroll") for (int k = 0; k < 2; ++k) \
;         acc[ai][bj][m][n] = __builtin_amdgcn_mfma_f32_16x16x32_bf16(Bt[n][k], At[m][k], acc[ai][bj][m][n], 0, 0, 0); __builtin_amdgcn_s_setprio(0); } while (0)
; #define PG8_WAIT_V(n) asm volatile("s_waitcnt vmcnt(" #n ")" ::: "memory")
; #define PG8_WAIT_L(n) asm volatile("s_waitcnt lgkmcnt(" #n ")" ::: "memory")
; #define PG8_BAR __builtin_amdgcn_s_barrier()
; #define PG8_SCHED __builtin_amdgcn_sched_barrier(0)
; template <class Epi, class Sched>
; DI void gemm_phase(LAS unsigned char* lds, const Gemm g, const Sched& S, const Epi& E) {
;     ...
;             PG8_LDB(B0, 0, 0); PG8_SCHED; PG8_LDA(At, 0, 0); PG8_STAGE(PG8_SA(1, 1), a1 + hstep, voffA);
;             PG8_WAIT_L(8); PG8_BAR; PG8_WAIT_L(0); PG8_MMA(0, 0, At, B0); PG8_BAR; PG8_SCHED;
;             PG8_LDB(B1, 0, 1); PG8_STAGE(PG8_SB(0, 0), b2, voffB);
;             PG8_BAR; PG8_WAIT_L(0); PG8_MMA(0, 1, At, B1); PG8_BAR;
;     ...
;             PG8_BAR; PG8_WAIT_L(0); PG8_MMA(1, 0, At, B0); PG8_BAR; PG8_SCHED;
;             PG8_STAGE(PG8_SB(1, 1), b3 + hstep, voffB);
;             PG8_WAIT_V(6); PG8_BAR; PG8_MMA(1, 1, At, B1); PG8_BAR;
	s_waitcnt lgkmcnt(0)
	s_setprio 1
	v_mfma_f32_16x16x32_bf16 v[52:55], v[144:147], v[168:171], v[52:55]
	v_mfma_f32_16x16x32_bf16 v[48:51], v[160:163], v[168:171], v[48:51]
	v_mfma_f32_16x16x32_bf16 v[36:39], v[144:147], v[176:179], v[36:39]
	v_mfma_f32_16x16x32_bf16 v[32:35], v[160:163], v[176:179], v[32:35]
	v_mfma_f32_16x16x32_bf16 v[20:23], v[144:147], v[188:191], v[20:23]
	v_mfma_f32_16x16x32_bf16 v[16:19], v[160:163], v[188:191], v[16:19]
	v_mfma_f32_16x16x32_bf16 v[4:7], v[144:147], v[210:213], v[4:7]
	v_mfma_f32_16x16x32_bf16 v[0:3], v[160:163], v[210:213], v[0:3]
	v_mfma_f32_16x16x32_bf16 v[52:55], v[156:159], v[172:175], v[52:55]
	v_mfma_f32_16x16x32_bf16 v[48:51], v[164:167], v[172:175], v[48:51]
	v_mfma_f32_16x16x32_bf16 v[36:39], v[156:159], v[180:183], v[36:39]
	v_mfma_f32_16x16x32_bf16 v[32:35], v[164:167], v[180:183], v[32:35]
	v_mfma_f32_16x16x32_bf16 v[20:23], v[156:159], v[206:209], v[20:23]
	v_mfma_f32_16x16x32_bf16 v[16:19], v[164:167], v[206:209], v[16:19]
	v_mfma_f32_16x16x32_bf16 v[4:7], v[156:159], v[214:217], v[4:7]
	v_mfma_f32_16x16x32_bf16 v[0:3], v[164:167], v[214:217], v[0:3]
	s_setprio 0
	s_barrier
	s_add_u32 s0, s40, 0x80080
	s_addc_u32 s1, s41, 0
	s_add_i32 s4, s5, s50
	s_mov_b32 m0, s4
	s_nop 0
	global_load_lds_dwordx4 v130, s[0:1]
	s_add_i32 m0, s4, 0x2000
	s_nop 0
	global_load_lds_dwordx4 v134, s[0:1]
	s_waitcnt vmcnt(6)
	s_barrier
	s_setprio 1
	v_mfma_f32_16x16x32_bf16 v[60:63], v[218:221], v[168:171], v[60:63]
	v_mfma_f32_16x16x32_bf16 v[56:59], v[226:229], v[168:171], v[56:59]
	v_mfma_f32_16x16x32_bf16 v[44:47], v[218:221], v[176:179], v[44:47]
	v_mfma_f32_16x16x32_bf16 v[40:43], v[226:229], v[176:179], v[40:43]
	v_mfma_f32_16x16x32_bf16 v[28:31], v[218:221], v[188:191], v[28:31]
	v_mfma_f32_16x16x32_bf16 v[24:27], v[226:229], v[188:191], v[24:27]
	v_mfma_f32_16x16x32_bf16 v[12:15], v[218:221], v[210:213], v[12:15]
	v_mfma_f32_16x16x32_bf16 v[8:11], v[226:229], v[210:213], v[8:11]
	v_mfma_f32_16x16x32_bf16 v[60:63], v[222:225], v[172:175], v[60:63]
	v_mfma_f32_16x16x32_bf16 v[56:59], v[230:233], v[172:175], v[56:59]
	v_mfma_f32_16x16x32_bf16 v[44:47], v[222:225], v[180:183], v[44:47]
	v_mfma_f32_16x16x32_bf16 v[40:43], v[230:233], v[180:183], v[40:43]
	v_mfma_f32_16x16x32_bf16 v[28:31], v[222:225], v[206:209], v[28:31]
	v_mfma_f32_16x16x32_bf16 v[24:27], v[230:233], v[206:209], v[24:27]
	v_mfma_f32_16x16x32_bf16 v[12:15], v[222:225], v[214:217], v[12:15]
	v_mfma_f32_16x16x32_bf16 v[8:11], v[230:233], v[214:217], v[8:11]
	s_setprio 0
	s_add_i32 s68, s68, 2
	s_add_u32 s8, s8, 0x100
	s_addc_u32 s9, s9, 0
	s_add_u32 s66, s66, 0x100
	s_addc_u32 s67, s67, 0
	s_cmp_gt_u32 s68, 29
	s_barrier
	s_cbranch_scc0 .LBB0_1668
	s_branch .Lpeel_done_1668
.LBB0_1668:
	ds_read_b128 v[144:147], v149
	ds_read_b128 v[156:159], v149 offset:1024
	ds_read_b128 v[160:163], v149 offset:2048
	ds_read_b128 v[164:167], v149 offset:3072
	s_add_u32 s0, s8, 0xfff80080
	s_addc_u32 s1, s9, -1
	s_cmp_eq_u32 s68, 28
	s_cselect_b32 s43, s29, s1
	s_cselect_b32 s42, s35, s0
	s_cselect_b32 s41, s19, s67
	s_cselect_b32 s40, s65, s66
	s_add_i32 m0, s39, 0xc000
	ds_read_b128 v[168:171], v150
	ds_read_b128 v[172:175], v150 offset:1024
	ds_read_b128 v[176:179], v150 offset:2048
	ds_read_b128 v[180:183], v150 offset:3072
	ds_read_b128 v[188:191], v150 offset:4096
	ds_read_b128 v[206:209], v150 offset:5120
	ds_read_b128 v[210:213], v150 offset:6144
	global_load_lds_dwordx4 v136, s[8:9]
	s_add_i32 m0, s39, 0xe000
	ds_read_b128 v[214:217], v150 offset:7168
	global_load_lds_dwordx4 v138, s[8:9]
	s_waitcnt lgkmcnt(8)
	s_barrier
	s_waitcnt lgkmcnt(0)
	s_setprio 1
	v_mfma_f32_16x16x32_bf16 v[116:119], v[144:147], v[168:171], v[116:119]
	v_mfma_f32_16x16x32_bf16 v[112:115], v[160:163], v[168:171], v[112:115]
	v_mfma_f32_16x16x32_bf16 v[100:103], v[144:147], v[176:179], v[100:103]
	v_mfma_f32_16x16x32_bf16 v[96:99], v[160:163], v[176:179], v[96:99]
	v_mfma_f32_16x16x32_bf16 v[84:87], v[144:147], v[188:191], v[84:87]
	v_mfma_f32_16x16x32_bf16 v[80:83], v[160:163], v[188:191], v[80:83]
	v_mfma_f32_16x16x32_bf16 v[68:71], v[144:147], v[210:213], v[68:71]
	v_mfma_f32_16x16x32_bf16 v[64:67], v[160:163], v[210:213], v[64:67]
	v_mfma_f32_16x16x32_bf16 v[116:119], v[156:159], v[172:175], v[116:119]
	v_mfma_f32_16x16x32_bf16 v[112:115], v[164:167], v[172:175], v[112:115]
	v_mfma_f32_16x16x32_bf16 v[100:103], v[156:159], v[180:183], v[100:103]
	v_mfma_f32_16x16x32_bf16 v[96:99], v[164:167], v[180:183], v[96:99]
	v_mfma_f32_16x16x32_bf16 v[84:87], v[156:159], v[206:209], v[84:87]
	v_mfma_f32_16x16x32_bf16 v[80:83], v[164:167], v[206:209], v[80:83]
	v_mfma_f32_16x16x32_bf16 v[68:71], v[156:159], v[214:217], v[68:71]
	v_mfma_f32_16x16x32_bf16 v[64:67], v[164:167], v[214:217], v[64:67]
	s_setprio 0
	s_barrier
	s_add_i32 s0, s61, s50
	s_mov_b32 m0, s0
	ds_read_b128 v[218:221], v151
	ds_read_b128 v[222:225], v151 offset:1024
	ds_read_b128 v[226:229], v151 offset:2048
	global_load_lds_dwordx4 v130, s[40:41]
	s_add_i32 m0, s0, 0x2000
	ds_read_b128 v[230:233], v151 offset:3072
	global_load_lds_dwordx4 v134, s[40:41]
	s_barrier
; #define PG8_STAGE(bufoff, gbase, voff) do { _Pragma("unroll") for (int _i = 0; _i < 2; ++_i) \
;         __builtin_amdgcn_global_load_lds((const unsigned*)((const char*)(gbase) + (voff)[_i]), (LAS unsigned*)(lds + (bufoff) + ldsw + _i * 8192), 16, 0, 0); } while (0)
; #define PG8_LDA(dst, b, h) do { _Pragma("unroll") for (int m = 0; m < 4; ++m) _Pragma("unroll") for (int k = 0; k < 2; ++k) dst[m][k] = *(const LAS bf16x8*)(lds + PG8_SA(b, h) + aoff + m * 2048 + k * 1024); } while (0)
; #define PG8_LDB(dst, b, h) do { _Pragma("unroll") for (int n = 0; n < 2; ++n) _Pragma("unroll") for (int k = 0; k < 2; ++k) dst[n][k] = *(const LAS bf16x8*)(lds + PG8_SB(b, h) + boff + n * 2048 + k * 1024); } while (0)
; #define PG8_MMA(ai, bj, At, Bt) do { __builtin_amdgcn_s_setprio(1); _Pragma("unroll") for (int m = 0; m < 4; ++m) _Pragma("unroll") for (int n = 0; n < 2; ++n) _Pragma("unroll") for (int k = 0; k < 2; ++k) \
;         acc[ai][bj][m][n] = __builtin_amdgcn_mfma_f32_16x16x32_bf16(Bt[n][k], At[m][k], acc[ai][bj][m][n], 0, 0, 0); __builtin_amdgcn_s_setprio(0); } while (0)
; #define PG8_WAIT_V(n) asm volatile("s_waitcnt vmcnt(" #n ")" ::: "memory")
; #define PG8_WAIT_L(n) asm volatile("s_waitcnt lgkmcnt(" #n ")" ::: "memory")
; #define PG8_BAR __builtin_amdgcn_s_barrier()
; #define PG8_SCHED __builtin_amdgcn_sched_barrier(0)
; template <class Epi, class Sched>
; DI void gemm_phase(LAS unsigned char* lds, const Gemm g, const Sched& S, const Epi& E) {
;     ...
;             PG8_BAR; PG8_WAIT_L(0); PG8_MMA(0, 1, At, B1); PG8_BAR;
;             PG8_LDA(At, 0, 1); PG8_STAGE(PG8_SA(0, 0), a2, voffA);
;             PG8_BAR; PG8_WAIT_L(0); PG8_MMA(1, 0, At, B0); PG8_BAR; PG8_SCHED;
;             PG8_STAGE(PG8_SB(0, 1), b2 + hstep, voffB);
;             PG8_WAIT_V(6); PG8_BAR; PG8_MMA(1, 1, At, B1); PG8_BAR;
;             PG8_LDB(B0, 1, 0); PG8_SCHED; PG8_LDA(At, 1, 0); PG8_STAGE(PG8_SA(0, 1), a2 + hstep, voffA);
;             PG8_WAIT_L(8); PG8_BAR; PG8_WAIT_L(0); PG8_MMA(0, 0, At, B0); PG8_BAR; PG8_SCHED;
;             PG8_LDB(B1, 1, 1); PG8_STAGE(PG8_SB(1, 0), b3, voffB);
	s_waitcnt lgkmcnt(0)
	s_setprio 1
	v_mfma_f32_16x16x32_bf16 v[124:127], v[218:221], v[168:171], v[124:127]
	v_mfma_f32_16x16x32_bf16 v[120:123], v[226:229], v[168:171], v[120:123]
	v_mfma_f32_16x16x32_bf16 v[108:111], v[218:221], v[176:179], v[108:111]
	v_mfma_f32_16x16x32_bf16 v[104:107], v[226:229], v[176:179], v[104:107]
	v_mfma_f32_16x16x32_bf16 v[92:95], v[218:221], v[188:191], v[92:95]
	v_mfma_f32_16x16x32_bf16 v[88:91], v[226:229], v[188:191], v[88:91]
	v_mfma_f32_16x16x32_bf16 v[76:79], v[218:221], v[210:213], v[76:79]
	v_mfma_f32_16x16x32_bf16 v[72:75], v[226:229], v[210:213], v[72:75]
	v_mfma_f32_16x16x32_bf16 v[124:127], v[222:225], v[172:175], v[124:127]
	v_mfma_f32_16x16x32_bf16 v[120:123], v[230:233], v[172:175], v[120:123]
	v_mfma_f32_16x16x32_bf16 v[108:111], v[222:225], v[180:183], v[108:111]
	v_mfma_f32_16x16x32_bf16 v[104:107], v[230:233], v[180:183], v[104:107]
	v_mfma_f32_16x16x32_bf16 v[92:95], v[222:225], v[206:209], v[92:95]
	v_mfma_f32_16x16x32_bf16 v[88:91], v[230:233], v[206:209], v[88:91]
	v_mfma_f32_16x16x32_bf16 v[76:79], v[222:225], v[214:217], v[76:79]
	v_mfma_f32_16x16x32_bf16 v[72:75], v[230:233], v[214:217], v[72:75]
	s_setprio 0
	s_mov_b32 m0, s39
	s_barrier
	ds_read_b128 v[168:171], v150 offset:16384
	ds_read_b128 v[172:175], v150 offset:17408
	ds_read_b128 v[176:179], v150 offset:18432
	ds_read_b128 v[180:183], v150 offset:19456
	ds_read_b128 v[188:191], v150 offset:20480
	ds_read_b128 v[206:209], v150 offset:21504
	ds_read_b128 v[210:213], v150 offset:22528
	global_load_lds_dwordx4 v128, s[42:43]
	s_mov_b32 m0, s51
	ds_read_b128 v[214:217], v150 offset:23552
	global_load_lds_dwordx4 v132, s[42:43]
	s_barrier
	s_waitcnt lgkmcnt(0)
	s_setprio 1
	v_mfma_f32_16x16x32_bf16 v[52:55], v[144:147], v[168:171], v[52:55]
	v_mfma_f32_16x16x32_bf16 v[48:51], v[160:163], v[168:171], v[48:51]
	v_mfma_f32_16x16x32_bf16 v[36:39], v[144:147], v[176:179], v[36:39]
	v_mfma_f32_16x16x32_bf16 v[32:35], v[160:163], v[176:179], v[32:35]
	v_mfma_f32_16x16x32_bf16 v[20:23], v[144:147], v[188:191], v[20:23]
	v_mfma_f32_16x16x32_bf16 v[16:19], v[160:163], v[188:191], v[16:19]
	v_mfma_f32_16x16x32_bf16 v[4:7], v[144:147], v[210:213], v[4:7]
	v_mfma_f32_16x16x32_bf16 v[0:3], v[160:163], v[210:213], v[0:3]
	v_mfma_f32_16x16x32_bf16 v[52:55], v[156:159], v[172:175], v[52:55]
	v_mfma_f32_16x16x32_bf16 v[48:51], v[164:167], v[172:175], v[48:51]
	v_mfma_f32_16x16x32_bf16 v[36:39], v[156:159], v[180:183], v[36:39]
	v_mfma_f32_16x16x32_bf16 v[32:35], v[164:167], v[180:183], v[32:35]
	v_mfma_f32_16x16x32_bf16 v[20:23], v[156:159], v[206:209], v[20:23]
	v_mfma_f32_16x16x32_bf16 v[16:19], v[164:167], v[206:209], v[16:19]
	v_mfma_f32_16x16x32_bf16 v[4:7], v[156:159], v[214:217], v[4:7]
	v_mfma_f32_16x16x32_bf16 v[0:3], v[164:167], v[214:217], v[0:3]
	s_setprio 0
	s_barrier
	s_add_u32 s0, s40, 0x80000
	s_addc_u32 s1, s41, 0
	s_add_i32 s4, s62, s50
	s_mov_b32 m0, s4
	s_nop 0
	global_load_lds_dwordx4 v130, s[0:1]
	s_add_i32 m0, s4, 0x2000
	s_nop 0
	global_load_lds_dwordx4 v134, s[0:1]
	s_waitcnt vmcnt(6)
	s_barrier
	s_setprio 1
	v_mfma_f32_16x16x32_bf16 v[60:63], v[218:221], v[168:171], v[60:63]
	v_mfma_f32_16x16x32_bf16 v[56:59], v[226:229], v[168:171], v[56:59]
	v_mfma_f32_16x16x32_bf16 v[44:47], v[218:221], v[176:179], v[44:47]
	v_mfma_f32_16x16x32_bf16 v[40:43], v[226:229], v[176:179], v[40:43]
	v_mfma_f32_16x16x32_bf16 v[28:31], v[218:221], v[188:191], v[28:31]
	v_mfma_f32_16x16x32_bf16 v[24:27], v[226:229], v[188:191], v[24:27]
	v_mfma_f32_16x16x32_bf16 v[12:15], v[218:221], v[210:213], v[12:15]
	v_mfma_f32_16x16x32_bf16 v[8:11], v[226:229], v[210:213], v[8:11]
	v_mfma_f32_16x16x32_bf16 v[60:63], v[222:225], v[172:175], v[60:63]
	v_mfma_f32_16x16x32_bf16 v[56:59], v[230:233], v[172:175], v[56:59]
	v_mfma_f32_16x16x32_bf16 v[44:47], v[222:225], v[180:183], v[44:47]
	v_mfma_f32_16x16x32_bf16 v[40:43], v[230:233], v[180:183], v[40:43]
	v_mfma_f32_16x16x32_bf16 v[28:31], v[222:225], v[206:209], v[28:31]
	v_mfma_f32_16x16x32_bf16 v[24:27], v[230:233], v[206:209], v[24:27]
	v_mfma_f32_16x16x32_bf16 v[12:15], v[222:225], v[214:217], v[12:15]
	v_mfma_f32_16x16x32_bf16 v[8:11], v[230:233], v[214:217], v[8:11]
	s_setprio 0
	s_add_i32 s4, 0, 0x18000
	v_add_u32_e32 v155, s4, v148
	s_barrier
	ds_read_b128 v[144:147], v155
	ds_read_b128 v[156:159], v155 offset:1024
	ds_read_b128 v[160:163], v155 offset:2048
	ds_read_b128 v[164:167], v155 offset:3072
	s_add_u32 s0, s42, 0x80000
	s_addc_u32 s1, s43, 0
	s_mov_b32 m0, s52
	ds_read_b128 v[168:171], v150 offset:32768
	ds_read_b128 v[172:175], v150 offset:33792
	ds_read_b128 v[176:179], v150 offset:34816
	ds_read_b128 v[180:183], v150 offset:35840
	ds_read_b128 v[188:191], v150 offset:36864
	ds_read_b128 v[206:209], v150 offset:37888
	ds_read_b128 v[210:213], v150 offset:38912
	global_load_lds_dwordx4 v128, s[0:1]
	s_mov_b32 m0, s53
	ds_read_b128 v[214:217], v150 offset:39936
	global_load_lds_dwordx4 v132, s[0:1]
	s_waitcnt lgkmcnt(8)
	s_barrier
; #define PG8_STAGE(bufoff, gbase, voff) do { _Pragma("unroll") for (int _i = 0; _i < 2; ++_i) \
;         __builtin_amdgcn_global_load_lds((const unsigned*)((const char*)(gbase) + (voff)[_i]), (LAS unsigned*)(lds + (bufoff) + ldsw + _i * 8192), 16, 0, 0); } while (0)
; #define PG8_LDA(dst, b, h) do { _Pragma("unroll") for (int m = 0; m < 4; ++m) _Pragma("unroll") for (int k = 0; k < 2; ++k) dst[m][k] = *(const LAS bf16x8*)(lds + PG8_SA(b, h) + aoff + m * 2048 + k * 1024); } while (0)
; #define PG8_LDB(dst, b, h) do { _Pragma("unroll") for (int n = 0; n < 2; ++n) _Pragma("unroll") for (int k = 0; k < 2; ++k) dst[n][k] = *(const LAS bf16x8*)(lds + PG8_SB(b, h) + boff + n * 2048 + k * 1024); } while (0)
; #define PG8_MMA(ai, bj, At, Bt) do { __builtin_amdgcn_s_setprio(1); _Pragma("unroll") for (int m = 0; m < 4; ++m) _Pragma("unroll") for (int n = 0; n < 2; ++n) _Pragma("unroll") for (int k = 0; k < 2; ++k) \
;         acc[ai][bj][m][n] = __builtin_amdgcn_mfma_f32_16x16x32_bf16(Bt[n][k], At[m][k], acc[ai][bj][m][n], 0, 0, 0); __builtin_amdgcn_s_setprio(0); } while (0)
; #define PG8_WAIT_V(n) asm volatile("s_waitcnt vmcnt(" #n ")" ::: "memory")
; #define PG8_WAIT_L(n) asm volatile("s_waitcnt lgkmcnt(" #n ")" ::: "memory")
; #define PG8_BAR __builtin_amdgcn_s_barrier()
; #define PG8_SCHED __builtin_amdgcn_sched_barrier(0)
; template <class Epi, class Sched>
; DI void gemm_phase(LAS unsigned char* lds, const Gemm g, const Sched& S, const Epi& E) {
;     ...
;             PG8_WAIT_L(8); PG8_BAR; PG8_WAIT_L(0); PG8_MMA(0, 0, At, B0); PG8_BAR; PG8_SCHED;
;             PG8_LDB(B1, 1, 1); PG8_STAGE(PG8_SB(1, 0), b3, voffB);
;             PG8_BAR; PG8_WAIT_L(0); PG8_MMA(0, 1, At, B1); PG8_BAR;
;             PG8_LDA(At, 1, 1); PG8_STAGE(PG8_SA(1, 0), a3, voffA);
;             PG8_BAR; PG8_WAIT_L(0); PG8_MMA(1, 0, At, B0); PG8_BAR; PG8_SCHED;
;             PG8_STAGE(PG8_SB(1, 1), b3 + hstep, voffB);
;             PG8_WAIT_V(6); PG8_BAR; PG8_MMA(1, 1, At, B1); PG8_BAR;
	s_waitcnt lgkmcnt(0)
	s_setprio 1
	v_mfma_f32_16x16x32_bf16 v[116:119], v[144:147], v[168:171], v[116:119]
	v_mfma_f32_16x16x32_bf16 v[112:115], v[160:163], v[168:171], v[112:115]
	v_mfma_f32_16x16x32_bf16 v[100:103], v[144:147], v[176:179], v[100:103]
	v_mfma_f32_16x16x32_bf16 v[96:99], v[160:163], v[176:179], v[96:99]
	v_mfma_f32_16x16x32_bf16 v[84:87], v[144:147], v[188:191], v[84:87]
	v_mfma_f32_16x16x32_bf16 v[80:83], v[160:163], v[188:191], v[80:83]
	v_mfma_f32_16x16x32_bf16 v[68:71], v[144:147], v[210:213], v[68:71]
	v_mfma_f32_16x16x32_bf16 v[64:67], v[160:163], v[210:213], v[64:67]
	v_mfma_f32_16x16x32_bf16 v[116:119], v[156:159], v[172:175], v[116:119]
	v_mfma_f32_16x16x32_bf16 v[112:115], v[164:167], v[172:175], v[112:115]
	v_mfma_f32_16x16x32_bf16 v[100:103], v[156:159], v[180:183], v[100:103]
	v_mfma_f32_16x16x32_bf16 v[96:99], v[164:167], v[180:183], v[96:99]
	v_mfma_f32_16x16x32_bf16 v[84:87], v[156:159], v[206:209], v[84:87]
	v_mfma_f32_16x16x32_bf16 v[80:83], v[164:167], v[206:209], v[80:83]
	v_mfma_f32_16x16x32_bf16 v[68:71], v[156:159], v[214:217], v[68:71]
	v_mfma_f32_16x16x32_bf16 v[64:67], v[164:167], v[214:217], v[64:67]
	s_setprio 0
	s_barrier
	s_add_i32 s5, 0, 0x1c000
	s_add_i32 s0, s4, s50
	v_add_u32_e32 v155, s5, v148
	s_add_i32 m0, s0, 0xffffff80
	ds_read_b128 v[218:221], v155
	ds_read_b128 v[222:225], v155 offset:1024
	ds_read_b128 v[226:229], v155 offset:2048
	global_load_lds_dwordx4 v130, s[40:41] offset:128
	s_add_i32 m0, s0, 0x1f80
	ds_read_b128 v[230:233], v155 offset:3072
	global_load_lds_dwordx4 v134, s[40:41] offset:128
	s_barrier
	s_waitcnt lgkmcnt(0)
	s_setprio 1
	v_mfma_f32_16x16x32_bf16 v[124:127], v[218:221], v[168:171], v[124:127]
	v_mfma_f32_16x16x32_bf16 v[120:123], v[226:229], v[168:171], v[120:123]
	v_mfma_f32_16x16x32_bf16 v[108:111], v[218:221], v[176:179], v[108:111]
	v_mfma_f32_16x16x32_bf16 v[104:107], v[226:229], v[176:179], v[104:107]
	v_mfma_f32_16x16x32_bf16 v[92:95], v[218:221], v[188:191], v[92:95]
	v_mfma_f32_16x16x32_bf16 v[88:91], v[226:229], v[188:191], v[88:91]
	v_mfma_f32_16x16x32_bf16 v[76:79], v[218:221], v[210:213], v[76:79]
	v_mfma_f32_16x16x32_bf16 v[72:75], v[226:229], v[210:213], v[72:75]
	v_mfma_f32_16x16x32_bf16 v[124:127], v[222:225], v[172:175], v[124:127]
	v_mfma_f32_16x16x32_bf16 v[120:123], v[230:233], v[172:175], v[120:123]
	v_mfma_f32_16x16x32_bf16 v[108:111], v[222:225], v[180:183], v[108:111]
	v_mfma_f32_16x16x32_bf16 v[104:107], v[230:233], v[180:183], v[104:107]
	v_mfma_f32_16x16x32_bf16 v[92:95], v[222:225], v[206:209], v[92:95]
	v_mfma_f32_16x16x32_bf16 v[88:91], v[230:233], v[206:209], v[88:91]
	v_mfma_f32_16x16x32_bf16 v[76:79], v[222:225], v[214:217], v[76:79]
	v_mfma_f32_16x16x32_bf16 v[72:75], v[230:233], v[214:217], v[72:75]
	s_setprio 0
	s_add_i32 m0, s57, 0xffffff80
	s_barrier
	ds_read_b128 v[168:171], v150 offset:49152
	ds_read_b128 v[172:175], v150 offset:50176
	ds_read_b128 v[176:179], v150 offset:51200
	ds_read_b128 v[180:183], v150 offset:52224
	ds_read_b128 v[188:191], v150 offset:53248
	ds_read_b128 v[206:209], v150 offset:54272
	ds_read_b128 v[210:213], v150 offset:55296
	global_load_lds_dwordx4 v128, s[42:43] offset:128
	s_add_i32 m0, s58, 0xffffff80
	ds_read_b128 v[214:217], v150 offset:56320
	global_load_lds_dwordx4 v132, s[42:43] offset:128
	s_barrier
	s_waitcnt lgkmcnt(0)
	s_setprio 1
	v_mfma_f32_16x16x32_bf16 v[52:55], v[144:147], v[168:171], v[52:55]
	v_mfma_f32_16x16x32_bf16 v[48:51], v[160:163], v[168:171], v[48:51]
	v_mfma_f32_16x16x32_bf16 v[36:39], v[144:147], v[176:179], v[36:39]
	v_mfma_f32_16x16x32_bf16 v[32:35], v[160:163], v[176:179], v[32:35]
	v_mfma_f32_16x16x32_bf16 v[20:23], v[144:147], v[188:191], v[20:23]
	v_mfma_f32_16x16x32_bf16 v[16:19], v[160:163], v[188:191], v[16:19]
	v_mfma_f32_16x16x32_bf16 v[4:7], v[144:147], v[210:213], v[4:7]
	v_mfma_f32_16x16x32_bf16 v[0:3], v[160:163], v[210:213], v[0:3]
	v_mfma_f32_16x16x32_bf16 v[52:55], v[156:159], v[172:175], v[52:55]
	v_mfma_f32_16x16x32_bf16 v[48:51], v[164:167], v[172:175], v[48:51]
	v_mfma_f32_16x16x32_bf16 v[36:39], v[156:159], v[180:183], v[36:39]
	v_mfma_f32_16x16x32_bf16 v[32:35], v[164:167], v[180:183], v[32:35]
	v_mfma_f32_16x16x32_bf16 v[20:23], v[156:159], v[206:209], v[20:23]
	v_mfma_f32_16x16x32_bf16 v[16:19], v[164:167], v[206:209], v[16:19]
	v_mfma_f32_16x16x32_bf16 v[4:7], v[156:159], v[214:217], v[4:7]
	v_mfma_f32_16x16x32_bf16 v[0:3], v[164:167], v[214:217], v[0:3]
	s_setprio 0
	s_barrier
	s_add_u32 s0, s40, 0x80080
	s_addc_u32 s1, s41, 0
	s_add_i32 s4, s5, s50
	s_mov_b32 m0, s4
	s_nop 0
	global_load_lds_dwordx4 v130, s[0:1]
	s_add_i32 m0, s4, 0x2000
	s_nop 0
	global_load_lds_dwordx4 v134, s[0:1]
	s_waitcnt vmcnt(6)
	s_barrier
	s_setprio 1
	v_mfma_f32_16x16x32_bf16 v[60:63], v[218:221], v[168:171], v[60:63]
	v_mfma_f32_16x16x32_bf16 v[56:59], v[226:229], v[168:171], v[56:59]
	v_mfma_f32_16x16x32_bf16 v[44:47], v[218:221], v[176:179], v[44:47]
	v_mfma_f32_16x16x32_bf16 v[40:43], v[226:229], v[176:179], v[40:43]
	v_mfma_f32_16x16x32_bf16 v[28:31], v[218:221], v[188:191], v[28:31]
	v_mfma_f32_16x16x32_bf16 v[24:27], v[226:229], v[188:191], v[24:27]
	v_mfma_f32_16x16x32_bf16 v[12:15], v[218:221], v[210:213], v[12:15]
	v_mfma_f32_16x16x32_bf16 v[8:11], v[226:229], v[210:213], v[8:11]
	v_mfma_f32_16x16x32_bf16 v[60:63], v[222:225], v[172:175], v[60:63]
	v_mfma_f32_16x16x32_bf16 v[56:59], v[230:233], v[172:175], v[56:59]
	v_mfma_f32_16x16x32_bf16 v[44:47], v[222:225], v[180:183], v[44:47]
	v_mfma_f32_16x16x32_bf16 v[40:43], v[230:233], v[180:183], v[40:43]
	v_mfma_f32_16x16x32_bf16 v[28:31], v[222:225], v[206:209], v[28:31]
	v_mfma_f32_16x16x32_bf16 v[24:27], v[230:233], v[206:209], v[24:27]
	v_mfma_f32_16x16x32_bf16 v[12:15], v[222:225], v[214:217], v[12:15]
	v_mfma_f32_16x16x32_bf16 v[8:11], v[230:233], v[214:217], v[8:11]
	s_setprio 0
	s_add_i32 s68, s68, 2
	s_add_u32 s8, s8, 0x100
	s_addc_u32 s9, s9, 0
	s_add_u32 s66, s66, 0x100
	s_addc_u32 s67, s67, 0
	s_cmp_gt_u32 s68, 29
	s_barrier
	s_cbranch_scc0 .LBB0_1668

;     DI size_t aoff(const Unit& u, size_t tstep) const { return (size_t)u.pm * tstep; }
;     DI size_t boff(const Unit& u, size_t tstep) const { return (size_t)u.pn * tstep; }
;     DI bool next(int i, Unit& u) const { const long L = (long)i * G + c; if (L >= np) return false; u.pm = pmv; u.pn = (int)(L % nN); u.ks = (int)(L / nN); return true; }
;     DI size_t aoff(const Unit& u, size_t) const { return (size_t)u.ks * kbytes; }
;     DI size_t boff(const Unit& u, size_t tstep) const { return (size_t)u.pn * tstep + (size_t)u.ks * kbytes; }
;     DI bool next(int i, Unit& u) const { Unit t; if (!S.next(i / 3, t)) return false; u.pm = t.pm; u.pn = t.pn; u.ks = i % 3; return true; }
;     DI size_t aoff(const Unit& u, size_t tstep) const { return (u.ks < 2 ? offU : offOA) + (size_t)u.pm * tstep; }
; #define PG8_WAIT_V(n) asm volatile("s_waitcnt vmcnt(" #n ")" ::: "memory")
; template <class Epi, class Sched>
; DI void gemm_phase(LAS unsigned char* lds, const Gemm g, const Sched& S, const Epi& E) {
;     ...
;     for (;;) {
;         const bool has_next = S.next(ui + 1, nxt);
;         const char* nA = has_next ? (const char*)g.A + S.aoff(nxt, tstep) : cA; const char* nB = has_next ? (const char*)g.Bt + S.boff(nxt, tstep) : cB;
;         for (int t = 0; t < nt; t += 2) {
;             if constexpr (Epi::HAS_MID) { if (t == E.mid_t(nt)) { int fr3 = fr, fq3 = fq; asm volatile("" : "+v"(fr3), "+v"(fq3)); E.mid(acc, cur, wr, wc, fr3, fq3); } }
;             const bool last = (t == nt - 2);
;             const char* a1 = cA + (size_t)(t + 1) * kstep;
;             const char* a2 = last ? nA : cA + (size_t)(t + 2) * kstep; const char* b2 = last ? nB : cB + (size_t)(t + 2) * kstep;
;             const char* a3 = a2 + kstep; const char* b3 = b2 + kstep;
;             PG8_LDB(B0, 0, 0); PG8_SCHED; PG8_LDA(At, 0, 0); PG8_STAGE(PG8_SA(1, 1), a1 + hstep, voffA);
;             PG8_WAIT_L(8); PG8_BAR; PG8_WAIT_L(0); PG8_MMA(0, 0, At, B0); PG8_BAR; PG8_SCHED;
;             PG8_LDB(B1, 0, 1); PG8_STAGE(PG8_SB(0, 0), b2, voffB);
;             PG8_BAR; PG8_WAIT_L(0); PG8_MMA(0, 1, At, B1); PG8_BAR;
;             PG8_LDA(At, 0, 1); PG8_STAGE(PG8_SA(0, 0), a2, voffA);
;             PG8_BAR; PG8_WAIT_L(0); PG8_MMA(1, 0, At, B0); PG8_BAR; PG8_SCHED;
;             PG8_STAGE(PG8_SB(0, 1), b2 + hstep, voffB);
;             PG8_WAIT_V(6); PG8_BAR; PG8_MMA(1, 1, At, B1); PG8_BAR;
.LBB0_1745:
	s_add_u32 s38, s38, 0x160080
	s_addc_u32 s39, s39, 0
	s_add_u32 s35, s40, 0x100
	v_mov_b32_e32 v0, 0
	s_addc_u32 s67, s41, 0
	s_mov_b32 s68, -2
	s_waitcnt lgkmcnt(0)
	ds_read_b128 v[144:147], v155
	ds_read_b128 v[160:163], v155 offset:1024
	ds_read_b128 v[164:167], v155 offset:2048
	ds_read_b128 v[168:171], v155 offset:3072
	s_add_u32 s0, s38, 0xffea0080
	s_addc_u32 s1, s39, -1
	s_cmpk_eq_i32 s68, 0x54
	s_cselect_b32 s43, s9, s1
	s_cselect_b32 s42, s8, s0
	s_cselect_b32 s41, s11, s67
	s_cselect_b32 s40, s10, s35
	s_add_i32 m0, s52, 0xc000
	ds_read_b128 v[172:175], v156
	ds_read_b128 v[176:179], v156 offset:1024
	ds_read_b128 v[180:183], v156 offset:2048
	ds_read_b128 v[188:191], v156 offset:3072
	ds_read_b128 v[206:209], v156 offset:4096
	ds_read_b128 v[210:213], v156 offset:5120
	ds_read_b128 v[214:217], v156 offset:6144
	global_load_lds_dwordx4 v136, s[38:39]
	s_add_i32 m0, s52, 0xe000
	ds_read_b128 v[218:221], v156 offset:7168
	global_load_lds_dwordx4 v138, s[38:39]
	s_waitcnt lgkmcnt(8)
	s_barrier
	s_waitcnt lgkmcnt(0)
	s_setprio 1
	v_mfma_f32_16x16x32_bf16 v[124:127], v[144:147], v[172:175], 0
	v_mfma_f32_16x16x32_bf16 v[120:123], v[164:167], v[172:175], 0
	v_mfma_f32_16x16x32_bf16 v[108:111], v[144:147], v[180:183], 0
	v_mfma_f32_16x16x32_bf16 v[104:107], v[164:167], v[180:183], 0
	v_mfma_f32_16x16x32_bf16 v[92:95], v[144:147], v[206:209], 0
	v_mfma_f32_16x16x32_bf16 v[88:91], v[164:167], v[206:209], 0
	v_mfma_f32_16x16x32_bf16 v[76:79], v[144:147], v[214:217], 0
	v_mfma_f32_16x16x32_bf16 v[72:75], v[164:167], v[214:217], 0
	v_mfma_f32_16x16x32_bf16 v[124:127], v[160:163], v[176:179], v[124:127]
	v_mfma_f32_16x16x32_bf16 v[120:123], v[168:171], v[176:179], v[120:123]
	v_mfma_f32_16x16x32_bf16 v[108:111], v[160:163], v[188:191], v[108:111]
	v_mfma_f32_16x16x32_bf16 v[104:107], v[168:171], v[188:191], v[104:107]
	v_mfma_f32_16x16x32_bf16 v[92:95], v[160:163], v[210:213], v[92:95]
	v_mfma_f32_16x16x32_bf16 v[88:91], v[168:171], v[210:213], v[88:91]
	v_mfma_f32_16x16x32_bf16 v[76:79], v[160:163], v[218:221], v[76:79]
	v_mfma_f32_16x16x32_bf16 v[72:75], v[168:171], v[218:221], v[72:75]
	s_setprio 0
	s_barrier
	s_add_i32 s0, s61, s51
	s_mov_b32 m0, s0
	ds_read_b128 v[222:225], v157
	ds_read_b128 v[226:229], v157 offset:1024
	ds_read_b128 v[230:233], v157 offset:2048
	global_load_lds_dwordx4 v130, s[40:41]
	s_add_i32 m0, s0, 0x2000
	ds_read_b128 v[234:237], v157 offset:3072
	global_load_lds_dwordx4 v134, s[40:41]
	s_barrier
	s_waitcnt lgkmcnt(0)
	s_setprio 1
	v_mfma_f32_16x16x32_bf16 v[116:119], v[222:225], v[172:175], 0
	v_mfma_f32_16x16x32_bf16 v[112:115], v[230:233], v[172:175], 0
	v_mfma_f32_16x16x32_bf16 v[100:103], v[222:225], v[180:183], 0
	v_mfma_f32_16x16x32_bf16 v[96:99], v[230:233], v[180:183], 0
	v_mfma_f32_16x16x32_bf16 v[84:87], v[222:225], v[206:209], 0
	v_mfma_f32_16x16x32_bf16 v[80:83], v[230:233], v[206:209], 0
	v_mfma_f32_16x16x32_bf16 v[68:71], v[222:225], v[214:217], 0
	v_mfma_f32_16x16x32_bf16 v[64:67], v[230:233], v[214:217], 0
	v_mfma_f32_16x16x32_bf16 v[116:119], v[226:229], v[176:179], v[116:119]
	v_mfma_f32_16x16x32_bf16 v[112:115], v[234:237], v[176:179], v[112:115]
	v_mfma_f32_16x16x32_bf16 v[100:103], v[226:229], v[188:191], v[100:103]
	v_mfma_f32_16x16x32_bf16 v[96:99], v[234:237], v[188:191], v[96:99]
	v_mfma_f32_16x16x32_bf16 v[84:87], v[226:229], v[210:213], v[84:87]
	v_mfma_f32_16x16x32_bf16 v[80:83], v[234:237], v[210:213], v[80:83]
	v_mfma_f32_16x16x32_bf16 v[68:71], v[226:229], v[218:221], v[68:71]
	v_mfma_f32_16x16x32_bf16 v[64:67], v[234:237], v[218:221], v[64:67]
	s_setprio 0
	s_mov_b32 m0, s52
	s_barrier
	ds_read_b128 v[172:175], v156 offset:16384
	ds_read_b128 v[176:179], v156 offset:17408
	ds_read_b128 v[180:183], v156 offset:18432
	ds_read_b128 v[188:191], v156 offset:19456
	ds_read_b128 v[206:209], v156 offset:20480
	ds_read_b128 v[210:213], v156 offset:21504
	ds_read_b128 v[214:217], v156 offset:22528
	global_load_lds_dwordx4 v128, s[42:43]
	s_mov_b32 m0, s53
	ds_read_b128 v[218:221], v156 offset:23552
	global_load_lds_dwordx4 v132, s[42:43]
	s_barrier
	s_waitcnt lgkmcnt(0)
	s_setprio 1
	v_mfma_f32_16x16x32_bf16 v[60:63], v[144:147], v[172:175], 0
	v_mfma_f32_16x16x32_bf16 v[56:59], v[164:167], v[172:175], 0
	v_mfma_f32_16x16x32_bf16 v[44:47], v[144:147], v[180:183], 0
	v_mfma_f32_16x16x32_bf16 v[40:43], v[164:167], v[180:183], 0
	v_mfma_f32_16x16x32_bf16 v[28:31], v[144:147], v[206:209], 0
	v_mfma_f32_16x16x32_bf16 v[24:27], v[164:167], v[206:209], 0
	v_mfma_f32_16x16x32_bf16 v[12:15], v[144:147], v[214:217], 0
	v_mfma_f32_16x16x32_bf16 v[8:11], v[164:167], v[214:217], 0
	v_mfma_f32_16x16x32_bf16 v[60:63], v[160:163], v[176:179], v[60:63]
	v_mfma_f32_16x16x32_bf16 v[56:59], v[168:171], v[176:179], v[56:59]
	v_mfma_f32_16x16x32_bf16 v[44:47], v[160:163], v[188:191], v[44:47]
	v_mfma_f32_16x16x32_bf16 v[40:43], v[168:171], v[188:191], v[40:43]
	v_mfma_f32_16x16x32_bf16 v[28:31], v[160:163], v[210:213], v[28:31]
	v_mfma_f32_16x16x32_bf16 v[24:27], v[168:171], v[210:213], v[24:27]
	v_mfma_f32_16x16x32_bf16 v[12:15], v[160:163], v[218:221], v[12:15]
	v_mfma_f32_16x16x32_bf16 v[8:11], v[168:171], v[218:221], v[8:11]
	s_setprio 0
	s_barrier
	s_add_u32 s0, s40, 0x160000
	s_addc_u32 s1, s41, 0
	s_add_i32 s4, s62, s51
	s_mov_b32 m0, s4
	s_nop 0
	global_load_lds_dwordx4 v130, s[0:1]
	s_add_i32 m0, s4, 0x2000
	s_nop 0
	global_load_lds_dwordx4 v134, s[0:1]
	s_waitcnt vmcnt(6)
	s_barrier
; #define PG8_STAGE(bufoff, gbase, voff) do { _Pragma("unroll") for (int _i = 0; _i < 2; ++_i) \
;         __builtin_amdgcn_global_load_lds((const unsigned*)((const char*)(gbase) + (voff)[_i]), (LAS unsigned*)(lds + (bufoff) + ldsw + _i * 8192), 16, 0, 0); } while (0)
; #define PG8_LDA(dst, b, h) do { _Pragma("unroll") for (int m = 0; m < 4; ++m) _Pragma("unroll") for (int k = 0; k < 2; ++k) dst[m][k] = *(const LAS bf16x8*)(lds + PG8_SA(b, h) + aoff + m * 2048 + k * 1024); } while (0)
; #define PG8_LDB(dst, b, h) do { _Pragma("unroll") for (int n = 0; n < 2; ++n) _Pragma("unroll") for (int k = 0; k < 2; ++k) dst[n][k] = *(const LAS bf16x8*)(lds + PG8_SB(b, h) + boff + n * 2048 + k * 1024); } while (0)
; #define PG8_MMA(ai, bj, At, Bt) do { __builtin_amdgcn_s_setprio(1); _Pragma("unroll") for (int m = 0; m < 4; ++m) _Pragma("unroll") for (int n = 0; n < 2; ++n) _Pragma("unroll") for (int k = 0; k < 2; ++k) \
;         acc[ai][bj][m][n] = __builtin_amdgcn_mfma_f32_16x16x32_bf16(Bt[n][k], At[m][k], acc[ai][bj][m][n], 0, 0, 0); __builtin_amdgcn_s_setprio(0); } while (0)
; #define PG8_WAIT_V(n) asm volatile("s_waitcnt vmcnt(" #n ")" ::: "memory")
; #define PG8_WAIT_L(n) asm volatile("s_waitcnt lgkmcnt(" #n ")" ::: "memory")
; #define PG8_BAR __builtin_amdgcn_s_barrier()
; #define PG8_SCHED __builtin_amdgcn_sched_barrier(0)
; template <class Epi, class Sched>
; DI void gemm_phase(LAS unsigned char* lds, const Gemm g, const Sched& S, const Epi& E) {
;     ...
;             PG8_STAGE(PG8_SB(0, 1), b2 + hstep, voffB);
;             PG8_WAIT_V(6); PG8_BAR; PG8_MMA(1, 1, At, B1); PG8_BAR;
;             PG8_LDB(B0, 1, 0); PG8_SCHED; PG8_LDA(At, 1, 0); PG8_STAGE(PG8_SA(0, 1), a2 + hstep, voffA);
;             PG8_WAIT_L(8); PG8_BAR; PG8_WAIT_L(0); PG8_MMA(0, 0, At, B0); PG8_BAR; PG8_SCHED;
;             PG8_LDB(B1, 1, 1); PG8_STAGE(PG8_SB(1, 0), b3, voffB);
;             PG8_BAR; PG8_WAIT_L(0); PG8_MMA(0, 1, At, B1); PG8_BAR;
;             PG8_LDA(At, 1, 1); PG8_STAGE(PG8_SA(1, 0), a3, voffA);
;             PG8_BAR; PG8_WAIT_L(0); PG8_MMA(1, 0, At, B0); PG8_BAR; PG8_SCHED;
	s_setprio 1
	v_mfma_f32_16x16x32_bf16 v[52:55], v[222:225], v[172:175], 0
	v_mfma_f32_16x16x32_bf16 v[48:51], v[230:233], v[172:175], 0
	v_mfma_f32_16x16x32_bf16 v[36:39], v[222:225], v[180:183], 0
	v_mfma_f32_16x16x32_bf16 v[32:35], v[230:233], v[180:183], 0
	v_mfma_f32_16x16x32_bf16 v[20:23], v[222:225], v[206:209], 0
	v_mfma_f32_16x16x32_bf16 v[16:19], v[230:233], v[206:209], 0
	v_mfma_f32_16x16x32_bf16 v[4:7], v[222:225], v[214:217], 0
	v_mfma_f32_16x16x32_bf16 v[0:3], v[230:233], v[214:217], 0
	v_mfma_f32_16x16x32_bf16 v[52:55], v[226:229], v[176:179], v[52:55]
	v_mfma_f32_16x16x32_bf16 v[48:51], v[234:237], v[176:179], v[48:51]
	v_mfma_f32_16x16x32_bf16 v[36:39], v[226:229], v[188:191], v[36:39]
	v_mfma_f32_16x16x32_bf16 v[32:35], v[234:237], v[188:191], v[32:35]
	v_mfma_f32_16x16x32_bf16 v[20:23], v[226:229], v[210:213], v[20:23]
	v_mfma_f32_16x16x32_bf16 v[16:19], v[234:237], v[210:213], v[16:19]
	v_mfma_f32_16x16x32_bf16 v[4:7], v[226:229], v[218:221], v[4:7]
	v_mfma_f32_16x16x32_bf16 v[0:3], v[234:237], v[218:221], v[0:3]
	s_setprio 0
	s_add_i32 s4, 0, 0x18000
	v_add_u32_e32 v159, s4, v154
	s_barrier
	ds_read_b128 v[144:147], v159
	ds_read_b128 v[160:163], v159 offset:1024
	ds_read_b128 v[164:167], v159 offset:2048
	ds_read_b128 v[168:171], v159 offset:3072
	s_add_u32 s0, s42, 0x160000
	s_addc_u32 s1, s43, 0
	s_mov_b32 m0, s54
	ds_read_b128 v[172:175], v156 offset:32768
	ds_read_b128 v[176:179], v156 offset:33792
	ds_read_b128 v[180:183], v156 offset:34816
	ds_read_b128 v[188:191], v156 offset:35840
	ds_read_b128 v[206:209], v156 offset:36864
	ds_read_b128 v[210:213], v156 offset:37888
	ds_read_b128 v[214:217], v156 offset:38912
	global_load_lds_dwordx4 v128, s[0:1]
	s_mov_b32 m0, s55
	ds_read_b128 v[218:221], v156 offset:39936
	global_load_lds_dwordx4 v132, s[0:1]
	s_waitcnt lgkmcnt(8)
	s_barrier
	s_waitcnt lgkmcnt(0)
	s_setprio 1
	v_mfma_f32_16x16x32_bf16 v[124:127], v[144:147], v[172:175], v[124:127]
	v_mfma_f32_16x16x32_bf16 v[120:123], v[164:167], v[172:175], v[120:123]
	v_mfma_f32_16x16x32_bf16 v[108:111], v[144:147], v[180:183], v[108:111]
	v_mfma_f32_16x16x32_bf16 v[104:107], v[164:167], v[180:183], v[104:107]
	v_mfma_f32_16x16x32_bf16 v[92:95], v[144:147], v[206:209], v[92:95]
	v_mfma_f32_16x16x32_bf16 v[88:91], v[164:167], v[206:209], v[88:91]
	v_mfma_f32_16x16x32_bf16 v[76:79], v[144:147], v[214:217], v[76:79]
	v_mfma_f32_16x16x32_bf16 v[72:75], v[164:167], v[214:217], v[72:75]
	v_mfma_f32_16x16x32_bf16 v[124:127], v[160:163], v[176:179], v[124:127]
	v_mfma_f32_16x16x32_bf16 v[120:123], v[168:171], v[176:179], v[120:123]
	v_mfma_f32_16x16x32_bf16 v[108:111], v[160:163], v[188:191], v[108:111]
	v_mfma_f32_16x16x32_bf16 v[104:107], v[168:171], v[188:191], v[104:107]
	v_mfma_f32_16x16x32_bf16 v[92:95], v[160:163], v[210:213], v[92:95]
	v_mfma_f32_16x16x32_bf16 v[88:91], v[168:171], v[210:213], v[88:91]
	v_mfma_f32_16x16x32_bf16 v[76:79], v[160:163], v[218:221], v[76:79]
	v_mfma_f32_16x16x32_bf16 v[72:75], v[168:171], v[218:221], v[72:75]
	s_setprio 0
	s_barrier
	s_add_i32 s5, 0, 0x1c000
	s_add_i32 s0, s4, s51
	v_add_u32_e32 v159, s5, v154
	s_add_i32 m0, s0, 0xffffff80
	ds_read_b128 v[222:225], v159
	ds_read_b128 v[226:229], v159 offset:1024
	ds_read_b128 v[230:233], v159 offset:2048
	global_load_lds_dwordx4 v130, s[40:41] offset:128
	s_add_i32 m0, s0, 0x1f80
	ds_read_b128 v[234:237], v159 offset:3072
	global_load_lds_dwordx4 v134, s[40:41] offset:128
	s_barrier
	s_waitcnt lgkmcnt(0)
	s_setprio 1
	v_mfma_f32_16x16x32_bf16 v[116:119], v[222:225], v[172:175], v[116:119]
	v_mfma_f32_16x16x32_bf16 v[112:115], v[230:233], v[172:175], v[112:115]
	v_mfma_f32_16x16x32_bf16 v[100:103], v[222:225], v[180:183], v[100:103]
	v_mfma_f32_16x16x32_bf16 v[96:99], v[230:233], v[180:183], v[96:99]
	v_mfma_f32_16x16x32_bf16 v[84:87], v[222:225], v[206:209], v[84:87]
	v_mfma_f32_16x16x32_bf16 v[80:83], v[230:233], v[206:209], v[80:83]
	v_mfma_f32_16x16x32_bf16 v[68:71], v[222:225], v[214:217], v[68:71]
	v_mfma_f32_16x16x32_bf16 v[64:67], v[230:233], v[214:217], v[64:67]
	v_mfma_f32_16x16x32_bf16 v[116:119], v[226:229], v[176:179], v[116:119]
	v_mfma_f32_16x16x32_bf16 v[112:115], v[234:237], v[176:179], v[112:115]
	v_mfma_f32_16x16x32_bf16 v[100:103], v[226:229], v[188:191], v[100:103]
	v_mfma_f32_16x16x32_bf16 v[96:99], v[234:237], v[188:191], v[96:99]
	v_mfma_f32_16x16x32_bf16 v[84:87], v[226:229], v[210:213], v[84:87]
	v_mfma_f32_16x16x32_bf16 v[80:83], v[234:237], v[210:213], v[80:83]
	v_mfma_f32_16x16x32_bf16 v[68:71], v[226:229], v[218:221], v[68:71]
	v_mfma_f32_16x16x32_bf16 v[64:67], v[234:237], v[218:221], v[64:67]
	s_setprio 0
	s_add_i32 m0, s59, 0xffffff80
	s_barrier
	ds_read_b128 v[172:175], v156 offset:49152
	ds_read_b128 v[176:179], v156 offset:50176
	ds_read_b128 v[180:183], v156 offset:51200
	ds_read_b128 v[188:191], v156 offset:52224
	ds_read_b128 v[206:209], v156 offset:53248
	ds_read_b128 v[210:213], v156 offset:54272
	ds_read_b128 v[214:217], v156 offset:55296
	global_load_lds_dwordx4 v128, s[42:43] offset:128
	s_add_i32 m0, s60, 0xffffff80
	ds_read_b128 v[218:221], v156 offset:56320
	global_load_lds_dwordx4 v132, s[42:43] offset:128
	s_barrier
; #define PG8_STAGE(bufoff, gbase, voff) do { _Pragma("unroll") for (int _i = 0; _i < 2; ++_i) \
;         __builtin_amdgcn_global_load_lds((const unsigned*)((const char*)(gbase) + (voff)[_i]), (LAS unsigned*)(lds + (bufoff) + ldsw + _i * 8192), 16, 0, 0); } while (0)
; #define PG8_LDA(dst, b, h) do { _Pragma("unroll") for (int m = 0; m < 4; ++m) _Pragma("unroll") for (int k = 0; k < 2; ++k) dst[m][k] = *(const LAS bf16x8*)(lds + PG8_SA(b, h) + aoff + m * 2048 + k * 1024); } while (0)
; #define PG8_LDB(dst, b, h) do { _Pragma("unroll") for (int n = 0; n < 2; ++n) _Pragma("unroll") for (int k = 0; k < 2; ++k) dst[n][k] = *(const LAS bf16x8*)(lds + PG8_SB(b, h) + boff + n * 2048 + k * 1024); } while (0)
; #define PG8_MMA(ai, bj, At, Bt) do { __builtin_amdgcn_s_setprio(1); _Pragma("unroll") for (int m = 0; m < 4; ++m) _Pragma("unroll") for (int n = 0; n < 2; ++n) _Pragma("unroll") for (int k = 0; k < 2; ++k) \
;         acc[ai][bj][m][n] = __builtin_amdgcn_mfma_f32_16x16x32_bf16(Bt[n][k], At[m][k], acc[ai][bj][m][n], 0, 0, 0); __builtin_amdgcn_s_setprio(0); } while (0)
; #define PG8_WAIT_V(n) asm volatile("s_waitcnt vmcnt(" #n ")" ::: "memory")
; #define PG8_WAIT_L(n) asm volatile("s_waitcnt lgkmcnt(" #n ")" ::: "memory")
; #define PG8_BAR __builtin_amdgcn_s_barrier()
; #define PG8_SCHED __builtin_amdgcn_sched_barrier(0)
; template <class Epi, class Sched>
; DI void gemm_phase(LAS unsigned char* lds, const Gemm g, const Sched& S, const Epi& E) {
;     ...
;             PG8_LDB(B0, 0, 0); PG8_SCHED; PG8_LDA(At, 0, 0); PG8_STAGE(PG8_SA(1, 1), a1 + hstep, voffA);
;             PG8_WAIT_L(8); PG8_BAR; PG8_WAIT_L(0); PG8_MMA(0, 0, At, B0); PG8_BAR; PG8_SCHED;
;             PG8_LDB(B1, 0, 1); PG8_STAGE(PG8_SB(0, 0), b2, voffB);
;             PG8_BAR; PG8_WAIT_L(0); PG8_MMA(0, 1, At, B1); PG8_BAR;
;     ...
;             PG8_BAR; PG8_WAIT_L(0); PG8_MMA(1, 0, At, B0); PG8_BAR; PG8_SCHED;
;             PG8_STAGE(PG8_SB(1, 1), b3 + hstep, voffB);
;             PG8_WAIT_V(6); PG8_BAR; PG8_MMA(1, 1, At, B1); PG8_BAR;
	s_waitcnt lgkmcnt(0)
	s_setprio 1
	v_mfma_f32_16x16x32_bf16 v[60:63], v[144:147], v[172:175], v[60:63]
	v_mfma_f32_16x16x32_bf16 v[56:59], v[164:167], v[172:175], v[56:59]
	v_mfma_f32_16x16x32_bf16 v[44:47], v[144:147], v[180:183], v[44:47]
	v_mfma_f32_16x16x32_bf16 v[40:43], v[164:167], v[180:183], v[40:43]
	v_mfma_f32_16x16x32_bf16 v[28:31], v[144:147], v[206:209], v[28:31]
	v_mfma_f32_16x16x32_bf16 v[24:27], v[164:167], v[206:209], v[24:27]
	v_mfma_f32_16x16x32_bf16 v[12:15], v[144:147], v[214:217], v[12:15]
	v_mfma_f32_16x16x32_bf16 v[8:11], v[164:167], v[214:217], v[8:11]
	v_mfma_f32_16x16x32_bf16 v[60:63], v[160:163], v[176:179], v[60:63]
	v_mfma_f32_16x16x32_bf16 v[56:59], v[168:171], v[176:179], v[56:59]
	v_mfma_f32_16x16x32_bf16 v[44:47], v[160:163], v[188:191], v[44:47]
	v_mfma_f32_16x16x32_bf16 v[40:43], v[168:171], v[188:191], v[40:43]
	v_mfma_f32_16x16x32_bf16 v[28:31], v[160:163], v[210:213], v[28:31]
	v_mfma_f32_16x16x32_bf16 v[24:27], v[168:171], v[210:213], v[24:27]
	v_mfma_f32_16x16x32_bf16 v[12:15], v[160:163], v[218:221], v[12:15]
	v_mfma_f32_16x16x32_bf16 v[8:11], v[168:171], v[218:221], v[8:11]
	s_setprio 0
	s_barrier
	s_add_u32 s0, s40, 0x160080
	s_addc_u32 s1, s41, 0
	s_add_i32 s4, s5, s51
	s_mov_b32 m0, s4
	s_nop 0
	global_load_lds_dwordx4 v130, s[0:1]
	s_add_i32 m0, s4, 0x2000
	s_nop 0
	global_load_lds_dwordx4 v134, s[0:1]
	s_waitcnt vmcnt(6)
	s_barrier
	s_setprio 1
	v_mfma_f32_16x16x32_bf16 v[52:55], v[222:225], v[172:175], v[52:55]
	v_mfma_f32_16x16x32_bf16 v[48:51], v[230:233], v[172:175], v[48:51]
	v_mfma_f32_16x16x32_bf16 v[36:39], v[222:225], v[180:183], v[36:39]
	v_mfma_f32_16x16x32_bf16 v[32:35], v[230:233], v[180:183], v[32:35]
	v_mfma_f32_16x16x32_bf16 v[20:23], v[222:225], v[206:209], v[20:23]
	v_mfma_f32_16x16x32_bf16 v[16:19], v[230:233], v[206:209], v[16:19]
	v_mfma_f32_16x16x32_bf16 v[4:7], v[222:225], v[214:217], v[4:7]
	v_mfma_f32_16x16x32_bf16 v[0:3], v[230:233], v[214:217], v[0:3]
	v_mfma_f32_16x16x32_bf16 v[52:55], v[226:229], v[176:179], v[52:55]
	v_mfma_f32_16x16x32_bf16 v[48:51], v[234:237], v[176:179], v[48:51]
	v_mfma_f32_16x16x32_bf16 v[36:39], v[226:229], v[188:191], v[36:39]
	v_mfma_f32_16x16x32_bf16 v[32:35], v[234:237], v[188:191], v[32:35]
	v_mfma_f32_16x16x32_bf16 v[20:23], v[226:229], v[210:213], v[20:23]
	v_mfma_f32_16x16x32_bf16 v[16:19], v[234:237], v[210:213], v[16:19]
	v_mfma_f32_16x16x32_bf16 v[4:7], v[226:229], v[218:221], v[4:7]
	v_mfma_f32_16x16x32_bf16 v[0:3], v[234:237], v[218:221], v[0:3]
	s_setprio 0
	s_add_i32 s68, s68, 2
	s_add_u32 s38, s38, 0x100
	s_addc_u32 s39, s39, 0
	s_add_u32 s35, s35, 0x100
	s_addc_u32 s67, s67, 0
	s_cmpk_gt_u32 s68, 0x55
	s_barrier
	s_cbranch_scc0 .LBB0_1746
	s_branch .Lpeel_done_1746
.LBB0_1746:
	ds_read_b128 v[144:147], v155
	ds_read_b128 v[160:163], v155 offset:1024
	ds_read_b128 v[164:167], v155 offset:2048
	ds_read_b128 v[168:171], v155 offset:3072
	s_add_u32 s0, s38, 0xffea0080
	s_addc_u32 s1, s39, -1
	s_cmpk_eq_i32 s68, 0x54
	s_cselect_b32 s43, s9, s1
	s_cselect_b32 s42, s8, s0
	s_cselect_b32 s41, s11, s67
	s_cselect_b32 s40, s10, s35
	s_add_i32 m0, s52, 0xc000
	ds_read_b128 v[172:175], v156
	ds_read_b128 v[176:179], v156 offset:1024
	ds_read_b128 v[180:183], v156 offset:2048
	ds_read_b128 v[188:191], v156 offset:3072
	ds_read_b128 v[206:209], v156 offset:4096
	ds_read_b128 v[210:213], v156 offset:5120
	ds_read_b128 v[214:217], v156 offset:6144
	global_load_lds_dwordx4 v136, s[38:39]
	s_add_i32 m0, s52, 0xe000
	ds_read_b128 v[218:221], v156 offset:7168
	global_load_lds_dwordx4 v138, s[38:39]
	s_waitcnt lgkmcnt(8)
	s_barrier
	s_waitcnt lgkmcnt(0)
	s_setprio 1
	v_mfma_f32_16x16x32_bf16 v[124:127], v[144:147], v[172:175], v[124:127]
	v_mfma_f32_16x16x32_bf16 v[120:123], v[164:167], v[172:175], v[120:123]
	v_mfma_f32_16x16x32_bf16 v[108:111], v[144:147], v[180:183], v[108:111]
	v_mfma_f32_16x16x32_bf16 v[104:107], v[164:167], v[180:183], v[104:107]
	v_mfma_f32_16x16x32_bf16 v[92:95], v[144:147], v[206:209], v[92:95]
	v_mfma_f32_16x16x32_bf16 v[88:91], v[164:167], v[206:209], v[88:91]
	v_mfma_f32_16x16x32_bf16 v[76:79], v[144:147], v[214:217], v[76:79]
	v_mfma_f32_16x16x32_bf16 v[72:75], v[164:167], v[214:217], v[72:75]
	v_mfma_f32_16x16x32_bf16 v[124:127], v[160:163], v[176:179], v[124:127]
	v_mfma_f32_16x16x32_bf16 v[120:123], v[168:171], v[176:179], v[120:123]
	v_mfma_f32_16x16x32_bf16 v[108:111], v[160:163], v[188:191], v[108:111]
	v_mfma_f32_16x16x32_bf16 v[104:107], v[168:171], v[188:191], v[104:107]
	v_mfma_f32_16x16x32_bf16 v[92:95], v[160:163], v[210:213], v[92:95]
	v_mfma_f32_16x16x32_bf16 v[88:91], v[168:171], v[210:213], v[88:91]
	v_mfma_f32_16x16x32_bf16 v[76:79], v[160:163], v[218:221], v[76:79]
	v_mfma_f32_16x16x32_bf16 v[72:75], v[168:171], v[218:221], v[72:75]
	s_setprio 0
	s_barrier
	s_add_i32 s0, s61, s51
	s_mov_b32 m0, s0
	ds_read_b128 v[222:225], v157
	ds_read_b128 v[226:229], v157 offset:1024
	ds_read_b128 v[230:233], v157 offset:2048
	global_load_lds_dwordx4 v130, s[40:41]
	s_add_i32 m0, s0, 0x2000
	ds_read_b128 v[234:237], v157 offset:3072
	global_load_lds_dwordx4 v134, s[40:41]
	s_barrier
; #define PG8_STAGE(bufoff, gbase, voff) do { _Pragma("unroll") for (int _i = 0; _i < 2; ++_i) \
;         __builtin_amdgcn_global_load_lds((const unsigned*)((const char*)(gbase) + (voff)[_i]), (LAS unsigned*)(lds + (bufoff) + ldsw + _i * 8192), 16, 0, 0); } while (0)
; #define PG8_LDA(dst, b, h) do { _Pragma("unroll") for (int m = 0; m < 4; ++m) _Pragma("unroll") for (int k = 0; k < 2; ++k) dst[m][k] = *(const LAS bf16x8*)(lds + PG8_SA(b, h) + aoff + m * 2048 + k * 1024); } while (0)
; #define PG8_LDB(dst, b, h) do { _Pragma("unroll") for (int n = 0; n < 2; ++n) _Pragma("unroll") for (int k = 0; k < 2; ++k) dst[n][k] = *(const LAS bf16x8*)(lds + PG8_SB(b, h) + boff + n * 2048 + k * 1024); } while (0)
; #define PG8_MMA(ai, bj, At, Bt) do { __builtin_amdgcn_s_setprio(1); _Pragma("unroll") for (int m = 0; m < 4; ++m) _Pragma("unroll") for (int n = 0; n < 2; ++n) _Pragma("unroll") for (int k = 0; k < 2; ++k) \
;         acc[ai][bj][m][n] = __builtin_amdgcn_mfma_f32_16x16x32_bf16(Bt[n][k], At[m][k], acc[ai][bj][m][n], 0, 0, 0); __builtin_amdgcn_s_setprio(0); } while (0)
; #define PG8_WAIT_V(n) asm volatile("s_waitcnt vmcnt(" #n ")" ::: "memory")
; #define PG8_WAIT_L(n) asm volatile("s_waitcnt lgkmcnt(" #n ")" ::: "memory")
; #define PG8_BAR __builtin_amdgcn_s_barrier()
; #define PG8_SCHED __builtin_amdgcn_sched_barrier(0)
; template <class Epi, class Sched>
; DI void gemm_phase(LAS unsigned char* lds, const Gemm g, const Sched& S, const Epi& E) {
;     ...
;             PG8_BAR; PG8_WAIT_L(0); PG8_MMA(0, 1, At, B1); PG8_BAR;
;             PG8_LDA(At, 0, 1); PG8_STAGE(PG8_SA(0, 0), a2, voffA);
;             PG8_BAR; PG8_WAIT_L(0); PG8_MMA(1, 0, At, B0); PG8_BAR; PG8_SCHED;
;             PG8_STAGE(PG8_SB(0, 1), b2 + hstep, voffB);
;             PG8_WAIT_V(6); PG8_BAR; PG8_MMA(1, 1, At, B1); PG8_BAR;
;             PG8_LDB(B0, 1, 0); PG8_SCHED; PG8_LDA(At, 1, 0); PG8_STAGE(PG8_SA(0, 1), a2 + hstep, voffA);
;             PG8_WAIT_L(8); PG8_BAR; PG8_WAIT_L(0); PG8_MMA(0, 0, At, B0); PG8_BAR; PG8_SCHED;
;             PG8_LDB(B1, 1, 1); PG8_STAGE(PG8_SB(1, 0), b3, voffB);
	s_waitcnt lgkmcnt(0)
	s_setprio 1
	v_mfma_f32_16x16x32_bf16 v[116:119], v[222:225], v[172:175], v[116:119]
	v_mfma_f32_16x16x32_bf16 v[112:115], v[230:233], v[172:175], v[112:115]
	v_mfma_f32_16x16x32_bf16 v[100:103], v[222:225], v[180:183], v[100:103]
	v_mfma_f32_16x16x32_bf16 v[96:99], v[230:233], v[180:183], v[96:99]
	v_mfma_f32_16x16x32_bf16 v[84:87], v[222:225], v[206:209], v[84:87]
	v_mfma_f32_16x16x32_bf16 v[80:83], v[230:233], v[206:209], v[80:83]
	v_mfma_f32_16x16x32_bf16 v[68:71], v[222:225], v[214:217], v[68:71]
	v_mfma_f32_16x16x32_bf16 v[64:67], v[230:233], v[214:217], v[64:67]
	v_mfma_f32_16x16x32_bf16 v[116:119], v[226:229], v[176:179], v[116:119]
	v_mfma_f32_16x16x32_bf16 v[112:115], v[234:237], v[176:179], v[112:115]
	v_mfma_f32_16x16x32_bf16 v[100:103], v[226:229], v[188:191], v[100:103]
	v_mfma_f32_16x16x32_bf16 v[96:99], v[234:237], v[188:191], v[96:99]
	v_mfma_f32_16x16x32_bf16 v[84:87], v[226:229], v[210:213], v[84:87]
	v_mfma_f32_16x16x32_bf16 v[80:83], v[234:237], v[210:213], v[80:83]
	v_mfma_f32_16x16x32_bf16 v[68:71], v[226:229], v[218:221], v[68:71]
	v_mfma_f32_16x16x32_bf16 v[64:67], v[234:237], v[218:221], v[64:67]
	s_setprio 0
	s_mov_b32 m0, s52
	s_barrier
	ds_read_b128 v[172:175], v156 offset:16384
	ds_read_b128 v[176:179], v156 offset:17408
	ds_read_b128 v[180:183], v156 offset:18432
	ds_read_b128 v[188:191], v156 offset:19456
	ds_read_b128 v[206:209], v156 offset:20480
	ds_read_b128 v[210:213], v156 offset:21504
	ds_read_b128 v[214:217], v156 offset:22528
	global_load_lds_dwordx4 v128, s[42:43]
	s_mov_b32 m0, s53
	ds_read_b128 v[218:221], v156 offset:23552
	global_load_lds_dwordx4 v132, s[42:43]
	s_barrier
	s_waitcnt lgkmcnt(0)
	s_setprio 1
	v_mfma_f32_16x16x32_bf16 v[60:63], v[144:147], v[172:175], v[60:63]
	v_mfma_f32_16x16x32_bf16 v[56:59], v[164:167], v[172:175], v[56:59]
	v_mfma_f32_16x16x32_bf16 v[44:47], v[144:147], v[180:183], v[44:47]
	v_mfma_f32_16x16x32_bf16 v[40:43], v[164:167], v[180:183], v[40:43]
	v_mfma_f32_16x16x32_bf16 v[28:31], v[144:147], v[206:209], v[28:31]
	v_mfma_f32_16x16x32_bf16 v[24:27], v[164:167], v[206:209], v[24:27]
	v_mfma_f32_16x16x32_bf16 v[12:15], v[144:147], v[214:217], v[12:15]
	v_mfma_f32_16x16x32_bf16 v[8:11], v[164:167], v[214:217], v[8:11]
	v_mfma_f32_16x16x32_bf16 v[60:63], v[160:163], v[176:179], v[60:63]
	v_mfma_f32_16x16x32_bf16 v[56:59], v[168:171], v[176:179], v[56:59]
	v_mfma_f32_16x16x32_bf16 v[44:47], v[160:163], v[188:191], v[44:47]
	v_mfma_f32_16x16x32_bf16 v[40:43], v[168:171], v[188:191], v[40:43]
	v_mfma_f32_16x16x32_bf16 v[28:31], v[160:163], v[210:213], v[28:31]
	v_mfma_f32_16x16x32_bf16 v[24:27], v[168:171], v[210:213], v[24:27]
	v_mfma_f32_16x16x32_bf16 v[12:15], v[160:163], v[218:221], v[12:15]
	v_mfma_f32_16x16x32_bf16 v[8:11], v[168:171], v[218:221], v[8:11]
	s_setprio 0
	s_barrier
	s_add_u32 s0, s40, 0x160000
	s_addc_u32 s1, s41, 0
	s_add_i32 s4, s62, s51
	s_mov_b32 m0, s4
	s_nop 0
	global_load_lds_dwordx4 v130, s[0:1]
	s_add_i32 m0, s4, 0x2000
	s_nop 0
	global_load_lds_dwordx4 v134, s[0:1]
	s_waitcnt vmcnt(6)
	s_barrier
	s_setprio 1
	v_mfma_f32_16x16x32_bf16 v[52:55], v[222:225], v[172:175], v[52:55]
	v_mfma_f32_16x16x32_bf16 v[48:51], v[230:233], v[172:175], v[48:51]
	v_mfma_f32_16x16x32_bf16 v[36:39], v[222:225], v[180:183], v[36:39]
	v_mfma_f32_16x16x32_bf16 v[32:35], v[230:233], v[180:183], v[32:35]
	v_mfma_f32_16x16x32_bf16 v[20:23], v[222:225], v[206:209], v[20:23]
	v_mfma_f32_16x16x32_bf16 v[16:19], v[230:233], v[206:209], v[16:19]
	v_mfma_f32_16x16x32_bf16 v[4:7], v[222:225], v[214:217], v[4:7]
	v_mfma_f32_16x16x32_bf16 v[0:3], v[230:233], v[214:217], v[0:3]
	v_mfma_f32_16x16x32_bf16 v[52:55], v[226:229], v[176:179], v[52:55]
	v_mfma_f32_16x16x32_bf16 v[48:51], v[234:237], v[176:179], v[48:51]
	v_mfma_f32_16x16x32_bf16 v[36:39], v[226:229], v[188:191], v[36:39]
	v_mfma_f32_16x16x32_bf16 v[32:35], v[234:237], v[188:191], v[32:35]
	v_mfma_f32_16x16x32_bf16 v[20:23], v[226:229], v[210:213], v[20:23]
	v_mfma_f32_16x16x32_bf16 v[16:19], v[234:237], v[210:213], v[16:19]
	v_mfma_f32_16x16x32_bf16 v[4:7], v[226:229], v[218:221], v[4:7]
	v_mfma_f32_16x16x32_bf16 v[0:3], v[234:237], v[218:221], v[0:3]
	s_setprio 0
	s_add_i32 s4, 0, 0x18000
	v_add_u32_e32 v159, s4, v154
	s_barrier
	ds_read_b128 v[144:147], v159
	ds_read_b128 v[160:163], v159 offset:1024
	ds_read_b128 v[164:167], v159 offset:2048
	ds_read_b128 v[168:171], v159 offset:3072
	s_add_u32 s0, s42, 0x160000
	s_addc_u32 s1, s43, 0
	s_mov_b32 m0, s54
	ds_read_b128 v[172:175], v156 offset:32768
	ds_read_b128 v[176:179], v156 offset:33792
	ds_read_b128 v[180:183], v156 offset:34816
	ds_read_b128 v[188:191], v156 offset:35840
	ds_read_b128 v[206:209], v156 offset:36864
	ds_read_b128 v[210:213], v156 offset:37888
	ds_read_b128 v[214:217], v156 offset:38912
	global_load_lds_dwordx4 v128, s[0:1]
	s_mov_b32 m0, s55
	ds_read_b128 v[218:221], v156 offset:39936
	global_load_lds_dwordx4 v132, s[0:1]
	s_waitcnt lgkmcnt(8)
	s_barrier
; #define PG8_STAGE(bufoff, gbase, voff) do { _Pragma("unroll") for (int _i = 0; _i < 2; ++_i) \
;         __builtin_amdgcn_global_load_lds((const unsigned*)((const char*)(gbase) + (voff)[_i]), (LAS unsigned*)(lds + (bufoff) + ldsw + _i * 8192), 16, 0, 0); } while (0)
; #define PG8_LDA(dst, b, h) do { _Pragma("unroll") for (int m = 0; m < 4; ++m) _Pragma("unroll") for (int k = 0; k < 2; ++k) dst[m][k] = *(const LAS bf16x8*)(lds + PG8_SA(b, h) + aoff + m * 2048 + k * 1024); } while (0)
; #define PG8_LDB(dst, b, h) do { _Pragma("unroll") for (int n = 0; n < 2; ++n) _Pragma("unroll") for (int k = 0; k < 2; ++k) dst[n][k] = *(const LAS bf16x8*)(lds + PG8_SB(b, h) + boff + n * 2048 + k * 1024); } while (0)
; #define PG8_MMA(ai, bj, At, Bt) do { __builtin_amdgcn_s_setprio(1); _Pragma("unroll") for (int m = 0; m < 4; ++m) _Pragma("unroll") for (int n = 0; n < 2; ++n) _Pragma("unroll") for (int k = 0; k < 2; ++k) \
;         acc[ai][bj][m][n] = __builtin_amdgcn_mfma_f32_16x16x32_bf16(Bt[n][k], At[m][k], acc[ai][bj][m][n], 0, 0, 0); __builtin_amdgcn_s_setprio(0); } while (0)
; #define PG8_WAIT_V(n) asm volatile("s_waitcnt vmcnt(" #n ")" ::: "memory")
; #define PG8_WAIT_L(n) asm volatile("s_waitcnt lgkmcnt(" #n ")" ::: "memory")
; #define PG8_BAR __builtin_amdgcn_s_barrier()
; #define PG8_SCHED __builtin_amdgcn_sched_barrier(0)
; template <class Epi, class Sched>
; DI void gemm_phase(LAS unsigned char* lds, const Gemm g, const Sched& S, const Epi& E) {
;     ...
;             PG8_WAIT_L(8); PG8_BAR; PG8_WAIT_L(0); PG8_MMA(0, 0, At, B0); PG8_BAR; PG8_SCHED;
;             PG8_LDB(B1, 1, 1); PG8_STAGE(PG8_SB(1, 0), b3, voffB);
;             PG8_BAR; PG8_WAIT_L(0); PG8_MMA(0, 1, At, B1); PG8_BAR;
;             PG8_LDA(At, 1, 1); PG8_STAGE(PG8_SA(1, 0), a3, voffA);
;             PG8_BAR; PG8_WAIT_L(0); PG8_MMA(1, 0, At, B0); PG8_BAR; PG8_SCHED;
;             PG8_STAGE(PG8_SB(1, 1), b3 + hstep, voffB);
;             PG8_WAIT_V(6); PG8_BAR; PG8_MMA(1, 1, At, B1); PG8_BAR;
	s_waitcnt lgkmcnt(0)
	s_setprio 1
	v_mfma_f32_16x16x32_bf16 v[124:127], v[144:147], v[172:175], v[124:127]
	v_mfma_f32_16x16x32_bf16 v[120:123], v[164:167], v[172:175], v[120:123]
	v_mfma_f32_16x16x32_bf16 v[108:111], v[144:147], v[180:183], v[108:111]
	v_mfma_f32_16x16x32_bf16 v[104:107], v[164:167], v[180:183], v[104:107]
	v_mfma_f32_16x16x32_bf16 v[92:95], v[144:147], v[206:209], v[92:95]
	v_mfma_f32_16x16x32_bf16 v[88:91], v[164:167], v[206:209], v[88:91]
	v_mfma_f32_16x16x32_bf16 v[76:79], v[144:147], v[214:217], v[76:79]
	v_mfma_f32_16x16x32_bf16 v[72:75], v[164:167], v[214:217], v[72:75]
	v_mfma_f32_16x16x32_bf16 v[124:127], v[160:163], v[176:179], v[124:127]
	v_mfma_f32_16x16x32_bf16 v[120:123], v[168:171], v[176:179], v[120:123]
	v_mfma_f32_16x16x32_bf16 v[108:111], v[160:163], v[188:191], v[108:111]
	v_mfma_f32_16x16x32_bf16 v[104:107], v[168:171], v[188:191], v[104:107]
	v_mfma_f32_16x16x32_bf16 v[92:95], v[160:163], v[210:213], v[92:95]
	v_mfma_f32_16x16x32_bf16 v[88:91], v[168:171], v[210:213], v[88:91]
	v_mfma_f32_16x16x32_bf16 v[76:79], v[160:163], v[218:221], v[76:79]
	v_mfma_f32_16x16x32_bf16 v[72:75], v[168:171], v[218:221], v[72:75]
	s_setprio 0
	s_barrier
	s_add_i32 s5, 0, 0x1c000
	s_add_i32 s0, s4, s51
	v_add_u32_e32 v159, s5, v154
	s_add_i32 m0, s0, 0xffffff80
	ds_read_b128 v[222:225], v159
	ds_read_b128 v[226:229], v159 offset:1024
	ds_read_b128 v[230:233], v159 offset:2048
	global_load_lds_dwordx4 v130, s[40:41] offset:128
	s_add_i32 m0, s0, 0x1f80
	ds_read_b128 v[234:237], v159 offset:3072
	global_load_lds_dwordx4 v134, s[40:41] offset:128
	s_barrier
	s_waitcnt lgkmcnt(0)
	s_setprio 1
	v_mfma_f32_16x16x32_bf16 v[116:119], v[222:225], v[172:175], v[116:119]
	v_mfma_f32_16x16x32_bf16 v[112:115], v[230:233], v[172:175], v[112:115]
	v_mfma_f32_16x16x32_bf16 v[100:103], v[222:225], v[180:183], v[100:103]
	v_mfma_f32_16x16x32_bf16 v[96:99], v[230:233], v[180:183], v[96:99]
	v_mfma_f32_16x16x32_bf16 v[84:87], v[222:225], v[206:209], v[84:87]
	v_mfma_f32_16x16x32_bf16 v[80:83], v[230:233], v[206:209], v[80:83]
	v_mfma_f32_16x16x32_bf16 v[68:71], v[222:225], v[214:217], v[68:71]
	v_mfma_f32_16x16x32_bf16 v[64:67], v[230:233], v[214:217], v[64:67]
	v_mfma_f32_16x16x32_bf16 v[116:119], v[226:229], v[176:179], v[116:119]
	v_mfma_f32_16x16x32_bf16 v[112:115], v[234:237], v[176:179], v[112:115]
	v_mfma_f32_16x16x32_bf16 v[100:103], v[226:229], v[188:191], v[100:103]
	v_mfma_f32_16x16x32_bf16 v[96:99], v[234:237], v[188:191], v[96:99]
	v_mfma_f32_16x16x32_bf16 v[84:87], v[226:229], v[210:213], v[84:87]
	v_mfma_f32_16x16x32_bf16 v[80:83], v[234:237], v[210:213], v[80:83]
	v_mfma_f32_16x16x32_bf16 v[68:71], v[226:229], v[218:221], v[68:71]
	v_mfma_f32_16x16x32_bf16 v[64:67], v[234:237], v[218:221], v[64:67]
	s_setprio 0
	s_add_i32 m0, s59, 0xffffff80
	s_barrier
	ds_read_b128 v[172:175], v156 offset:49152
	ds_read_b128 v[176:179], v156 offset:50176
	ds_read_b128 v[180:183], v156 offset:51200
	ds_read_b128 v[188:191], v156 offset:52224
	ds_read_b128 v[206:209], v156 offset:53248
	ds_read_b128 v[210:213], v156 offset:54272
	ds_read_b128 v[214:217], v156 offset:55296
	global_load_lds_dwordx4 v128, s[42:43] offset:128
	s_add_i32 m0, s60, 0xffffff80
	ds_read_b128 v[218:221], v156 offset:56320
	global_load_lds_dwordx4 v132, s[42:43] offset:128
	s_barrier
	s_waitcnt lgkmcnt(0)
	s_setprio 1
	v_mfma_f32_16x16x32_bf16 v[60:63], v[144:147], v[172:175], v[60:63]
	v_mfma_f32_16x16x32_bf16 v[56:59], v[164:167], v[172:175], v[56:59]
	v_mfma_f32_16x16x32_bf16 v[44:47], v[144:147], v[180:183], v[44:47]
	v_mfma_f32_16x16x32_bf16 v[40:43], v[164:167], v[180:183], v[40:43]
	v_mfma_f32_16x16x32_bf16 v[28:31], v[144:147], v[206:209], v[28:31]
	v_mfma_f32_16x16x32_bf16 v[24:27], v[164:167], v[206:209], v[24:27]
	v_mfma_f32_16x16x32_bf16 v[12:15], v[144:147], v[214:217], v[12:15]
	v_mfma_f32_16x16x32_bf16 v[8:11], v[164:167], v[214:217], v[8:11]
	v_mfma_f32_16x16x32_bf16 v[60:63], v[160:163], v[176:179], v[60:63]
	v_mfma_f32_16x16x32_bf16 v[56:59], v[168:171], v[176:179], v[56:59]
	v_mfma_f32_16x16x32_bf16 v[44:47], v[160:163], v[188:191], v[44:47]
	v_mfma_f32_16x16x32_bf16 v[40:43], v[168:171], v[188:191], v[40:43]
	v_mfma_f32_16x16x32_bf16 v[28:31], v[160:163], v[210:213], v[28:31]
	v_mfma_f32_16x16x32_bf16 v[24:27], v[168:171], v[210:213], v[24:27]
	v_mfma_f32_16x16x32_bf16 v[12:15], v[160:163], v[218:221], v[12:15]
	v_mfma_f32_16x16x32_bf16 v[8:11], v[168:171], v[218:221], v[8:11]
	s_setprio 0
	s_barrier
	s_add_u32 s0, s40, 0x160080
	s_addc_u32 s1, s41, 0
	s_add_i32 s4, s5, s51
	s_mov_b32 m0, s4
	s_nop 0
	global_load_lds_dwordx4 v130, s[0:1]
	s_add_i32 m0, s4, 0x2000
	s_nop 0
	global_load_lds_dwordx4 v134, s[0:1]
	s_waitcnt vmcnt(6)
	s_barrier
	s_setprio 1
	v_mfma_f32_16x16x32_bf16 v[52:55], v[222:225], v[172:175], v[52:55]
	v_mfma_f32_16x16x32_bf16 v[48:51], v[230:233], v[172:175], v[48:51]
	v_mfma_f32_16x16x32_bf16 v[36:39], v[222:225], v[180:183], v[36:39]
	v_mfma_f32_16x16x32_bf16 v[32:35], v[230:233], v[180:183], v[32:35]
	v_mfma_f32_16x16x32_bf16 v[20:23], v[222:225], v[206:209], v[20:23]
	v_mfma_f32_16x16x32_bf16 v[16:19], v[230:233], v[206:209], v[16:19]
	v_mfma_f32_16x16x32_bf16 v[4:7], v[222:225], v[214:217], v[4:7]
	v_mfma_f32_16x16x32_bf16 v[0:3], v[230:233], v[214:217], v[0:3]
	v_mfma_f32_16x16x32_bf16 v[52:55], v[226:229], v[176:179], v[52:55]
	v_mfma_f32_16x16x32_bf16 v[48:51], v[234:237], v[176:179], v[48:51]
	v_mfma_f32_16x16x32_bf16 v[36:39], v[226:229], v[188:191], v[36:39]
	v_mfma_f32_16x16x32_bf16 v[32:35], v[234:237], v[188:191], v[32:35]
	v_mfma_f32_16x16x32_bf16 v[20:23], v[226:229], v[210:213], v[20:23]
	v_mfma_f32_16x16x32_bf16 v[16:19], v[234:237], v[210:213], v[16:19]
	v_mfma_f32_16x16x32_bf16 v[4:7], v[226:229], v[218:221], v[4:7]
	v_mfma_f32_16x16x32_bf16 v[0:3], v[234:237], v[218:221], v[0:3]
	s_setprio 0
	s_add_i32 s68, s68, 2
	s_add_u32 s38, s38, 0x100
	s_addc_u32 s39, s39, 0
	s_add_u32 s35, s35, 0x100
	s_addc_u32 s67, s67, 0
	s_cmpk_gt_u32 s68, 0x55
	s_barrier
	s_cbranch_scc0 .LBB0_1746

;     DI size_t aoff(const Unit& u, size_t tstep) const { return (size_t)u.pm * tstep; }
;     DI size_t boff(const Unit& u, size_t tstep) const { return (size_t)u.pn * tstep; }
;     DI bool next(int i, Unit& u) const { const long L = (long)i * G + c; if (L >= np) return false; u.pm = pmv; u.pn = (int)(L % nN); u.ks = (int)(L / nN); return true; }
;     DI size_t aoff(const Unit& u, size_t) const { return (size_t)u.ks * kbytes; }
;     DI size_t boff(const Unit& u, size_t tstep) const { return (size_t)u.pn * tstep + (size_t)u.ks * kbytes; }
;     DI bool next(int i, Unit& u) const { Unit t; if (!S.next(i / 3, t)) return false; u.pm = t.pm; u.pn = t.pn; u.ks = i % 3; return true; }
;     DI size_t aoff(const Unit& u, size_t tstep) const { return (u.ks < 2 ? offU : offOA) + (size_t)u.pm * tstep; }
; #define PG8_WAIT_V(n) asm volatile("s_waitcnt vmcnt(" #n ")" ::: "memory")
; template <class Epi, class Sched>
; DI void gemm_phase(LAS unsigned char* lds, const Gemm g, const Sched& S, const Epi& E) {
;     ...
;     for (;;) {
;         const bool has_next = S.next(ui + 1, nxt);
;         const char* nA = has_next ? (const char*)g.A + S.aoff(nxt, tstep) : cA; const char* nB = has_next ? (const char*)g.Bt + S.boff(nxt, tstep) : cB;
;         for (int t = 0; t < nt; t += 2) {
;             if constexpr (Epi::HAS_MID) { if (t == E.mid_t(nt)) { int fr3 = fr, fq3 = fq; asm volatile("" : "+v"(fr3), "+v"(fq3)); E.mid(acc, cur, wr, wc, fr3, fq3); } }
;             const bool last = (t == nt - 2);
;             const char* a1 = cA + (size_t)(t + 1) * kstep;
;             const char* a2 = last ? nA : cA + (size_t)(t + 2) * kstep; const char* b2 = last ? nB : cB + (size_t)(t + 2) * kstep;
;             const char* a3 = a2 + kstep; const char* b3 = b2 + kstep;
;             PG8_LDB(B0, 0, 0); PG8_SCHED; PG8_LDA(At, 0, 0); PG8_STAGE(PG8_SA(1, 1), a1 + hstep, voffA);
;             PG8_WAIT_L(8); PG8_BAR; PG8_WAIT_L(0); PG8_MMA(0, 0, At, B0); PG8_BAR; PG8_SCHED;
;             PG8_LDB(B1, 0, 1); PG8_STAGE(PG8_SB(0, 0), b2, voffB);
;             PG8_BAR; PG8_WAIT_L(0); PG8_MMA(0, 1, At, B1); PG8_BAR;
;             PG8_LDA(At, 0, 1); PG8_STAGE(PG8_SA(0, 0), a2, voffA);
;             PG8_BAR; PG8_WAIT_L(0); PG8_MMA(1, 0, At, B0); PG8_BAR; PG8_SCHED;
;             PG8_STAGE(PG8_SB(0, 1), b2 + hstep, voffB);
;             PG8_WAIT_V(6); PG8_BAR; PG8_MMA(1, 1, At, B1); PG8_BAR;
.LBB0_1774:
	s_add_u32 s28, s38, s28
	s_addc_u32 s29, s39, s29
	s_and_b64 s[0:1], s[8:9], exec
	s_cselect_b32 s15, s29, s37
	s_cselect_b32 s17, s28, s36
	s_add_u32 s8, s36, 0x160080
	s_addc_u32 s9, s37, 0
	s_add_u32 s64, s30, 0x100
	v_mov_b32_e32 v0, 0
	s_addc_u32 s65, s31, 0
	s_mov_b32 s66, -2
	ds_read_b128 v[146:149], v141
	ds_read_b128 v[154:157], v141 offset:1024
	ds_read_b128 v[158:161], v141 offset:2048
	ds_read_b128 v[162:165], v141 offset:3072
	s_add_u32 s0, s8, 0xffea0080
	s_addc_u32 s1, s9, -1
	s_cmp_eq_u32 s66, 4
	s_cselect_b32 s37, s15, s1
	s_cselect_b32 s36, s17, s0
	s_cselect_b32 s31, s19, s65
	s_cselect_b32 s30, s18, s64
	s_mov_b32 m0, s56
	ds_read_b128 v[166:169], v142
	ds_read_b128 v[170:173], v142 offset:1024
	ds_read_b128 v[174:177], v142 offset:2048
	ds_read_b128 v[178:181], v142 offset:3072
	ds_read_b128 v[188:191], v142 offset:4096
	ds_read_b128 v[206:209], v142 offset:5120
	ds_read_b128 v[210:213], v142 offset:6144
	global_load_lds_dwordx4 v132, s[8:9]
	s_mov_b32 m0, s57
	ds_read_b128 v[214:217], v142 offset:7168
	global_load_lds_dwordx4 v134, s[8:9]
	s_waitcnt lgkmcnt(8)
	s_barrier
	s_waitcnt lgkmcnt(0)
	s_setprio 1
	v_mfma_f32_16x16x32_bf16 v[124:127], v[146:149], v[166:169], 0
	v_mfma_f32_16x16x32_bf16 v[120:123], v[158:161], v[166:169], 0
	v_mfma_f32_16x16x32_bf16 v[116:119], v[146:149], v[174:177], 0
	v_mfma_f32_16x16x32_bf16 v[112:115], v[158:161], v[174:177], 0
	v_mfma_f32_16x16x32_bf16 v[104:107], v[146:149], v[188:191], 0
	v_mfma_f32_16x16x32_bf16 v[96:99], v[158:161], v[188:191], 0
	v_mfma_f32_16x16x32_bf16 v[88:91], v[146:149], v[210:213], 0
	v_mfma_f32_16x16x32_bf16 v[80:83], v[158:161], v[210:213], 0
	v_mfma_f32_16x16x32_bf16 v[124:127], v[154:157], v[170:173], v[124:127]
	v_mfma_f32_16x16x32_bf16 v[120:123], v[162:165], v[170:173], v[120:123]
	v_mfma_f32_16x16x32_bf16 v[116:119], v[154:157], v[178:181], v[116:119]
	v_mfma_f32_16x16x32_bf16 v[112:115], v[162:165], v[178:181], v[112:115]
	v_mfma_f32_16x16x32_bf16 v[104:107], v[154:157], v[206:209], v[104:107]
	v_mfma_f32_16x16x32_bf16 v[96:99], v[162:165], v[206:209], v[96:99]
	v_mfma_f32_16x16x32_bf16 v[88:91], v[154:157], v[214:217], v[88:91]
	v_mfma_f32_16x16x32_bf16 v[80:83], v[162:165], v[214:217], v[80:83]
	s_setprio 0
	s_barrier
	s_mov_b32 m0, s58
	ds_read_b128 v[218:221], v143
	ds_read_b128 v[222:225], v143 offset:1024
	ds_read_b128 v[226:229], v143 offset:2048
	global_load_lds_dwordx4 v130, s[30:31]
	s_mov_b32 m0, s59
	ds_read_b128 v[230:233], v143 offset:3072
	global_load_lds_dwordx4 v128, s[30:31]
	s_barrier
	s_waitcnt lgkmcnt(0)
	s_setprio 1
	v_mfma_f32_16x16x32_bf16 v[108:111], v[218:221], v[166:169], 0
	v_mfma_f32_16x16x32_bf16 v[100:103], v[226:229], v[166:169], 0
	v_mfma_f32_16x16x32_bf16 v[92:95], v[218:221], v[174:177], 0
	v_mfma_f32_16x16x32_bf16 v[84:87], v[226:229], v[174:177], 0
	v_mfma_f32_16x16x32_bf16 v[76:79], v[218:221], v[188:191], 0
	v_mfma_f32_16x16x32_bf16 v[72:75], v[226:229], v[188:191], 0
	v_mfma_f32_16x16x32_bf16 v[68:71], v[218:221], v[210:213], 0
	v_mfma_f32_16x16x32_bf16 v[64:67], v[226:229], v[210:213], 0
	v_mfma_f32_16x16x32_bf16 v[108:111], v[222:225], v[170:173], v[108:111]
	v_mfma_f32_16x16x32_bf16 v[100:103], v[230:233], v[170:173], v[100:103]
	v_mfma_f32_16x16x32_bf16 v[92:95], v[222:225], v[178:181], v[92:95]
	v_mfma_f32_16x16x32_bf16 v[84:87], v[230:233], v[178:181], v[84:87]
	v_mfma_f32_16x16x32_bf16 v[76:79], v[222:225], v[206:209], v[76:79]
	v_mfma_f32_16x16x32_bf16 v[72:75], v[230:233], v[206:209], v[72:75]
	v_mfma_f32_16x16x32_bf16 v[68:71], v[222:225], v[214:217], v[68:71]
	v_mfma_f32_16x16x32_bf16 v[64:67], v[230:233], v[214:217], v[64:67]
	s_setprio 0
	s_mov_b32 m0, s40
	s_barrier
	ds_read_b128 v[166:169], v142 offset:16384
	ds_read_b128 v[170:173], v142 offset:17408
	ds_read_b128 v[174:177], v142 offset:18432
	ds_read_b128 v[178:181], v142 offset:19456
	ds_read_b128 v[188:191], v142 offset:20480
	ds_read_b128 v[206:209], v142 offset:21504
	ds_read_b128 v[210:213], v142 offset:22528
	global_load_lds_dwordx4 v130, s[36:37]
	s_mov_b32 m0, s41
	ds_read_b128 v[214:217], v142 offset:23552
	global_load_lds_dwordx4 v128, s[36:37]
	s_barrier
	s_waitcnt lgkmcnt(0)
	s_setprio 1
	v_mfma_f32_16x16x32_bf16 v[60:63], v[146:149], v[166:169], 0
	v_mfma_f32_16x16x32_bf16 v[56:59], v[158:161], v[166:169], 0
	v_mfma_f32_16x16x32_bf16 v[52:55], v[146:149], v[174:177], 0
	v_mfma_f32_16x16x32_bf16 v[48:51], v[158:161], v[174:177], 0
	v_mfma_f32_16x16x32_bf16 v[40:43], v[146:149], v[188:191], 0
	v_mfma_f32_16x16x32_bf16 v[32:35], v[158:161], v[188:191], 0
	v_mfma_f32_16x16x32_bf16 v[24:27], v[146:149], v[210:213], 0
	v_mfma_f32_16x16x32_bf16 v[16:19], v[158:161], v[210:213], 0
	v_mfma_f32_16x16x32_bf16 v[60:63], v[154:157], v[170:173], v[60:63]
	v_mfma_f32_16x16x32_bf16 v[56:59], v[162:165], v[170:173], v[56:59]
	v_mfma_f32_16x16x32_bf16 v[52:55], v[154:157], v[178:181], v[52:55]
	v_mfma_f32_16x16x32_bf16 v[48:51], v[162:165], v[178:181], v[48:51]
	v_mfma_f32_16x16x32_bf16 v[40:43], v[154:157], v[206:209], v[40:43]
	v_mfma_f32_16x16x32_bf16 v[32:35], v[162:165], v[206:209], v[32:35]
	v_mfma_f32_16x16x32_bf16 v[24:27], v[154:157], v[214:217], v[24:27]
	v_mfma_f32_16x16x32_bf16 v[16:19], v[162:165], v[214:217], v[16:19]
	s_setprio 0
	s_barrier
	s_add_u32 s0, s30, 0x160000
	s_addc_u32 s1, s31, 0
	s_mov_b32 m0, s60
	s_nop 0
	global_load_lds_dwordx4 v130, s[0:1]
	s_mov_b32 m0, s61
	s_nop 0
	global_load_lds_dwordx4 v128, s[0:1]
	s_waitcnt vmcnt(6)
	s_barrier
; #define PG8_STAGE(bufoff, gbase, voff) do { _Pragma("unroll") for (int _i = 0; _i < 2; ++_i) \
;         __builtin_amdgcn_global_load_lds((const unsigned*)((const char*)(gbase) + (voff)[_i]), (LAS unsigned*)(lds + (bufoff) + ldsw + _i * 8192), 16, 0, 0); } while (0)
; #define PG8_LDA(dst, b, h) do { _Pragma("unroll") for (int m = 0; m < 4; ++m) _Pragma("unroll") for (int k = 0; k < 2; ++k) dst[m][k] = *(const LAS bf16x8*)(lds + PG8_SA(b, h) + aoff + m * 2048 + k * 1024); } while (0)
; #define PG8_LDB(dst, b, h) do { _Pragma("unroll") for (int n = 0; n < 2; ++n) _Pragma("unroll") for (int k = 0; k < 2; ++k) dst[n][k] = *(const LAS bf16x8*)(lds + PG8_SB(b, h) + boff + n * 2048 + k * 1024); } while (0)
; #define PG8_MMA(ai, bj, At, Bt) do { __builtin_amdgcn_s_setprio(1); _Pragma("unroll") for (int m = 0; m < 4; ++m) _Pragma("unroll") for (int n = 0; n < 2; ++n) _Pragma("unroll") for (int k = 0; k < 2; ++k) \
;         acc[ai][bj][m][n] = __builtin_amdgcn_mfma_f32_16x16x32_bf16(Bt[n][k], At[m][k], acc[ai][bj][m][n], 0, 0, 0); __builtin_amdgcn_s_setprio(0); } while (0)
; #define PG8_WAIT_V(n) asm volatile("s_waitcnt vmcnt(" #n ")" ::: "memory")
; #define PG8_WAIT_L(n) asm volatile("s_waitcnt lgkmcnt(" #n ")" ::: "memory")
; #define PG8_BAR __builtin_amdgcn_s_barrier()
; #define PG8_SCHED __builtin_amdgcn_sched_barrier(0)
; template <class Epi, class Sched>
; DI void gemm_phase(LAS unsigned char* lds, const Gemm g, const Sched& S, const Epi& E) {
;     ...
;             PG8_STAGE(PG8_SB(0, 1), b2 + hstep, voffB);
;             PG8_WAIT_V(6); PG8_BAR; PG8_MMA(1, 1, At, B1); PG8_BAR;
;             PG8_LDB(B0, 1, 0); PG8_SCHED; PG8_LDA(At, 1, 0); PG8_STAGE(PG8_SA(0, 1), a2 + hstep, voffA);
;             PG8_WAIT_L(8); PG8_BAR; PG8_WAIT_L(0); PG8_MMA(0, 0, At, B0); PG8_BAR; PG8_SCHED;
;             PG8_LDB(B1, 1, 1); PG8_STAGE(PG8_SB(1, 0), b3, voffB);
;             PG8_BAR; PG8_WAIT_L(0); PG8_MMA(0, 1, At, B1); PG8_BAR;
;             PG8_LDA(At, 1, 1); PG8_STAGE(PG8_SA(1, 0), a3, voffA);
;             PG8_BAR; PG8_WAIT_L(0); PG8_MMA(1, 0, At, B0); PG8_BAR; PG8_SCHED;
	s_setprio 1
	v_mfma_f32_16x16x32_bf16 v[44:47], v[218:221], v[166:169], 0
	v_mfma_f32_16x16x32_bf16 v[36:39], v[226:229], v[166:169], 0
	v_mfma_f32_16x16x32_bf16 v[28:31], v[218:221], v[174:177], 0
	v_mfma_f32_16x16x32_bf16 v[20:23], v[226:229], v[174:177], 0
	v_mfma_f32_16x16x32_bf16 v[12:15], v[218:221], v[188:191], 0
	v_mfma_f32_16x16x32_bf16 v[8:11], v[226:229], v[188:191], 0
	v_mfma_f32_16x16x32_bf16 v[4:7], v[218:221], v[210:213], 0
	v_mfma_f32_16x16x32_bf16 v[0:3], v[226:229], v[210:213], 0
	v_mfma_f32_16x16x32_bf16 v[44:47], v[222:225], v[170:173], v[44:47]
	v_mfma_f32_16x16x32_bf16 v[36:39], v[230:233], v[170:173], v[36:39]
	v_mfma_f32_16x16x32_bf16 v[28:31], v[222:225], v[178:181], v[28:31]
	v_mfma_f32_16x16x32_bf16 v[20:23], v[230:233], v[178:181], v[20:23]
	v_mfma_f32_16x16x32_bf16 v[12:15], v[222:225], v[206:209], v[12:15]
	v_mfma_f32_16x16x32_bf16 v[8:11], v[230:233], v[206:209], v[8:11]
	v_mfma_f32_16x16x32_bf16 v[4:7], v[222:225], v[214:217], v[4:7]
	v_mfma_f32_16x16x32_bf16 v[0:3], v[230:233], v[214:217], v[0:3]
	s_setprio 0
	s_barrier
	ds_read_b128 v[146:149], v144
	ds_read_b128 v[154:157], v144 offset:1024
	ds_read_b128 v[158:161], v144 offset:2048
	ds_read_b128 v[162:165], v144 offset:3072
	s_add_u32 s0, s36, 0x160000
	s_addc_u32 s1, s37, 0
	s_mov_b32 m0, s42
	ds_read_b128 v[166:169], v142 offset:32768
	ds_read_b128 v[170:173], v142 offset:33792
	ds_read_b128 v[174:177], v142 offset:34816
	ds_read_b128 v[178:181], v142 offset:35840
	ds_read_b128 v[188:191], v142 offset:36864
	ds_read_b128 v[206:209], v142 offset:37888
	ds_read_b128 v[210:213], v142 offset:38912
	global_load_lds_dwordx4 v130, s[0:1]
	s_mov_b32 m0, s43
	ds_read_b128 v[214:217], v142 offset:39936
	global_load_lds_dwordx4 v128, s[0:1]
	s_waitcnt lgkmcnt(8)
	s_barrier
	s_waitcnt lgkmcnt(0)
	s_setprio 1
	v_mfma_f32_16x16x32_bf16 v[124:127], v[146:149], v[166:169], v[124:127]
	v_mfma_f32_16x16x32_bf16 v[120:123], v[158:161], v[166:169], v[120:123]
	v_mfma_f32_16x16x32_bf16 v[116:119], v[146:149], v[174:177], v[116:119]
	v_mfma_f32_16x16x32_bf16 v[112:115], v[158:161], v[174:177], v[112:115]
	v_mfma_f32_16x16x32_bf16 v[104:107], v[146:149], v[188:191], v[104:107]
	v_mfma_f32_16x16x32_bf16 v[96:99], v[158:161], v[188:191], v[96:99]
	v_mfma_f32_16x16x32_bf16 v[88:91], v[146:149], v[210:213], v[88:91]
	v_mfma_f32_16x16x32_bf16 v[80:83], v[158:161], v[210:213], v[80:83]
	v_mfma_f32_16x16x32_bf16 v[124:127], v[154:157], v[170:173], v[124:127]
	v_mfma_f32_16x16x32_bf16 v[120:123], v[162:165], v[170:173], v[120:123]
	v_mfma_f32_16x16x32_bf16 v[116:119], v[154:157], v[178:181], v[116:119]
	v_mfma_f32_16x16x32_bf16 v[112:115], v[162:165], v[178:181], v[112:115]
	v_mfma_f32_16x16x32_bf16 v[104:107], v[154:157], v[206:209], v[104:107]
	v_mfma_f32_16x16x32_bf16 v[96:99], v[162:165], v[206:209], v[96:99]
	v_mfma_f32_16x16x32_bf16 v[88:91], v[154:157], v[214:217], v[88:91]
	v_mfma_f32_16x16x32_bf16 v[80:83], v[162:165], v[214:217], v[80:83]
	s_setprio 0
	s_barrier
	s_add_i32 s4, 0, 0x1c000
	s_add_i32 s0, s62, s35
	v_add_u32_e32 v145, s4, v140
	s_add_i32 m0, s0, 0xffffff80
	ds_read_b128 v[218:221], v145
	ds_read_b128 v[222:225], v145 offset:1024
	ds_read_b128 v[226:229], v145 offset:2048
	global_load_lds_dwordx4 v130, s[30:31] offset:128
	s_add_i32 m0, s0, 0x1f80
	ds_read_b128 v[230:233], v145 offset:3072
	global_load_lds_dwordx4 v128, s[30:31] offset:128
	s_barrier
	s_waitcnt lgkmcnt(0)
	s_setprio 1
	v_mfma_f32_16x16x32_bf16 v[108:111], v[218:221], v[166:169], v[108:111]
	v_mfma_f32_16x16x32_bf16 v[100:103], v[226:229], v[166:169], v[100:103]
	v_mfma_f32_16x16x32_bf16 v[92:95], v[218:221], v[174:177], v[92:95]
	v_mfma_f32_16x16x32_bf16 v[84:87], v[226:229], v[174:177], v[84:87]
	v_mfma_f32_16x16x32_bf16 v[76:79], v[218:221], v[188:191], v[76:79]
	v_mfma_f32_16x16x32_bf16 v[72:75], v[226:229], v[188:191], v[72:75]
	v_mfma_f32_16x16x32_bf16 v[68:71], v[218:221], v[210:213], v[68:71]
	v_mfma_f32_16x16x32_bf16 v[64:67], v[226:229], v[210:213], v[64:67]
	v_mfma_f32_16x16x32_bf16 v[108:111], v[222:225], v[170:173], v[108:111]
	v_mfma_f32_16x16x32_bf16 v[100:103], v[230:233], v[170:173], v[100:103]
	v_mfma_f32_16x16x32_bf16 v[92:95], v[222:225], v[178:181], v[92:95]
	v_mfma_f32_16x16x32_bf16 v[84:87], v[230:233], v[178:181], v[84:87]
	v_mfma_f32_16x16x32_bf16 v[76:79], v[222:225], v[206:209], v[76:79]
	v_mfma_f32_16x16x32_bf16 v[72:75], v[230:233], v[206:209], v[72:75]
	v_mfma_f32_16x16x32_bf16 v[68:71], v[222:225], v[214:217], v[68:71]
	v_mfma_f32_16x16x32_bf16 v[64:67], v[230:233], v[214:217], v[64:67]
	s_setprio 0
	s_add_i32 m0, s54, 0xffffff80
	s_barrier
	ds_read_b128 v[166:169], v142 offset:49152
	ds_read_b128 v[170:173], v142 offset:50176
	ds_read_b128 v[174:177], v142 offset:51200
	ds_read_b128 v[178:181], v142 offset:52224
	ds_read_b128 v[188:191], v142 offset:53248
	ds_read_b128 v[206:209], v142 offset:54272
	ds_read_b128 v[210:213], v142 offset:55296
	global_load_lds_dwordx4 v130, s[36:37] offset:128
	s_add_i32 m0, s55, 0xffffff80
	ds_read_b128 v[214:217], v142 offset:56320
	global_load_lds_dwordx4 v128, s[36:37] offset:128
	s_barrier
; #define PG8_STAGE(bufoff, gbase, voff) do { _Pragma("unroll") for (int _i = 0; _i < 2; ++_i) \
;         __builtin_amdgcn_global_load_lds((const unsigned*)((const char*)(gbase) + (voff)[_i]), (LAS unsigned*)(lds + (bufoff) + ldsw + _i * 8192), 16, 0, 0); } while (0)
; #define PG8_LDA(dst, b, h) do { _Pragma("unroll") for (int m = 0; m < 4; ++m) _Pragma("unroll") for (int k = 0; k < 2; ++k) dst[m][k] = *(const LAS bf16x8*)(lds + PG8_SA(b, h) + aoff + m * 2048 + k * 1024); } while (0)
; #define PG8_LDB(dst, b, h) do { _Pragma("unroll") for (int n = 0; n < 2; ++n) _Pragma("unroll") for (int k = 0; k < 2; ++k) dst[n][k] = *(const LAS bf16x8*)(lds + PG8_SB(b, h) + boff + n * 2048 + k * 1024); } while (0)
; #define PG8_MMA(ai, bj, At, Bt) do { __builtin_amdgcn_s_setprio(1); _Pragma("unroll") for (int m = 0; m < 4; ++m) _Pragma("unroll") for (int n = 0; n < 2; ++n) _Pragma("unroll") for (int k = 0; k < 2; ++k) \
;         acc[ai][bj][m][n] = __builtin_amdgcn_mfma_f32_16x16x32_bf16(Bt[n][k], At[m][k], acc[ai][bj][m][n], 0, 0, 0); __builtin_amdgcn_s_setprio(0); } while (0)
; #define PG8_WAIT_V(n) asm volatile("s_waitcnt vmcnt(" #n ")" ::: "memory")
; #define PG8_WAIT_L(n) asm volatile("s_waitcnt lgkmcnt(" #n ")" ::: "memory")
; #define PG8_BAR __builtin_amdgcn_s_barrier()
; #define PG8_SCHED __builtin_amdgcn_sched_barrier(0)
; template <class Epi, class Sched>
; DI void gemm_phase(LAS unsigned char* lds, const Gemm g, const Sched& S, const Epi& E) {
;     ...
;             PG8_LDB(B0, 0, 0); PG8_SCHED; PG8_LDA(At, 0, 0); PG8_STAGE(PG8_SA(1, 1), a1 + hstep, voffA);
;             PG8_WAIT_L(8); PG8_BAR; PG8_WAIT_L(0); PG8_MMA(0, 0, At, B0); PG8_BAR; PG8_SCHED;
;             PG8_LDB(B1, 0, 1); PG8_STAGE(PG8_SB(0, 0), b2, voffB);
;             PG8_BAR; PG8_WAIT_L(0); PG8_MMA(0, 1, At, B1); PG8_BAR;
;     ...
;             PG8_BAR; PG8_WAIT_L(0); PG8_MMA(1, 0, At, B0); PG8_BAR; PG8_SCHED;
;             PG8_STAGE(PG8_SB(1, 1), b3 + hstep, voffB);
;             PG8_WAIT_V(6); PG8_BAR; PG8_MMA(1, 1, At, B1); PG8_BAR;
	s_waitcnt lgkmcnt(0)
	s_setprio 1
	v_mfma_f32_16x16x32_bf16 v[60:63], v[146:149], v[166:169], v[60:63]
	v_mfma_f32_16x16x32_bf16 v[56:59], v[158:161], v[166:169], v[56:59]
	v_mfma_f32_16x16x32_bf16 v[52:55], v[146:149], v[174:177], v[52:55]
	v_mfma_f32_16x16x32_bf16 v[48:51], v[158:161], v[174:177], v[48:51]
	v_mfma_f32_16x16x32_bf16 v[40:43], v[146:149], v[188:191], v[40:43]
	v_mfma_f32_16x16x32_bf16 v[32:35], v[158:161], v[188:191], v[32:35]
	v_mfma_f32_16x16x32_bf16 v[24:27], v[146:149], v[210:213], v[24:27]
	v_mfma_f32_16x16x32_bf16 v[16:19], v[158:161], v[210:213], v[16:19]
	v_mfma_f32_16x16x32_bf16 v[60:63], v[154:157], v[170:173], v[60:63]
	v_mfma_f32_16x16x32_bf16 v[56:59], v[162:165], v[170:173], v[56:59]
	v_mfma_f32_16x16x32_bf16 v[52:55], v[154:157], v[178:181], v[52:55]
	v_mfma_f32_16x16x32_bf16 v[48:51], v[162:165], v[178:181], v[48:51]
	v_mfma_f32_16x16x32_bf16 v[40:43], v[154:157], v[206:209], v[40:43]
	v_mfma_f32_16x16x32_bf16 v[32:35], v[162:165], v[206:209], v[32:35]
	v_mfma_f32_16x16x32_bf16 v[24:27], v[154:157], v[214:217], v[24:27]
	v_mfma_f32_16x16x32_bf16 v[16:19], v[162:165], v[214:217], v[16:19]
	s_setprio 0
	s_barrier
	s_add_u32 s0, s30, 0x160080
	s_addc_u32 s1, s31, 0
	s_add_i32 s4, s4, s35
	s_mov_b32 m0, s4
	s_nop 0
	global_load_lds_dwordx4 v130, s[0:1]
	s_add_i32 m0, s4, 0x2000
	s_nop 0
	global_load_lds_dwordx4 v128, s[0:1]
	s_waitcnt vmcnt(6)
	s_barrier
	s_setprio 1
	v_mfma_f32_16x16x32_bf16 v[44:47], v[218:221], v[166:169], v[44:47]
	v_mfma_f32_16x16x32_bf16 v[36:39], v[226:229], v[166:169], v[36:39]
	v_mfma_f32_16x16x32_bf16 v[28:31], v[218:221], v[174:177], v[28:31]
	v_mfma_f32_16x16x32_bf16 v[20:23], v[226:229], v[174:177], v[20:23]
	v_mfma_f32_16x16x32_bf16 v[12:15], v[218:221], v[188:191], v[12:15]
	v_mfma_f32_16x16x32_bf16 v[8:11], v[226:229], v[188:191], v[8:11]
	v_mfma_f32_16x16x32_bf16 v[4:7], v[218:221], v[210:213], v[4:7]
	v_mfma_f32_16x16x32_bf16 v[0:3], v[226:229], v[210:213], v[0:3]
	v_mfma_f32_16x16x32_bf16 v[44:47], v[222:225], v[170:173], v[44:47]
	v_mfma_f32_16x16x32_bf16 v[36:39], v[230:233], v[170:173], v[36:39]
	v_mfma_f32_16x16x32_bf16 v[28:31], v[222:225], v[178:181], v[28:31]
	v_mfma_f32_16x16x32_bf16 v[20:23], v[230:233], v[178:181], v[20:23]
	v_mfma_f32_16x16x32_bf16 v[12:15], v[222:225], v[206:209], v[12:15]
	v_mfma_f32_16x16x32_bf16 v[8:11], v[230:233], v[206:209], v[8:11]
	v_mfma_f32_16x16x32_bf16 v[4:7], v[222:225], v[214:217], v[4:7]
	v_mfma_f32_16x16x32_bf16 v[0:3], v[230:233], v[214:217], v[0:3]
	s_setprio 0
	s_add_i32 s66, s66, 2
	s_add_u32 s8, s8, 0x100
	s_addc_u32 s9, s9, 0
	s_add_u32 s64, s64, 0x100
	s_addc_u32 s65, s65, 0
	s_cmp_gt_u32 s66, 5
	s_barrier
	s_cbranch_scc0 .LBB0_1775
	s_branch .Lpeel_done_1775
.LBB0_1775:
	ds_read_b128 v[146:149], v141
	ds_read_b128 v[154:157], v141 offset:1024
	ds_read_b128 v[158:161], v141 offset:2048
	ds_read_b128 v[162:165], v141 offset:3072
	s_add_u32 s0, s8, 0xffea0080
	s_addc_u32 s1, s9, -1
	s_cmp_eq_u32 s66, 4
	s_cselect_b32 s37, s15, s1
	s_cselect_b32 s36, s17, s0
	s_cselect_b32 s31, s19, s65
	s_cselect_b32 s30, s18, s64
	s_mov_b32 m0, s56
	ds_read_b128 v[166:169], v142
	ds_read_b128 v[170:173], v142 offset:1024
	ds_read_b128 v[174:177], v142 offset:2048
	ds_read_b128 v[178:181], v142 offset:3072
	ds_read_b128 v[188:191], v142 offset:4096
	ds_read_b128 v[206:209], v142 offset:5120
	ds_read_b128 v[210:213], v142 offset:6144
	global_load_lds_dwordx4 v132, s[8:9]
	s_mov_b32 m0, s57
	ds_read_b128 v[214:217], v142 offset:7168
	global_load_lds_dwordx4 v134, s[8:9]
	s_waitcnt lgkmcnt(8)
	s_barrier
	s_waitcnt lgkmcnt(0)
	s_setprio 1
	v_mfma_f32_16x16x32_bf16 v[124:127], v[146:149], v[166:169], v[124:127]
	v_mfma_f32_16x16x32_bf16 v[120:123], v[158:161], v[166:169], v[120:123]
	v_mfma_f32_16x16x32_bf16 v[116:119], v[146:149], v[174:177], v[116:119]
	v_mfma_f32_16x16x32_bf16 v[112:115], v[158:161], v[174:177], v[112:115]
	v_mfma_f32_16x16x32_bf16 v[104:107], v[146:149], v[188:191], v[104:107]
	v_mfma_f32_16x16x32_bf16 v[96:99], v[158:161], v[188:191], v[96:99]
	v_mfma_f32_16x16x32_bf16 v[88:91], v[146:149], v[210:213], v[88:91]
	v_mfma_f32_16x16x32_bf16 v[80:83], v[158:161], v[210:213], v[80:83]
	v_mfma_f32_16x16x32_bf16 v[124:127], v[154:157], v[170:173], v[124:127]
	v_mfma_f32_16x16x32_bf16 v[120:123], v[162:165], v[170:173], v[120:123]
	v_mfma_f32_16x16x32_bf16 v[116:119], v[154:157], v[178:181], v[116:119]
	v_mfma_f32_16x16x32_bf16 v[112:115], v[162:165], v[178:181], v[112:115]
	v_mfma_f32_16x16x32_bf16 v[104:107], v[154:157], v[206:209], v[104:107]
	v_mfma_f32_16x16x32_bf16 v[96:99], v[162:165], v[206:209], v[96:99]
	v_mfma_f32_16x16x32_bf16 v[88:91], v[154:157], v[214:217], v[88:91]
	v_mfma_f32_16x16x32_bf16 v[80:83], v[162:165], v[214:217], v[80:83]
	s_setprio 0
	s_barrier
	s_mov_b32 m0, s58
	ds_read_b128 v[218:221], v143
	ds_read_b128 v[222:225], v143 offset:1024
	ds_read_b128 v[226:229], v143 offset:2048
	global_load_lds_dwordx4 v130, s[30:31]
	s_mov_b32 m0, s59
	ds_read_b128 v[230:233], v143 offset:3072
	global_load_lds_dwordx4 v128, s[30:31]
	s_barrier
; #define PG8_STAGE(bufoff, gbase, voff) do { _Pragma("unroll") for (int _i = 0; _i < 2; ++_i) \
;         __builtin_amdgcn_global_load_lds((const unsigned*)((const char*)(gbase) + (voff)[_i]), (LAS unsigned*)(lds + (bufoff) + ldsw + _i * 8192), 16, 0, 0); } while (0)
; #define PG8_LDA(dst, b, h) do { _Pragma("unroll") for (int m = 0; m < 4; ++m) _Pragma("unroll") for (int k = 0; k < 2; ++k) dst[m][k] = *(const LAS bf16x8*)(lds + PG8_SA(b, h) + aoff + m * 2048 + k * 1024); } while (0)
; #define PG8_LDB(dst, b, h) do { _Pragma("unroll") for (int n = 0; n < 2; ++n) _Pragma("unroll") for (int k = 0; k < 2; ++k) dst[n][k] = *(const LAS bf16x8*)(lds + PG8_SB(b, h) + boff + n * 2048 + k * 1024); } while (0)
; #define PG8_MMA(ai, bj, At, Bt) do { __builtin_amdgcn_s_setprio(1); _Pragma("unroll") for (int m = 0; m < 4; ++m) _Pragma("unroll") for (int n = 0; n < 2; ++n) _Pragma("unroll") for (int k = 0; k < 2; ++k) \
;         acc[ai][bj][m][n] = __builtin_amdgcn_mfma_f32_16x16x32_bf16(Bt[n][k], At[m][k], acc[ai][bj][m][n], 0, 0, 0); __builtin_amdgcn_s_setprio(0); } while (0)
; #define PG8_WAIT_V(n) asm volatile("s_waitcnt vmcnt(" #n ")" ::: "memory")
; #define PG8_WAIT_L(n) asm volatile("s_waitcnt lgkmcnt(" #n ")" ::: "memory")
; #define PG8_BAR __builtin_amdgcn_s_barrier()
; #define PG8_SCHED __builtin_amdgcn_sched_barrier(0)
; template <class Epi, class Sched>
; DI void gemm_phase(LAS unsigned char* lds, const Gemm g, const Sched& S, const Epi& E) {
;     ...
;             PG8_BAR; PG8_WAIT_L(0); PG8_MMA(0, 1, At, B1); PG8_BAR;
;             PG8_LDA(At, 0, 1); PG8_STAGE(PG8_SA(0, 0), a2, voffA);
;             PG8_BAR; PG8_WAIT_L(0); PG8_MMA(1, 0, At, B0); PG8_BAR; PG8_SCHED;
;             PG8_STAGE(PG8_SB(0, 1), b2 + hstep, voffB);
;             PG8_WAIT_V(6); PG8_BAR; PG8_MMA(1, 1, At, B1); PG8_BAR;
;             PG8_LDB(B0, 1, 0); PG8_SCHED; PG8_LDA(At, 1, 0); PG8_STAGE(PG8_SA(0, 1), a2 + hstep, voffA);
;             PG8_WAIT_L(8); PG8_BAR; PG8_WAIT_L(0); PG8_MMA(0, 0, At, B0); PG8_BAR; PG8_SCHED;
;             PG8_LDB(B1, 1, 1); PG8_STAGE(PG8_SB(1, 0), b3, voffB);
	s_waitcnt lgkmcnt(0)
	s_setprio 1
	v_mfma_f32_16x16x32_bf16 v[108:111], v[218:221], v[166:169], v[108:111]
	v_mfma_f32_16x16x32_bf16 v[100:103], v[226:229], v[166:169], v[100:103]
	v_mfma_f32_16x16x32_bf16 v[92:95], v[218:221], v[174:177], v[92:95]
	v_mfma_f32_16x16x32_bf16 v[84:87], v[226:229], v[174:177], v[84:87]
	v_mfma_f32_16x16x32_bf16 v[76:79], v[218:221], v[188:191], v[76:79]
	v_mfma_f32_16x16x32_bf16 v[72:75], v[226:229], v[188:191], v[72:75]
	v_mfma_f32_16x16x32_bf16 v[68:71], v[218:221], v[210:213], v[68:71]
	v_mfma_f32_16x16x32_bf16 v[64:67], v[226:229], v[210:213], v[64:67]
	v_mfma_f32_16x16x32_bf16 v[108:111], v[222:225], v[170:173], v[108:111]
	v_mfma_f32_16x16x32_bf16 v[100:103], v[230:233], v[170:173], v[100:103]
	v_mfma_f32_16x16x32_bf16 v[92:95], v[222:225], v[178:181], v[92:95]
	v_mfma_f32_16x16x32_bf16 v[84:87], v[230:233], v[178:181], v[84:87]
	v_mfma_f32_16x16x32_bf16 v[76:79], v[222:225], v[206:209], v[76:79]
	v_mfma_f32_16x16x32_bf16 v[72:75], v[230:233], v[206:209], v[72:75]
	v_mfma_f32_16x16x32_bf16 v[68:71], v[222:225], v[214:217], v[68:71]
	v_mfma_f32_16x16x32_bf16 v[64:67], v[230:233], v[214:217], v[64:67]
	s_setprio 0
	s_mov_b32 m0, s40
	s_barrier
	ds_read_b128 v[166:169], v142 offset:16384
	ds_read_b128 v[170:173], v142 offset:17408
	ds_read_b128 v[174:177], v142 offset:18432
	ds_read_b128 v[178:181], v142 offset:19456
	ds_read_b128 v[188:191], v142 offset:20480
	ds_read_b128 v[206:209], v142 offset:21504
	ds_read_b128 v[210:213], v142 offset:22528
	global_load_lds_dwordx4 v130, s[36:37]
	s_mov_b32 m0, s41
	ds_read_b128 v[214:217], v142 offset:23552
	global_load_lds_dwordx4 v128, s[36:37]
	s_barrier
	s_waitcnt lgkmcnt(0)
	s_setprio 1
	v_mfma_f32_16x16x32_bf16 v[60:63], v[146:149], v[166:169], v[60:63]
	v_mfma_f32_16x16x32_bf16 v[56:59], v[158:161], v[166:169], v[56:59]
	v_mfma_f32_16x16x32_bf16 v[52:55], v[146:149], v[174:177], v[52:55]
	v_mfma_f32_16x16x32_bf16 v[48:51], v[158:161], v[174:177], v[48:51]
	v_mfma_f32_16x16x32_bf16 v[40:43], v[146:149], v[188:191], v[40:43]
	v_mfma_f32_16x16x32_bf16 v[32:35], v[158:161], v[188:191], v[32:35]
	v_mfma_f32_16x16x32_bf16 v[24:27], v[146:149], v[210:213], v[24:27]
	v_mfma_f32_16x16x32_bf16 v[16:19], v[158:161], v[210:213], v[16:19]
	v_mfma_f32_16x16x32_bf16 v[60:63], v[154:157], v[170:173], v[60:63]
	v_mfma_f32_16x16x32_bf16 v[56:59], v[162:165], v[170:173], v[56:59]
	v_mfma_f32_16x16x32_bf16 v[52:55], v[154:157], v[178:181], v[52:55]
	v_mfma_f32_16x16x32_bf16 v[48:51], v[162:165], v[178:181], v[48:51]
	v_mfma_f32_16x16x32_bf16 v[40:43], v[154:157], v[206:209], v[40:43]
	v_mfma_f32_16x16x32_bf16 v[32:35], v[162:165], v[206:209], v[32:35]
	v_mfma_f32_16x16x32_bf16 v[24:27], v[154:157], v[214:217], v[24:27]
	v_mfma_f32_16x16x32_bf16 v[16:19], v[162:165], v[214:217], v[16:19]
	s_setprio 0
	s_barrier
	s_add_u32 s0, s30, 0x160000
	s_addc_u32 s1, s31, 0
	s_mov_b32 m0, s60
	s_nop 0
	global_load_lds_dwordx4 v130, s[0:1]
	s_mov_b32 m0, s61
	s_nop 0
	global_load_lds_dwordx4 v128, s[0:1]
	s_waitcnt vmcnt(6)
	s_barrier
	s_setprio 1
	v_mfma_f32_16x16x32_bf16 v[44:47], v[218:221], v[166:169], v[44:47]
	v_mfma_f32_16x16x32_bf16 v[36:39], v[226:229], v[166:169], v[36:39]
	v_mfma_f32_16x16x32_bf16 v[28:31], v[218:221], v[174:177], v[28:31]
	v_mfma_f32_16x16x32_bf16 v[20:23], v[226:229], v[174:177], v[20:23]
	v_mfma_f32_16x16x32_bf16 v[12:15], v[218:221], v[188:191], v[12:15]
	v_mfma_f32_16x16x32_bf16 v[8:11], v[226:229], v[188:191], v[8:11]
	v_mfma_f32_16x16x32_bf16 v[4:7], v[218:221], v[210:213], v[4:7]
	v_mfma_f32_16x16x32_bf16 v[0:3], v[226:229], v[210:213], v[0:3]
	v_mfma_f32_16x16x32_bf16 v[44:47], v[222:225], v[170:173], v[44:47]
	v_mfma_f32_16x16x32_bf16 v[36:39], v[230:233], v[170:173], v[36:39]
	v_mfma_f32_16x16x32_bf16 v[28:31], v[222:225], v[178:181], v[28:31]
	v_mfma_f32_16x16x32_bf16 v[20:23], v[230:233], v[178:181], v[20:23]
	v_mfma_f32_16x16x32_bf16 v[12:15], v[222:225], v[206:209], v[12:15]
	v_mfma_f32_16x16x32_bf16 v[8:11], v[230:233], v[206:209], v[8:11]
	v_mfma_f32_16x16x32_bf16 v[4:7], v[222:225], v[214:217], v[4:7]
	v_mfma_f32_16x16x32_bf16 v[0:3], v[230:233], v[214:217], v[0:3]
	s_setprio 0
	s_barrier
	ds_read_b128 v[146:149], v144
	ds_read_b128 v[154:157], v144 offset:1024
	ds_read_b128 v[158:161], v144 offset:2048
	ds_read_b128 v[162:165], v144 offset:3072
	s_add_u32 s0, s36, 0x160000
	s_addc_u32 s1, s37, 0
	s_mov_b32 m0, s42
	ds_read_b128 v[166:169], v142 offset:32768
	ds_read_b128 v[170:173], v142 offset:33792
	ds_read_b128 v[174:177], v142 offset:34816
	ds_read_b128 v[178:181], v142 offset:35840
	ds_read_b128 v[188:191], v142 offset:36864
	ds_read_b128 v[206:209], v142 offset:37888
	ds_read_b128 v[210:213], v142 offset:38912
	global_load_lds_dwordx4 v130, s[0:1]
	s_mov_b32 m0, s43
	ds_read_b128 v[214:217], v142 offset:39936
	global_load_lds_dwordx4 v128, s[0:1]
	s_waitcnt lgkmcnt(8)
	s_barrier
; #define PG8_STAGE(bufoff, gbase, voff) do { _Pragma("unroll") for (int _i = 0; _i < 2; ++_i) \
;         __builtin_amdgcn_global_load_lds((const unsigned*)((const char*)(gbase) + (voff)[_i]), (LAS unsigned*)(lds + (bufoff) + ldsw + _i * 8192), 16, 0, 0); } while (0)
; #define PG8_LDA(dst, b, h) do { _Pragma("unroll") for (int m = 0; m < 4; ++m) _Pragma("unroll") for (int k = 0; k < 2; ++k) dst[m][k] = *(const LAS bf16x8*)(lds + PG8_SA(b, h) + aoff + m * 2048 + k * 1024); } while (0)
; #define PG8_LDB(dst, b, h) do { _Pragma("unroll") for (int n = 0; n < 2; ++n) _Pragma("unroll") for (int k = 0; k < 2; ++k) dst[n][k] = *(const LAS bf16x8*)(lds + PG8_SB(b, h) + boff + n * 2048 + k * 1024); } while (0)
; #define PG8_MMA(ai, bj, At, Bt) do { __builtin_amdgcn_s_setprio(1); _Pragma("unroll") for (int m = 0; m < 4; ++m) _Pragma("unroll") for (int n = 0; n < 2; ++n) _Pragma("unroll") for (int k = 0; k < 2; ++k) \
;         acc[ai][bj][m][n] = __builtin_amdgcn_mfma_f32_16x16x32_bf16(Bt[n][k], At[m][k], acc[ai][bj][m][n], 0, 0, 0); __builtin_amdgcn_s_setprio(0); } while (0)
; #define PG8_WAIT_V(n) asm volatile("s_waitcnt vmcnt(" #n ")" ::: "memory")
; #define PG8_WAIT_L(n) asm volatile("s_waitcnt lgkmcnt(" #n ")" ::: "memory")
; #define PG8_BAR __builtin_amdgcn_s_barrier()
; #define PG8_SCHED __builtin_amdgcn_sched_barrier(0)
; template <class Epi, class Sched>
; DI void gemm_phase(LAS unsigned char* lds, const Gemm g, const Sched& S, const Epi& E) {
;     ...
;             PG8_WAIT_L(8); PG8_BAR; PG8_WAIT_L(0); PG8_MMA(0, 0, At, B0); PG8_BAR; PG8_SCHED;
;             PG8_LDB(B1, 1, 1); PG8_STAGE(PG8_SB(1, 0), b3, voffB);
;             PG8_BAR; PG8_WAIT_L(0); PG8_MMA(0, 1, At, B1); PG8_BAR;
;             PG8_LDA(At, 1, 1); PG8_STAGE(PG8_SA(1, 0), a3, voffA);
;             PG8_BAR; PG8_WAIT_L(0); PG8_MMA(1, 0, At, B0); PG8_BAR; PG8_SCHED;
;             PG8_STAGE(PG8_SB(1, 1), b3 + hstep, voffB);
;             PG8_WAIT_V(6); PG8_BAR; PG8_MMA(1, 1, At, B1); PG8_BAR;
	s_waitcnt lgkmcnt(0)
	s_setprio 1
	v_mfma_f32_16x16x32_bf16 v[124:127], v[146:149], v[166:169], v[124:127]
	v_mfma_f32_16x16x32_bf16 v[120:123], v[158:161], v[166:169], v[120:123]
	v_mfma_f32_16x16x32_bf16 v[116:119], v[146:149], v[174:177], v[116:119]
	v_mfma_f32_16x16x32_bf16 v[112:115], v[158:161], v[174:177], v[112:115]
	v_mfma_f32_16x16x32_bf16 v[104:107], v[146:149], v[188:191], v[104:107]
	v_mfma_f32_16x16x32_bf16 v[96:99], v[158:161], v[188:191], v[96:99]
	v_mfma_f32_16x16x32_bf16 v[88:91], v[146:149], v[210:213], v[88:91]
	v_mfma_f32_16x16x32_bf16 v[80:83], v[158:161], v[210:213], v[80:83]
	v_mfma_f32_16x16x32_bf16 v[124:127], v[154:157], v[170:173], v[124:127]
	v_mfma_f32_16x16x32_bf16 v[120:123], v[162:165], v[170:173], v[120:123]
	v_mfma_f32_16x16x32_bf16 v[116:119], v[154:157], v[178:181], v[116:119]
	v_mfma_f32_16x16x32_bf16 v[112:115], v[162:165], v[178:181], v[112:115]
	v_mfma_f32_16x16x32_bf16 v[104:107], v[154:157], v[206:209], v[104:107]
	v_mfma_f32_16x16x32_bf16 v[96:99], v[162:165], v[206:209], v[96:99]
	v_mfma_f32_16x16x32_bf16 v[88:91], v[154:157], v[214:217], v[88:91]
	v_mfma_f32_16x16x32_bf16 v[80:83], v[162:165], v[214:217], v[80:83]
	s_setprio 0
	s_barrier
	s_add_i32 s4, 0, 0x1c000
	s_add_i32 s0, s62, s35
	v_add_u32_e32 v145, s4, v140
	s_add_i32 m0, s0, 0xffffff80
	ds_read_b128 v[218:221], v145
	ds_read_b128 v[222:225], v145 offset:1024
	ds_read_b128 v[226:229], v145 offset:2048
	global_load_lds_dwordx4 v130, s[30:31] offset:128
	s_add_i32 m0, s0, 0x1f80
	ds_read_b128 v[230:233], v145 offset:3072
	global_load_lds_dwordx4 v128, s[30:31] offset:128
	s_barrier
	s_waitcnt lgkmcnt(0)
	s_setprio 1
	v_mfma_f32_16x16x32_bf16 v[108:111], v[218:221], v[166:169], v[108:111]
	v_mfma_f32_16x16x32_bf16 v[100:103], v[226:229], v[166:169], v[100:103]
	v_mfma_f32_16x16x32_bf16 v[92:95], v[218:221], v[174:177], v[92:95]
	v_mfma_f32_16x16x32_bf16 v[84:87], v[226:229], v[174:177], v[84:87]
	v_mfma_f32_16x16x32_bf16 v[76:79], v[218:221], v[188:191], v[76:79]
	v_mfma_f32_16x16x32_bf16 v[72:75], v[226:229], v[188:191], v[72:75]
	v_mfma_f32_16x16x32_bf16 v[68:71], v[218:221], v[210:213], v[68:71]
	v_mfma_f32_16x16x32_bf16 v[64:67], v[226:229], v[210:213], v[64:67]
	v_mfma_f32_16x16x32_bf16 v[108:111], v[222:225], v[170:173], v[108:111]
	v_mfma_f32_16x16x32_bf16 v[100:103], v[230:233], v[170:173], v[100:103]
	v_mfma_f32_16x16x32_bf16 v[92:95], v[222:225], v[178:181], v[92:95]
	v_mfma_f32_16x16x32_bf16 v[84:87], v[230:233], v[178:181], v[84:87]
	v_mfma_f32_16x16x32_bf16 v[76:79], v[222:225], v[206:209], v[76:79]
	v_mfma_f32_16x16x32_bf16 v[72:75], v[230:233], v[206:209], v[72:75]
	v_mfma_f32_16x16x32_bf16 v[68:71], v[222:225], v[214:217], v[68:71]
	v_mfma_f32_16x16x32_bf16 v[64:67], v[230:233], v[214:217], v[64:67]
	s_setprio 0
	s_add_i32 m0, s54, 0xffffff80
	s_barrier
	ds_read_b128 v[166:169], v142 offset:49152
	ds_read_b128 v[170:173], v142 offset:50176
	ds_read_b128 v[174:177], v142 offset:51200
	ds_read_b128 v[178:181], v142 offset:52224
	ds_read_b128 v[188:191], v142 offset:53248
	ds_read_b128 v[206:209], v142 offset:54272
	ds_read_b128 v[210:213], v142 offset:55296
	global_load_lds_dwordx4 v130, s[36:37] offset:128
	s_add_i32 m0, s55, 0xffffff80
	ds_read_b128 v[214:217], v142 offset:56320
	global_load_lds_dwordx4 v128, s[36:37] offset:128
	s_barrier
	s_waitcnt lgkmcnt(0)
	s_setprio 1
	v_mfma_f32_16x16x32_bf16 v[60:63], v[146:149], v[166:169], v[60:63]
	v_mfma_f32_16x16x32_bf16 v[56:59], v[158:161], v[166:169], v[56:59]
	v_mfma_f32_16x16x32_bf16 v[52:55], v[146:149], v[174:177], v[52:55]
	v_mfma_f32_16x16x32_bf16 v[48:51], v[158:161], v[174:177], v[48:51]
	v_mfma_f32_16x16x32_bf16 v[40:43], v[146:149], v[188:191], v[40:43]
	v_mfma_f32_16x16x32_bf16 v[32:35], v[158:161], v[188:191], v[32:35]
	v_mfma_f32_16x16x32_bf16 v[24:27], v[146:149], v[210:213], v[24:27]
	v_mfma_f32_16x16x32_bf16 v[16:19], v[158:161], v[210:213], v[16:19]
	v_mfma_f32_16x16x32_bf16 v[60:63], v[154:157], v[170:173], v[60:63]
	v_mfma_f32_16x16x32_bf16 v[56:59], v[162:165], v[170:173], v[56:59]
	v_mfma_f32_16x16x32_bf16 v[52:55], v[154:157], v[178:181], v[52:55]
	v_mfma_f32_16x16x32_bf16 v[48:51], v[162:165], v[178:181], v[48:51]
	v_mfma_f32_16x16x32_bf16 v[40:43], v[154:157], v[206:209], v[40:43]
	v_mfma_f32_16x16x32_bf16 v[32:35], v[162:165], v[206:209], v[32:35]
	v_mfma_f32_16x16x32_bf16 v[24:27], v[154:157], v[214:217], v[24:27]
	v_mfma_f32_16x16x32_bf16 v[16:19], v[162:165], v[214:217], v[16:19]
	s_setprio 0
	s_barrier
	s_add_u32 s0, s30, 0x160080
	s_addc_u32 s1, s31, 0
	s_add_i32 s4, s4, s35
	s_mov_b32 m0, s4
	s_nop 0
	global_load_lds_dwordx4 v130, s[0:1]
	s_add_i32 m0, s4, 0x2000
	s_nop 0
	global_load_lds_dwordx4 v128, s[0:1]
	s_waitcnt vmcnt(6)
	s_barrier
	s_setprio 1
	v_mfma_f32_16x16x32_bf16 v[44:47], v[218:221], v[166:169], v[44:47]
	v_mfma_f32_16x16x32_bf16 v[36:39], v[226:229], v[166:169], v[36:39]
	v_mfma_f32_16x16x32_bf16 v[28:31], v[218:221], v[174:177], v[28:31]
	v_mfma_f32_16x16x32_bf16 v[20:23], v[226:229], v[174:177], v[20:23]
	v_mfma_f32_16x16x32_bf16 v[12:15], v[218:221], v[188:191], v[12:15]
	v_mfma_f32_16x16x32_bf16 v[8:11], v[226:229], v[188:191], v[8:11]
	v_mfma_f32_16x16x32_bf16 v[4:7], v[218:221], v[210:213], v[4:7]
	v_mfma_f32_16x16x32_bf16 v[0:3], v[226:229], v[210:213], v[0:3]
	v_mfma_f32_16x16x32_bf16 v[44:47], v[222:225], v[170:173], v[44:47]
	v_mfma_f32_16x16x32_bf16 v[36:39], v[230:233], v[170:173], v[36:39]
	v_mfma_f32_16x16x32_bf16 v[28:31], v[222:225], v[178:181], v[28:31]
	v_mfma_f32_16x16x32_bf16 v[20:23], v[230:233], v[178:181], v[20:23]
	v_mfma_f32_16x16x32_bf16 v[12:15], v[222:225], v[206:209], v[12:15]
	v_mfma_f32_16x16x32_bf16 v[8:11], v[230:233], v[206:209], v[8:11]
	v_mfma_f32_16x16x32_bf16 v[4:7], v[222:225], v[214:217], v[4:7]
	v_mfma_f32_16x16x32_bf16 v[0:3], v[230:233], v[214:217], v[0:3]
	s_setprio 0
	s_add_i32 s66, s66, 2
	s_add_u32 s8, s8, 0x100
	s_addc_u32 s9, s9, 0
	s_add_u32 s64, s64, 0x100
	s_addc_u32 s65, s65, 0
	s_cmp_gt_u32 s66, 5
	s_barrier
	s_cbranch_scc0 .LBB0_1775

; #define PG8_STAGE(bufoff, gbase, voff) do { _Pragma("unroll") for (int _i = 0; _i < 2; ++_i) \
;         __builtin_amdgcn_global_load_lds((const unsigned*)((const char*)(gbase) + (voff)[_i]), (LAS unsigned*)(lds + (bufoff) + ldsw + _i * 8192), 16, 0, 0); } while (0)
; #define PG8_LDA(dst, b, h) do { _Pragma("unroll") for (int m = 0; m < 4; ++m) _Pragma("unroll") for (int k = 0; k < 2; ++k) dst[m][k] = *(const LAS bf16x8*)(lds + PG8_SA(b, h) + aoff + m * 2048 + k * 1024); } while (0)
; #define PG8_LDB(dst, b, h) do { _Pragma("unroll") for (int n = 0; n < 2; ++n) _Pragma("unroll") for (int k = 0; k < 2; ++k) dst[n][k] = *(const LAS bf16x8*)(lds + PG8_SB(b, h) + boff + n * 2048 + k * 1024); } while (0)
; #define PG8_MMA(ai, bj, At, Bt) do { __builtin_amdgcn_s_setprio(1); _Pragma("unroll") for (int m = 0; m < 4; ++m) _Pragma("unroll") for (int n = 0; n < 2; ++n) _Pragma("unroll") for (int k = 0; k < 2; ++k) \
;         acc[ai][bj][m][n] = __builtin_amdgcn_mfma_f32_16x16x32_bf16(Bt[n][k], At[m][k], acc[ai][bj][m][n], 0, 0, 0); __builtin_amdgcn_s_setprio(0); } while (0)
; template <class Epi, class Sched>
; DI void gemm_phase(LAS unsigned char* lds, const Gemm g, const Sched& S, const Epi& E) {
;     ...
;         for (int t = 0; t < nt; t += 2) {
;             if constexpr (Epi::HAS_MID) { if (t == E.mid_t(nt)) { int fr3 = fr, fq3 = fq; asm volatile("" : "+v"(fr3), "+v"(fq3)); E.mid(acc, cur, wr, wc, fr3, fq3); } }
;             const bool last = (t == nt - 2);
;             const char* a1 = cA + (size_t)(t + 1) * kstep;
;             const char* a2 = last ? nA : cA + (size_t)(t + 2) * kstep; const char* b2 = last ? nB : cB + (size_t)(t + 2) * kstep;
;             const char* a3 = a2 + kstep; const char* b3 = b2 + kstep;
;             PG8_LDB(B0, 0, 0); PG8_SCHED; PG8_LDA(At, 0, 0); PG8_STAGE(PG8_SA(1, 1), a1 + hstep, voffA);
;             PG8_WAIT_L(8); PG8_BAR; PG8_WAIT_L(0); PG8_MMA(0, 0, At, B0); PG8_BAR; PG8_SCHED;
;             PG8_LDB(B1, 0, 1); PG8_STAGE(PG8_SB(0, 0), b2, voffB);
;             PG8_BAR; PG8_WAIT_L(0); PG8_MMA(0, 1, At, B1); PG8_BAR;
;             PG8_LDA(At, 0, 1); PG8_STAGE(PG8_SA(0, 0), a2, voffA);
;             PG8_BAR; PG8_WAIT_L(0); PG8_MMA(1, 0, At, B0); PG8_BAR; PG8_SCHED;
;             PG8_STAGE(PG8_SB(0, 1), b2 + hstep, voffB);
;             PG8_WAIT_V(6); PG8_BAR; PG8_MMA(1, 1, At, B1); PG8_BAR;
.LBB0_1920:
	v_add_u32_e32 v161, s62, v157
	s_add_u32 s0, s38, s8
	ds_read_b128 v[148:151], v161
	ds_read_b128 v[162:165], v161 offset:1024
	ds_read_b128 v[166:169], v161 offset:2048
	ds_read_b128 v[170:173], v161 offset:3072
	s_addc_u32 s1, s39, s9
	s_add_u32 s0, s0, 0x100
	s_addc_u32 s1, s1, 0
	s_add_u32 s4, s68, s8
	s_addc_u32 s5, s69, s9
	s_cmpk_eq_i32 s8, 0x1100
	s_cselect_b32 s43, s37, s1
	s_cselect_b32 s42, s36, s0
	s_cselect_b32 s41, s11, s5
	s_cselect_b32 s40, s10, s4
	v_lshl_add_u64 v[182:183], v[144:145], 0, s[8:9]
	s_add_i32 m0, s53, 0xc000
	ds_read_b128 v[174:177], v158
	ds_read_b128 v[178:181], v158 offset:1024
	ds_read_b128 v[188:191], v158 offset:2048
	ds_read_b128 v[196:199], v158 offset:3072
	ds_read_b128 v[200:203], v158 offset:4096
	ds_read_b128 v[206:209], v158 offset:5120
	ds_read_b128 v[210:213], v158 offset:6144
	ds_read_b128 v[214:217], v158 offset:7168
	global_load_lds_dwordx4 v[182:183], off
	v_lshl_add_u64 v[182:183], v[146:147], 0, s[8:9]
	s_add_i32 m0, s53, 0xe000
	s_nop 0
	global_load_lds_dwordx4 v[182:183], off
	s_waitcnt lgkmcnt(8)
	s_barrier
	s_waitcnt lgkmcnt(0)
	s_setprio 1
	v_mfma_f32_16x16x32_bf16 v[124:127], v[148:151], v[174:177], v[124:127]
	v_mfma_f32_16x16x32_bf16 v[120:123], v[166:169], v[174:177], v[120:123]
	v_mfma_f32_16x16x32_bf16 v[108:111], v[148:151], v[188:191], v[108:111]
	v_mfma_f32_16x16x32_bf16 v[104:107], v[166:169], v[188:191], v[104:107]
	v_mfma_f32_16x16x32_bf16 v[92:95], v[148:151], v[200:203], v[92:95]
	v_mfma_f32_16x16x32_bf16 v[88:91], v[166:169], v[200:203], v[88:91]
	v_mfma_f32_16x16x32_bf16 v[76:79], v[148:151], v[210:213], v[76:79]
	v_mfma_f32_16x16x32_bf16 v[72:75], v[166:169], v[210:213], v[72:75]
	v_mfma_f32_16x16x32_bf16 v[124:127], v[162:165], v[178:181], v[124:127]
	v_mfma_f32_16x16x32_bf16 v[120:123], v[170:173], v[178:181], v[120:123]
	v_mfma_f32_16x16x32_bf16 v[108:111], v[162:165], v[196:199], v[108:111]
	v_mfma_f32_16x16x32_bf16 v[104:107], v[170:173], v[196:199], v[104:107]
	v_mfma_f32_16x16x32_bf16 v[92:95], v[162:165], v[206:209], v[92:95]
	v_mfma_f32_16x16x32_bf16 v[88:91], v[170:173], v[206:209], v[88:91]
	v_mfma_f32_16x16x32_bf16 v[76:79], v[162:165], v[214:217], v[76:79]
	v_mfma_f32_16x16x32_bf16 v[72:75], v[170:173], v[214:217], v[72:75]
	s_setprio 0
	s_barrier
	s_add_i32 s0, s62, s52
	v_add_u32_e32 v161, s63, v157
	s_mov_b32 m0, s0
	ds_read_b128 v[218:221], v161
	ds_read_b128 v[222:225], v161 offset:1024
	ds_read_b128 v[226:229], v161 offset:2048
	global_load_lds_dwordx4 v130, s[40:41]
	s_add_i32 m0, s0, 0x2000
	ds_read_b128 v[230:233], v161 offset:3072
	global_load_lds_dwordx4 v134, s[40:41]
	s_barrier
	s_waitcnt lgkmcnt(0)
	s_setprio 1
	v_mfma_f32_16x16x32_bf16 v[116:119], v[218:221], v[174:177], v[116:119]
	v_mfma_f32_16x16x32_bf16 v[112:115], v[226:229], v[174:177], v[112:115]
	v_mfma_f32_16x16x32_bf16 v[100:103], v[218:221], v[188:191], v[100:103]
	v_mfma_f32_16x16x32_bf16 v[96:99], v[226:229], v[188:191], v[96:99]
	v_mfma_f32_16x16x32_bf16 v[84:87], v[218:221], v[200:203], v[84:87]
	v_mfma_f32_16x16x32_bf16 v[80:83], v[226:229], v[200:203], v[80:83]
	v_mfma_f32_16x16x32_bf16 v[68:71], v[218:221], v[210:213], v[68:71]
	v_mfma_f32_16x16x32_bf16 v[64:67], v[226:229], v[210:213], v[64:67]
	v_mfma_f32_16x16x32_bf16 v[116:119], v[222:225], v[178:181], v[116:119]
	v_mfma_f32_16x16x32_bf16 v[112:115], v[230:233], v[178:181], v[112:115]
	v_mfma_f32_16x16x32_bf16 v[100:103], v[222:225], v[196:199], v[100:103]
	v_mfma_f32_16x16x32_bf16 v[96:99], v[230:233], v[196:199], v[96:99]
	v_mfma_f32_16x16x32_bf16 v[84:87], v[222:225], v[206:209], v[84:87]
	v_mfma_f32_16x16x32_bf16 v[80:83], v[230:233], v[206:209], v[80:83]
	v_mfma_f32_16x16x32_bf16 v[68:71], v[222:225], v[214:217], v[68:71]
	v_mfma_f32_16x16x32_bf16 v[64:67], v[230:233], v[214:217], v[64:67]
	s_setprio 0
	s_mov_b32 m0, s53
	s_barrier
	ds_read_b128 v[174:177], v158 offset:16384
	ds_read_b128 v[178:181], v158 offset:17408
	ds_read_b128 v[188:191], v158 offset:18432
	ds_read_b128 v[196:199], v158 offset:19456
	ds_read_b128 v[200:203], v158 offset:20480
	ds_read_b128 v[206:209], v158 offset:21504
	ds_read_b128 v[210:213], v158 offset:22528
	global_load_lds_dwordx4 v128, s[42:43]
	s_mov_b32 m0, s54
	ds_read_b128 v[214:217], v158 offset:23552
	global_load_lds_dwordx4 v132, s[42:43]
	s_barrier
	s_waitcnt lgkmcnt(0)
	s_setprio 1
	v_mfma_f32_16x16x32_bf16 v[60:63], v[148:151], v[174:177], v[60:63]
	v_mfma_f32_16x16x32_bf16 v[56:59], v[166:169], v[174:177], v[56:59]
	v_mfma_f32_16x16x32_bf16 v[44:47], v[148:151], v[188:191], v[44:47]
	v_mfma_f32_16x16x32_bf16 v[40:43], v[166:169], v[188:191], v[40:43]
	v_mfma_f32_16x16x32_bf16 v[28:31], v[148:151], v[200:203], v[28:31]
	v_mfma_f32_16x16x32_bf16 v[24:27], v[166:169], v[200:203], v[24:27]
	v_mfma_f32_16x16x32_bf16 v[12:15], v[148:151], v[210:213], v[12:15]
	v_mfma_f32_16x16x32_bf16 v[8:11], v[166:169], v[210:213], v[8:11]
	v_mfma_f32_16x16x32_bf16 v[60:63], v[162:165], v[178:181], v[60:63]
	v_mfma_f32_16x16x32_bf16 v[56:59], v[170:173], v[178:181], v[56:59]
	v_mfma_f32_16x16x32_bf16 v[44:47], v[162:165], v[196:199], v[44:47]
	v_mfma_f32_16x16x32_bf16 v[40:43], v[170:173], v[196:199], v[40:43]
	v_mfma_f32_16x16x32_bf16 v[28:31], v[162:165], v[206:209], v[28:31]
	v_mfma_f32_16x16x32_bf16 v[24:27], v[170:173], v[206:209], v[24:27]
	v_mfma_f32_16x16x32_bf16 v[12:15], v[162:165], v[214:217], v[12:15]
	v_mfma_f32_16x16x32_bf16 v[8:11], v[170:173], v[214:217], v[8:11]
	s_setprio 0
	s_barrier
	s_add_u32 s0, s40, 0x90000
	s_addc_u32 s1, s41, 0
	s_add_i32 s4, s63, s52
	s_mov_b32 m0, s4
	s_nop 0
	global_load_lds_dwordx4 v130, s[0:1]
	s_add_i32 m0, s4, 0x2000
	s_nop 0
	global_load_lds_dwordx4 v134, s[0:1]
	s_waitcnt vmcnt(6)
	s_barrier
; #define PG8_STAGE(bufoff, gbase, voff) do { _Pragma("unroll") for (int _i = 0; _i < 2; ++_i) \
;         __builtin_amdgcn_global_load_lds((const unsigned*)((const char*)(gbase) + (voff)[_i]), (LAS unsigned*)(lds + (bufoff) + ldsw + _i * 8192), 16, 0, 0); } while (0)
; #define PG8_LDA(dst, b, h) do { _Pragma("unroll") for (int m = 0; m < 4; ++m) _Pragma("unroll") for (int k = 0; k < 2; ++k) dst[m][k] = *(const LAS bf16x8*)(lds + PG8_SA(b, h) + aoff + m * 2048 + k * 1024); } while (0)
; #define PG8_LDB(dst, b, h) do { _Pragma("unroll") for (int n = 0; n < 2; ++n) _Pragma("unroll") for (int k = 0; k < 2; ++k) dst[n][k] = *(const LAS bf16x8*)(lds + PG8_SB(b, h) + boff + n * 2048 + k * 1024); } while (0)
; #define PG8_MMA(ai, bj, At, Bt) do { __builtin_amdgcn_s_setprio(1); _Pragma("unroll") for (int m = 0; m < 4; ++m) _Pragma("unroll") for (int n = 0; n < 2; ++n) _Pragma("unroll") for (int k = 0; k < 2; ++k) \
;         acc[ai][bj][m][n] = __builtin_amdgcn_mfma_f32_16x16x32_bf16(Bt[n][k], At[m][k], acc[ai][bj][m][n], 0, 0, 0); __builtin_amdgcn_s_setprio(0); } while (0)
; #define PG8_WAIT_V(n) asm volatile("s_waitcnt vmcnt(" #n ")" ::: "memory")
; #define PG8_WAIT_L(n) asm volatile("s_waitcnt lgkmcnt(" #n ")" ::: "memory")
; #define PG8_BAR __builtin_amdgcn_s_barrier()
; #define PG8_SCHED __builtin_amdgcn_sched_barrier(0)
; template <class Epi, class Sched>
; DI void gemm_phase(LAS unsigned char* lds, const Gemm g, const Sched& S, const Epi& E) {
;     ...
;             PG8_STAGE(PG8_SB(0, 1), b2 + hstep, voffB);
;             PG8_WAIT_V(6); PG8_BAR; PG8_MMA(1, 1, At, B1); PG8_BAR;
;             PG8_LDB(B0, 1, 0); PG8_SCHED; PG8_LDA(At, 1, 0); PG8_STAGE(PG8_SA(0, 1), a2 + hstep, voffA);
;             PG8_WAIT_L(8); PG8_BAR; PG8_WAIT_L(0); PG8_MMA(0, 0, At, B0); PG8_BAR; PG8_SCHED;
;             PG8_LDB(B1, 1, 1); PG8_STAGE(PG8_SB(1, 0), b3, voffB);
;             PG8_BAR; PG8_WAIT_L(0); PG8_MMA(0, 1, At, B1); PG8_BAR;
;             PG8_LDA(At, 1, 1); PG8_STAGE(PG8_SA(1, 0), a3, voffA);
	s_setprio 1
	v_mfma_f32_16x16x32_bf16 v[52:55], v[218:221], v[174:177], v[52:55]
	v_mfma_f32_16x16x32_bf16 v[48:51], v[226:229], v[174:177], v[48:51]
	v_mfma_f32_16x16x32_bf16 v[36:39], v[218:221], v[188:191], v[36:39]
	v_mfma_f32_16x16x32_bf16 v[32:35], v[226:229], v[188:191], v[32:35]
	v_mfma_f32_16x16x32_bf16 v[20:23], v[218:221], v[200:203], v[20:23]
	v_mfma_f32_16x16x32_bf16 v[16:19], v[226:229], v[200:203], v[16:19]
	v_mfma_f32_16x16x32_bf16 v[4:7], v[218:221], v[210:213], v[4:7]
	v_mfma_f32_16x16x32_bf16 v[0:3], v[226:229], v[210:213], v[0:3]
	v_mfma_f32_16x16x32_bf16 v[52:55], v[222:225], v[178:181], v[52:55]
	v_mfma_f32_16x16x32_bf16 v[48:51], v[230:233], v[178:181], v[48:51]
	v_mfma_f32_16x16x32_bf16 v[36:39], v[222:225], v[196:199], v[36:39]
	v_mfma_f32_16x16x32_bf16 v[32:35], v[230:233], v[196:199], v[32:35]
	v_mfma_f32_16x16x32_bf16 v[20:23], v[222:225], v[206:209], v[20:23]
	v_mfma_f32_16x16x32_bf16 v[16:19], v[230:233], v[206:209], v[16:19]
	v_mfma_f32_16x16x32_bf16 v[4:7], v[222:225], v[214:217], v[4:7]
	v_mfma_f32_16x16x32_bf16 v[0:3], v[230:233], v[214:217], v[0:3]
	s_setprio 0
	s_add_i32 s4, 0, 0x18000
	v_add_u32_e32 v161, s4, v157
	s_barrier
	ds_read_b128 v[148:151], v161
	ds_read_b128 v[162:165], v161 offset:1024
	ds_read_b128 v[166:169], v161 offset:2048
	ds_read_b128 v[170:173], v161 offset:3072
	s_add_u32 s0, s42, 0x90000
	s_addc_u32 s1, s43, 0
	s_mov_b32 m0, s55
	ds_read_b128 v[174:177], v158 offset:32768
	ds_read_b128 v[178:181], v158 offset:33792
	ds_read_b128 v[188:191], v158 offset:34816
	ds_read_b128 v[196:199], v158 offset:35840
	ds_read_b128 v[200:203], v158 offset:36864
	ds_read_b128 v[206:209], v158 offset:37888
	ds_read_b128 v[210:213], v158 offset:38912
	global_load_lds_dwordx4 v128, s[0:1]
	s_mov_b32 m0, s56
	ds_read_b128 v[214:217], v158 offset:39936
	global_load_lds_dwordx4 v132, s[0:1]
	s_waitcnt lgkmcnt(8)
	s_barrier
	s_waitcnt lgkmcnt(0)
	s_setprio 1
	v_mfma_f32_16x16x32_bf16 v[124:127], v[148:151], v[174:177], v[124:127]
	v_mfma_f32_16x16x32_bf16 v[120:123], v[166:169], v[174:177], v[120:123]
	v_mfma_f32_16x16x32_bf16 v[108:111], v[148:151], v[188:191], v[108:111]
	v_mfma_f32_16x16x32_bf16 v[104:107], v[166:169], v[188:191], v[104:107]
	v_mfma_f32_16x16x32_bf16 v[92:95], v[148:151], v[200:203], v[92:95]
	v_mfma_f32_16x16x32_bf16 v[88:91], v[166:169], v[200:203], v[88:91]
	v_mfma_f32_16x16x32_bf16 v[76:79], v[148:151], v[210:213], v[76:79]
	v_mfma_f32_16x16x32_bf16 v[72:75], v[166:169], v[210:213], v[72:75]
	v_mfma_f32_16x16x32_bf16 v[124:127], v[162:165], v[178:181], v[124:127]
	v_mfma_f32_16x16x32_bf16 v[120:123], v[170:173], v[178:181], v[120:123]
	v_mfma_f32_16x16x32_bf16 v[108:111], v[162:165], v[196:199], v[108:111]
	v_mfma_f32_16x16x32_bf16 v[104:107], v[170:173], v[196:199], v[104:107]
	v_mfma_f32_16x16x32_bf16 v[92:95], v[162:165], v[206:209], v[92:95]
	v_mfma_f32_16x16x32_bf16 v[88:91], v[170:173], v[206:209], v[88:91]
	v_mfma_f32_16x16x32_bf16 v[76:79], v[162:165], v[214:217], v[76:79]
	v_mfma_f32_16x16x32_bf16 v[72:75], v[170:173], v[214:217], v[72:75]
	s_setprio 0
	s_barrier
	s_add_i32 s5, 0, 0x1c000
	s_add_i32 s0, s4, s52
	v_add_u32_e32 v161, s5, v157
	s_add_i32 m0, s0, 0xffffff80
	ds_read_b128 v[218:221], v161
	ds_read_b128 v[222:225], v161 offset:1024
	ds_read_b128 v[226:229], v161 offset:2048
	global_load_lds_dwordx4 v130, s[40:41] offset:128
	s_add_i32 m0, s0, 0x1f80
	ds_read_b128 v[230:233], v161 offset:3072
	global_load_lds_dwordx4 v134, s[40:41] offset:128
	s_barrier
; #define PG8_STAGE(bufoff, gbase, voff) do { _Pragma("unroll") for (int _i = 0; _i < 2; ++_i) \
;         __builtin_amdgcn_global_load_lds((const unsigned*)((const char*)(gbase) + (voff)[_i]), (LAS unsigned*)(lds + (bufoff) + ldsw + _i * 8192), 16, 0, 0); } while (0)
; #define PG8_MMA(ai, bj, At, Bt) do { __builtin_amdgcn_s_setprio(1); _Pragma("unroll") for (int m = 0; m < 4; ++m) _Pragma("unroll") for (int n = 0; n < 2; ++n) _Pragma("unroll") for (int k = 0; k < 2; ++k) \
;         acc[ai][bj][m][n] = __builtin_amdgcn_mfma_f32_16x16x32_bf16(Bt[n][k], At[m][k], acc[ai][bj][m][n], 0, 0, 0); __builtin_amdgcn_s_setprio(0); } while (0)
; #define PG8_WAIT_V(n) asm volatile("s_waitcnt vmcnt(" #n ")" ::: "memory")
; #define PG8_WAIT_L(n) asm volatile("s_waitcnt lgkmcnt(" #n ")" ::: "memory")
; #define PG8_BAR __builtin_amdgcn_s_barrier()
; #define PG8_SCHED __builtin_amdgcn_sched_barrier(0)
; template <class Epi, class Sched>
; DI void gemm_phase(LAS unsigned char* lds, const Gemm g, const Sched& S, const Epi& E) {
;     ...
;             PG8_BAR; PG8_WAIT_L(0); PG8_MMA(1, 0, At, B0); PG8_BAR; PG8_SCHED;
;             PG8_STAGE(PG8_SB(1, 1), b3 + hstep, voffB);
;             PG8_WAIT_V(6); PG8_BAR; PG8_MMA(1, 1, At, B1); PG8_BAR;
	s_waitcnt lgkmcnt(0)
	s_setprio 1
	v_mfma_f32_16x16x32_bf16 v[116:119], v[218:221], v[174:177], v[116:119]
	v_mfma_f32_16x16x32_bf16 v[112:115], v[226:229], v[174:177], v[112:115]
	v_mfma_f32_16x16x32_bf16 v[100:103], v[218:221], v[188:191], v[100:103]
	v_mfma_f32_16x16x32_bf16 v[96:99], v[226:229], v[188:191], v[96:99]
	v_mfma_f32_16x16x32_bf16 v[84:87], v[218:221], v[200:203], v[84:87]
	v_mfma_f32_16x16x32_bf16 v[80:83], v[226:229], v[200:203], v[80:83]
	v_mfma_f32_16x16x32_bf16 v[68:71], v[218:221], v[210:213], v[68:71]
	v_mfma_f32_16x16x32_bf16 v[64:67], v[226:229], v[210:213], v[64:67]
	v_mfma_f32_16x16x32_bf16 v[116:119], v[222:225], v[178:181], v[116:119]
	v_mfma_f32_16x16x32_bf16 v[112:115], v[230:233], v[178:181], v[112:115]
	v_mfma_f32_16x16x32_bf16 v[100:103], v[222:225], v[196:199], v[100:103]
	v_mfma_f32_16x16x32_bf16 v[96:99], v[230:233], v[196:199], v[96:99]
	v_mfma_f32_16x16x32_bf16 v[84:87], v[222:225], v[206:209], v[84:87]
	v_mfma_f32_16x16x32_bf16 v[80:83], v[230:233], v[206:209], v[80:83]
	v_mfma_f32_16x16x32_bf16 v[68:71], v[222:225], v[214:217], v[68:71]
	v_mfma_f32_16x16x32_bf16 v[64:67], v[230:233], v[214:217], v[64:67]
	s_setprio 0
	s_add_i32 m0, s59, 0xffffff80
	s_barrier
	ds_read_b128 v[174:177], v158 offset:49152
	ds_read_b128 v[178:181], v158 offset:50176
	ds_read_b128 v[188:191], v158 offset:51200
	ds_read_b128 v[196:199], v158 offset:52224
	ds_read_b128 v[200:203], v158 offset:53248
	ds_read_b128 v[206:209], v158 offset:54272
	ds_read_b128 v[210:213], v158 offset:55296
	global_load_lds_dwordx4 v128, s[42:43] offset:128
	s_add_i32 m0, s60, 0xffffff80
	ds_read_b128 v[214:217], v158 offset:56320
	global_load_lds_dwordx4 v132, s[42:43] offset:128
	s_barrier
	s_waitcnt lgkmcnt(0)
	s_setprio 1
	v_mfma_f32_16x16x32_bf16 v[60:63], v[148:151], v[174:177], v[60:63]
	v_mfma_f32_16x16x32_bf16 v[56:59], v[166:169], v[174:177], v[56:59]
	v_mfma_f32_16x16x32_bf16 v[44:47], v[148:151], v[188:191], v[44:47]
	v_mfma_f32_16x16x32_bf16 v[40:43], v[166:169], v[188:191], v[40:43]
	v_mfma_f32_16x16x32_bf16 v[28:31], v[148:151], v[200:203], v[28:31]
	v_mfma_f32_16x16x32_bf16 v[24:27], v[166:169], v[200:203], v[24:27]
	v_mfma_f32_16x16x32_bf16 v[12:15], v[148:151], v[210:213], v[12:15]
	v_mfma_f32_16x16x32_bf16 v[8:11], v[166:169], v[210:213], v[8:11]
	v_mfma_f32_16x16x32_bf16 v[60:63], v[162:165], v[178:181], v[60:63]
	v_mfma_f32_16x16x32_bf16 v[56:59], v[170:173], v[178:181], v[56:59]
	v_mfma_f32_16x16x32_bf16 v[44:47], v[162:165], v[196:199], v[44:47]
	v_mfma_f32_16x16x32_bf16 v[40:43], v[170:173], v[196:199], v[40:43]
	v_mfma_f32_16x16x32_bf16 v[28:31], v[162:165], v[206:209], v[28:31]
	v_mfma_f32_16x16x32_bf16 v[24:27], v[170:173], v[206:209], v[24:27]
	v_mfma_f32_16x16x32_bf16 v[12:15], v[162:165], v[214:217], v[12:15]
	v_mfma_f32_16x16x32_bf16 v[8:11], v[170:173], v[214:217], v[8:11]
	s_setprio 0
	s_barrier
	s_add_u32 s0, s40, 0x90080
	s_addc_u32 s1, s41, 0
	s_add_i32 s4, s5, s52
	s_mov_b32 m0, s4
	s_nop 0
	global_load_lds_dwordx4 v130, s[0:1]
	s_add_i32 m0, s4, 0x2000
	s_nop 0
	global_load_lds_dwordx4 v134, s[0:1]
	s_waitcnt vmcnt(6)
	s_barrier
	s_setprio 1
	v_mfma_f32_16x16x32_bf16 v[52:55], v[218:221], v[174:177], v[52:55]
	v_mfma_f32_16x16x32_bf16 v[48:51], v[226:229], v[174:177], v[48:51]
	v_mfma_f32_16x16x32_bf16 v[36:39], v[218:221], v[188:191], v[36:39]
	v_mfma_f32_16x16x32_bf16 v[32:35], v[226:229], v[188:191], v[32:35]
	v_mfma_f32_16x16x32_bf16 v[20:23], v[218:221], v[200:203], v[20:23]
	v_mfma_f32_16x16x32_bf16 v[16:19], v[226:229], v[200:203], v[16:19]
	v_mfma_f32_16x16x32_bf16 v[4:7], v[218:221], v[210:213], v[4:7]
	v_mfma_f32_16x16x32_bf16 v[0:3], v[226:229], v[210:213], v[0:3]
	v_mfma_f32_16x16x32_bf16 v[52:55], v[222:225], v[178:181], v[52:55]
	v_mfma_f32_16x16x32_bf16 v[48:51], v[230:233], v[178:181], v[48:51]
	v_mfma_f32_16x16x32_bf16 v[36:39], v[222:225], v[196:199], v[36:39]
	v_mfma_f32_16x16x32_bf16 v[32:35], v[230:233], v[196:199], v[32:35]
	v_mfma_f32_16x16x32_bf16 v[20:23], v[222:225], v[206:209], v[20:23]
	v_mfma_f32_16x16x32_bf16 v[16:19], v[230:233], v[206:209], v[16:19]
	v_mfma_f32_16x16x32_bf16 v[4:7], v[222:225], v[214:217], v[4:7]
	v_mfma_f32_16x16x32_bf16 v[0:3], v[230:233], v[214:217], v[0:3]
	s_setprio 0
	s_add_i32 s70, s70, 2
	s_add_u32 s8, s8, 0x100
	s_addc_u32 s9, s9, 0
	s_cmp_gt_u32 s70, 33
	s_barrier
	s_cbranch_scc1 .LBB0_1908

;     DI size_t aoff(const Unit& u, size_t tstep) const { return (size_t)u.pm * tstep; }
;     DI size_t boff(const Unit& u, size_t tstep) const { return (size_t)u.pn * tstep; }
;     DI bool next(int i, Unit& u) const { const long L = (long)i * G + c; if (L >= np) return false; u.pm = pmv; u.pn = (int)(L % nN); u.ks = (int)(L / nN); return true; }
;     DI size_t aoff(const Unit& u, size_t) const { return (size_t)u.ks * kbytes; }
;     DI size_t boff(const Unit& u, size_t tstep) const { return (size_t)u.pn * tstep + (size_t)u.ks * kbytes; }
;     DI bool next(int i, Unit& u) const { Unit t; if (!S.next(i / 3, t)) return false; u.pm = t.pm; u.pn = t.pn; u.ks = i % 3; return true; }
;     DI size_t aoff(const Unit& u, size_t tstep) const { return (u.ks < 2 ? offU : offOA) + (size_t)u.pm * tstep; }
; #define PG8_WAIT_V(n) asm volatile("s_waitcnt vmcnt(" #n ")" ::: "memory")
; template <class Epi, class Sched>
; DI void gemm_phase(LAS unsigned char* lds, const Gemm g, const Sched& S, const Epi& E) {
;     ...
;     for (;;) {
;         const bool has_next = S.next(ui + 1, nxt);
;         const char* nA = has_next ? (const char*)g.A + S.aoff(nxt, tstep) : cA; const char* nB = has_next ? (const char*)g.Bt + S.boff(nxt, tstep) : cB;
;         for (int t = 0; t < nt; t += 2) {
;             if constexpr (Epi::HAS_MID) { if (t == E.mid_t(nt)) { int fr3 = fr, fq3 = fq; asm volatile("" : "+v"(fr3), "+v"(fq3)); E.mid(acc, cur, wr, wc, fr3, fq3); } }
;             const bool last = (t == nt - 2);
;             const char* a1 = cA + (size_t)(t + 1) * kstep;
;             const char* a2 = last ? nA : cA + (size_t)(t + 2) * kstep; const char* b2 = last ? nB : cB + (size_t)(t + 2) * kstep;
;             const char* a3 = a2 + kstep; const char* b3 = b2 + kstep;
;             PG8_LDB(B0, 0, 0); PG8_SCHED; PG8_LDA(At, 0, 0); PG8_STAGE(PG8_SA(1, 1), a1 + hstep, voffA);
;             PG8_WAIT_L(8); PG8_BAR; PG8_WAIT_L(0); PG8_MMA(0, 0, At, B0); PG8_BAR; PG8_SCHED;
;             PG8_LDB(B1, 0, 1); PG8_STAGE(PG8_SB(0, 0), b2, voffB);
;             PG8_BAR; PG8_WAIT_L(0); PG8_MMA(0, 1, At, B1); PG8_BAR;
;             PG8_LDA(At, 0, 1); PG8_STAGE(PG8_SA(0, 0), a2, voffA);
;             PG8_BAR; PG8_WAIT_L(0); PG8_MMA(1, 0, At, B0); PG8_BAR; PG8_SCHED;
;             PG8_STAGE(PG8_SB(0, 1), b2 + hstep, voffB);
;             PG8_WAIT_V(6); PG8_BAR; PG8_MMA(1, 1, At, B1); PG8_BAR;
.LBB0_1935:
	s_add_u32 s33, s18, s0
	s_addc_u32 s40, s19, 0
	s_add_u32 s1, s33, 0x100
	s_addc_u32 s41, s40, 0
	s_and_b64 s[4:5], s[38:39], exec
	s_cselect_b32 s45, s15, s41
	s_cselect_b32 s44, s29, s1
	s_add_u32 s0, s16, s0
	s_addc_u32 s1, s17, 0
	s_add_u32 s4, s0, 0x100
	s_addc_u32 s5, s1, 0
	s_and_b64 s[0:1], s[38:39], exec
	s_cselect_b32 s47, s31, s5
	s_cselect_b32 s46, s30, s4
	s_add_u32 s48, s33, 0x90080
	s_addc_u32 s49, s40, 0
	s_add_u32 s42, s46, 0x90000
	ds_read_b128 v[140:143], v137
	ds_read_b128 v[144:147], v137 offset:1024
	ds_read_b128 v[148:151], v137 offset:2048
	ds_read_b128 v[154:157], v137 offset:3072
	s_addc_u32 s43, s47, 0
	s_add_i32 s33, s72, 0x2000
	s_add_i32 s5, 0, 0x18000
	s_add_u32 s40, s44, 0x90000
	s_addc_u32 s41, s45, 0
	s_add_i32 s4, s5, s52
	s_add_i32 s1, 0, 0x1c000
	s_add_i32 s0, s4, 0x2000
	s_add_u32 s38, s46, 0x90080
	s_addc_u32 s39, s47, 0
	s_add_i32 s75, s1, s52
	s_add_i32 s74, s75, 0x2000
	s_mov_b32 m0, s68
	ds_read_b128 v[158:161], v138
	ds_read_b128 v[162:165], v138 offset:1024
	ds_read_b128 v[166:169], v138 offset:2048
	ds_read_b128 v[170:173], v138 offset:3072
	ds_read_b128 v[174:177], v138 offset:4096
	ds_read_b128 v[178:181], v138 offset:5120
	ds_read_b128 v[188:191], v138 offset:6144
	global_load_lds_dwordx4 v130, s[48:49]
	s_mov_b32 m0, s69
	ds_read_b128 v[196:199], v138 offset:7168
	global_load_lds_dwordx4 v128, s[48:49]
	s_waitcnt lgkmcnt(8)
	s_barrier
	s_waitcnt lgkmcnt(0)
	s_setprio 1
	v_mfma_f32_16x16x32_bf16 v[124:127], v[140:143], v[158:161], v[124:127]
	v_mfma_f32_16x16x32_bf16 v[120:123], v[148:151], v[158:161], v[120:123]
	v_mfma_f32_16x16x32_bf16 v[116:119], v[140:143], v[166:169], v[116:119]
	v_mfma_f32_16x16x32_bf16 v[112:115], v[148:151], v[166:169], v[112:115]
	v_mfma_f32_16x16x32_bf16 v[104:107], v[140:143], v[174:177], v[104:107]
	v_mfma_f32_16x16x32_bf16 v[96:99], v[148:151], v[174:177], v[96:99]
	v_mfma_f32_16x16x32_bf16 v[88:91], v[140:143], v[188:191], v[88:91]
	v_mfma_f32_16x16x32_bf16 v[80:83], v[148:151], v[188:191], v[80:83]
	v_mfma_f32_16x16x32_bf16 v[124:127], v[144:147], v[162:165], v[124:127]
	v_mfma_f32_16x16x32_bf16 v[120:123], v[154:157], v[162:165], v[120:123]
	v_mfma_f32_16x16x32_bf16 v[116:119], v[144:147], v[170:173], v[116:119]
	v_mfma_f32_16x16x32_bf16 v[112:115], v[154:157], v[170:173], v[112:115]
	v_mfma_f32_16x16x32_bf16 v[104:107], v[144:147], v[178:181], v[104:107]
	v_mfma_f32_16x16x32_bf16 v[96:99], v[154:157], v[178:181], v[96:99]
	v_mfma_f32_16x16x32_bf16 v[88:91], v[144:147], v[196:199], v[88:91]
	v_mfma_f32_16x16x32_bf16 v[80:83], v[154:157], v[196:199], v[80:83]
	s_setprio 0
	s_barrier
	s_mov_b32 m0, s70
	ds_read_b128 v[200:203], v139
	ds_read_b128 v[206:209], v139 offset:1024
	ds_read_b128 v[210:213], v139 offset:2048
	global_load_lds_dwordx4 v130, s[46:47]
	s_mov_b32 m0, s71
	ds_read_b128 v[214:217], v139 offset:3072
	global_load_lds_dwordx4 v128, s[46:47]
	s_barrier
	s_waitcnt lgkmcnt(0)
	s_setprio 1
	v_mfma_f32_16x16x32_bf16 v[108:111], v[200:203], v[158:161], v[108:111]
	v_mfma_f32_16x16x32_bf16 v[100:103], v[210:213], v[158:161], v[100:103]
	v_mfma_f32_16x16x32_bf16 v[92:95], v[200:203], v[166:169], v[92:95]
	v_mfma_f32_16x16x32_bf16 v[84:87], v[210:213], v[166:169], v[84:87]
	v_mfma_f32_16x16x32_bf16 v[76:79], v[200:203], v[174:177], v[76:79]
	v_mfma_f32_16x16x32_bf16 v[72:75], v[210:213], v[174:177], v[72:75]
	v_mfma_f32_16x16x32_bf16 v[68:71], v[200:203], v[188:191], v[68:71]
	v_mfma_f32_16x16x32_bf16 v[64:67], v[210:213], v[188:191], v[64:67]
	v_mfma_f32_16x16x32_bf16 v[108:111], v[206:209], v[162:165], v[108:111]
	v_mfma_f32_16x16x32_bf16 v[100:103], v[214:217], v[162:165], v[100:103]
	v_mfma_f32_16x16x32_bf16 v[92:95], v[206:209], v[170:173], v[92:95]
	v_mfma_f32_16x16x32_bf16 v[84:87], v[214:217], v[170:173], v[84:87]
	v_mfma_f32_16x16x32_bf16 v[76:79], v[206:209], v[178:181], v[76:79]
	v_mfma_f32_16x16x32_bf16 v[72:75], v[214:217], v[178:181], v[72:75]
	v_mfma_f32_16x16x32_bf16 v[68:71], v[206:209], v[196:199], v[68:71]
	v_mfma_f32_16x16x32_bf16 v[64:67], v[214:217], v[196:199], v[64:67]
	s_setprio 0
	s_mov_b32 m0, s56
	s_barrier
	ds_read_b128 v[158:161], v138 offset:16384
	ds_read_b128 v[162:165], v138 offset:17408
	ds_read_b128 v[166:169], v138 offset:18432
	ds_read_b128 v[170:173], v138 offset:19456
	ds_read_b128 v[174:177], v138 offset:20480
	ds_read_b128 v[178:181], v138 offset:21504
	ds_read_b128 v[188:191], v138 offset:22528
	global_load_lds_dwordx4 v130, s[44:45]
	s_mov_b32 m0, s57
	ds_read_b128 v[196:199], v138 offset:23552
	global_load_lds_dwordx4 v128, s[44:45]
	s_barrier
	s_waitcnt lgkmcnt(0)
	s_setprio 1
	v_mfma_f32_16x16x32_bf16 v[60:63], v[140:143], v[158:161], v[60:63]
	v_mfma_f32_16x16x32_bf16 v[56:59], v[148:151], v[158:161], v[56:59]
	v_mfma_f32_16x16x32_bf16 v[52:55], v[140:143], v[166:169], v[52:55]
	v_mfma_f32_16x16x32_bf16 v[48:51], v[148:151], v[166:169], v[48:51]
	v_mfma_f32_16x16x32_bf16 v[40:43], v[140:143], v[174:177], v[40:43]
	v_mfma_f32_16x16x32_bf16 v[32:35], v[148:151], v[174:177], v[32:35]
	v_mfma_f32_16x16x32_bf16 v[24:27], v[140:143], v[188:191], v[24:27]
	v_mfma_f32_16x16x32_bf16 v[16:19], v[148:151], v[188:191], v[16:19]
	v_mfma_f32_16x16x32_bf16 v[60:63], v[144:147], v[162:165], v[60:63]
	v_mfma_f32_16x16x32_bf16 v[56:59], v[154:157], v[162:165], v[56:59]
	v_mfma_f32_16x16x32_bf16 v[52:55], v[144:147], v[170:173], v[52:55]
	v_mfma_f32_16x16x32_bf16 v[48:51], v[154:157], v[170:173], v[48:51]
	v_mfma_f32_16x16x32_bf16 v[40:43], v[144:147], v[178:181], v[40:43]
	v_mfma_f32_16x16x32_bf16 v[32:35], v[154:157], v[178:181], v[32:35]
	v_mfma_f32_16x16x32_bf16 v[24:27], v[144:147], v[196:199], v[24:27]
	v_mfma_f32_16x16x32_bf16 v[16:19], v[154:157], v[196:199], v[16:19]
	s_setprio 0
	s_barrier
; #define PG8_STAGE(bufoff, gbase, voff) do { _Pragma("unroll") for (int _i = 0; _i < 2; ++_i) \
;         __builtin_amdgcn_global_load_lds((const unsigned*)((const char*)(gbase) + (voff)[_i]), (LAS unsigned*)(lds + (bufoff) + ldsw + _i * 8192), 16, 0, 0); } while (0)
; #define PG8_LDA(dst, b, h) do { _Pragma("unroll") for (int m = 0; m < 4; ++m) _Pragma("unroll") for (int k = 0; k < 2; ++k) dst[m][k] = *(const LAS bf16x8*)(lds + PG8_SA(b, h) + aoff + m * 2048 + k * 1024); } while (0)
; #define PG8_LDB(dst, b, h) do { _Pragma("unroll") for (int n = 0; n < 2; ++n) _Pragma("unroll") for (int k = 0; k < 2; ++k) dst[n][k] = *(const LAS bf16x8*)(lds + PG8_SB(b, h) + boff + n * 2048 + k * 1024); } while (0)
; #define PG8_MMA(ai, bj, At, Bt) do { __builtin_amdgcn_s_setprio(1); _Pragma("unroll") for (int m = 0; m < 4; ++m) _Pragma("unroll") for (int n = 0; n < 2; ++n) _Pragma("unroll") for (int k = 0; k < 2; ++k) \
;         acc[ai][bj][m][n] = __builtin_amdgcn_mfma_f32_16x16x32_bf16(Bt[n][k], At[m][k], acc[ai][bj][m][n], 0, 0, 0); __builtin_amdgcn_s_setprio(0); } while (0)
; #define PG8_WAIT_V(n) asm volatile("s_waitcnt vmcnt(" #n ")" ::: "memory")
; #define PG8_WAIT_L(n) asm volatile("s_waitcnt lgkmcnt(" #n ")" ::: "memory")
; #define PG8_BAR __builtin_amdgcn_s_barrier()
; #define PG8_SCHED __builtin_amdgcn_sched_barrier(0)
; template <class Epi, class Sched>
; DI void gemm_phase(LAS unsigned char* lds, const Gemm g, const Sched& S, const Epi& E) {
;     ...
;             PG8_STAGE(PG8_SB(0, 1), b2 + hstep, voffB);
;             PG8_WAIT_V(6); PG8_BAR; PG8_MMA(1, 1, At, B1); PG8_BAR;
;             PG8_LDB(B0, 1, 0); PG8_SCHED; PG8_LDA(At, 1, 0); PG8_STAGE(PG8_SA(0, 1), a2 + hstep, voffA);
;             PG8_WAIT_L(8); PG8_BAR; PG8_WAIT_L(0); PG8_MMA(0, 0, At, B0); PG8_BAR; PG8_SCHED;
;             PG8_LDB(B1, 1, 1); PG8_STAGE(PG8_SB(1, 0), b3, voffB);
;             PG8_BAR; PG8_WAIT_L(0); PG8_MMA(0, 1, At, B1); PG8_BAR;
;             PG8_LDA(At, 1, 1); PG8_STAGE(PG8_SA(1, 0), a3, voffA);
;             PG8_BAR; PG8_WAIT_L(0); PG8_MMA(1, 0, At, B0); PG8_BAR; PG8_SCHED;
	s_mov_b32 m0, s72
	s_nop 0
	global_load_lds_dwordx4 v130, s[42:43]
	s_mov_b32 m0, s33
	s_nop 0
	global_load_lds_dwordx4 v128, s[42:43]
	s_waitcnt vmcnt(6)
	s_barrier
	s_setprio 1
	v_mfma_f32_16x16x32_bf16 v[44:47], v[200:203], v[158:161], v[44:47]
	v_mfma_f32_16x16x32_bf16 v[36:39], v[210:213], v[158:161], v[36:39]
	v_mfma_f32_16x16x32_bf16 v[28:31], v[200:203], v[166:169], v[28:31]
	v_mfma_f32_16x16x32_bf16 v[20:23], v[210:213], v[166:169], v[20:23]
	v_mfma_f32_16x16x32_bf16 v[12:15], v[200:203], v[174:177], v[12:15]
	v_mfma_f32_16x16x32_bf16 v[8:11], v[210:213], v[174:177], v[8:11]
	v_mfma_f32_16x16x32_bf16 v[4:7], v[200:203], v[188:191], v[4:7]
	v_mfma_f32_16x16x32_bf16 v[0:3], v[210:213], v[188:191], v[0:3]
	v_mfma_f32_16x16x32_bf16 v[44:47], v[206:209], v[162:165], v[44:47]
	v_mfma_f32_16x16x32_bf16 v[36:39], v[214:217], v[162:165], v[36:39]
	v_mfma_f32_16x16x32_bf16 v[28:31], v[206:209], v[170:173], v[28:31]
	v_mfma_f32_16x16x32_bf16 v[20:23], v[214:217], v[170:173], v[20:23]
	v_mfma_f32_16x16x32_bf16 v[12:15], v[206:209], v[178:181], v[12:15]
	v_mfma_f32_16x16x32_bf16 v[8:11], v[214:217], v[178:181], v[8:11]
	v_mfma_f32_16x16x32_bf16 v[4:7], v[206:209], v[196:199], v[4:7]
	v_mfma_f32_16x16x32_bf16 v[0:3], v[214:217], v[196:199], v[0:3]
	s_setprio 0
	v_add_u32_e32 v153, s5, v136
	s_barrier
	ds_read_b128 v[140:143], v153
	ds_read_b128 v[144:147], v153 offset:1024
	ds_read_b128 v[148:151], v153 offset:2048
	ds_read_b128 v[154:157], v153 offset:3072
	s_mov_b32 m0, s58
	ds_read_b128 v[158:161], v138 offset:32768
	ds_read_b128 v[162:165], v138 offset:33792
	ds_read_b128 v[166:169], v138 offset:34816
	ds_read_b128 v[170:173], v138 offset:35840
	ds_read_b128 v[174:177], v138 offset:36864
	ds_read_b128 v[178:181], v138 offset:37888
	ds_read_b128 v[188:191], v138 offset:38912
	global_load_lds_dwordx4 v130, s[40:41]
	s_mov_b32 m0, s59
	ds_read_b128 v[196:199], v138 offset:39936
	global_load_lds_dwordx4 v128, s[40:41]
	s_waitcnt lgkmcnt(8)
	s_barrier
	s_waitcnt lgkmcnt(0)
	s_setprio 1
	v_mfma_f32_16x16x32_bf16 v[124:127], v[140:143], v[158:161], v[124:127]
	v_mfma_f32_16x16x32_bf16 v[120:123], v[148:151], v[158:161], v[120:123]
	v_mfma_f32_16x16x32_bf16 v[116:119], v[140:143], v[166:169], v[116:119]
	v_mfma_f32_16x16x32_bf16 v[112:115], v[148:151], v[166:169], v[112:115]
	v_mfma_f32_16x16x32_bf16 v[104:107], v[140:143], v[174:177], v[104:107]
	v_mfma_f32_16x16x32_bf16 v[96:99], v[148:151], v[174:177], v[96:99]
	v_mfma_f32_16x16x32_bf16 v[88:91], v[140:143], v[188:191], v[88:91]
	v_mfma_f32_16x16x32_bf16 v[80:83], v[148:151], v[188:191], v[80:83]
	v_mfma_f32_16x16x32_bf16 v[124:127], v[144:147], v[162:165], v[124:127]
	v_mfma_f32_16x16x32_bf16 v[120:123], v[154:157], v[162:165], v[120:123]
	v_mfma_f32_16x16x32_bf16 v[116:119], v[144:147], v[170:173], v[116:119]
	v_mfma_f32_16x16x32_bf16 v[112:115], v[154:157], v[170:173], v[112:115]
	v_mfma_f32_16x16x32_bf16 v[104:107], v[144:147], v[178:181], v[104:107]
	v_mfma_f32_16x16x32_bf16 v[96:99], v[154:157], v[178:181], v[96:99]
	v_mfma_f32_16x16x32_bf16 v[88:91], v[144:147], v[196:199], v[88:91]
	v_mfma_f32_16x16x32_bf16 v[80:83], v[154:157], v[196:199], v[80:83]
	s_setprio 0
	s_barrier
	s_add_i32 m0, s4, 0xffffff80
	v_add_u32_e32 v153, s1, v136
	ds_read_b128 v[200:203], v153
	ds_read_b128 v[206:209], v153 offset:1024
	ds_read_b128 v[210:213], v153 offset:2048
	global_load_lds_dwordx4 v130, s[46:47] offset:128
	s_add_i32 m0, s0, 0xffffff80
	ds_read_b128 v[214:217], v153 offset:3072
	global_load_lds_dwordx4 v128, s[46:47] offset:128
	s_barrier
	s_waitcnt lgkmcnt(0)
	s_setprio 1
	v_mfma_f32_16x16x32_bf16 v[108:111], v[200:203], v[158:161], v[108:111]
	v_mfma_f32_16x16x32_bf16 v[100:103], v[210:213], v[158:161], v[100:103]
	v_mfma_f32_16x16x32_bf16 v[92:95], v[200:203], v[166:169], v[92:95]
	v_mfma_f32_16x16x32_bf16 v[84:87], v[210:213], v[166:169], v[84:87]
	v_mfma_f32_16x16x32_bf16 v[76:79], v[200:203], v[174:177], v[76:79]
	v_mfma_f32_16x16x32_bf16 v[72:75], v[210:213], v[174:177], v[72:75]
	v_mfma_f32_16x16x32_bf16 v[68:71], v[200:203], v[188:191], v[68:71]
	v_mfma_f32_16x16x32_bf16 v[64:67], v[210:213], v[188:191], v[64:67]
	v_mfma_f32_16x16x32_bf16 v[108:111], v[206:209], v[162:165], v[108:111]
	v_mfma_f32_16x16x32_bf16 v[100:103], v[214:217], v[162:165], v[100:103]
	v_mfma_f32_16x16x32_bf16 v[92:95], v[206:209], v[170:173], v[92:95]
	v_mfma_f32_16x16x32_bf16 v[84:87], v[214:217], v[170:173], v[84:87]
	v_mfma_f32_16x16x32_bf16 v[76:79], v[206:209], v[178:181], v[76:79]
	v_mfma_f32_16x16x32_bf16 v[72:75], v[214:217], v[178:181], v[72:75]
	v_mfma_f32_16x16x32_bf16 v[68:71], v[206:209], v[196:199], v[68:71]
	v_mfma_f32_16x16x32_bf16 v[64:67], v[214:217], v[196:199], v[64:67]
	s_setprio 0
	s_add_i32 m0, s66, 0xffffff80
	s_barrier
	ds_read_b128 v[158:161], v138 offset:49152
	ds_read_b128 v[162:165], v138 offset:50176
	ds_read_b128 v[166:169], v138 offset:51200
	ds_read_b128 v[170:173], v138 offset:52224
	ds_read_b128 v[174:177], v138 offset:53248
	ds_read_b128 v[178:181], v138 offset:54272
	ds_read_b128 v[188:191], v138 offset:55296
	global_load_lds_dwordx4 v130, s[44:45] offset:128
	s_add_i32 m0, s67, 0xffffff80
	ds_read_b128 v[196:199], v138 offset:56320
	global_load_lds_dwordx4 v128, s[44:45] offset:128
	s_barrier
; #define PG8_STAGE(bufoff, gbase, voff) do { _Pragma("unroll") for (int _i = 0; _i < 2; ++_i) \
;         __builtin_amdgcn_global_load_lds((const unsigned*)((const char*)(gbase) + (voff)[_i]), (LAS unsigned*)(lds + (bufoff) + ldsw + _i * 8192), 16, 0, 0); } while (0)
; #define PG8_MMA(ai, bj, At, Bt) do { __builtin_amdgcn_s_setprio(1); _Pragma("unroll") for (int m = 0; m < 4; ++m) _Pragma("unroll") for (int n = 0; n < 2; ++n) _Pragma("unroll") for (int k = 0; k < 2; ++k) \
;         acc[ai][bj][m][n] = __builtin_amdgcn_mfma_f32_16x16x32_bf16(Bt[n][k], At[m][k], acc[ai][bj][m][n], 0, 0, 0); __builtin_amdgcn_s_setprio(0); } while (0)
; #define PG8_WAIT_V(n) asm volatile("s_waitcnt vmcnt(" #n ")" ::: "memory")
; #define PG8_WAIT_L(n) asm volatile("s_waitcnt lgkmcnt(" #n ")" ::: "memory")
; #define PG8_BAR __builtin_amdgcn_s_barrier()
; #define PG8_SCHED __builtin_amdgcn_sched_barrier(0)
; template <class Epi, class Sched>
; DI void gemm_phase(LAS unsigned char* lds, const Gemm g, const Sched& S, const Epi& E) {
;     ...
;             PG8_BAR; PG8_WAIT_L(0); PG8_MMA(1, 0, At, B0); PG8_BAR; PG8_SCHED;
;             PG8_STAGE(PG8_SB(1, 1), b3 + hstep, voffB);
;             PG8_WAIT_V(6); PG8_BAR; PG8_MMA(1, 1, At, B1); PG8_BAR;
;         }
;         { int fr2 = fr, fq2 = fq; asm volatile("" : "+v"(fr2), "+v"(fq2)); E(acc, cur, wr, wc, fr2, fq2); }
;         if (!has_next) break;
;     DI void operator()(AccRef acc, const Unit& u, int wr, int wc, int fr, int fq) const {
;         float* base = P + (size_t)slot0 * 256 * DM + (size_t)u.ks * 256 * ld; const int col0 = u.pn * 256 + wc * 32 + 4 * fq;
; #pragma unroll
;         for (int ai = 0; ai < 2; ++ai)
; #pragma unroll
;             for (int m = 0; m < 4; ++m) { const size_t off = (size_t)(ai * 128 + wr * 64 + m * 16 + fr) * ld + col0;
; #pragma unroll
;                 for (int bj = 0; bj < 2; ++bj)
; #pragma unroll
;                     for (int n = 0; n < 2; ++n) *(f32x4*)(base + off + bj * 128 + n * 16) = acc[ai][bj][m][n]; }
;     }
	s_waitcnt lgkmcnt(0)
	s_setprio 1
	v_mfma_f32_16x16x32_bf16 v[60:63], v[140:143], v[158:161], v[60:63]
	v_mfma_f32_16x16x32_bf16 v[56:59], v[148:151], v[158:161], v[56:59]
	v_mfma_f32_16x16x32_bf16 v[52:55], v[140:143], v[166:169], v[52:55]
	v_mfma_f32_16x16x32_bf16 v[48:51], v[148:151], v[166:169], v[48:51]
	v_mfma_f32_16x16x32_bf16 v[40:43], v[140:143], v[174:177], v[40:43]
	v_mfma_f32_16x16x32_bf16 v[32:35], v[148:151], v[174:177], v[32:35]
	v_mfma_f32_16x16x32_bf16 v[24:27], v[140:143], v[188:191], v[24:27]
	v_mfma_f32_16x16x32_bf16 v[16:19], v[148:151], v[188:191], v[16:19]
	v_mfma_f32_16x16x32_bf16 v[60:63], v[144:147], v[162:165], v[60:63]
	v_mfma_f32_16x16x32_bf16 v[56:59], v[154:157], v[162:165], v[56:59]
	v_mfma_f32_16x16x32_bf16 v[52:55], v[144:147], v[170:173], v[52:55]
	v_mfma_f32_16x16x32_bf16 v[48:51], v[154:157], v[170:173], v[48:51]
	v_mfma_f32_16x16x32_bf16 v[40:43], v[144:147], v[178:181], v[40:43]
	v_mfma_f32_16x16x32_bf16 v[32:35], v[154:157], v[178:181], v[32:35]
	v_mfma_f32_16x16x32_bf16 v[24:27], v[144:147], v[196:199], v[24:27]
	v_mfma_f32_16x16x32_bf16 v[16:19], v[154:157], v[196:199], v[16:19]
	s_setprio 0
	s_barrier
	s_mov_b32 m0, s75
	s_nop 0
	global_load_lds_dwordx4 v130, s[38:39]
	s_mov_b32 m0, s74
	s_nop 0
	global_load_lds_dwordx4 v128, s[38:39]
	s_waitcnt vmcnt(6)
	s_barrier
	s_setprio 1
	v_mfma_f32_16x16x32_bf16 v[44:47], v[200:203], v[158:161], v[44:47]
	v_mfma_f32_16x16x32_bf16 v[36:39], v[210:213], v[158:161], v[36:39]
	v_mfma_f32_16x16x32_bf16 v[28:31], v[200:203], v[166:169], v[28:31]
	v_mfma_f32_16x16x32_bf16 v[20:23], v[210:213], v[166:169], v[20:23]
	v_mfma_f32_16x16x32_bf16 v[12:15], v[200:203], v[174:177], v[12:15]
	v_mfma_f32_16x16x32_bf16 v[8:11], v[210:213], v[174:177], v[8:11]
	v_mfma_f32_16x16x32_bf16 v[4:7], v[200:203], v[188:191], v[4:7]
	v_mfma_f32_16x16x32_bf16 v[0:3], v[210:213], v[188:191], v[0:3]
	v_mfma_f32_16x16x32_bf16 v[44:47], v[206:209], v[162:165], v[44:47]
	v_mfma_f32_16x16x32_bf16 v[36:39], v[214:217], v[162:165], v[36:39]
	v_mfma_f32_16x16x32_bf16 v[28:31], v[206:209], v[170:173], v[28:31]
	v_mfma_f32_16x16x32_bf16 v[20:23], v[214:217], v[170:173], v[20:23]
	v_mfma_f32_16x16x32_bf16 v[12:15], v[206:209], v[178:181], v[12:15]
	v_mfma_f32_16x16x32_bf16 v[8:11], v[214:217], v[178:181], v[8:11]
	v_mfma_f32_16x16x32_bf16 v[4:7], v[206:209], v[196:199], v[4:7]
	v_mfma_f32_16x16x32_bf16 v[0:3], v[214:217], v[196:199], v[0:3]
	s_setprio 0
	s_movk_i32 s0, 0x100
	s_andn2_b64 vcc, exec, s[8:9]
	s_mov_b64 s[38:39], -1
	s_mov_b64 s[8:9], 0
	s_barrier
	s_cbranch_vccz .LBB0_1935
	s_ashr_i32 s15, s14, 31
	s_lshl_b64 s[0:1], s[14:15], 21
	s_add_u32 s0, s63, s0
	v_mov_b32_e32 v141, v194
	v_mov_b32_e32 v140, v192
	s_addc_u32 s1, s64, s1
	s_lshl_b32 s4, s65, 8
	s_or_b32 s4, s4, s62
	v_lshl_add_u32 v140, v140, 2, s4
	v_add_u32_e32 v142, s61, v141
	v_ashrrev_i32_e32 v141, 31, v140
	v_ashrrev_i32_e32 v143, 31, v142
	v_lshl_add_u64 v[140:141], v[140:141], 2, s[0:1]
	v_lshlrev_b64 v[144:145], 13, v[142:143]
	v_lshl_add_u64 v[144:145], v[140:141], 0, v[144:145]
	global_store_dwordx4 v[144:145], v[124:127], off
	global_store_dwordx4 v[144:145], v[120:123], off offset:64
	global_store_dwordx4 v[144:145], v[108:111], off offset:512
	global_store_dwordx4 v[144:145], v[100:103], off offset:576
	s_and_b64 vcc, exec, s[6:7]
	s_mov_b32 s14, s28
	v_add_u32_e32 v100, 16, v142
	v_ashrrev_i32_e32 v101, 31, v100
	v_lshlrev_b64 v[100:101], 13, v[100:101]
	v_lshl_add_u64 v[100:101], v[140:141], 0, v[100:101]
	global_store_dwordx4 v[100:101], v[116:119], off
	global_store_dwordx4 v[100:101], v[112:115], off offset:64
	global_store_dwordx4 v[100:101], v[92:95], off offset:512
	global_store_dwordx4 v[100:101], v[84:87], off offset:576
	s_mov_b32 s65, s73
	s_mov_b64 s[16:17], s[30:31]
	v_add_u32_e32 v84, 32, v142
	v_ashrrev_i32_e32 v85, 31, v84
	v_lshlrev_b64 v[84:85], 13, v[84:85]
	v_lshl_add_u64 v[84:85], v[140:141], 0, v[84:85]
	global_store_dwordx4 v[84:85], v[104:107], off
	global_store_dwordx4 v[84:85], v[96:99], off offset:64
	global_store_dwordx4 v[84:85], v[76:79], off offset:512
	global_store_dwordx4 v[84:85], v[72:75], off offset:576
	s_mov_b64 s[18:19], s[36:37]
	s_nop 0
	v_add_u32_e32 v72, 48, v142
	v_ashrrev_i32_e32 v73, 31, v72
	v_lshlrev_b64 v[72:73], 13, v[72:73]
	v_lshl_add_u64 v[72:73], v[140:141], 0, v[72:73]
	global_store_dwordx4 v[72:73], v[88:91], off
	global_store_dwordx4 v[72:73], v[80:83], off offset:64
	global_store_dwordx4 v[72:73], v[68:71], off offset:512
	global_store_dwordx4 v[72:73], v[64:67], off offset:576
	s_nop 1
	v_add_u32_e32 v64, 0x80, v142
	v_ashrrev_i32_e32 v65, 31, v64
	v_lshlrev_b64 v[64:65], 13, v[64:65]
	v_lshl_add_u64 v[64:65], v[140:141], 0, v[64:65]
	global_store_dwordx4 v[64:65], v[60:63], off
	global_store_dwordx4 v[64:65], v[56:59], off offset:64
	global_store_dwordx4 v[64:65], v[44:47], off offset:512
	global_store_dwordx4 v[64:65], v[36:39], off offset:576
	s_nop 1
	v_add_u32_e32 v36, 0x90, v142
	v_ashrrev_i32_e32 v37, 31, v36
	v_lshlrev_b64 v[36:37], 13, v[36:37]
	v_lshl_add_u64 v[36:37], v[140:141], 0, v[36:37]
	global_store_dwordx4 v[36:37], v[52:55], off
	global_store_dwordx4 v[36:37], v[48:51], off offset:64
	global_store_dwordx4 v[36:37], v[28:31], off offset:512
	global_store_dwordx4 v[36:37], v[20:23], off offset:576
	s_nop 1
	v_add_u32_e32 v20, 0xa0, v142
	v_ashrrev_i32_e32 v21, 31, v20
	v_lshlrev_b64 v[20:21], 13, v[20:21]
	v_lshl_add_u64 v[20:21], v[140:141], 0, v[20:21]
	global_store_dwordx4 v[20:21], v[40:43], off
	global_store_dwordx4 v[20:21], v[32:35], off offset:64
	global_store_dwordx4 v[20:21], v[12:15], off offset:512
	global_store_dwordx4 v[20:21], v[8:11], off offset:576
	s_nop 1
	v_add_u32_e32 v8, 0xb0, v142
	v_ashrrev_i32_e32 v9, 31, v8
	v_lshlrev_b64 v[8:9], 13, v[8:9]
	v_lshl_add_u64 v[8:9], v[140:141], 0, v[8:9]
	global_store_dwordx4 v[8:9], v[24:27], off
	global_store_dwordx4 v[8:9], v[16:19], off offset:64
	global_store_dwordx4 v[8:9], v[4:7], off offset:512
	global_store_dwordx4 v[8:9], v[0:3], off offset:576
	s_cbranch_vccz .LBB0_1930
	s_waitcnt vmcnt(0)
	s_cmpk_gt_u32 s35, 0xff
	s_cbranch_scc1 .LBB0_1939
	s_barrier
